# v063 + GEMM loops: compiler's duplicate s_waitcnt lgkmcnt(0) behind the template's identical asm wait deleted
# speedup vs baseline: 1.0024x; 1.0014x over previous
.LBB0_329:
	s_add_u32 s19, s16, 0xfff80080
	s_addc_u32 s26, s17, -1
	s_add_i32 s31, 0, 0x10000
	v_add_u32_e32 v2, s31, v158
	ds_read_b128 v[132:135], v2
	ds_read_b128 v[148:151], v2 offset:1024
	ds_read_b128 v[152:155], v2 offset:2048
	ds_read_b128 v[160:163], v2 offset:3072
	s_cmp_eq_u32 s15, 28
	s_cselect_b32 s39, s37, s26
	s_cselect_b32 s38, s36, s19
	s_cselect_b32 s27, s49, s14
	s_cselect_b32 s26, s48, s10
	v_lshl_add_u64 v[196:197], s[16:17], 0, v[144:145]
	s_add_i32 m0, s6, 0xc000
	ds_read_b128 v[164:167], v159
	ds_read_b128 v[168:171], v159 offset:1024
	ds_read_b128 v[172:175], v159 offset:2048
	ds_read_b128 v[176:179], v159 offset:3072
	ds_read_b128 v[180:183], v159 offset:4096
	ds_read_b128 v[184:187], v159 offset:5120
	ds_read_b128 v[188:191], v159 offset:6144
	ds_read_b128 v[192:195], v159 offset:7168
	global_load_lds_dwordx4 v[196:197], off
	v_lshl_add_u64 v[196:197], s[16:17], 0, v[146:147]
	s_add_i32 m0, s6, 0xe000
	s_nop 0
	global_load_lds_dwordx4 v[196:197], off
	s_waitcnt lgkmcnt(8)
	s_barrier
	s_waitcnt lgkmcnt(0)
	v_mfma_f32_16x16x32_f16 v[128:131], v[132:135], v[164:167], v[128:131]
	v_mfma_f32_16x16x32_f16 v[124:127], v[152:155], v[164:167], v[124:127]
	v_mfma_f32_16x16x32_f16 v[112:115], v[132:135], v[172:175], v[112:115]
	v_mfma_f32_16x16x32_f16 v[108:111], v[152:155], v[172:175], v[108:111]
	v_mfma_f32_16x16x32_f16 v[96:99], v[132:135], v[180:183], v[96:99]
	v_mfma_f32_16x16x32_f16 v[92:95], v[152:155], v[180:183], v[92:95]
	v_mfma_f32_16x16x32_f16 v[80:83], v[132:135], v[188:191], v[80:83]
	v_mfma_f32_16x16x32_f16 v[76:79], v[152:155], v[188:191], v[76:79]
	v_mfma_f32_16x16x32_f16 v[128:131], v[148:151], v[168:171], v[128:131]
	v_mfma_f32_16x16x32_f16 v[124:127], v[160:163], v[168:171], v[124:127]
	v_mfma_f32_16x16x32_f16 v[112:115], v[148:151], v[176:179], v[112:115]
	v_mfma_f32_16x16x32_f16 v[108:111], v[160:163], v[176:179], v[108:111]
	v_mfma_f32_16x16x32_f16 v[96:99], v[148:151], v[184:187], v[96:99]
	v_mfma_f32_16x16x32_f16 v[92:95], v[160:163], v[184:187], v[92:95]
	v_mfma_f32_16x16x32_f16 v[80:83], v[148:151], v[192:195], v[80:83]
	v_mfma_f32_16x16x32_f16 v[76:79], v[160:163], v[192:195], v[76:79]
	s_barrier
	s_add_i32 s19, 0, 0x14000
	s_add_i32 s31, s31, s5
	v_add_u32_e32 v2, s19, v158
	v_lshl_add_u64 v[214:215], s[26:27], 0, v[138:139]
	s_mov_b32 m0, s31
	ds_read_b128 v[196:199], v2
	ds_read_b128 v[200:203], v2 offset:1024
	ds_read_b128 v[206:209], v2 offset:2048
	ds_read_b128 v[210:213], v2 offset:3072
	global_load_lds_dwordx4 v[214:215], off
	v_lshl_add_u64 v[216:217], s[26:27], 0, v[142:143]
	s_add_i32 m0, s31, 0x2000
	s_nop 0
	global_load_lds_dwordx4 v[216:217], off
	s_barrier
	s_waitcnt lgkmcnt(0)
	v_mfma_f32_16x16x32_f16 v[120:123], v[196:199], v[164:167], v[120:123]
	v_mfma_f32_16x16x32_f16 v[116:119], v[206:209], v[164:167], v[116:119]
	v_mfma_f32_16x16x32_f16 v[104:107], v[196:199], v[172:175], v[104:107]
	v_mfma_f32_16x16x32_f16 v[100:103], v[206:209], v[172:175], v[100:103]
	v_mfma_f32_16x16x32_f16 v[88:91], v[196:199], v[180:183], v[88:91]
	v_mfma_f32_16x16x32_f16 v[84:87], v[206:209], v[180:183], v[84:87]
	v_mfma_f32_16x16x32_f16 v[72:75], v[196:199], v[188:191], v[72:75]
	v_mfma_f32_16x16x32_f16 v[68:71], v[206:209], v[188:191], v[68:71]
	v_mfma_f32_16x16x32_f16 v[120:123], v[200:203], v[168:171], v[120:123]
	v_mfma_f32_16x16x32_f16 v[116:119], v[210:213], v[168:171], v[116:119]
	v_mfma_f32_16x16x32_f16 v[104:107], v[200:203], v[176:179], v[104:107]
	v_mfma_f32_16x16x32_f16 v[100:103], v[210:213], v[176:179], v[100:103]
	v_mfma_f32_16x16x32_f16 v[88:91], v[200:203], v[184:187], v[88:91]
	v_mfma_f32_16x16x32_f16 v[84:87], v[210:213], v[184:187], v[84:87]
	v_mfma_f32_16x16x32_f16 v[72:75], v[200:203], v[192:195], v[72:75]
	v_mfma_f32_16x16x32_f16 v[68:71], v[210:213], v[192:195], v[68:71]
	s_mov_b32 m0, s6
	v_lshl_add_u64 v[218:219], s[38:39], 0, v[136:137]
	s_barrier
	ds_read_b128 v[164:167], v159 offset:16384
	ds_read_b128 v[168:171], v159 offset:17408
	ds_read_b128 v[172:175], v159 offset:18432
	ds_read_b128 v[176:179], v159 offset:19456
	ds_read_b128 v[180:183], v159 offset:20480
	ds_read_b128 v[184:187], v159 offset:21504
	ds_read_b128 v[188:191], v159 offset:22528
	ds_read_b128 v[192:195], v159 offset:23552
	global_load_lds_dwordx4 v[218:219], off
	v_lshl_add_u64 v[220:221], s[38:39], 0, v[140:141]
	s_mov_b32 m0, s7
	s_nop 0
	global_load_lds_dwordx4 v[220:221], off
	s_barrier
	s_waitcnt lgkmcnt(0)
	v_mfma_f32_16x16x32_f16 v[64:67], v[132:135], v[164:167], v[64:67]
	v_mfma_f32_16x16x32_f16 v[60:63], v[152:155], v[164:167], v[60:63]
	v_mfma_f32_16x16x32_f16 v[48:51], v[132:135], v[172:175], v[48:51]
	v_mfma_f32_16x16x32_f16 v[44:47], v[152:155], v[172:175], v[44:47]
	v_mfma_f32_16x16x32_f16 v[32:35], v[132:135], v[180:183], v[32:35]
	v_mfma_f32_16x16x32_f16 v[28:31], v[152:155], v[180:183], v[28:31]
	v_mfma_f32_16x16x32_f16 v[16:19], v[132:135], v[188:191], v[16:19]
	v_mfma_f32_16x16x32_f16 v[12:15], v[152:155], v[188:191], v[12:15]
	v_mfma_f32_16x16x32_f16 v[64:67], v[148:151], v[168:171], v[64:67]
	v_mfma_f32_16x16x32_f16 v[60:63], v[160:163], v[168:171], v[60:63]
	v_mfma_f32_16x16x32_f16 v[48:51], v[148:151], v[176:179], v[48:51]
	v_mfma_f32_16x16x32_f16 v[44:47], v[160:163], v[176:179], v[44:47]
	v_mfma_f32_16x16x32_f16 v[32:35], v[148:151], v[184:187], v[32:35]
	v_mfma_f32_16x16x32_f16 v[28:31], v[160:163], v[184:187], v[28:31]
	v_mfma_f32_16x16x32_f16 v[16:19], v[148:151], v[192:195], v[16:19]
	v_mfma_f32_16x16x32_f16 v[12:15], v[160:163], v[192:195], v[12:15]
	s_barrier
	s_add_u32 s42, s26, 0x80000
	s_addc_u32 s43, s27, 0
	s_add_i32 s19, s19, s5
	v_lshl_add_u64 v[132:133], s[42:43], 0, v[138:139]
	s_mov_b32 m0, s19
	s_nop 0
	global_load_lds_dwordx4 v[132:133], off
	v_lshl_add_u64 v[132:133], s[42:43], 0, v[142:143]
	s_add_i32 m0, s19, 0x2000
	s_nop 0
	global_load_lds_dwordx4 v[132:133], off
	s_waitcnt vmcnt(6)
	s_barrier
	v_mfma_f32_16x16x32_f16 v[56:59], v[196:199], v[164:167], v[56:59]
	v_mfma_f32_16x16x32_f16 v[52:55], v[206:209], v[164:167], v[52:55]
	v_mfma_f32_16x16x32_f16 v[40:43], v[196:199], v[172:175], v[40:43]
	v_mfma_f32_16x16x32_f16 v[36:39], v[206:209], v[172:175], v[36:39]
	v_mfma_f32_16x16x32_f16 v[24:27], v[196:199], v[180:183], v[24:27]
	v_mfma_f32_16x16x32_f16 v[20:23], v[206:209], v[180:183], v[20:23]
	v_mfma_f32_16x16x32_f16 v[8:11], v[196:199], v[188:191], v[8:11]
	v_mfma_f32_16x16x32_f16 v[4:7], v[206:209], v[188:191], v[4:7]
	v_mfma_f32_16x16x32_f16 v[56:59], v[200:203], v[168:171], v[56:59]
	v_mfma_f32_16x16x32_f16 v[52:55], v[210:213], v[168:171], v[52:55]
	v_mfma_f32_16x16x32_f16 v[40:43], v[200:203], v[176:179], v[40:43]
	v_mfma_f32_16x16x32_f16 v[36:39], v[210:213], v[176:179], v[36:39]
	v_mfma_f32_16x16x32_f16 v[24:27], v[200:203], v[184:187], v[24:27]
	v_mfma_f32_16x16x32_f16 v[20:23], v[210:213], v[184:187], v[20:23]
	v_mfma_f32_16x16x32_f16 v[8:11], v[200:203], v[192:195], v[8:11]
	v_mfma_f32_16x16x32_f16 v[4:7], v[210:213], v[192:195], v[4:7]
	s_add_i32 s19, 0, 0x18000
	v_add_u32_e32 v2, s19, v158
	s_barrier
	ds_read_b128 v[132:135], v2
	ds_read_b128 v[148:151], v2 offset:1024
	ds_read_b128 v[152:155], v2 offset:2048
	ds_read_b128 v[160:163], v2 offset:3072
	s_add_u32 s38, s38, 0x80000
	s_addc_u32 s39, s39, 0
	s_mov_b32 m0, s8
	v_lshl_add_u64 v[196:197], s[38:39], 0, v[136:137]
	ds_read_b128 v[164:167], v159 offset:32768
	ds_read_b128 v[168:171], v159 offset:33792
	ds_read_b128 v[172:175], v159 offset:34816
	ds_read_b128 v[176:179], v159 offset:35840
	ds_read_b128 v[180:183], v159 offset:36864
	ds_read_b128 v[184:187], v159 offset:37888
	ds_read_b128 v[188:191], v159 offset:38912
	ds_read_b128 v[192:195], v159 offset:39936
	global_load_lds_dwordx4 v[196:197], off
	v_lshl_add_u64 v[196:197], s[38:39], 0, v[140:141]
	s_mov_b32 m0, s9
	s_nop 0
	global_load_lds_dwordx4 v[196:197], off
	s_waitcnt lgkmcnt(8)
	s_barrier
	s_waitcnt lgkmcnt(0)
	v_mfma_f32_16x16x32_f16 v[128:131], v[132:135], v[164:167], v[128:131]
	v_mfma_f32_16x16x32_f16 v[124:127], v[152:155], v[164:167], v[124:127]
	v_mfma_f32_16x16x32_f16 v[112:115], v[132:135], v[172:175], v[112:115]
	v_mfma_f32_16x16x32_f16 v[108:111], v[152:155], v[172:175], v[108:111]
	v_mfma_f32_16x16x32_f16 v[96:99], v[132:135], v[180:183], v[96:99]
	v_mfma_f32_16x16x32_f16 v[92:95], v[152:155], v[180:183], v[92:95]
	v_mfma_f32_16x16x32_f16 v[80:83], v[132:135], v[188:191], v[80:83]
	v_mfma_f32_16x16x32_f16 v[76:79], v[152:155], v[188:191], v[76:79]
	v_mfma_f32_16x16x32_f16 v[128:131], v[148:151], v[168:171], v[128:131]
	v_mfma_f32_16x16x32_f16 v[124:127], v[160:163], v[168:171], v[124:127]
	v_mfma_f32_16x16x32_f16 v[112:115], v[148:151], v[176:179], v[112:115]
	v_mfma_f32_16x16x32_f16 v[108:111], v[160:163], v[176:179], v[108:111]
	v_mfma_f32_16x16x32_f16 v[96:99], v[148:151], v[184:187], v[96:99]
	v_mfma_f32_16x16x32_f16 v[92:95], v[160:163], v[184:187], v[92:95]
	v_mfma_f32_16x16x32_f16 v[80:83], v[148:151], v[192:195], v[80:83]
	v_mfma_f32_16x16x32_f16 v[76:79], v[160:163], v[192:195], v[76:79]
	s_barrier
	s_add_i32 s31, 0, 0x1c000
	s_add_i32 s19, s19, s5
	v_add_u32_e32 v2, s31, v158
	v_lshl_add_u64 v[214:215], v[214:215], 0, s[88:89]
	s_mov_b32 m0, s19
	ds_read_b128 v[196:199], v2
	ds_read_b128 v[200:203], v2 offset:1024
	ds_read_b128 v[206:209], v2 offset:2048
	ds_read_b128 v[210:213], v2 offset:3072
	global_load_lds_dwordx4 v[214:215], off
	v_lshl_add_u64 v[214:215], v[216:217], 0, s[88:89]
	s_add_i32 m0, s19, 0x2000
	s_nop 0
	global_load_lds_dwordx4 v[214:215], off
	s_barrier
	s_waitcnt lgkmcnt(0)
	v_mfma_f32_16x16x32_f16 v[120:123], v[196:199], v[164:167], v[120:123]
	v_mfma_f32_16x16x32_f16 v[116:119], v[206:209], v[164:167], v[116:119]
	v_mfma_f32_16x16x32_f16 v[104:107], v[196:199], v[172:175], v[104:107]
	v_mfma_f32_16x16x32_f16 v[100:103], v[206:209], v[172:175], v[100:103]
	v_mfma_f32_16x16x32_f16 v[88:91], v[196:199], v[180:183], v[88:91]
	v_mfma_f32_16x16x32_f16 v[84:87], v[206:209], v[180:183], v[84:87]
	v_mfma_f32_16x16x32_f16 v[72:75], v[196:199], v[188:191], v[72:75]
	v_mfma_f32_16x16x32_f16 v[68:71], v[206:209], v[188:191], v[68:71]
	v_mfma_f32_16x16x32_f16 v[120:123], v[200:203], v[168:171], v[120:123]
	v_mfma_f32_16x16x32_f16 v[116:119], v[210:213], v[168:171], v[116:119]
	v_mfma_f32_16x16x32_f16 v[104:107], v[200:203], v[176:179], v[104:107]
	v_mfma_f32_16x16x32_f16 v[100:103], v[210:213], v[176:179], v[100:103]
	v_mfma_f32_16x16x32_f16 v[88:91], v[200:203], v[184:187], v[88:91]
	v_mfma_f32_16x16x32_f16 v[84:87], v[210:213], v[184:187], v[84:87]
	v_mfma_f32_16x16x32_f16 v[72:75], v[200:203], v[192:195], v[72:75]
	v_mfma_f32_16x16x32_f16 v[68:71], v[210:213], v[192:195], v[68:71]
	s_mov_b32 m0, s30
	v_lshl_add_u64 v[214:215], v[218:219], 0, s[88:89]
	s_barrier
	ds_read_b128 v[164:167], v159 offset:49152
	ds_read_b128 v[168:171], v159 offset:50176
	ds_read_b128 v[172:175], v159 offset:51200
	ds_read_b128 v[176:179], v159 offset:52224
	ds_read_b128 v[180:183], v159 offset:53248
	ds_read_b128 v[184:187], v159 offset:54272
	ds_read_b128 v[188:191], v159 offset:55296
	ds_read_b128 v[192:195], v159 offset:56320
	global_load_lds_dwordx4 v[214:215], off
	v_lshl_add_u64 v[214:215], v[220:221], 0, s[88:89]
	s_mov_b32 m0, s52
	s_nop 0
	global_load_lds_dwordx4 v[214:215], off
	s_barrier
	s_waitcnt lgkmcnt(0)
	v_mfma_f32_16x16x32_f16 v[64:67], v[132:135], v[164:167], v[64:67]
	v_mfma_f32_16x16x32_f16 v[60:63], v[152:155], v[164:167], v[60:63]
	v_mfma_f32_16x16x32_f16 v[48:51], v[132:135], v[172:175], v[48:51]
	v_mfma_f32_16x16x32_f16 v[44:47], v[152:155], v[172:175], v[44:47]
	v_mfma_f32_16x16x32_f16 v[32:35], v[132:135], v[180:183], v[32:35]
	v_mfma_f32_16x16x32_f16 v[28:31], v[152:155], v[180:183], v[28:31]
	v_mfma_f32_16x16x32_f16 v[16:19], v[132:135], v[188:191], v[16:19]
	v_mfma_f32_16x16x32_f16 v[12:15], v[152:155], v[188:191], v[12:15]
	v_mfma_f32_16x16x32_f16 v[64:67], v[148:151], v[168:171], v[64:67]
	v_mfma_f32_16x16x32_f16 v[60:63], v[160:163], v[168:171], v[60:63]
	v_mfma_f32_16x16x32_f16 v[48:51], v[148:151], v[176:179], v[48:51]
	v_mfma_f32_16x16x32_f16 v[44:47], v[160:163], v[176:179], v[44:47]
	v_mfma_f32_16x16x32_f16 v[32:35], v[148:151], v[184:187], v[32:35]
	v_mfma_f32_16x16x32_f16 v[28:31], v[160:163], v[184:187], v[28:31]
	v_mfma_f32_16x16x32_f16 v[16:19], v[148:151], v[192:195], v[16:19]
	v_mfma_f32_16x16x32_f16 v[12:15], v[160:163], v[192:195], v[12:15]
	s_barrier
	s_add_u32 s26, s26, 0x80080
	s_addc_u32 s27, s27, 0
	s_add_i32 s19, s31, s5
	v_lshl_add_u64 v[132:133], s[26:27], 0, v[138:139]
	s_mov_b32 m0, s19
	s_nop 0
	global_load_lds_dwordx4 v[132:133], off
	v_lshl_add_u64 v[132:133], s[26:27], 0, v[142:143]
	s_add_i32 m0, s19, 0x2000
	s_nop 0
	global_load_lds_dwordx4 v[132:133], off
	s_waitcnt vmcnt(6)
	s_barrier
	v_mfma_f32_16x16x32_f16 v[56:59], v[196:199], v[164:167], v[56:59]
	v_mfma_f32_16x16x32_f16 v[52:55], v[206:209], v[164:167], v[52:55]
	v_mfma_f32_16x16x32_f16 v[40:43], v[196:199], v[172:175], v[40:43]
	v_mfma_f32_16x16x32_f16 v[36:39], v[206:209], v[172:175], v[36:39]
	v_mfma_f32_16x16x32_f16 v[24:27], v[196:199], v[180:183], v[24:27]
	v_mfma_f32_16x16x32_f16 v[20:23], v[206:209], v[180:183], v[20:23]
	v_mfma_f32_16x16x32_f16 v[8:11], v[196:199], v[188:191], v[8:11]
	v_mfma_f32_16x16x32_f16 v[4:7], v[206:209], v[188:191], v[4:7]
	v_mfma_f32_16x16x32_f16 v[56:59], v[200:203], v[168:171], v[56:59]
	v_mfma_f32_16x16x32_f16 v[52:55], v[210:213], v[168:171], v[52:55]
	v_mfma_f32_16x16x32_f16 v[40:43], v[200:203], v[176:179], v[40:43]
	v_mfma_f32_16x16x32_f16 v[36:39], v[210:213], v[176:179], v[36:39]
	v_mfma_f32_16x16x32_f16 v[24:27], v[200:203], v[184:187], v[24:27]
	v_mfma_f32_16x16x32_f16 v[20:23], v[210:213], v[184:187], v[20:23]
	v_mfma_f32_16x16x32_f16 v[8:11], v[200:203], v[192:195], v[8:11]
	v_mfma_f32_16x16x32_f16 v[4:7], v[210:213], v[192:195], v[4:7]
	s_add_i32 s15, s15, 2
	s_add_u32 s16, s16, 0x100
	s_addc_u32 s17, s17, 0
	s_add_u32 s10, s10, 0x100
	s_addc_u32 s14, s14, 0
	s_cmp_gt_u32 s15, 29
	s_barrier
	s_cbranch_scc0 .LBB0_329
	s_lshl_b32 s19, s11, 8
	v_mov_b32_e32 v2, v156
	s_add_i32 s10, s19, s12
	v_mov_b32_e32 v132, v157
	v_add_u32_e32 v161, s10, v2
	s_lshl_b32 s10, s29, 8
	s_or_b32 s14, s10, s13
	s_cmp_gt_i32 s29, 1
	v_lshlrev_b32_e32 v154, 3, v132
	v_add_u32_e32 v160, s14, v154
	s_cselect_b64 s[16:17], -1, 0
	s_add_i32 s14, s29, -14
	s_cmp_gt_u32 s14, 5
	s_cselect_b64 s[38:39], -1, 0
	s_sub_i32 s14, s29, 20
	s_cmp_gt_u32 s14, 23
	s_cselect_b64 s[50:51], -1, 0
	s_cmp_eq_u32 s29, 44
	s_mul_i32 s14, s29, 0x42
	s_cselect_b64 s[42:43], -1, 0
	s_addk_i32 s14, 0xfad8
	s_ashr_i32 s15, s14, 31
	s_ashr_i32 s26, s11, 31
	s_add_u32 s14, s14, s11
	s_addc_u32 s15, s15, s26
	v_lshlrev_b32_e32 v133, 7, v2
	s_lshl_b64 s[26:27], s[14:15], 17
	v_and_b32_e32 v132, 0xffffe000, v161
	v_and_b32_e32 v162, 0x1f80, v133
	v_bfe_u32 v133, v161, 6, 7
	s_movk_i32 s14, 0x4000
	v_or3_b32 v132, v132, v133, v162
	v_cmp_gt_i32_e32 vcc, s14, v161
	s_sub_i32 s29, s10, s19
	s_addk_i32 s29, 0xf200
	v_cndmask_b32_e32 v132, v161, v132, vcc
	v_mad_i64_i32 v[152:153], s[14:15], v132, s33, 0
	v_add_u32_e32 v132, s12, v2
	v_ashrrev_i32_e32 v133, 31, v132
	v_lshlrev_b64 v[150:151], 9, v[132:133]
	v_add_u32_e32 v132, s29, v161
	s_mov_b32 s14, 0x8400
	v_mad_i64_i32 v[148:149], s[14:15], v132, s14, 0
	s_sub_i32 s11, s19, s10
	v_cvt_pk_f16_f32 v135, v126, v127
	v_cvt_pk_f16_f32 v134, v124, v125
	v_cvt_pk_f16_f32 v133, v130, v131
	v_cvt_pk_f16_f32 v132, v128, v129
	s_mov_b64 s[14:15], -1
	s_and_b64 vcc, exec, s[16:17]
	s_cbranch_vccz .LBB0_340
	s_and_b64 vcc, exec, s[38:39]
	s_cbranch_vccz .LBB0_337
	s_and_b64 vcc, exec, s[50:51]
	s_cbranch_vccz .LBB0_334
	v_add_u32_e32 v155, 0xffffe200, v160
	v_cndmask_b32_e64 v166, v160, v155, s[42:43]
	v_lshl_add_u64 v[164:165], s[22:23], 0, v[152:153]
	v_ashrrev_i32_e32 v167, 31, v166
	v_lshl_add_u64 v[164:165], v[166:167], 1, v[164:165]
	global_store_dwordx4 v[164:165], v[132:135], off
	s_mov_b64 s[14:15], 0

.LBB0_885:
	s_add_i32 s37, 0, 0x10000
	v_add_u32_e32 v216, s37, v12
	ds_read_b128 v[14:17], v216
	ds_read_b128 v[18:21], v216 offset:1024
	ds_read_b128 v[22:25], v216 offset:2048
	ds_read_b128 v[26:29], v216 offset:3072
	s_add_u32 s30, s38, 0x400080
	s_addc_u32 s31, s39, 0
	s_add_i32 s42, s6, 0xc000
	v_lshl_add_u64 v[62:63], s[30:31], 0, v[8:9]
	s_mov_b32 m0, s42
	s_add_i32 s17, s6, 0xe000
	ds_read_b128 v[30:33], v13
	ds_read_b128 v[34:37], v13 offset:1024
	ds_read_b128 v[38:41], v13 offset:2048
	ds_read_b128 v[42:45], v13 offset:3072
	ds_read_b128 v[46:49], v13 offset:4096
	ds_read_b128 v[50:53], v13 offset:5120
	ds_read_b128 v[54:57], v13 offset:6144
	ds_read_b128 v[58:61], v13 offset:7168
	global_load_lds_dwordx4 v[62:63], off
	v_lshl_add_u64 v[62:63], s[30:31], 0, v[6:7]
	s_mov_b32 m0, s17
	s_nop 0
	global_load_lds_dwordx4 v[62:63], off
	s_waitcnt lgkmcnt(8)
	s_barrier
	s_waitcnt lgkmcnt(0)
	v_mfma_f32_16x16x32_f16 v[62:65], v[14:17], v[30:33], 0
	v_mfma_f32_16x16x32_f16 v[66:69], v[22:25], v[30:33], 0
	v_mfma_f32_16x16x32_f16 v[70:73], v[14:17], v[38:41], 0
	v_mfma_f32_16x16x32_f16 v[74:77], v[22:25], v[38:41], 0
	v_mfma_f32_16x16x32_f16 v[78:81], v[14:17], v[46:49], 0
	v_mfma_f32_16x16x32_f16 v[82:85], v[22:25], v[46:49], 0
	v_mfma_f32_16x16x32_f16 v[86:89], v[14:17], v[54:57], 0
	v_mfma_f32_16x16x32_f16 v[90:93], v[22:25], v[54:57], 0
	v_mfma_f32_16x16x32_f16 v[62:65], v[18:21], v[34:37], v[62:65]
	v_mfma_f32_16x16x32_f16 v[66:69], v[26:29], v[34:37], v[66:69]
	v_mfma_f32_16x16x32_f16 v[70:73], v[18:21], v[42:45], v[70:73]
	v_mfma_f32_16x16x32_f16 v[74:77], v[26:29], v[42:45], v[74:77]
	v_mfma_f32_16x16x32_f16 v[78:81], v[18:21], v[50:53], v[78:81]
	v_mfma_f32_16x16x32_f16 v[82:85], v[26:29], v[50:53], v[82:85]
	v_mfma_f32_16x16x32_f16 v[86:89], v[18:21], v[58:61], v[86:89]
	v_mfma_f32_16x16x32_f16 v[90:93], v[26:29], v[58:61], v[90:93]
	s_barrier
	s_add_i32 s43, 0, 0x14000
	v_lshl_add_u64 v[202:203], s[40:41], 0, v[2:3]
	s_mov_b64 s[44:45], 0x100
	s_add_i32 s37, s37, s5
	v_add_u32_e32 v217, s43, v12
	v_lshl_add_u64 v[110:111], v[202:203], 0, s[44:45]
	s_mov_b32 m0, s37
	v_lshl_add_u64 v[210:211], s[40:41], 0, v[4:5]
	s_add_i32 s30, s37, 0x2000
	ds_read_b128 v[94:97], v217
	ds_read_b128 v[98:101], v217 offset:1024
	ds_read_b128 v[102:105], v217 offset:2048
	ds_read_b128 v[106:109], v217 offset:3072
	global_load_lds_dwordx4 v[110:111], off
	v_lshl_add_u64 v[110:111], v[210:211], 0, s[44:45]
	s_mov_b32 m0, s30
	s_nop 0
	global_load_lds_dwordx4 v[110:111], off
	s_barrier
	s_waitcnt lgkmcnt(0)
	v_mfma_f32_16x16x32_f16 v[110:113], v[94:97], v[30:33], 0
	v_mfma_f32_16x16x32_f16 v[30:33], v[102:105], v[30:33], 0
	v_mfma_f32_16x16x32_f16 v[110:113], v[98:101], v[34:37], v[110:113]
	v_mfma_f32_16x16x32_f16 v[30:33], v[106:109], v[34:37], v[30:33]
	v_mfma_f32_16x16x32_f16 v[34:37], v[94:97], v[38:41], 0
	v_mfma_f32_16x16x32_f16 v[38:41], v[102:105], v[38:41], 0
	v_mfma_f32_16x16x32_f16 v[34:37], v[98:101], v[42:45], v[34:37]
	v_mfma_f32_16x16x32_f16 v[38:41], v[106:109], v[42:45], v[38:41]
	v_mfma_f32_16x16x32_f16 v[42:45], v[94:97], v[46:49], 0
	v_mfma_f32_16x16x32_f16 v[46:49], v[102:105], v[46:49], 0
	v_mfma_f32_16x16x32_f16 v[42:45], v[98:101], v[50:53], v[42:45]
	v_mfma_f32_16x16x32_f16 v[46:49], v[106:109], v[50:53], v[46:49]
	v_mfma_f32_16x16x32_f16 v[50:53], v[94:97], v[54:57], 0
	v_mfma_f32_16x16x32_f16 v[54:57], v[102:105], v[54:57], 0
	v_mfma_f32_16x16x32_f16 v[50:53], v[98:101], v[58:61], v[50:53]
	v_mfma_f32_16x16x32_f16 v[54:57], v[106:109], v[58:61], v[54:57]
	v_lshl_add_u64 v[212:213], s[38:39], 0, v[8:9]
	s_mov_b32 m0, s6
	v_lshl_add_u64 v[142:143], v[212:213], 0, s[44:45]
	v_lshl_add_u64 v[214:215], s[38:39], 0, v[6:7]
	s_barrier
	ds_read_b128 v[58:61], v13 offset:16384
	ds_read_b128 v[114:117], v13 offset:17408
	ds_read_b128 v[118:121], v13 offset:18432
	ds_read_b128 v[122:125], v13 offset:19456
	ds_read_b128 v[126:129], v13 offset:20480
	ds_read_b128 v[130:133], v13 offset:21504
	ds_read_b128 v[134:137], v13 offset:22528
	ds_read_b128 v[138:141], v13 offset:23552
	global_load_lds_dwordx4 v[142:143], off
	v_lshl_add_u64 v[142:143], v[214:215], 0, s[44:45]
	s_mov_b32 m0, s7
	s_nop 0
	global_load_lds_dwordx4 v[142:143], off
	s_barrier
	s_waitcnt lgkmcnt(0)
	v_mfma_f32_16x16x32_f16 v[142:145], v[14:17], v[58:61], 0
	v_mfma_f32_16x16x32_f16 v[150:153], v[14:17], v[118:121], 0
	v_mfma_f32_16x16x32_f16 v[158:161], v[14:17], v[126:129], 0
	v_mfma_f32_16x16x32_f16 v[14:17], v[14:17], v[134:137], 0
	v_mfma_f32_16x16x32_f16 v[142:145], v[18:21], v[114:117], v[142:145]
	v_mfma_f32_16x16x32_f16 v[146:149], v[22:25], v[58:61], 0
	v_mfma_f32_16x16x32_f16 v[150:153], v[18:21], v[122:125], v[150:153]
	v_mfma_f32_16x16x32_f16 v[154:157], v[22:25], v[118:121], 0
	v_mfma_f32_16x16x32_f16 v[158:161], v[18:21], v[130:133], v[158:161]
	v_mfma_f32_16x16x32_f16 v[162:165], v[22:25], v[126:129], 0
	v_mfma_f32_16x16x32_f16 v[14:17], v[18:21], v[138:141], v[14:17]
	v_mfma_f32_16x16x32_f16 v[18:21], v[22:25], v[134:137], 0
	v_mfma_f32_16x16x32_f16 v[146:149], v[26:29], v[114:117], v[146:149]
	v_mfma_f32_16x16x32_f16 v[154:157], v[26:29], v[122:125], v[154:157]
	v_mfma_f32_16x16x32_f16 v[162:165], v[26:29], v[130:133], v[162:165]
	v_mfma_f32_16x16x32_f16 v[18:21], v[26:29], v[138:141], v[18:21]
	s_barrier
	s_add_u32 s44, s40, 0x10100
	s_addc_u32 s45, s41, 0
	s_add_i32 s43, s43, s5
	v_lshl_add_u64 v[22:23], s[44:45], 0, v[2:3]
	s_mov_b32 m0, s43
	s_add_i32 s31, s43, 0x2000
	global_load_lds_dwordx4 v[22:23], off
	v_lshl_add_u64 v[22:23], s[44:45], 0, v[4:5]
	s_mov_b32 m0, s31
	s_nop 0
	global_load_lds_dwordx4 v[22:23], off
	s_waitcnt vmcnt(6)
	s_barrier
	v_mfma_f32_16x16x32_f16 v[22:25], v[94:97], v[58:61], 0
	v_mfma_f32_16x16x32_f16 v[26:29], v[102:105], v[58:61], 0
	v_mfma_f32_16x16x32_f16 v[22:25], v[98:101], v[114:117], v[22:25]
	v_mfma_f32_16x16x32_f16 v[26:29], v[106:109], v[114:117], v[26:29]
	v_mfma_f32_16x16x32_f16 v[58:61], v[94:97], v[118:121], 0
	v_mfma_f32_16x16x32_f16 v[114:117], v[102:105], v[118:121], 0
	v_mfma_f32_16x16x32_f16 v[118:121], v[94:97], v[126:129], 0
	v_mfma_f32_16x16x32_f16 v[94:97], v[94:97], v[134:137], 0
	v_mfma_f32_16x16x32_f16 v[58:61], v[98:101], v[122:125], v[58:61]
	v_mfma_f32_16x16x32_f16 v[114:117], v[106:109], v[122:125], v[114:117]
	v_mfma_f32_16x16x32_f16 v[118:121], v[98:101], v[130:133], v[118:121]
	v_mfma_f32_16x16x32_f16 v[122:125], v[102:105], v[126:129], 0
	v_mfma_f32_16x16x32_f16 v[94:97], v[98:101], v[138:141], v[94:97]
	v_mfma_f32_16x16x32_f16 v[98:101], v[102:105], v[134:137], 0
	v_mfma_f32_16x16x32_f16 v[122:125], v[106:109], v[130:133], v[122:125]
	v_mfma_f32_16x16x32_f16 v[98:101], v[106:109], v[138:141], v[98:101]
	s_add_i32 s46, 0, 0x18000
	v_add_u32_e32 v218, s46, v12
	s_barrier
	ds_read_b128 v[102:105], v218
	ds_read_b128 v[106:109], v218 offset:1024
	ds_read_b128 v[126:129], v218 offset:2048
	ds_read_b128 v[130:133], v218 offset:3072
	s_add_u32 s44, s38, 0x400100
	s_addc_u32 s45, s39, 0
	s_mov_b32 m0, s8
	v_lshl_add_u64 v[190:191], s[44:45], 0, v[8:9]
	ds_read_b128 v[134:137], v13 offset:32768
	ds_read_b128 v[138:141], v13 offset:33792
	ds_read_b128 v[166:169], v13 offset:34816
	ds_read_b128 v[170:173], v13 offset:35840
	ds_read_b128 v[174:177], v13 offset:36864
	ds_read_b128 v[178:181], v13 offset:37888
	ds_read_b128 v[182:185], v13 offset:38912
	ds_read_b128 v[186:189], v13 offset:39936
	global_load_lds_dwordx4 v[190:191], off
	v_lshl_add_u64 v[190:191], s[44:45], 0, v[6:7]
	s_mov_b32 m0, s9
	s_nop 0
	global_load_lds_dwordx4 v[190:191], off
	s_waitcnt lgkmcnt(8)
	s_barrier
	s_waitcnt lgkmcnt(0)
	v_mfma_f32_16x16x32_f16 v[62:65], v[102:105], v[134:137], v[62:65]
	v_mfma_f32_16x16x32_f16 v[66:69], v[126:129], v[134:137], v[66:69]
	v_mfma_f32_16x16x32_f16 v[70:73], v[102:105], v[166:169], v[70:73]
	v_mfma_f32_16x16x32_f16 v[74:77], v[126:129], v[166:169], v[74:77]
	v_mfma_f32_16x16x32_f16 v[78:81], v[102:105], v[174:177], v[78:81]
	v_mfma_f32_16x16x32_f16 v[82:85], v[126:129], v[174:177], v[82:85]
	v_mfma_f32_16x16x32_f16 v[86:89], v[102:105], v[182:185], v[86:89]
	v_mfma_f32_16x16x32_f16 v[90:93], v[126:129], v[182:185], v[90:93]
	v_mfma_f32_16x16x32_f16 v[62:65], v[106:109], v[138:141], v[62:65]
	v_mfma_f32_16x16x32_f16 v[66:69], v[130:133], v[138:141], v[66:69]
	v_mfma_f32_16x16x32_f16 v[70:73], v[106:109], v[170:173], v[70:73]
	v_mfma_f32_16x16x32_f16 v[74:77], v[130:133], v[170:173], v[74:77]
	v_mfma_f32_16x16x32_f16 v[78:81], v[106:109], v[178:181], v[78:81]
	v_mfma_f32_16x16x32_f16 v[82:85], v[130:133], v[178:181], v[82:85]
	v_mfma_f32_16x16x32_f16 v[86:89], v[106:109], v[186:189], v[86:89]
	v_mfma_f32_16x16x32_f16 v[90:93], v[130:133], v[186:189], v[90:93]
	s_barrier
	s_add_i32 s48, 0, 0x1c000
	s_mov_b64 s[50:51], 0x180
	s_add_i32 s45, s46, s5
	v_add_u32_e32 v219, s48, v12
	v_lshl_add_u64 v[202:203], v[202:203], 0, s[50:51]
	s_mov_b32 m0, s45
	s_add_i32 s44, s45, 0x2000
	ds_read_b128 v[190:193], v219
	ds_read_b128 v[194:197], v219 offset:1024
	ds_read_b128 v[198:201], v219 offset:2048
	ds_read_b128 v[206:209], v219 offset:3072
	global_load_lds_dwordx4 v[202:203], off
	v_lshl_add_u64 v[202:203], v[210:211], 0, s[50:51]
	s_mov_b32 m0, s44
	s_nop 0
	global_load_lds_dwordx4 v[202:203], off
	s_barrier
	s_waitcnt lgkmcnt(0)
	v_mfma_f32_16x16x32_f16 v[110:113], v[190:193], v[134:137], v[110:113]
	v_mfma_f32_16x16x32_f16 v[30:33], v[198:201], v[134:137], v[30:33]
	v_mfma_f32_16x16x32_f16 v[34:37], v[190:193], v[166:169], v[34:37]
	v_mfma_f32_16x16x32_f16 v[38:41], v[198:201], v[166:169], v[38:41]
	v_mfma_f32_16x16x32_f16 v[42:45], v[190:193], v[174:177], v[42:45]
	v_mfma_f32_16x16x32_f16 v[46:49], v[198:201], v[174:177], v[46:49]
	v_mfma_f32_16x16x32_f16 v[50:53], v[190:193], v[182:185], v[50:53]
	v_mfma_f32_16x16x32_f16 v[54:57], v[198:201], v[182:185], v[54:57]
	v_mfma_f32_16x16x32_f16 v[110:113], v[194:197], v[138:141], v[110:113]
	v_mfma_f32_16x16x32_f16 v[30:33], v[206:209], v[138:141], v[30:33]
	v_mfma_f32_16x16x32_f16 v[34:37], v[194:197], v[170:173], v[34:37]
	v_mfma_f32_16x16x32_f16 v[38:41], v[206:209], v[170:173], v[38:41]
	v_mfma_f32_16x16x32_f16 v[42:45], v[194:197], v[178:181], v[42:45]
	v_mfma_f32_16x16x32_f16 v[46:49], v[206:209], v[178:181], v[46:49]
	v_mfma_f32_16x16x32_f16 v[50:53], v[194:197], v[186:189], v[50:53]
	v_mfma_f32_16x16x32_f16 v[54:57], v[206:209], v[186:189], v[54:57]
	s_mov_b32 m0, s10
	v_lshl_add_u64 v[202:203], v[212:213], 0, s[50:51]
	s_barrier
	ds_read_b128 v[134:137], v13 offset:49152
	ds_read_b128 v[138:141], v13 offset:50176
	ds_read_b128 v[166:169], v13 offset:51200
	ds_read_b128 v[170:173], v13 offset:52224
	ds_read_b128 v[174:177], v13 offset:53248
	ds_read_b128 v[178:181], v13 offset:54272
	ds_read_b128 v[182:185], v13 offset:55296
	ds_read_b128 v[186:189], v13 offset:56320
	global_load_lds_dwordx4 v[202:203], off
	v_lshl_add_u64 v[202:203], v[214:215], 0, s[50:51]
	s_mov_b32 m0, s11
	s_nop 0
	global_load_lds_dwordx4 v[202:203], off
	s_barrier
	s_waitcnt lgkmcnt(0)
	v_mfma_f32_16x16x32_f16 v[142:145], v[102:105], v[134:137], v[142:145]
	v_mfma_f32_16x16x32_f16 v[146:149], v[126:129], v[134:137], v[146:149]
	v_mfma_f32_16x16x32_f16 v[150:153], v[102:105], v[166:169], v[150:153]
	v_mfma_f32_16x16x32_f16 v[154:157], v[126:129], v[166:169], v[154:157]
	v_mfma_f32_16x16x32_f16 v[158:161], v[102:105], v[174:177], v[158:161]
	v_mfma_f32_16x16x32_f16 v[162:165], v[126:129], v[174:177], v[162:165]
	v_mfma_f32_16x16x32_f16 v[14:17], v[102:105], v[182:185], v[14:17]
	v_mfma_f32_16x16x32_f16 v[18:21], v[126:129], v[182:185], v[18:21]
	v_mfma_f32_16x16x32_f16 v[142:145], v[106:109], v[138:141], v[142:145]
	v_mfma_f32_16x16x32_f16 v[146:149], v[130:133], v[138:141], v[146:149]
	v_mfma_f32_16x16x32_f16 v[150:153], v[106:109], v[170:173], v[150:153]
	v_mfma_f32_16x16x32_f16 v[154:157], v[130:133], v[170:173], v[154:157]
	v_mfma_f32_16x16x32_f16 v[158:161], v[106:109], v[178:181], v[158:161]
	v_mfma_f32_16x16x32_f16 v[162:165], v[130:133], v[178:181], v[162:165]
	v_mfma_f32_16x16x32_f16 v[14:17], v[106:109], v[186:189], v[14:17]
	v_mfma_f32_16x16x32_f16 v[18:21], v[130:133], v[186:189], v[18:21]
	s_barrier
	s_add_u32 s46, s40, 0x10180
	s_addc_u32 s47, s41, 0
	s_add_i32 s41, s48, s5
	v_lshl_add_u64 v[102:103], s[46:47], 0, v[2:3]
	s_mov_b32 m0, s41
	s_add_i32 s40, s41, 0x2000
	global_load_lds_dwordx4 v[102:103], off
	v_lshl_add_u64 v[102:103], s[46:47], 0, v[4:5]
	s_mov_b32 m0, s40
	s_nop 0
	global_load_lds_dwordx4 v[102:103], off
	s_waitcnt vmcnt(6)
	s_barrier
	v_mfma_f32_16x16x32_f16 v[22:25], v[190:193], v[134:137], v[22:25]
	v_mfma_f32_16x16x32_f16 v[26:29], v[198:201], v[134:137], v[26:29]
	v_mfma_f32_16x16x32_f16 v[58:61], v[190:193], v[166:169], v[58:61]
	v_mfma_f32_16x16x32_f16 v[102:105], v[198:201], v[166:169], v[114:117]
	v_mfma_f32_16x16x32_f16 v[106:109], v[190:193], v[174:177], v[118:121]
	v_mfma_f32_16x16x32_f16 v[114:117], v[198:201], v[174:177], v[122:125]
	v_mfma_f32_16x16x32_f16 v[94:97], v[190:193], v[182:185], v[94:97]
	v_mfma_f32_16x16x32_f16 v[98:101], v[198:201], v[182:185], v[98:101]
	v_mfma_f32_16x16x32_f16 v[22:25], v[194:197], v[138:141], v[22:25]
	v_mfma_f32_16x16x32_f16 v[26:29], v[206:209], v[138:141], v[26:29]
	v_mfma_f32_16x16x32_f16 v[58:61], v[194:197], v[170:173], v[58:61]
	v_mfma_f32_16x16x32_f16 v[102:105], v[206:209], v[170:173], v[102:105]
	v_mfma_f32_16x16x32_f16 v[106:109], v[194:197], v[178:181], v[106:109]
	v_mfma_f32_16x16x32_f16 v[114:117], v[206:209], v[178:181], v[114:117]
	v_mfma_f32_16x16x32_f16 v[94:97], v[194:197], v[186:189], v[94:97]
	v_mfma_f32_16x16x32_f16 v[98:101], v[206:209], v[186:189], v[98:101]
	s_barrier
	ds_read_b128 v[118:121], v216
	ds_read_b128 v[122:125], v216 offset:1024
	ds_read_b128 v[126:129], v216 offset:2048
	ds_read_b128 v[130:133], v216 offset:3072
	s_add_u32 s38, s38, 0x400180
	s_addc_u32 s39, s39, 0
	s_mov_b32 m0, s42
	v_lshl_add_u64 v[190:191], s[38:39], 0, v[8:9]
	ds_read_b128 v[134:137], v13
	ds_read_b128 v[138:141], v13 offset:1024
	ds_read_b128 v[166:169], v13 offset:2048
	ds_read_b128 v[170:173], v13 offset:3072
	ds_read_b128 v[174:177], v13 offset:4096
	ds_read_b128 v[178:181], v13 offset:5120
	ds_read_b128 v[182:185], v13 offset:6144
	ds_read_b128 v[186:189], v13 offset:7168
	global_load_lds_dwordx4 v[190:191], off
	v_lshl_add_u64 v[190:191], s[38:39], 0, v[6:7]
	s_mov_b32 m0, s17
	s_nop 0
	global_load_lds_dwordx4 v[190:191], off
	s_waitcnt lgkmcnt(8)
	s_barrier
	s_waitcnt lgkmcnt(0)
	v_mfma_f32_16x16x32_f16 v[62:65], v[118:121], v[134:137], v[62:65]
	v_mfma_f32_16x16x32_f16 v[66:69], v[126:129], v[134:137], v[66:69]
	v_mfma_f32_16x16x32_f16 v[70:73], v[118:121], v[166:169], v[70:73]
	v_mfma_f32_16x16x32_f16 v[74:77], v[126:129], v[166:169], v[74:77]
	v_mfma_f32_16x16x32_f16 v[78:81], v[118:121], v[174:177], v[78:81]
	v_mfma_f32_16x16x32_f16 v[82:85], v[126:129], v[174:177], v[82:85]
	v_mfma_f32_16x16x32_f16 v[86:89], v[118:121], v[182:185], v[86:89]
	v_mfma_f32_16x16x32_f16 v[90:93], v[126:129], v[182:185], v[90:93]
	v_mfma_f32_16x16x32_f16 v[62:65], v[122:125], v[138:141], v[62:65]
	v_mfma_f32_16x16x32_f16 v[66:69], v[130:133], v[138:141], v[66:69]
	v_mfma_f32_16x16x32_f16 v[70:73], v[122:125], v[170:173], v[70:73]
	v_mfma_f32_16x16x32_f16 v[74:77], v[130:133], v[170:173], v[74:77]
	v_mfma_f32_16x16x32_f16 v[78:81], v[122:125], v[178:181], v[78:81]
	v_mfma_f32_16x16x32_f16 v[82:85], v[130:133], v[178:181], v[82:85]
	v_mfma_f32_16x16x32_f16 v[86:89], v[122:125], v[186:189], v[86:89]
	v_mfma_f32_16x16x32_f16 v[90:93], v[130:133], v[186:189], v[90:93]
	s_barrier
	s_mov_b32 m0, s37
	v_lshl_add_u64 v[202:203], s[26:27], 0, v[2:3]
	ds_read_b128 v[190:193], v217
	ds_read_b128 v[194:197], v217 offset:1024
	ds_read_b128 v[198:201], v217 offset:2048
	ds_read_b128 v[206:209], v217 offset:3072
	global_load_lds_dwordx4 v[202:203], off
	v_lshl_add_u64 v[210:211], s[26:27], 0, v[4:5]
	s_mov_b32 m0, s30
	s_nop 0
	global_load_lds_dwordx4 v[210:211], off
	s_barrier
	s_waitcnt lgkmcnt(0)
	v_mfma_f32_16x16x32_f16 v[110:113], v[190:193], v[134:137], v[110:113]
	v_mfma_f32_16x16x32_f16 v[30:33], v[198:201], v[134:137], v[30:33]
	v_mfma_f32_16x16x32_f16 v[34:37], v[190:193], v[166:169], v[34:37]
	v_mfma_f32_16x16x32_f16 v[38:41], v[198:201], v[166:169], v[38:41]
	v_mfma_f32_16x16x32_f16 v[42:45], v[190:193], v[174:177], v[42:45]
	v_mfma_f32_16x16x32_f16 v[46:49], v[198:201], v[174:177], v[46:49]
	v_mfma_f32_16x16x32_f16 v[50:53], v[190:193], v[182:185], v[50:53]
	v_mfma_f32_16x16x32_f16 v[54:57], v[198:201], v[182:185], v[54:57]
	v_mfma_f32_16x16x32_f16 v[110:113], v[194:197], v[138:141], v[110:113]
	v_mfma_f32_16x16x32_f16 v[30:33], v[206:209], v[138:141], v[30:33]
	v_mfma_f32_16x16x32_f16 v[34:37], v[194:197], v[170:173], v[34:37]
	v_mfma_f32_16x16x32_f16 v[38:41], v[206:209], v[170:173], v[38:41]
	v_mfma_f32_16x16x32_f16 v[42:45], v[194:197], v[178:181], v[42:45]
	v_mfma_f32_16x16x32_f16 v[46:49], v[206:209], v[178:181], v[46:49]
	v_mfma_f32_16x16x32_f16 v[50:53], v[194:197], v[186:189], v[50:53]
	v_mfma_f32_16x16x32_f16 v[54:57], v[206:209], v[186:189], v[54:57]
	s_mov_b32 m0, s6
	v_lshl_add_u64 v[212:213], s[18:19], 0, v[8:9]
	s_barrier
	ds_read_b128 v[134:137], v13 offset:16384
	ds_read_b128 v[138:141], v13 offset:17408
	ds_read_b128 v[166:169], v13 offset:18432
	ds_read_b128 v[170:173], v13 offset:19456
	ds_read_b128 v[174:177], v13 offset:20480
	ds_read_b128 v[178:181], v13 offset:21504
	ds_read_b128 v[182:185], v13 offset:22528
	ds_read_b128 v[186:189], v13 offset:23552
	global_load_lds_dwordx4 v[212:213], off
	v_lshl_add_u64 v[214:215], s[18:19], 0, v[6:7]
	s_mov_b32 m0, s7
	s_nop 0
	global_load_lds_dwordx4 v[214:215], off
	s_barrier
	s_waitcnt lgkmcnt(0)
	v_mfma_f32_16x16x32_f16 v[142:145], v[118:121], v[134:137], v[142:145]
	v_mfma_f32_16x16x32_f16 v[146:149], v[126:129], v[134:137], v[146:149]
	v_mfma_f32_16x16x32_f16 v[150:153], v[118:121], v[166:169], v[150:153]
	v_mfma_f32_16x16x32_f16 v[154:157], v[126:129], v[166:169], v[154:157]
	v_mfma_f32_16x16x32_f16 v[158:161], v[118:121], v[174:177], v[158:161]
	v_mfma_f32_16x16x32_f16 v[162:165], v[126:129], v[174:177], v[162:165]
	v_mfma_f32_16x16x32_f16 v[14:17], v[118:121], v[182:185], v[14:17]
	v_mfma_f32_16x16x32_f16 v[18:21], v[126:129], v[182:185], v[18:21]
	v_mfma_f32_16x16x32_f16 v[142:145], v[122:125], v[138:141], v[142:145]
	v_mfma_f32_16x16x32_f16 v[146:149], v[130:133], v[138:141], v[146:149]
	v_mfma_f32_16x16x32_f16 v[150:153], v[122:125], v[170:173], v[150:153]
	v_mfma_f32_16x16x32_f16 v[154:157], v[130:133], v[170:173], v[154:157]
	v_mfma_f32_16x16x32_f16 v[158:161], v[122:125], v[178:181], v[158:161]
	v_mfma_f32_16x16x32_f16 v[162:165], v[130:133], v[178:181], v[162:165]
	v_mfma_f32_16x16x32_f16 v[14:17], v[122:125], v[186:189], v[14:17]
	v_mfma_f32_16x16x32_f16 v[18:21], v[130:133], v[186:189], v[18:21]
	s_barrier
	s_add_u32 s38, s26, 0x10000
	s_addc_u32 s39, s27, 0
	s_mov_b32 m0, s43
	v_lshl_add_u64 v[118:119], s[38:39], 0, v[2:3]
	global_load_lds_dwordx4 v[118:119], off
	v_lshl_add_u64 v[118:119], s[38:39], 0, v[4:5]
	s_mov_b32 m0, s31
	s_nop 0
	global_load_lds_dwordx4 v[118:119], off
	s_waitcnt vmcnt(6)
	s_barrier
	v_mfma_f32_16x16x32_f16 v[22:25], v[190:193], v[134:137], v[22:25]
	v_mfma_f32_16x16x32_f16 v[26:29], v[198:201], v[134:137], v[26:29]
	v_mfma_f32_16x16x32_f16 v[58:61], v[190:193], v[166:169], v[58:61]
	v_mfma_f32_16x16x32_f16 v[102:105], v[198:201], v[166:169], v[102:105]
	v_mfma_f32_16x16x32_f16 v[106:109], v[190:193], v[174:177], v[106:109]
	v_mfma_f32_16x16x32_f16 v[114:117], v[198:201], v[174:177], v[114:117]
	v_mfma_f32_16x16x32_f16 v[94:97], v[190:193], v[182:185], v[94:97]
	v_mfma_f32_16x16x32_f16 v[98:101], v[198:201], v[182:185], v[98:101]
	v_mfma_f32_16x16x32_f16 v[22:25], v[194:197], v[138:141], v[22:25]
	v_mfma_f32_16x16x32_f16 v[26:29], v[206:209], v[138:141], v[26:29]
	v_mfma_f32_16x16x32_f16 v[58:61], v[194:197], v[170:173], v[58:61]
	v_mfma_f32_16x16x32_f16 v[102:105], v[206:209], v[170:173], v[102:105]
	v_mfma_f32_16x16x32_f16 v[106:109], v[194:197], v[178:181], v[106:109]
	v_mfma_f32_16x16x32_f16 v[114:117], v[206:209], v[178:181], v[114:117]
	v_mfma_f32_16x16x32_f16 v[94:97], v[194:197], v[186:189], v[94:97]
	v_mfma_f32_16x16x32_f16 v[98:101], v[206:209], v[186:189], v[98:101]
	s_barrier
	ds_read_b128 v[118:121], v218
	ds_read_b128 v[122:125], v218 offset:1024
	ds_read_b128 v[126:129], v218 offset:2048
	ds_read_b128 v[130:133], v218 offset:3072
	s_add_u32 s30, s18, 0x400000
	s_addc_u32 s31, s19, 0
	s_mov_b32 m0, s8
	v_lshl_add_u64 v[190:191], s[30:31], 0, v[8:9]
	ds_read_b128 v[134:137], v13 offset:32768
	ds_read_b128 v[138:141], v13 offset:33792
	ds_read_b128 v[166:169], v13 offset:34816
	ds_read_b128 v[170:173], v13 offset:35840
	ds_read_b128 v[174:177], v13 offset:36864
	ds_read_b128 v[178:181], v13 offset:37888
	ds_read_b128 v[182:185], v13 offset:38912
	ds_read_b128 v[186:189], v13 offset:39936
	global_load_lds_dwordx4 v[190:191], off
	v_lshl_add_u64 v[190:191], s[30:31], 0, v[6:7]
	s_mov_b32 m0, s9
	s_nop 0
	global_load_lds_dwordx4 v[190:191], off
	s_waitcnt lgkmcnt(8)
	s_barrier
	s_waitcnt lgkmcnt(0)
	v_mfma_f32_16x16x32_f16 v[62:65], v[118:121], v[134:137], v[62:65]
	v_mfma_f32_16x16x32_f16 v[66:69], v[126:129], v[134:137], v[66:69]
	v_mfma_f32_16x16x32_f16 v[70:73], v[118:121], v[166:169], v[70:73]
	v_mfma_f32_16x16x32_f16 v[74:77], v[126:129], v[166:169], v[74:77]
	v_mfma_f32_16x16x32_f16 v[78:81], v[118:121], v[174:177], v[78:81]
	v_mfma_f32_16x16x32_f16 v[82:85], v[126:129], v[174:177], v[82:85]
	v_mfma_f32_16x16x32_f16 v[86:89], v[118:121], v[182:185], v[86:89]
	v_mfma_f32_16x16x32_f16 v[90:93], v[126:129], v[182:185], v[90:93]
	v_mfma_f32_16x16x32_f16 v[62:65], v[122:125], v[138:141], v[62:65]
	v_mfma_f32_16x16x32_f16 v[66:69], v[130:133], v[138:141], v[66:69]
	v_mfma_f32_16x16x32_f16 v[70:73], v[122:125], v[170:173], v[70:73]
	v_mfma_f32_16x16x32_f16 v[74:77], v[130:133], v[170:173], v[74:77]
	v_mfma_f32_16x16x32_f16 v[78:81], v[122:125], v[178:181], v[78:81]
	v_mfma_f32_16x16x32_f16 v[82:85], v[130:133], v[178:181], v[82:85]
	v_mfma_f32_16x16x32_f16 v[86:89], v[122:125], v[186:189], v[86:89]
	v_mfma_f32_16x16x32_f16 v[90:93], v[130:133], v[186:189], v[90:93]
	s_barrier
	s_mov_b32 m0, s45
	v_lshl_add_u64 v[202:203], v[202:203], 0, s[88:89]
	ds_read_b128 v[190:193], v219
	ds_read_b128 v[194:197], v219 offset:1024
	ds_read_b128 v[198:201], v219 offset:2048
	ds_read_b128 v[206:209], v219 offset:3072
	global_load_lds_dwordx4 v[202:203], off
	v_lshl_add_u64 v[202:203], v[210:211], 0, s[88:89]
	s_mov_b32 m0, s44
	s_nop 0
	global_load_lds_dwordx4 v[202:203], off
	s_barrier
	s_waitcnt lgkmcnt(0)
	v_mfma_f32_16x16x32_f16 v[110:113], v[190:193], v[134:137], v[110:113]
	v_mfma_f32_16x16x32_f16 v[30:33], v[198:201], v[134:137], v[30:33]
	v_mfma_f32_16x16x32_f16 v[34:37], v[190:193], v[166:169], v[34:37]
	v_mfma_f32_16x16x32_f16 v[38:41], v[198:201], v[166:169], v[38:41]
	v_mfma_f32_16x16x32_f16 v[42:45], v[190:193], v[174:177], v[42:45]
	v_mfma_f32_16x16x32_f16 v[46:49], v[198:201], v[174:177], v[46:49]
	v_mfma_f32_16x16x32_f16 v[50:53], v[190:193], v[182:185], v[50:53]
	v_mfma_f32_16x16x32_f16 v[54:57], v[198:201], v[182:185], v[54:57]
	v_mfma_f32_16x16x32_f16 v[110:113], v[194:197], v[138:141], v[110:113]
	v_mfma_f32_16x16x32_f16 v[30:33], v[206:209], v[138:141], v[30:33]
	v_mfma_f32_16x16x32_f16 v[34:37], v[194:197], v[170:173], v[34:37]
	v_mfma_f32_16x16x32_f16 v[38:41], v[206:209], v[170:173], v[38:41]
	v_mfma_f32_16x16x32_f16 v[42:45], v[194:197], v[178:181], v[42:45]
	v_mfma_f32_16x16x32_f16 v[46:49], v[206:209], v[178:181], v[46:49]
	v_mfma_f32_16x16x32_f16 v[50:53], v[194:197], v[186:189], v[50:53]
	v_mfma_f32_16x16x32_f16 v[54:57], v[206:209], v[186:189], v[54:57]
	s_mov_b32 m0, s10
	v_lshl_add_u64 v[202:203], v[212:213], 0, s[88:89]
	s_barrier
	ds_read_b128 v[134:137], v13 offset:49152
	ds_read_b128 v[138:141], v13 offset:50176
	ds_read_b128 v[166:169], v13 offset:51200
	ds_read_b128 v[170:173], v13 offset:52224
	ds_read_b128 v[174:177], v13 offset:53248
	ds_read_b128 v[178:181], v13 offset:54272
	ds_read_b128 v[182:185], v13 offset:55296
	ds_read_b128 v[186:189], v13 offset:56320
	global_load_lds_dwordx4 v[202:203], off
	v_lshl_add_u64 v[202:203], v[214:215], 0, s[88:89]
	s_mov_b32 m0, s11
	s_nop 0
	global_load_lds_dwordx4 v[202:203], off
	s_barrier
	s_waitcnt lgkmcnt(0)
	v_mfma_f32_16x16x32_f16 v[142:145], v[118:121], v[134:137], v[142:145]
	v_mfma_f32_16x16x32_f16 v[146:149], v[126:129], v[134:137], v[146:149]
	v_mfma_f32_16x16x32_f16 v[150:153], v[118:121], v[166:169], v[150:153]
	v_mfma_f32_16x16x32_f16 v[154:157], v[126:129], v[166:169], v[154:157]
	v_mfma_f32_16x16x32_f16 v[158:161], v[118:121], v[174:177], v[158:161]
	v_mfma_f32_16x16x32_f16 v[162:165], v[126:129], v[174:177], v[162:165]
	v_mfma_f32_16x16x32_f16 v[14:17], v[118:121], v[182:185], v[14:17]
	v_mfma_f32_16x16x32_f16 v[18:21], v[126:129], v[182:185], v[18:21]
	v_mfma_f32_16x16x32_f16 v[142:145], v[122:125], v[138:141], v[142:145]
	v_mfma_f32_16x16x32_f16 v[146:149], v[130:133], v[138:141], v[146:149]
	v_mfma_f32_16x16x32_f16 v[150:153], v[122:125], v[170:173], v[150:153]
	v_mfma_f32_16x16x32_f16 v[154:157], v[130:133], v[170:173], v[154:157]
	v_mfma_f32_16x16x32_f16 v[158:161], v[122:125], v[178:181], v[158:161]
	v_mfma_f32_16x16x32_f16 v[162:165], v[130:133], v[178:181], v[162:165]
	v_mfma_f32_16x16x32_f16 v[14:17], v[122:125], v[186:189], v[14:17]
	v_mfma_f32_16x16x32_f16 v[18:21], v[130:133], v[186:189], v[18:21]
	s_barrier
	s_add_u32 s30, s26, 0x10080
	s_addc_u32 s31, s27, 0
	s_mov_b32 m0, s41
	v_lshl_add_u64 v[118:119], s[30:31], 0, v[2:3]
	global_load_lds_dwordx4 v[118:119], off
	v_lshl_add_u64 v[118:119], s[30:31], 0, v[4:5]
	s_mov_b32 m0, s40
	s_nop 0
	global_load_lds_dwordx4 v[118:119], off
	s_waitcnt vmcnt(6)
	s_barrier
	v_mfma_f32_16x16x32_f16 v[22:25], v[190:193], v[134:137], v[22:25]
	v_mfma_f32_16x16x32_f16 v[26:29], v[198:201], v[134:137], v[26:29]
	v_mfma_f32_16x16x32_f16 v[58:61], v[190:193], v[166:169], v[58:61]
	v_mfma_f32_16x16x32_f16 v[102:105], v[198:201], v[166:169], v[102:105]
	v_mfma_f32_16x16x32_f16 v[106:109], v[190:193], v[174:177], v[106:109]
	v_mfma_f32_16x16x32_f16 v[114:117], v[198:201], v[174:177], v[114:117]
	v_mfma_f32_16x16x32_f16 v[94:97], v[190:193], v[182:185], v[94:97]
	v_mfma_f32_16x16x32_f16 v[98:101], v[198:201], v[182:185], v[98:101]
	v_mfma_f32_16x16x32_f16 v[22:25], v[194:197], v[138:141], v[22:25]
	v_mfma_f32_16x16x32_f16 v[26:29], v[206:209], v[138:141], v[26:29]
	v_mfma_f32_16x16x32_f16 v[58:61], v[194:197], v[170:173], v[58:61]
	v_mfma_f32_16x16x32_f16 v[102:105], v[206:209], v[170:173], v[102:105]
	v_mfma_f32_16x16x32_f16 v[106:109], v[194:197], v[178:181], v[106:109]
	v_mfma_f32_16x16x32_f16 v[114:117], v[206:209], v[178:181], v[114:117]
	v_mfma_f32_16x16x32_f16 v[94:97], v[194:197], v[186:189], v[94:97]
	v_mfma_f32_16x16x32_f16 v[98:101], v[206:209], v[186:189], v[98:101]
	v_mov_b32_e32 v118, v10
	s_lshl_b32 s17, s29, 8
	s_barrier
	v_mov_b32_e32 v119, v11
	s_add_i32 s17, s17, s12
	v_add_u32_e32 v118, s17, v118
	s_ashr_i32 s37, s36, 31
	v_lshl_add_u32 v120, v119, 2, s13
	s_lshl_b64 s[30:31], s[36:37], 10
	v_ashrrev_i32_e32 v119, 31, v118
	v_readlane_b32 s36, v252, 62
	v_lshlrev_b64 v[118:119], 15, v[118:119]
	v_readlane_b32 s37, v252, 63
	v_ashrrev_i32_e32 v121, 31, v120
	s_mov_b32 s17, 0x80000
	v_lshl_add_u64 v[118:119], s[36:37], 0, v[118:119]
	v_lshl_add_u64 v[118:119], v[118:119], 0, s[30:31]
	v_lshl_add_u64 v[118:119], v[120:121], 2, v[118:119]
	global_store_dwordx4 v[118:119], v[62:65], off
	global_store_dwordx4 v[118:119], v[66:69], off offset:64
	global_store_dwordx4 v[118:119], v[110:113], off offset:512
	global_store_dwordx4 v[118:119], v[30:33], off offset:576
	s_mov_b64 s[30:31], 0x80000
	s_mov_b32 s36, s15
	v_add_co_u32_e32 v32, vcc, s17, v118
	s_mov_b32 s17, 0x100000
	s_nop 0
	v_addc_co_u32_e32 v33, vcc, 0, v119, vcc
	v_lshl_add_u64 v[30:31], v[118:119], 0, s[30:31]
	global_store_dwordx4 v[32:33], v[70:73], off
	global_store_dwordx4 v[30:31], v[74:77], off offset:64
	global_store_dwordx4 v[30:31], v[34:37], off offset:512
	global_store_dwordx4 v[30:31], v[38:41], off offset:576
	v_add_co_u32_e32 v32, vcc, s17, v118
	s_mov_b64 s[30:31], 0x100000
	s_nop 0
	v_addc_co_u32_e32 v33, vcc, 0, v119, vcc
	s_mov_b32 s17, 0x180000
	v_lshl_add_u64 v[30:31], v[118:119], 0, s[30:31]
	global_store_dwordx4 v[32:33], v[78:81], off
	global_store_dwordx4 v[30:31], v[82:85], off offset:64
	global_store_dwordx4 v[30:31], v[42:45], off offset:512
	global_store_dwordx4 v[30:31], v[46:49], off offset:576
	v_add_co_u32_e32 v32, vcc, s17, v118
	s_mov_b64 s[30:31], 0x180000
	s_nop 0
	v_addc_co_u32_e32 v33, vcc, 0, v119, vcc
	s_mov_b32 s17, 0x400000
	v_lshl_add_u64 v[30:31], v[118:119], 0, s[30:31]
	global_store_dwordx4 v[32:33], v[86:89], off
	global_store_dwordx4 v[30:31], v[90:93], off offset:64
	global_store_dwordx4 v[30:31], v[50:53], off offset:512
	global_store_dwordx4 v[30:31], v[54:57], off offset:576
	v_add_co_u32_e32 v32, vcc, s17, v118
	s_mov_b64 s[30:31], 0x400000
	s_nop 0
	v_addc_co_u32_e32 v33, vcc, 0, v119, vcc
	s_mov_b32 s17, 0x480000
	v_lshl_add_u64 v[30:31], v[118:119], 0, s[30:31]
	global_store_dwordx4 v[32:33], v[142:145], off
	global_store_dwordx4 v[30:31], v[146:149], off offset:64
	global_store_dwordx4 v[30:31], v[22:25], off offset:512
	global_store_dwordx4 v[30:31], v[26:29], off offset:576
	s_mov_b64 s[30:31], 0x480000
	v_add_co_u32_e32 v24, vcc, s17, v118
	s_mov_b32 s17, 0x500000
	s_nop 0
	v_addc_co_u32_e32 v25, vcc, 0, v119, vcc
	v_lshl_add_u64 v[22:23], v[118:119], 0, s[30:31]
	global_store_dwordx4 v[24:25], v[150:153], off
	global_store_dwordx4 v[22:23], v[154:157], off offset:64
	global_store_dwordx4 v[22:23], v[58:61], off offset:512
	global_store_dwordx4 v[22:23], v[102:105], off offset:576
	v_add_co_u32_e32 v24, vcc, s17, v118
	s_mov_b64 s[30:31], 0x500000
	s_nop 0
	v_addc_co_u32_e32 v25, vcc, 0, v119, vcc
	v_lshl_add_u64 v[22:23], v[118:119], 0, s[30:31]
	global_store_dwordx4 v[24:25], v[158:161], off
	global_store_dwordx4 v[22:23], v[162:165], off offset:64
	global_store_dwordx4 v[22:23], v[106:109], off offset:512
	global_store_dwordx4 v[22:23], v[114:117], off offset:576
	v_add_co_u32_e32 v24, vcc, 0x580000, v118
	s_mov_b64 s[30:31], 0x580000
	s_nop 0
	v_addc_co_u32_e32 v25, vcc, 0, v119, vcc
	s_andn2_b64 vcc, exec, s[34:35]
	s_mov_b32 s29, s16
	s_mov_b64 s[40:41], s[26:27]
	s_mov_b64 s[38:39], s[18:19]
	v_lshl_add_u64 v[22:23], v[118:119], 0, s[30:31]
	global_store_dwordx4 v[24:25], v[14:17], off
	global_store_dwordx4 v[22:23], v[18:21], off offset:64
	global_store_dwordx4 v[22:23], v[94:97], off offset:512
	global_store_dwordx4 v[22:23], v[98:101], off offset:576
	s_cbranch_vccz .LBB0_888

.LBB0_1341:
	s_add_u32 s29, s26, 0xffc00080
	s_addc_u32 s31, s27, -1
	s_add_i32 s48, 0, 0x10000
	v_add_u32_e32 v2, s48, v190
	ds_read_b128 v[28:31], v2
	ds_read_b128 v[32:35], v2 offset:1024
	ds_read_b128 v[100:103], v2 offset:2048
	ds_read_b128 v[112:115], v2 offset:3072
	s_cmp_eq_u32 s19, 4
	s_cselect_b32 s43, s35, s31
	s_cselect_b32 s42, s34, s29
	s_cselect_b32 s39, s37, s17
	s_cselect_b32 s38, s36, s11
	v_lshl_add_u64 v[196:197], s[26:27], 0, v[180:181]
	s_add_i32 m0, s7, 0xc000
	ds_read_b128 v[124:127], v191
	ds_read_b128 v[136:139], v191 offset:1024
	ds_read_b128 v[148:151], v191 offset:2048
	ds_read_b128 v[156:159], v191 offset:3072
	ds_read_b128 v[164:167], v191 offset:4096
	ds_read_b128 v[168:171], v191 offset:5120
	ds_read_b128 v[184:187], v191 offset:6144
	ds_read_b128 v[192:195], v191 offset:7168
	global_load_lds_dwordx4 v[196:197], off
	v_lshl_add_u64 v[196:197], s[26:27], 0, v[182:183]
	s_add_i32 m0, s7, 0xe000
	s_nop 0
	global_load_lds_dwordx4 v[196:197], off
	s_waitcnt lgkmcnt(8)
	s_barrier
	s_waitcnt lgkmcnt(0)
	v_mfma_f32_16x16x32_f16 v[160:163], v[28:31], v[124:127], v[160:163]
	v_mfma_f32_16x16x32_f16 v[152:155], v[100:103], v[124:127], v[152:155]
	v_mfma_f32_16x16x32_f16 v[132:135], v[28:31], v[148:151], v[132:135]
	v_mfma_f32_16x16x32_f16 v[128:131], v[100:103], v[148:151], v[128:131]
	v_mfma_f32_16x16x32_f16 v[108:111], v[28:31], v[164:167], v[108:111]
	v_mfma_f32_16x16x32_f16 v[104:107], v[100:103], v[164:167], v[104:107]
	v_mfma_f32_16x16x32_f16 v[88:91], v[28:31], v[184:187], v[88:91]
	v_mfma_f32_16x16x32_f16 v[84:87], v[100:103], v[184:187], v[84:87]
	v_mfma_f32_16x16x32_f16 v[160:163], v[32:35], v[136:139], v[160:163]
	v_mfma_f32_16x16x32_f16 v[152:155], v[112:115], v[136:139], v[152:155]
	v_mfma_f32_16x16x32_f16 v[132:135], v[32:35], v[156:159], v[132:135]
	v_mfma_f32_16x16x32_f16 v[128:131], v[112:115], v[156:159], v[128:131]
	v_mfma_f32_16x16x32_f16 v[108:111], v[32:35], v[168:171], v[108:111]
	v_mfma_f32_16x16x32_f16 v[104:107], v[112:115], v[168:171], v[104:107]
	v_mfma_f32_16x16x32_f16 v[88:91], v[32:35], v[192:195], v[88:91]
	v_mfma_f32_16x16x32_f16 v[84:87], v[112:115], v[192:195], v[84:87]
	s_barrier
	s_add_i32 s29, 0, 0x14000
	s_add_i32 s31, s48, s6
	v_add_u32_e32 v2, s29, v190
	v_lshl_add_u64 v[214:215], s[38:39], 0, v[176:177]
	s_mov_b32 m0, s31
	ds_read_b128 v[196:199], v2
	ds_read_b128 v[200:203], v2 offset:1024
	ds_read_b128 v[206:209], v2 offset:2048
	ds_read_b128 v[210:213], v2 offset:3072
	global_load_lds_dwordx4 v[214:215], off
	v_lshl_add_u64 v[216:217], s[38:39], 0, v[172:173]
	s_add_i32 m0, s31, 0x2000
	s_nop 0
	global_load_lds_dwordx4 v[216:217], off
	s_barrier
	s_waitcnt lgkmcnt(0)
	v_mfma_f32_16x16x32_f16 v[144:147], v[196:199], v[124:127], v[144:147]
	v_mfma_f32_16x16x32_f16 v[120:123], v[196:199], v[148:151], v[120:123]
	v_mfma_f32_16x16x32_f16 v[116:119], v[206:209], v[148:151], v[116:119]
	v_mfma_f32_16x16x32_f16 v[96:99], v[196:199], v[164:167], v[96:99]
	v_mfma_f32_16x16x32_f16 v[92:95], v[206:209], v[164:167], v[92:95]
	v_mfma_f32_16x16x32_f16 v[80:83], v[196:199], v[184:187], v[80:83]
	v_mfma_f32_16x16x32_f16 v[76:79], v[206:209], v[184:187], v[76:79]
	v_mfma_f32_16x16x32_f16 v[144:147], v[200:203], v[136:139], v[144:147]
	v_mfma_f32_16x16x32_f16 v[124:127], v[206:209], v[124:127], v[140:143]
	v_mfma_f32_16x16x32_f16 v[120:123], v[200:203], v[156:159], v[120:123]
	v_mfma_f32_16x16x32_f16 v[116:119], v[210:213], v[156:159], v[116:119]
	v_mfma_f32_16x16x32_f16 v[96:99], v[200:203], v[168:171], v[96:99]
	v_mfma_f32_16x16x32_f16 v[92:95], v[210:213], v[168:171], v[92:95]
	v_mfma_f32_16x16x32_f16 v[80:83], v[200:203], v[192:195], v[80:83]
	v_mfma_f32_16x16x32_f16 v[76:79], v[210:213], v[192:195], v[76:79]
	v_mfma_f32_16x16x32_f16 v[124:127], v[210:213], v[136:139], v[124:127]
	s_mov_b32 m0, s7
	v_lshl_add_u64 v[218:219], s[42:43], 0, v[178:179]
	s_barrier
	ds_read_b128 v[136:139], v191 offset:16384
	ds_read_b128 v[140:143], v191 offset:17408
	ds_read_b128 v[148:151], v191 offset:18432
	ds_read_b128 v[156:159], v191 offset:19456
	ds_read_b128 v[164:167], v191 offset:20480
	ds_read_b128 v[168:171], v191 offset:21504
	ds_read_b128 v[184:187], v191 offset:22528
	ds_read_b128 v[192:195], v191 offset:23552
	global_load_lds_dwordx4 v[218:219], off
	v_lshl_add_u64 v[220:221], s[42:43], 0, v[174:175]
	s_mov_b32 m0, s8
	s_nop 0
	global_load_lds_dwordx4 v[220:221], off
	s_barrier
	s_waitcnt lgkmcnt(0)
	v_mfma_f32_16x16x32_f16 v[72:75], v[28:31], v[136:139], v[72:75]
	v_mfma_f32_16x16x32_f16 v[68:71], v[100:103], v[136:139], v[68:71]
	v_mfma_f32_16x16x32_f16 v[56:59], v[28:31], v[148:151], v[56:59]
	v_mfma_f32_16x16x32_f16 v[52:55], v[100:103], v[148:151], v[52:55]
	v_mfma_f32_16x16x32_f16 v[40:43], v[28:31], v[164:167], v[40:43]
	v_mfma_f32_16x16x32_f16 v[36:39], v[100:103], v[164:167], v[36:39]
	v_mfma_f32_16x16x32_f16 v[16:19], v[28:31], v[184:187], v[16:19]
	v_mfma_f32_16x16x32_f16 v[12:15], v[100:103], v[184:187], v[12:15]
	v_mfma_f32_16x16x32_f16 v[72:75], v[32:35], v[140:143], v[72:75]
	v_mfma_f32_16x16x32_f16 v[68:71], v[112:115], v[140:143], v[68:71]
	v_mfma_f32_16x16x32_f16 v[56:59], v[32:35], v[156:159], v[56:59]
	v_mfma_f32_16x16x32_f16 v[52:55], v[112:115], v[156:159], v[52:55]
	v_mfma_f32_16x16x32_f16 v[40:43], v[32:35], v[168:171], v[40:43]
	v_mfma_f32_16x16x32_f16 v[36:39], v[112:115], v[168:171], v[36:39]
	v_mfma_f32_16x16x32_f16 v[16:19], v[32:35], v[192:195], v[16:19]
	v_mfma_f32_16x16x32_f16 v[12:15], v[112:115], v[192:195], v[12:15]
	s_barrier
	s_add_u32 s48, s38, 0x20000
	s_addc_u32 s49, s39, 0
	s_add_i32 s29, s29, s6
	v_lshl_add_u64 v[28:29], s[48:49], 0, v[176:177]
	s_mov_b32 m0, s29
	s_nop 0
	global_load_lds_dwordx4 v[28:29], off
	v_lshl_add_u64 v[28:29], s[48:49], 0, v[172:173]
	s_add_i32 m0, s29, 0x2000
	s_nop 0
	global_load_lds_dwordx4 v[28:29], off
	s_waitcnt vmcnt(6)
	s_barrier
	v_mfma_f32_16x16x32_f16 v[48:51], v[196:199], v[148:151], v[48:51]
	v_mfma_f32_16x16x32_f16 v[44:47], v[206:209], v[148:151], v[44:47]
	v_mfma_f32_16x16x32_f16 v[24:27], v[196:199], v[164:167], v[24:27]
	v_mfma_f32_16x16x32_f16 v[20:23], v[206:209], v[164:167], v[20:23]
	v_mfma_f32_16x16x32_f16 v[8:11], v[196:199], v[184:187], v[8:11]
	v_mfma_f32_16x16x32_f16 v[4:7], v[206:209], v[184:187], v[4:7]
	v_mfma_f32_16x16x32_f16 v[28:31], v[196:199], v[136:139], v[64:67]
	v_mfma_f32_16x16x32_f16 v[32:35], v[206:209], v[136:139], v[60:63]
	v_mfma_f32_16x16x32_f16 v[48:51], v[200:203], v[156:159], v[48:51]
	v_mfma_f32_16x16x32_f16 v[44:47], v[210:213], v[156:159], v[44:47]
	v_mfma_f32_16x16x32_f16 v[24:27], v[200:203], v[168:171], v[24:27]
	v_mfma_f32_16x16x32_f16 v[20:23], v[210:213], v[168:171], v[20:23]
	v_mfma_f32_16x16x32_f16 v[8:11], v[200:203], v[192:195], v[8:11]
	v_mfma_f32_16x16x32_f16 v[4:7], v[210:213], v[192:195], v[4:7]
	v_mfma_f32_16x16x32_f16 v[28:31], v[200:203], v[140:143], v[28:31]
	v_mfma_f32_16x16x32_f16 v[32:35], v[210:213], v[140:143], v[32:35]
	s_add_i32 s29, 0, 0x18000
	v_add_u32_e32 v2, s29, v190
	s_barrier
	ds_read_b128 v[60:63], v2
	ds_read_b128 v[64:67], v2 offset:1024
	ds_read_b128 v[100:103], v2 offset:2048
	ds_read_b128 v[112:115], v2 offset:3072
	s_add_u32 s42, s42, 0x400000
	s_addc_u32 s43, s43, 0
	s_mov_b32 m0, s9
	v_lshl_add_u64 v[196:197], s[42:43], 0, v[178:179]
	ds_read_b128 v[136:139], v191 offset:32768
	ds_read_b128 v[140:143], v191 offset:33792
	ds_read_b128 v[148:151], v191 offset:34816
	ds_read_b128 v[156:159], v191 offset:35840
	ds_read_b128 v[164:167], v191 offset:36864
	ds_read_b128 v[168:171], v191 offset:37888
	ds_read_b128 v[184:187], v191 offset:38912
	ds_read_b128 v[192:195], v191 offset:39936
	global_load_lds_dwordx4 v[196:197], off
	v_lshl_add_u64 v[196:197], s[42:43], 0, v[174:175]
	s_mov_b32 m0, s12
	s_nop 0
	global_load_lds_dwordx4 v[196:197], off
	s_waitcnt lgkmcnt(8)
	s_barrier
	s_waitcnt lgkmcnt(0)
	v_mfma_f32_16x16x32_f16 v[160:163], v[60:63], v[136:139], v[160:163]
	v_mfma_f32_16x16x32_f16 v[152:155], v[100:103], v[136:139], v[152:155]
	v_mfma_f32_16x16x32_f16 v[132:135], v[60:63], v[148:151], v[132:135]
	v_mfma_f32_16x16x32_f16 v[128:131], v[100:103], v[148:151], v[128:131]
	v_mfma_f32_16x16x32_f16 v[108:111], v[60:63], v[164:167], v[108:111]
	v_mfma_f32_16x16x32_f16 v[104:107], v[100:103], v[164:167], v[104:107]
	v_mfma_f32_16x16x32_f16 v[88:91], v[60:63], v[184:187], v[88:91]
	v_mfma_f32_16x16x32_f16 v[84:87], v[100:103], v[184:187], v[84:87]
	v_mfma_f32_16x16x32_f16 v[160:163], v[64:67], v[140:143], v[160:163]
	v_mfma_f32_16x16x32_f16 v[152:155], v[112:115], v[140:143], v[152:155]
	v_mfma_f32_16x16x32_f16 v[132:135], v[64:67], v[156:159], v[132:135]
	v_mfma_f32_16x16x32_f16 v[128:131], v[112:115], v[156:159], v[128:131]
	v_mfma_f32_16x16x32_f16 v[108:111], v[64:67], v[168:171], v[108:111]
	v_mfma_f32_16x16x32_f16 v[104:107], v[112:115], v[168:171], v[104:107]
	v_mfma_f32_16x16x32_f16 v[88:91], v[64:67], v[192:195], v[88:91]
	v_mfma_f32_16x16x32_f16 v[84:87], v[112:115], v[192:195], v[84:87]
	s_barrier
	s_add_i32 s31, 0, 0x1c000
	s_add_i32 s29, s29, s6
	v_add_u32_e32 v2, s31, v190
	v_lshl_add_u64 v[214:215], v[214:215], 0, s[88:89]
	s_mov_b32 m0, s29
	ds_read_b128 v[196:199], v2
	ds_read_b128 v[200:203], v2 offset:1024
	ds_read_b128 v[206:209], v2 offset:2048
	ds_read_b128 v[210:213], v2 offset:3072
	global_load_lds_dwordx4 v[214:215], off
	v_lshl_add_u64 v[214:215], v[216:217], 0, s[88:89]
	s_add_i32 m0, s29, 0x2000
	s_nop 0
	global_load_lds_dwordx4 v[214:215], off
	s_barrier
	s_waitcnt lgkmcnt(0)
	v_mfma_f32_16x16x32_f16 v[144:147], v[196:199], v[136:139], v[144:147]
	v_mfma_f32_16x16x32_f16 v[124:127], v[206:209], v[136:139], v[124:127]
	v_mfma_f32_16x16x32_f16 v[120:123], v[196:199], v[148:151], v[120:123]
	v_mfma_f32_16x16x32_f16 v[116:119], v[206:209], v[148:151], v[116:119]
	v_mfma_f32_16x16x32_f16 v[96:99], v[196:199], v[164:167], v[96:99]
	v_mfma_f32_16x16x32_f16 v[92:95], v[206:209], v[164:167], v[92:95]
	v_mfma_f32_16x16x32_f16 v[80:83], v[196:199], v[184:187], v[80:83]
	v_mfma_f32_16x16x32_f16 v[76:79], v[206:209], v[184:187], v[76:79]
	v_mfma_f32_16x16x32_f16 v[144:147], v[200:203], v[140:143], v[144:147]
	v_mfma_f32_16x16x32_f16 v[140:143], v[210:213], v[140:143], v[124:127]
	v_mfma_f32_16x16x32_f16 v[120:123], v[200:203], v[156:159], v[120:123]
	v_mfma_f32_16x16x32_f16 v[116:119], v[210:213], v[156:159], v[116:119]
	v_mfma_f32_16x16x32_f16 v[96:99], v[200:203], v[168:171], v[96:99]
	v_mfma_f32_16x16x32_f16 v[92:95], v[210:213], v[168:171], v[92:95]
	v_mfma_f32_16x16x32_f16 v[80:83], v[200:203], v[192:195], v[80:83]
	v_mfma_f32_16x16x32_f16 v[76:79], v[210:213], v[192:195], v[76:79]
	s_mov_b32 m0, s15
	v_lshl_add_u64 v[214:215], v[218:219], 0, s[88:89]
	s_barrier
	ds_read_b128 v[124:127], v191 offset:49152
	ds_read_b128 v[136:139], v191 offset:50176
	ds_read_b128 v[148:151], v191 offset:51200
	ds_read_b128 v[156:159], v191 offset:52224
	ds_read_b128 v[164:167], v191 offset:53248
	ds_read_b128 v[168:171], v191 offset:54272
	ds_read_b128 v[184:187], v191 offset:55296
	ds_read_b128 v[192:195], v191 offset:56320
	global_load_lds_dwordx4 v[214:215], off
	v_lshl_add_u64 v[214:215], v[220:221], 0, s[88:89]
	s_mov_b32 m0, s30
	s_nop 0
	global_load_lds_dwordx4 v[214:215], off
	s_barrier
	s_waitcnt lgkmcnt(0)
	v_mfma_f32_16x16x32_f16 v[72:75], v[60:63], v[124:127], v[72:75]
	v_mfma_f32_16x16x32_f16 v[68:71], v[100:103], v[124:127], v[68:71]
	v_mfma_f32_16x16x32_f16 v[56:59], v[60:63], v[148:151], v[56:59]
	v_mfma_f32_16x16x32_f16 v[52:55], v[100:103], v[148:151], v[52:55]
	v_mfma_f32_16x16x32_f16 v[40:43], v[60:63], v[164:167], v[40:43]
	v_mfma_f32_16x16x32_f16 v[36:39], v[100:103], v[164:167], v[36:39]
	v_mfma_f32_16x16x32_f16 v[16:19], v[60:63], v[184:187], v[16:19]
	v_mfma_f32_16x16x32_f16 v[12:15], v[100:103], v[184:187], v[12:15]
	v_mfma_f32_16x16x32_f16 v[72:75], v[64:67], v[136:139], v[72:75]
	v_mfma_f32_16x16x32_f16 v[68:71], v[112:115], v[136:139], v[68:71]
	v_mfma_f32_16x16x32_f16 v[56:59], v[64:67], v[156:159], v[56:59]
	v_mfma_f32_16x16x32_f16 v[52:55], v[112:115], v[156:159], v[52:55]
	v_mfma_f32_16x16x32_f16 v[40:43], v[64:67], v[168:171], v[40:43]
	v_mfma_f32_16x16x32_f16 v[36:39], v[112:115], v[168:171], v[36:39]
	v_mfma_f32_16x16x32_f16 v[16:19], v[64:67], v[192:195], v[16:19]
	v_mfma_f32_16x16x32_f16 v[12:15], v[112:115], v[192:195], v[12:15]
	s_barrier
	s_add_u32 s38, s38, 0x20080
	s_addc_u32 s39, s39, 0
	s_add_i32 s29, s31, s6
	v_lshl_add_u64 v[60:61], s[38:39], 0, v[176:177]
	s_mov_b32 m0, s29
	s_nop 0
	global_load_lds_dwordx4 v[60:61], off
	v_lshl_add_u64 v[60:61], s[38:39], 0, v[172:173]
	s_add_i32 m0, s29, 0x2000
	s_nop 0
	global_load_lds_dwordx4 v[60:61], off
	s_waitcnt vmcnt(6)
	s_barrier
	v_mfma_f32_16x16x32_f16 v[28:31], v[196:199], v[124:127], v[28:31]
	v_mfma_f32_16x16x32_f16 v[64:67], v[200:203], v[136:139], v[28:31]
	v_mfma_f32_16x16x32_f16 v[28:31], v[206:209], v[124:127], v[32:35]
	v_mfma_f32_16x16x32_f16 v[60:63], v[210:213], v[136:139], v[28:31]
	v_mfma_f32_16x16x32_f16 v[28:31], v[196:199], v[148:151], v[48:51]
	v_mfma_f32_16x16x32_f16 v[48:51], v[200:203], v[156:159], v[28:31]
	v_mfma_f32_16x16x32_f16 v[28:31], v[206:209], v[148:151], v[44:47]
	v_mfma_f32_16x16x32_f16 v[24:27], v[196:199], v[164:167], v[24:27]
	v_mfma_f32_16x16x32_f16 v[20:23], v[206:209], v[164:167], v[20:23]
	v_mfma_f32_16x16x32_f16 v[8:11], v[196:199], v[184:187], v[8:11]
	v_mfma_f32_16x16x32_f16 v[4:7], v[206:209], v[184:187], v[4:7]
	v_mfma_f32_16x16x32_f16 v[44:47], v[210:213], v[156:159], v[28:31]
	v_mfma_f32_16x16x32_f16 v[24:27], v[200:203], v[168:171], v[24:27]
	v_mfma_f32_16x16x32_f16 v[20:23], v[210:213], v[168:171], v[20:23]
	v_mfma_f32_16x16x32_f16 v[8:11], v[200:203], v[192:195], v[8:11]
	v_mfma_f32_16x16x32_f16 v[4:7], v[210:213], v[192:195], v[4:7]
	s_add_i32 s19, s19, 2
	s_add_u32 s26, s26, 0x100
	s_addc_u32 s27, s27, 0
	s_add_u32 s11, s11, 0x100
	s_addc_u32 s17, s17, 0
	s_cmp_gt_u32 s19, 5
	s_barrier
	s_cbranch_scc0 .LBB0_1341
	v_mov_b32_e32 v2, v188
	s_lshl_b32 s10, s10, 8
	s_lshl_b32 s26, s16, 4
	v_mov_b32_e32 v28, v189
	s_add_i32 s10, s10, s44
	s_ashr_i32 s27, s26, 31
	v_add_u32_e32 v100, s10, v2
	v_lshlrev_b32_e32 v2, 3, v28
	s_lshl_b64 s[10:11], s[26:27], 2
	v_and_b32_e32 v193, 8, v2
	s_add_u32 s10, s13, s10
	v_add_u32_e32 v186, s45, v2
	s_addc_u32 s11, s14, s11
	v_lshlrev_b32_e32 v2, 2, v193
	s_ashr_i32 s17, s16, 31
	v_lshl_add_u64 v[28:29], s[10:11], 0, v[2:3]
	s_lshl_b64 s[10:11], s[16:17], 10
	v_readlane_b32 s16, v253, 2
	v_readlane_b32 s17, v253, 3
	s_add_u32 s10, s16, s10
	v_ashrrev_i32_e32 v187, 31, v186
	s_addc_u32 s11, s17, s11
	v_ashrrev_i32_e32 v101, 31, v100
	v_lshlrev_b32_e32 v192, 4, v100
	v_lshl_add_u64 v[102:103], v[186:187], 1, s[10:11]
	v_lshlrev_b64 v[100:101], 15, v[100:101]
	v_lshl_add_u64 v[184:185], v[102:103], 0, v[100:101]
	s_mov_b64 s[10:11], 0x80000
	v_lshl_add_u64 v[148:149], v[184:185], 0, s[10:11]
	s_mov_b64 s[10:11], 0x100000
	v_lshl_add_u64 v[124:125], v[184:185], 0, s[10:11]
	s_mov_b64 s[10:11], 0x180000
	v_lshl_add_u64 v[100:101], v[184:185], 0, s[10:11]
	s_mov_b32 s10, 0x180000
	v_add_co_u32_e32 v102, vcc, s10, v184
	s_mov_b32 s10, 0x100000
	s_nop 0
	v_addc_co_u32_e32 v103, vcc, 0, v185, vcc
	flat_load_dwordx4 v[32:35], v[28:29]
	s_nop 0
	flat_load_dwordx4 v[28:31], v[28:29] offset:16
	s_mov_b32 s38, 0x3a800000
	global_load_dwordx4 v[112:115], v[102:103], off
	v_add_co_u32_e32 v102, vcc, s10, v184
	s_mov_b32 s10, 0x80000
	s_nop 0
	v_addc_co_u32_e32 v103, vcc, 0, v185, vcc
	global_load_dwordx4 v[136:139], v[102:103], off
	v_add_co_u32_e32 v102, vcc, s10, v184
	v_readlane_b32 s16, v253, 25
	s_nop 0
	v_addc_co_u32_e32 v103, vcc, 0, v185, vcc
	global_load_dwordx4 v[156:159], v[102:103], off
	global_load_dwordx4 v[164:167], v[184:185], off offset:256
	global_load_dwordx4 v[168:171], v[184:185], off
	s_nop 0
	global_load_dwordx4 v[100:103], v[100:101], off offset:256
	s_nop 0
	global_load_dwordx4 v[124:127], v[124:125], off offset:256
	s_nop 0
	global_load_dwordx4 v[148:151], v[148:149], off offset:256
	v_readlane_b32 s17, v253, 26
	s_lshl_b64 s[42:43], s[26:27], 1
	s_mov_b64 s[10:11], 0x400000
	s_mov_b64 s[26:27], s[34:35]
	s_waitcnt vmcnt(0)
	s_nop 0
	v_cvt_f32_f16_e32 v194, v168
	v_cvt_f32_f16_sdwa v195, v168 dst_sel:DWORD dst_unused:UNUSED_PAD src0_sel:WORD_1
	s_waitcnt lgkmcnt(0)
	v_pk_mul_f32 v[194:195], v[32:33], v[194:195]
	s_nop 0
	v_pk_fma_f32 v[160:161], v[160:161], s[38:39], v[194:195] op_sel_hi:[1,0,1]
	s_nop 0
	v_mul_f32_e32 v2, 0x3d372713, v160
	v_mul_f32_e32 v2, v160, v2
	v_fma_f32 v2, v160, v2, v160
	v_mul_f32_e32 v2, 0x3f4c422a, v2
	v_mul_f32_e32 v2, -2.0, v2
	v_mul_f32_e32 v2, 0x3fb8aa3b, v2
	v_exp_f32_e32 v2, v2
	s_nop 0
	v_add_f32_e32 v2, 1.0, v2
	v_rcp_f32_e32 v194, v2
	v_mul_f32_e32 v2, 0x3d372713, v161
	v_mul_f32_e32 v2, v161, v2
	v_fma_f32 v2, v161, v2, v161
	v_mul_f32_e32 v2, 0x3f4c422a, v2
	v_mul_f32_e32 v2, -2.0, v2
	v_mul_f32_e32 v2, 0x3fb8aa3b, v2
	v_exp_f32_e32 v2, v2
	s_nop 0
	v_add_f32_e32 v2, 1.0, v2
	v_rcp_f32_e32 v195, v2
	s_nop 0
	v_pk_mul_f32 v[160:161], v[160:161], v[194:195]
	s_nop 0
	v_cvt_pk_f16_f32 v2, v160, v161
	v_cvt_f32_f16_e32 v160, v170
	v_cvt_f32_f16_sdwa v161, v170 dst_sel:DWORD dst_unused:UNUSED_PAD src0_sel:WORD_1
	v_pk_mul_f32 v[160:161], v[28:29], v[160:161]
	s_nop 0
	v_pk_fma_f32 v[152:153], v[152:153], s[38:39], v[160:161] op_sel_hi:[1,0,1]
	s_nop 0
	v_mul_f32_e32 v160, 0x3d372713, v152
	v_mul_f32_e32 v161, 0x3d372713, v153
	v_mul_f32_e32 v160, v152, v160
	v_mul_f32_e32 v161, v153, v161
	v_fma_f32 v160, v152, v160, v152
	v_fma_f32 v161, v153, v161, v153
	v_mul_f32_e32 v160, 0x3f4c422a, v160
	v_mul_f32_e32 v161, 0x3f4c422a, v161
	v_mul_f32_e32 v160, -2.0, v160
	v_mul_f32_e32 v161, -2.0, v161
	v_mul_f32_e32 v160, 0x3fb8aa3b, v160
	v_mul_f32_e32 v161, 0x3fb8aa3b, v161
	v_exp_f32_e32 v160, v160
	v_exp_f32_e32 v161, v161
	v_add_f32_e32 v160, 1.0, v160
	v_add_f32_e32 v161, 1.0, v161
	v_rcp_f32_e32 v160, v160
	v_rcp_f32_e32 v161, v161
	s_nop 0
	v_pk_mul_f32 v[152:153], v[152:153], v[160:161]
	s_nop 0
	v_cvt_pk_f16_f32 v168, v152, v153
	v_cvt_f32_f16_e32 v152, v169
	v_cvt_f32_f16_sdwa v153, v169 dst_sel:DWORD dst_unused:UNUSED_PAD src0_sel:WORD_1
	v_pk_mul_f32 v[152:153], v[34:35], v[152:153]
	s_nop 0
	v_pk_fma_f32 v[152:153], v[162:163], s[38:39], v[152:153] op_sel_hi:[1,0,1]
	s_nop 0
	v_mul_f32_e32 v160, 0x3d372713, v152
	v_mul_f32_e32 v161, 0x3d372713, v153
	v_mul_f32_e32 v160, v152, v160
	v_mul_f32_e32 v161, v153, v161
	v_fma_f32 v160, v152, v160, v152
	v_fma_f32 v161, v153, v161, v153
	v_mul_f32_e32 v160, 0x3f4c422a, v160
	v_mul_f32_e32 v161, 0x3f4c422a, v161
	v_mul_f32_e32 v160, -2.0, v160
	v_mul_f32_e32 v161, -2.0, v161
	v_mul_f32_e32 v160, 0x3fb8aa3b, v160
	v_mul_f32_e32 v161, 0x3fb8aa3b, v161
	v_exp_f32_e32 v160, v160
	v_exp_f32_e32 v161, v161
	v_add_f32_e32 v160, 1.0, v160
	v_add_f32_e32 v161, 1.0, v161
	v_rcp_f32_e32 v160, v160
	v_rcp_f32_e32 v161, v161
	s_nop 0
	v_pk_mul_f32 v[152:153], v[152:153], v[160:161]
	s_nop 0
	v_cvt_pk_f16_f32 v161, v152, v153
	v_cvt_f32_f16_e32 v152, v171
	v_cvt_f32_f16_sdwa v153, v171 dst_sel:DWORD dst_unused:UNUSED_PAD src0_sel:WORD_1
	v_pk_mul_f32 v[152:153], v[30:31], v[152:153]
	s_nop 0
	v_pk_fma_f32 v[152:153], v[154:155], s[38:39], v[152:153] op_sel_hi:[1,0,1]
	s_nop 0
	v_mul_f32_e32 v154, 0x3d372713, v152
	v_mul_f32_e32 v155, 0x3d372713, v153
	v_mul_f32_e32 v154, v152, v154
	v_mul_f32_e32 v155, v153, v155
	v_fma_f32 v154, v152, v154, v152
	v_fma_f32 v155, v153, v155, v153
	v_mul_f32_e32 v154, 0x3f4c422a, v154
	v_mul_f32_e32 v155, 0x3f4c422a, v155
	v_mul_f32_e32 v154, -2.0, v154
	v_mul_f32_e32 v155, -2.0, v155
	v_mul_f32_e32 v154, 0x3fb8aa3b, v154
	v_mul_f32_e32 v155, 0x3fb8aa3b, v155
	v_exp_f32_e32 v154, v154
	v_exp_f32_e32 v155, v155
	v_add_f32_e32 v154, 1.0, v154
	v_add_f32_e32 v155, 1.0, v155
	v_rcp_f32_e32 v154, v154
	v_rcp_f32_e32 v155, v155
	s_nop 0
	v_pk_mul_f32 v[152:153], v[152:153], v[154:155]
	v_lshrrev_b32_e32 v154, 4, v2
	v_and_b32_e32 v154, 0x10001, v154
	v_add3_u32 v2, v2, v154, s21
	v_and_b32_e32 v160, 0xfff0fff0, v2
	v_lshrrev_b32_e32 v2, 4, v161
	v_and_b32_e32 v2, 0x10001, v2
	v_add3_u32 v2, v161, v2, s21
	v_and_b32_e32 v161, 0xfff0fff0, v2
	v_lshrrev_b32_e32 v2, 4, v168
	v_cvt_pk_f16_f32 v153, v152, v153
	v_ashrrev_i32_e32 v152, 4, v186
	v_and_b32_e32 v2, 0x10001, v2
	v_add3_u32 v2, v168, v2, s21
	v_add_u32_e32 v154, v152, v192
	v_and_b32_e32 v162, 0xfff0fff0, v2
	v_lshrrev_b32_e32 v2, 4, v153
	v_ashrrev_i32_e32 v155, 31, v154
	v_and_b32_e32 v2, 0x10001, v2
	v_lshlrev_b64 v[154:155], 10, v[154:155]
	v_add3_u32 v2, v153, v2, s21
	v_lshl_add_u64 v[154:155], s[16:17], 0, v[154:155]
	v_and_b32_e32 v163, 0xfff0fff0, v2
	v_lshl_add_u64 v[154:155], v[154:155], 0, s[42:43]
	v_lshlrev_b32_e32 v2, 1, v193
	v_lshl_add_u64 v[154:155], v[154:155], 0, v[2:3]
	global_store_dwordx4 v[154:155], v[160:163], off
	v_cvt_f32_f16_e32 v154, v164
	v_cvt_f32_f16_sdwa v155, v164 dst_sel:DWORD dst_unused:UNUSED_PAD src0_sel:WORD_1
	v_add_u32_e32 v153, 0x80, v186
	v_pk_mul_f32 v[154:155], v[32:33], v[154:155]
	s_nop 0
	v_pk_fma_f32 v[144:145], v[144:145], s[38:39], v[154:155] op_sel_hi:[1,0,1]
	s_nop 0
	v_mul_f32_e32 v154, 0x3d372713, v144
	v_mul_f32_e32 v155, 0x3d372713, v145
	v_mul_f32_e32 v154, v144, v154
	v_mul_f32_e32 v155, v145, v155
	v_fma_f32 v154, v144, v154, v144
	v_fma_f32 v155, v145, v155, v145
	v_mul_f32_e32 v154, 0x3f4c422a, v154
	v_mul_f32_e32 v155, 0x3f4c422a, v155
	v_mul_f32_e32 v154, -2.0, v154
	v_mul_f32_e32 v155, -2.0, v155
	v_mul_f32_e32 v154, 0x3fb8aa3b, v154
	v_mul_f32_e32 v155, 0x3fb8aa3b, v155
	v_exp_f32_e32 v154, v154
	v_exp_f32_e32 v155, v155
	v_add_f32_e32 v154, 1.0, v154
	v_add_f32_e32 v155, 1.0, v155
	v_rcp_f32_e32 v154, v154
	v_rcp_f32_e32 v155, v155
	s_nop 0
	v_pk_mul_f32 v[144:145], v[144:145], v[154:155]
	s_nop 0
	v_cvt_pk_f16_f32 v154, v144, v145
	v_cvt_f32_f16_e32 v144, v166
	v_cvt_f32_f16_sdwa v145, v166 dst_sel:DWORD dst_unused:UNUSED_PAD src0_sel:WORD_1
	v_pk_mul_f32 v[144:145], v[28:29], v[144:145]
	s_nop 0
	v_pk_fma_f32 v[140:141], v[140:141], s[38:39], v[144:145] op_sel_hi:[1,0,1]
	s_nop 0
	v_mul_f32_e32 v144, 0x3d372713, v140
	v_mul_f32_e32 v145, 0x3d372713, v141
	v_mul_f32_e32 v144, v140, v144
	v_mul_f32_e32 v145, v141, v145
	v_fma_f32 v144, v140, v144, v140
	v_fma_f32 v145, v141, v145, v141
	v_mul_f32_e32 v144, 0x3f4c422a, v144
	v_mul_f32_e32 v145, 0x3f4c422a, v145
	v_mul_f32_e32 v144, -2.0, v144
	v_mul_f32_e32 v145, -2.0, v145
	v_mul_f32_e32 v144, 0x3fb8aa3b, v144
	v_mul_f32_e32 v145, 0x3fb8aa3b, v145
	v_exp_f32_e32 v144, v144
	v_exp_f32_e32 v145, v145
	v_add_f32_e32 v144, 1.0, v144
	v_add_f32_e32 v145, 1.0, v145
	v_rcp_f32_e32 v144, v144
	v_rcp_f32_e32 v145, v145
	s_nop 0
	v_pk_mul_f32 v[140:141], v[140:141], v[144:145]
	s_nop 0
	v_cvt_pk_f16_f32 v155, v140, v141
	v_cvt_f32_f16_e32 v140, v165
	v_cvt_f32_f16_sdwa v141, v165 dst_sel:DWORD dst_unused:UNUSED_PAD src0_sel:WORD_1
	v_pk_mul_f32 v[140:141], v[34:35], v[140:141]
	s_nop 0
	v_pk_fma_f32 v[140:141], v[146:147], s[38:39], v[140:141] op_sel_hi:[1,0,1]
	s_nop 0
	v_mul_f32_e32 v144, 0x3d372713, v140
	v_mul_f32_e32 v145, 0x3d372713, v141
	v_mul_f32_e32 v144, v140, v144
	v_mul_f32_e32 v145, v141, v145
	v_fma_f32 v144, v140, v144, v140
	v_fma_f32 v145, v141, v145, v141
	v_mul_f32_e32 v144, 0x3f4c422a, v144
	v_mul_f32_e32 v145, 0x3f4c422a, v145
	v_mul_f32_e32 v144, -2.0, v144
	v_mul_f32_e32 v145, -2.0, v145
	v_mul_f32_e32 v144, 0x3fb8aa3b, v144
	v_mul_f32_e32 v145, 0x3fb8aa3b, v145
	v_exp_f32_e32 v144, v144
	v_exp_f32_e32 v145, v145
	v_add_f32_e32 v144, 1.0, v144
	v_add_f32_e32 v145, 1.0, v145
	v_rcp_f32_e32 v144, v144
	v_rcp_f32_e32 v145, v145
	s_nop 0
	v_pk_mul_f32 v[140:141], v[140:141], v[144:145]
	s_nop 0
	v_cvt_pk_f16_f32 v144, v140, v141
	v_cvt_f32_f16_e32 v140, v167
	v_cvt_f32_f16_sdwa v141, v167 dst_sel:DWORD dst_unused:UNUSED_PAD src0_sel:WORD_1
	v_pk_mul_f32 v[140:141], v[30:31], v[140:141]
	s_nop 0
	v_pk_fma_f32 v[140:141], v[142:143], s[38:39], v[140:141] op_sel_hi:[1,0,1]
	s_nop 0
	v_mul_f32_e32 v142, 0x3d372713, v140
	v_mul_f32_e32 v143, 0x3d372713, v141
	v_mul_f32_e32 v142, v140, v142
	v_mul_f32_e32 v143, v141, v143
	v_fma_f32 v142, v140, v142, v140
	v_fma_f32 v143, v141, v143, v141
	v_mul_f32_e32 v142, 0x3f4c422a, v142
	v_mul_f32_e32 v143, 0x3f4c422a, v143
	v_mul_f32_e32 v142, -2.0, v142
	v_mul_f32_e32 v143, -2.0, v143
	v_mul_f32_e32 v142, 0x3fb8aa3b, v142
	v_mul_f32_e32 v143, 0x3fb8aa3b, v143
	v_exp_f32_e32 v142, v142
	v_exp_f32_e32 v143, v143
	v_add_f32_e32 v142, 1.0, v142
	v_add_f32_e32 v143, 1.0, v143
	v_rcp_f32_e32 v142, v142
	v_rcp_f32_e32 v143, v143
	s_nop 0
	v_pk_mul_f32 v[140:141], v[140:141], v[142:143]
	s_nop 0
	v_cvt_pk_f16_f32 v141, v140, v141
	v_ashrrev_i32_e32 v140, 4, v153
	v_lshrrev_b32_e32 v143, 4, v144
	v_add_u32_e32 v146, v140, v192
	v_and_b32_e32 v143, 0x10001, v143
	v_ashrrev_i32_e32 v147, 31, v146
	v_lshrrev_b32_e32 v142, 4, v154
	v_add3_u32 v143, v144, v143, s21
	v_lshrrev_b32_e32 v144, 4, v155
	v_lshrrev_b32_e32 v145, 4, v141
	v_lshlrev_b64 v[146:147], 10, v[146:147]
	v_and_b32_e32 v142, 0x10001, v142
	v_and_b32_e32 v144, 0x10001, v144
	v_and_b32_e32 v145, 0x10001, v145
	v_lshl_add_u64 v[146:147], s[16:17], 0, v[146:147]
	v_add3_u32 v142, v154, v142, s21
	v_add3_u32 v144, v155, v144, s21
	v_add3_u32 v141, v141, v145, s21
	v_lshl_add_u64 v[146:147], v[146:147], 0, s[42:43]
	v_and_b32_e32 v142, 0xfff0fff0, v142
	v_and_b32_e32 v143, 0xfff0fff0, v143
	v_and_b32_e32 v144, 0xfff0fff0, v144
	v_and_b32_e32 v145, 0xfff0fff0, v141
	v_lshl_add_u64 v[146:147], v[146:147], 0, v[2:3]
	global_store_dwordx4 v[146:147], v[142:145], off
	v_add_u32_e32 v141, 0x100, v192
	s_nop 0
	v_cvt_f32_f16_e32 v142, v156
	v_cvt_f32_f16_sdwa v143, v156 dst_sel:DWORD dst_unused:UNUSED_PAD src0_sel:WORD_1
	v_pk_mul_f32 v[142:143], v[32:33], v[142:143]
	s_nop 0
	v_pk_fma_f32 v[132:133], v[132:133], s[38:39], v[142:143] op_sel_hi:[1,0,1]
	s_nop 0
	v_mul_f32_e32 v142, 0x3d372713, v132
	v_mul_f32_e32 v143, 0x3d372713, v133
	v_mul_f32_e32 v142, v132, v142
	v_mul_f32_e32 v143, v133, v143
	v_fma_f32 v142, v132, v142, v132
	v_fma_f32 v143, v133, v143, v133
	v_mul_f32_e32 v142, 0x3f4c422a, v142
	v_mul_f32_e32 v143, 0x3f4c422a, v143
	v_mul_f32_e32 v142, -2.0, v142
	v_mul_f32_e32 v143, -2.0, v143
	v_mul_f32_e32 v142, 0x3fb8aa3b, v142
	v_mul_f32_e32 v143, 0x3fb8aa3b, v143
	v_exp_f32_e32 v142, v142
	v_exp_f32_e32 v143, v143
	v_add_f32_e32 v142, 1.0, v142
	v_add_f32_e32 v143, 1.0, v143
	v_rcp_f32_e32 v142, v142
	v_rcp_f32_e32 v143, v143
	s_nop 0
	v_pk_mul_f32 v[132:133], v[132:133], v[142:143]
	s_nop 0
	v_cvt_pk_f16_f32 v142, v132, v133
	v_cvt_f32_f16_e32 v132, v158
	v_cvt_f32_f16_sdwa v133, v158 dst_sel:DWORD dst_unused:UNUSED_PAD src0_sel:WORD_1
	v_pk_mul_f32 v[132:133], v[28:29], v[132:133]
	s_nop 0
	v_pk_fma_f32 v[128:129], v[128:129], s[38:39], v[132:133] op_sel_hi:[1,0,1]
	s_nop 0
	v_mul_f32_e32 v132, 0x3d372713, v128
	v_mul_f32_e32 v133, 0x3d372713, v129
	v_mul_f32_e32 v132, v128, v132
	v_mul_f32_e32 v133, v129, v133
	v_fma_f32 v132, v128, v132, v128
	v_fma_f32 v133, v129, v133, v129
	v_mul_f32_e32 v132, 0x3f4c422a, v132
	v_mul_f32_e32 v133, 0x3f4c422a, v133
	v_mul_f32_e32 v132, -2.0, v132
	v_mul_f32_e32 v133, -2.0, v133
	v_mul_f32_e32 v132, 0x3fb8aa3b, v132
	v_mul_f32_e32 v133, 0x3fb8aa3b, v133
	v_exp_f32_e32 v132, v132
	v_exp_f32_e32 v133, v133
	v_add_f32_e32 v132, 1.0, v132
	v_add_f32_e32 v133, 1.0, v133
	v_rcp_f32_e32 v132, v132
	v_rcp_f32_e32 v133, v133
	s_nop 0
	v_pk_mul_f32 v[128:129], v[128:129], v[132:133]
	s_nop 0
	v_cvt_pk_f16_f32 v143, v128, v129
	v_cvt_f32_f16_e32 v128, v157
	v_cvt_f32_f16_sdwa v129, v157 dst_sel:DWORD dst_unused:UNUSED_PAD src0_sel:WORD_1
	v_pk_mul_f32 v[128:129], v[34:35], v[128:129]
	s_nop 0
	v_pk_fma_f32 v[128:129], v[134:135], s[38:39], v[128:129] op_sel_hi:[1,0,1]
	s_nop 0
	v_mul_f32_e32 v132, 0x3d372713, v128
	v_mul_f32_e32 v133, 0x3d372713, v129
	v_mul_f32_e32 v132, v128, v132
	v_mul_f32_e32 v133, v129, v133
	v_fma_f32 v132, v128, v132, v128
	v_fma_f32 v133, v129, v133, v129
	v_mul_f32_e32 v132, 0x3f4c422a, v132
	v_mul_f32_e32 v133, 0x3f4c422a, v133
	v_mul_f32_e32 v132, -2.0, v132
	v_mul_f32_e32 v133, -2.0, v133
	v_mul_f32_e32 v132, 0x3fb8aa3b, v132
	v_mul_f32_e32 v133, 0x3fb8aa3b, v133
	v_exp_f32_e32 v132, v132
	v_exp_f32_e32 v133, v133
	v_add_f32_e32 v132, 1.0, v132
	v_add_f32_e32 v133, 1.0, v133
	v_rcp_f32_e32 v132, v132
	v_rcp_f32_e32 v133, v133
	s_nop 0
	v_pk_mul_f32 v[128:129], v[128:129], v[132:133]
	s_nop 0
	v_cvt_pk_f16_f32 v132, v128, v129
	v_cvt_f32_f16_e32 v128, v159
	v_cvt_f32_f16_sdwa v129, v159 dst_sel:DWORD dst_unused:UNUSED_PAD src0_sel:WORD_1
	v_pk_mul_f32 v[128:129], v[30:31], v[128:129]
	s_nop 0
	v_pk_fma_f32 v[128:129], v[130:131], s[38:39], v[128:129] op_sel_hi:[1,0,1]
	s_nop 0
	v_mul_f32_e32 v130, 0x3d372713, v128
	v_mul_f32_e32 v131, 0x3d372713, v129
	v_mul_f32_e32 v130, v128, v130
	v_mul_f32_e32 v131, v129, v131
	v_fma_f32 v130, v128, v130, v128
	v_fma_f32 v131, v129, v131, v129
	v_mul_f32_e32 v130, 0x3f4c422a, v130
	v_mul_f32_e32 v131, 0x3f4c422a, v131
	v_mul_f32_e32 v130, -2.0, v130
	v_mul_f32_e32 v131, -2.0, v131
	v_mul_f32_e32 v130, 0x3fb8aa3b, v130
	v_mul_f32_e32 v131, 0x3fb8aa3b, v131
	v_exp_f32_e32 v130, v130
	v_exp_f32_e32 v131, v131
	v_add_f32_e32 v130, 1.0, v130
	v_add_f32_e32 v131, 1.0, v131
	v_rcp_f32_e32 v130, v130
	v_rcp_f32_e32 v131, v131
	s_nop 0
	v_pk_mul_f32 v[128:129], v[128:129], v[130:131]
	s_nop 0
	v_cvt_pk_f16_f32 v131, v128, v129
	v_lshrrev_b32_e32 v129, 4, v132
	v_and_b32_e32 v129, 0x10001, v129
	v_add3_u32 v129, v132, v129, s21
	v_lshrrev_b32_e32 v132, 4, v131
	v_and_b32_e32 v132, 0x10001, v132
	v_add3_u32 v131, v131, v132, s21
	v_add_u32_e32 v132, v152, v141
	v_ashrrev_i32_e32 v133, 31, v132
	v_lshrrev_b32_e32 v128, 4, v142
	v_lshrrev_b32_e32 v130, 4, v143
	v_lshlrev_b64 v[132:133], 10, v[132:133]
	v_and_b32_e32 v128, 0x10001, v128
	v_and_b32_e32 v130, 0x10001, v130
	v_lshl_add_u64 v[132:133], s[16:17], 0, v[132:133]
	v_add3_u32 v128, v142, v128, s21
	v_add3_u32 v130, v143, v130, s21
	v_lshl_add_u64 v[132:133], v[132:133], 0, s[42:43]
	v_and_b32_e32 v128, 0xfff0fff0, v128
	v_and_b32_e32 v129, 0xfff0fff0, v129
	v_and_b32_e32 v130, 0xfff0fff0, v130
	v_and_b32_e32 v131, 0xfff0fff0, v131
	v_lshl_add_u64 v[132:133], v[132:133], 0, v[2:3]
	global_store_dwordx4 v[132:133], v[128:131], off
	s_nop 1
	v_cvt_f32_f16_e32 v128, v148
	v_cvt_f32_f16_sdwa v129, v148 dst_sel:DWORD dst_unused:UNUSED_PAD src0_sel:WORD_1
	v_pk_mul_f32 v[128:129], v[32:33], v[128:129]
	s_nop 0
	v_pk_fma_f32 v[120:121], v[120:121], s[38:39], v[128:129] op_sel_hi:[1,0,1]
	s_nop 0
	v_mul_f32_e32 v128, 0x3d372713, v120
	v_mul_f32_e32 v129, 0x3d372713, v121
	v_mul_f32_e32 v128, v120, v128
	v_mul_f32_e32 v129, v121, v129
	v_fma_f32 v128, v120, v128, v120
	v_fma_f32 v129, v121, v129, v121
	v_mul_f32_e32 v128, 0x3f4c422a, v128
	v_mul_f32_e32 v129, 0x3f4c422a, v129
	v_mul_f32_e32 v128, -2.0, v128
	v_mul_f32_e32 v129, -2.0, v129
	v_mul_f32_e32 v128, 0x3fb8aa3b, v128
	v_mul_f32_e32 v129, 0x3fb8aa3b, v129
	v_exp_f32_e32 v128, v128
	v_exp_f32_e32 v129, v129
	v_add_f32_e32 v128, 1.0, v128
	v_add_f32_e32 v129, 1.0, v129
	v_rcp_f32_e32 v128, v128
	v_rcp_f32_e32 v129, v129
	s_nop 0
	v_pk_mul_f32 v[120:121], v[120:121], v[128:129]
	s_nop 0
	v_cvt_pk_f16_f32 v128, v120, v121
	v_cvt_f32_f16_e32 v120, v150
	v_cvt_f32_f16_sdwa v121, v150 dst_sel:DWORD dst_unused:UNUSED_PAD src0_sel:WORD_1
	v_pk_mul_f32 v[120:121], v[28:29], v[120:121]
	s_nop 0
	v_pk_fma_f32 v[116:117], v[116:117], s[38:39], v[120:121] op_sel_hi:[1,0,1]
	s_nop 0
	v_mul_f32_e32 v120, 0x3d372713, v116
	v_mul_f32_e32 v121, 0x3d372713, v117
	v_mul_f32_e32 v120, v116, v120
	v_mul_f32_e32 v121, v117, v121
	v_fma_f32 v120, v116, v120, v116
	v_fma_f32 v121, v117, v121, v117
	v_mul_f32_e32 v120, 0x3f4c422a, v120
	v_mul_f32_e32 v121, 0x3f4c422a, v121
	v_mul_f32_e32 v120, -2.0, v120
	v_mul_f32_e32 v121, -2.0, v121
	v_mul_f32_e32 v120, 0x3fb8aa3b, v120
	v_mul_f32_e32 v121, 0x3fb8aa3b, v121
	v_exp_f32_e32 v120, v120
	v_exp_f32_e32 v121, v121
	v_add_f32_e32 v120, 1.0, v120
	v_add_f32_e32 v121, 1.0, v121
	v_rcp_f32_e32 v120, v120
	v_rcp_f32_e32 v121, v121
	s_nop 0
	v_pk_mul_f32 v[116:117], v[116:117], v[120:121]
	s_nop 0
	v_cvt_pk_f16_f32 v129, v116, v117
	v_cvt_f32_f16_e32 v116, v149
	v_cvt_f32_f16_sdwa v117, v149 dst_sel:DWORD dst_unused:UNUSED_PAD src0_sel:WORD_1
	v_pk_mul_f32 v[116:117], v[34:35], v[116:117]
	s_nop 0
	v_pk_fma_f32 v[116:117], v[122:123], s[38:39], v[116:117] op_sel_hi:[1,0,1]
	s_nop 0
	v_mul_f32_e32 v120, 0x3d372713, v116
	v_mul_f32_e32 v121, 0x3d372713, v117
	v_mul_f32_e32 v120, v116, v120
	v_mul_f32_e32 v121, v117, v121
	v_fma_f32 v120, v116, v120, v116
	v_fma_f32 v121, v117, v121, v117
	v_mul_f32_e32 v120, 0x3f4c422a, v120
	v_mul_f32_e32 v121, 0x3f4c422a, v121
	v_mul_f32_e32 v120, -2.0, v120
	v_mul_f32_e32 v121, -2.0, v121
	v_mul_f32_e32 v120, 0x3fb8aa3b, v120
	v_mul_f32_e32 v121, 0x3fb8aa3b, v121
	v_exp_f32_e32 v120, v120
	v_exp_f32_e32 v121, v121
	v_add_f32_e32 v120, 1.0, v120
	v_add_f32_e32 v121, 1.0, v121
	v_rcp_f32_e32 v120, v120
	v_rcp_f32_e32 v121, v121
	s_nop 0
	v_pk_mul_f32 v[116:117], v[116:117], v[120:121]
	s_nop 0
	v_cvt_pk_f16_f32 v120, v116, v117
	v_cvt_f32_f16_e32 v116, v151
	v_cvt_f32_f16_sdwa v117, v151 dst_sel:DWORD dst_unused:UNUSED_PAD src0_sel:WORD_1
	v_pk_mul_f32 v[116:117], v[30:31], v[116:117]
	s_nop 0
	v_pk_fma_f32 v[116:117], v[118:119], s[38:39], v[116:117] op_sel_hi:[1,0,1]
	s_nop 0
	v_mul_f32_e32 v118, 0x3d372713, v116
	v_mul_f32_e32 v119, 0x3d372713, v117
	v_mul_f32_e32 v118, v116, v118
	v_mul_f32_e32 v119, v117, v119
	v_fma_f32 v118, v116, v118, v116
	v_fma_f32 v119, v117, v119, v117
	v_mul_f32_e32 v118, 0x3f4c422a, v118
	v_mul_f32_e32 v119, 0x3f4c422a, v119
	v_mul_f32_e32 v118, -2.0, v118
	v_mul_f32_e32 v119, -2.0, v119
	v_mul_f32_e32 v118, 0x3fb8aa3b, v118
	v_mul_f32_e32 v119, 0x3fb8aa3b, v119
	v_exp_f32_e32 v118, v118
	v_exp_f32_e32 v119, v119
	v_add_f32_e32 v118, 1.0, v118
	v_add_f32_e32 v119, 1.0, v119
	v_rcp_f32_e32 v118, v118
	v_rcp_f32_e32 v119, v119
	s_nop 0
	v_pk_mul_f32 v[116:117], v[116:117], v[118:119]
	s_nop 0
	v_cvt_pk_f16_f32 v119, v116, v117
	v_lshrrev_b32_e32 v117, 4, v120
	v_and_b32_e32 v117, 0x10001, v117
	v_add3_u32 v117, v120, v117, s21
	v_lshrrev_b32_e32 v120, 4, v119
	v_and_b32_e32 v120, 0x10001, v120
	v_add3_u32 v119, v119, v120, s21
	v_add_u32_e32 v120, v140, v141
	v_ashrrev_i32_e32 v121, 31, v120
	v_lshrrev_b32_e32 v116, 4, v128
	v_lshrrev_b32_e32 v118, 4, v129
	v_lshlrev_b64 v[120:121], 10, v[120:121]
	v_and_b32_e32 v116, 0x10001, v116
	v_and_b32_e32 v118, 0x10001, v118
	v_lshl_add_u64 v[120:121], s[16:17], 0, v[120:121]
	v_add3_u32 v116, v128, v116, s21
	v_add3_u32 v118, v129, v118, s21
	v_lshl_add_u64 v[120:121], v[120:121], 0, s[42:43]
	v_and_b32_e32 v116, 0xfff0fff0, v116
	v_and_b32_e32 v117, 0xfff0fff0, v117
	v_and_b32_e32 v118, 0xfff0fff0, v118
	v_and_b32_e32 v119, 0xfff0fff0, v119
	v_lshl_add_u64 v[120:121], v[120:121], 0, v[2:3]
	global_store_dwordx4 v[120:121], v[116:119], off
	s_nop 1
	v_cvt_f32_f16_e32 v118, v136
	v_cvt_f32_f16_sdwa v119, v136 dst_sel:DWORD dst_unused:UNUSED_PAD src0_sel:WORD_1
	v_add_u32_e32 v116, 0x200, v192
	v_pk_mul_f32 v[118:119], v[32:33], v[118:119]
	s_nop 0
	v_pk_fma_f32 v[108:109], v[108:109], s[38:39], v[118:119] op_sel_hi:[1,0,1]
	s_nop 0
	v_mul_f32_e32 v117, 0x3d372713, v108
	v_mul_f32_e32 v117, v108, v117
	v_fma_f32 v117, v108, v117, v108
	v_mul_f32_e32 v117, 0x3f4c422a, v117
	v_mul_f32_e32 v117, -2.0, v117
	v_mul_f32_e32 v117, 0x3fb8aa3b, v117
	v_exp_f32_e32 v117, v117
	s_nop 0
	v_add_f32_e32 v117, 1.0, v117
	v_rcp_f32_e32 v118, v117
	v_mul_f32_e32 v117, 0x3d372713, v109
	v_mul_f32_e32 v117, v109, v117
	v_fma_f32 v117, v109, v117, v109
	v_mul_f32_e32 v117, 0x3f4c422a, v117
	v_mul_f32_e32 v117, -2.0, v117
	v_mul_f32_e32 v117, 0x3fb8aa3b, v117
	v_exp_f32_e32 v117, v117
	s_nop 0
	v_add_f32_e32 v117, 1.0, v117
	v_rcp_f32_e32 v119, v117
	s_nop 0
	v_pk_mul_f32 v[108:109], v[108:109], v[118:119]
	s_nop 0
	v_cvt_pk_f16_f32 v117, v108, v109
	v_cvt_f32_f16_e32 v108, v138
	v_cvt_f32_f16_sdwa v109, v138 dst_sel:DWORD dst_unused:UNUSED_PAD src0_sel:WORD_1
	v_pk_mul_f32 v[108:109], v[28:29], v[108:109]
	s_nop 0
	v_pk_fma_f32 v[104:105], v[104:105], s[38:39], v[108:109] op_sel_hi:[1,0,1]
	s_nop 0
	v_mul_f32_e32 v108, 0x3d372713, v104
	v_mul_f32_e32 v109, 0x3d372713, v105
	v_mul_f32_e32 v108, v104, v108
	v_mul_f32_e32 v109, v105, v109
	v_fma_f32 v108, v104, v108, v104
	v_fma_f32 v109, v105, v109, v105
	v_mul_f32_e32 v108, 0x3f4c422a, v108
	v_mul_f32_e32 v109, 0x3f4c422a, v109
	v_mul_f32_e32 v108, -2.0, v108
	v_mul_f32_e32 v109, -2.0, v109
	v_mul_f32_e32 v108, 0x3fb8aa3b, v108
	v_mul_f32_e32 v109, 0x3fb8aa3b, v109
	v_exp_f32_e32 v108, v108
	v_exp_f32_e32 v109, v109
	v_add_f32_e32 v108, 1.0, v108
	v_add_f32_e32 v109, 1.0, v109
	v_rcp_f32_e32 v108, v108
	v_rcp_f32_e32 v109, v109
	s_nop 0
	v_pk_mul_f32 v[104:105], v[104:105], v[108:109]
	s_nop 0
	v_cvt_pk_f16_f32 v118, v104, v105
	v_cvt_f32_f16_e32 v104, v137
	v_cvt_f32_f16_sdwa v105, v137 dst_sel:DWORD dst_unused:UNUSED_PAD src0_sel:WORD_1
	v_pk_mul_f32 v[104:105], v[34:35], v[104:105]
	s_nop 0
	v_pk_fma_f32 v[104:105], v[110:111], s[38:39], v[104:105] op_sel_hi:[1,0,1]
	s_nop 0
	v_mul_f32_e32 v108, 0x3d372713, v104
	v_mul_f32_e32 v109, 0x3d372713, v105
	v_mul_f32_e32 v108, v104, v108
	v_mul_f32_e32 v109, v105, v109
	v_fma_f32 v108, v104, v108, v104
	v_fma_f32 v109, v105, v109, v105
	v_mul_f32_e32 v108, 0x3f4c422a, v108
	v_mul_f32_e32 v109, 0x3f4c422a, v109
	v_mul_f32_e32 v108, -2.0, v108
	v_mul_f32_e32 v109, -2.0, v109
	v_mul_f32_e32 v108, 0x3fb8aa3b, v108
	v_mul_f32_e32 v109, 0x3fb8aa3b, v109
	v_exp_f32_e32 v108, v108
	v_exp_f32_e32 v109, v109
	v_add_f32_e32 v108, 1.0, v108
	v_add_f32_e32 v109, 1.0, v109
	v_rcp_f32_e32 v108, v108
	v_rcp_f32_e32 v109, v109
	s_nop 0
	v_pk_mul_f32 v[104:105], v[104:105], v[108:109]
	s_nop 0
	v_cvt_pk_f16_f32 v108, v104, v105
	v_cvt_f32_f16_e32 v104, v139
	v_cvt_f32_f16_sdwa v105, v139 dst_sel:DWORD dst_unused:UNUSED_PAD src0_sel:WORD_1
	v_pk_mul_f32 v[104:105], v[30:31], v[104:105]
	s_nop 0
	v_pk_fma_f32 v[104:105], v[106:107], s[38:39], v[104:105] op_sel_hi:[1,0,1]
	s_nop 0
	v_mul_f32_e32 v106, 0x3d372713, v104
	v_mul_f32_e32 v107, 0x3d372713, v105
	v_mul_f32_e32 v106, v104, v106
	v_mul_f32_e32 v107, v105, v107
	v_fma_f32 v106, v104, v106, v104
	v_fma_f32 v107, v105, v107, v105
	v_mul_f32_e32 v106, 0x3f4c422a, v106
	v_mul_f32_e32 v107, 0x3f4c422a, v107
	v_mul_f32_e32 v106, -2.0, v106
	v_mul_f32_e32 v107, -2.0, v107
	v_mul_f32_e32 v106, 0x3fb8aa3b, v106
	v_mul_f32_e32 v107, 0x3fb8aa3b, v107
	v_exp_f32_e32 v106, v106
	v_exp_f32_e32 v107, v107
	v_add_f32_e32 v106, 1.0, v106
	v_add_f32_e32 v107, 1.0, v107
	v_rcp_f32_e32 v106, v106
	v_rcp_f32_e32 v107, v107
	s_nop 0
	v_pk_mul_f32 v[104:105], v[104:105], v[106:107]
	s_nop 0
	v_cvt_pk_f16_f32 v107, v104, v105
	v_lshrrev_b32_e32 v105, 4, v108
	v_and_b32_e32 v105, 0x10001, v105
	v_add3_u32 v105, v108, v105, s21
	v_lshrrev_b32_e32 v108, 4, v107
	v_and_b32_e32 v108, 0x10001, v108
	v_add3_u32 v107, v107, v108, s21
	v_add_u32_e32 v108, v152, v116
	v_ashrrev_i32_e32 v109, 31, v108
	v_lshrrev_b32_e32 v104, 4, v117
	v_lshrrev_b32_e32 v106, 4, v118
	v_lshlrev_b64 v[108:109], 10, v[108:109]
	v_and_b32_e32 v104, 0x10001, v104
	v_and_b32_e32 v106, 0x10001, v106
	v_lshl_add_u64 v[108:109], s[16:17], 0, v[108:109]
	v_add3_u32 v104, v117, v104, s21
	v_add3_u32 v106, v118, v106, s21
	v_lshl_add_u64 v[108:109], v[108:109], 0, s[42:43]
	v_and_b32_e32 v104, 0xfff0fff0, v104
	v_and_b32_e32 v105, 0xfff0fff0, v105
	v_and_b32_e32 v106, 0xfff0fff0, v106
	v_and_b32_e32 v107, 0xfff0fff0, v107
	v_lshl_add_u64 v[108:109], v[108:109], 0, v[2:3]
	global_store_dwordx4 v[108:109], v[104:107], off
	s_nop 1
	v_cvt_f32_f16_e32 v104, v124
	v_cvt_f32_f16_sdwa v105, v124 dst_sel:DWORD dst_unused:UNUSED_PAD src0_sel:WORD_1
	v_pk_mul_f32 v[104:105], v[32:33], v[104:105]
	s_nop 0
	v_pk_fma_f32 v[96:97], v[96:97], s[38:39], v[104:105] op_sel_hi:[1,0,1]
	s_nop 0
	v_mul_f32_e32 v104, 0x3d372713, v96
	v_mul_f32_e32 v105, 0x3d372713, v97
	v_mul_f32_e32 v104, v96, v104
	v_mul_f32_e32 v105, v97, v105
	v_fma_f32 v104, v96, v104, v96
	v_fma_f32 v105, v97, v105, v97
	v_mul_f32_e32 v104, 0x3f4c422a, v104
	v_mul_f32_e32 v105, 0x3f4c422a, v105
	v_mul_f32_e32 v104, -2.0, v104
	v_mul_f32_e32 v105, -2.0, v105
	v_mul_f32_e32 v104, 0x3fb8aa3b, v104
	v_mul_f32_e32 v105, 0x3fb8aa3b, v105
	v_exp_f32_e32 v104, v104
	v_exp_f32_e32 v105, v105
	v_add_f32_e32 v104, 1.0, v104
	v_add_f32_e32 v105, 1.0, v105
	v_rcp_f32_e32 v104, v104
	v_rcp_f32_e32 v105, v105
	s_nop 0
	v_pk_mul_f32 v[96:97], v[96:97], v[104:105]
	s_nop 0
	v_cvt_pk_f16_f32 v104, v96, v97
	v_cvt_f32_f16_e32 v96, v126
	v_cvt_f32_f16_sdwa v97, v126 dst_sel:DWORD dst_unused:UNUSED_PAD src0_sel:WORD_1
	v_pk_mul_f32 v[96:97], v[28:29], v[96:97]
	s_nop 0
	v_pk_fma_f32 v[92:93], v[92:93], s[38:39], v[96:97] op_sel_hi:[1,0,1]
	s_nop 0
	v_mul_f32_e32 v96, 0x3d372713, v92
	v_mul_f32_e32 v97, 0x3d372713, v93
	v_mul_f32_e32 v96, v92, v96
	v_mul_f32_e32 v97, v93, v97
	v_fma_f32 v96, v92, v96, v92
	v_fma_f32 v97, v93, v97, v93
	v_mul_f32_e32 v96, 0x3f4c422a, v96
	v_mul_f32_e32 v97, 0x3f4c422a, v97
	v_mul_f32_e32 v96, -2.0, v96
	v_mul_f32_e32 v97, -2.0, v97
	v_mul_f32_e32 v96, 0x3fb8aa3b, v96
	v_mul_f32_e32 v97, 0x3fb8aa3b, v97
	v_exp_f32_e32 v96, v96
	v_exp_f32_e32 v97, v97
	v_add_f32_e32 v96, 1.0, v96
	v_add_f32_e32 v97, 1.0, v97
	v_rcp_f32_e32 v96, v96
	v_rcp_f32_e32 v97, v97
	s_nop 0
	v_pk_mul_f32 v[92:93], v[92:93], v[96:97]
	s_nop 0
	v_cvt_pk_f16_f32 v105, v92, v93
	v_cvt_f32_f16_e32 v92, v125
	v_cvt_f32_f16_sdwa v93, v125 dst_sel:DWORD dst_unused:UNUSED_PAD src0_sel:WORD_1
	v_pk_mul_f32 v[92:93], v[34:35], v[92:93]
	s_nop 0
	v_pk_fma_f32 v[92:93], v[98:99], s[38:39], v[92:93] op_sel_hi:[1,0,1]
	s_nop 0
	v_mul_f32_e32 v96, 0x3d372713, v92
	v_mul_f32_e32 v97, 0x3d372713, v93
	v_mul_f32_e32 v96, v92, v96
	v_mul_f32_e32 v97, v93, v97
	v_fma_f32 v96, v92, v96, v92
	v_fma_f32 v97, v93, v97, v93
	v_mul_f32_e32 v96, 0x3f4c422a, v96
	v_mul_f32_e32 v97, 0x3f4c422a, v97
	v_mul_f32_e32 v96, -2.0, v96
	v_mul_f32_e32 v97, -2.0, v97
	v_mul_f32_e32 v96, 0x3fb8aa3b, v96
	v_mul_f32_e32 v97, 0x3fb8aa3b, v97
	v_exp_f32_e32 v96, v96
	v_exp_f32_e32 v97, v97
	v_add_f32_e32 v96, 1.0, v96
	v_add_f32_e32 v97, 1.0, v97
	v_rcp_f32_e32 v96, v96
	v_rcp_f32_e32 v97, v97
	s_nop 0
	v_pk_mul_f32 v[92:93], v[92:93], v[96:97]
	s_nop 0
	v_cvt_pk_f16_f32 v96, v92, v93
	v_cvt_f32_f16_e32 v92, v127
	v_cvt_f32_f16_sdwa v93, v127 dst_sel:DWORD dst_unused:UNUSED_PAD src0_sel:WORD_1
	v_pk_mul_f32 v[92:93], v[30:31], v[92:93]
	s_nop 0
	v_pk_fma_f32 v[92:93], v[94:95], s[38:39], v[92:93] op_sel_hi:[1,0,1]
	s_nop 0
	v_mul_f32_e32 v94, 0x3d372713, v92
	v_mul_f32_e32 v95, 0x3d372713, v93
	v_mul_f32_e32 v94, v92, v94
	v_mul_f32_e32 v95, v93, v95
	v_fma_f32 v94, v92, v94, v92
	v_fma_f32 v95, v93, v95, v93
	v_mul_f32_e32 v94, 0x3f4c422a, v94
	v_mul_f32_e32 v95, 0x3f4c422a, v95
	v_mul_f32_e32 v94, -2.0, v94
	v_mul_f32_e32 v95, -2.0, v95
	v_mul_f32_e32 v94, 0x3fb8aa3b, v94
	v_mul_f32_e32 v95, 0x3fb8aa3b, v95
	v_exp_f32_e32 v94, v94
	v_exp_f32_e32 v95, v95
	v_add_f32_e32 v94, 1.0, v94
	v_add_f32_e32 v95, 1.0, v95
	v_rcp_f32_e32 v94, v94
	v_rcp_f32_e32 v95, v95
	s_nop 0
	v_pk_mul_f32 v[92:93], v[92:93], v[94:95]
	s_nop 0
	v_cvt_pk_f16_f32 v95, v92, v93
	v_lshrrev_b32_e32 v93, 4, v96
	v_and_b32_e32 v93, 0x10001, v93
	v_add3_u32 v93, v96, v93, s21
	v_lshrrev_b32_e32 v96, 4, v95
	v_and_b32_e32 v96, 0x10001, v96
	v_add3_u32 v95, v95, v96, s21
	v_add_u32_e32 v96, v140, v116
	v_ashrrev_i32_e32 v97, 31, v96
	v_lshrrev_b32_e32 v92, 4, v104
	v_lshrrev_b32_e32 v94, 4, v105
	v_lshlrev_b64 v[96:97], 10, v[96:97]
	v_and_b32_e32 v92, 0x10001, v92
	v_and_b32_e32 v94, 0x10001, v94
	v_lshl_add_u64 v[96:97], s[16:17], 0, v[96:97]
	v_add3_u32 v92, v104, v92, s21
	v_add3_u32 v94, v105, v94, s21
	v_lshl_add_u64 v[96:97], v[96:97], 0, s[42:43]
	v_and_b32_e32 v92, 0xfff0fff0, v92
	v_and_b32_e32 v93, 0xfff0fff0, v93
	v_and_b32_e32 v94, 0xfff0fff0, v94
	v_and_b32_e32 v95, 0xfff0fff0, v95
	v_lshl_add_u64 v[96:97], v[96:97], 0, v[2:3]
	global_store_dwordx4 v[96:97], v[92:95], off
	v_add_u32_e32 v104, 0x800, v192
	s_nop 0
	v_cvt_f32_f16_e32 v94, v112
	v_cvt_f32_f16_sdwa v95, v112 dst_sel:DWORD dst_unused:UNUSED_PAD src0_sel:WORD_1
	v_add_u32_e32 v92, 0x300, v192
	v_pk_mul_f32 v[94:95], v[32:33], v[94:95]
	s_nop 0
	v_pk_fma_f32 v[88:89], v[88:89], s[38:39], v[94:95] op_sel_hi:[1,0,1]
	s_nop 0
	v_mul_f32_e32 v93, 0x3d372713, v88
	v_mul_f32_e32 v93, v88, v93
	v_fma_f32 v93, v88, v93, v88
	v_mul_f32_e32 v93, 0x3f4c422a, v93
	v_mul_f32_e32 v93, -2.0, v93
	v_mul_f32_e32 v93, 0x3fb8aa3b, v93
	v_exp_f32_e32 v93, v93
	s_nop 0
	v_add_f32_e32 v93, 1.0, v93
	v_rcp_f32_e32 v94, v93
	v_mul_f32_e32 v93, 0x3d372713, v89
	v_mul_f32_e32 v93, v89, v93
	v_fma_f32 v93, v89, v93, v89
	v_mul_f32_e32 v93, 0x3f4c422a, v93
	v_mul_f32_e32 v93, -2.0, v93
	v_mul_f32_e32 v93, 0x3fb8aa3b, v93
	v_exp_f32_e32 v93, v93
	s_nop 0
	v_add_f32_e32 v93, 1.0, v93
	v_rcp_f32_e32 v95, v93
	s_nop 0
	v_pk_mul_f32 v[88:89], v[88:89], v[94:95]
	s_nop 0
	v_cvt_pk_f16_f32 v93, v88, v89
	v_cvt_f32_f16_e32 v88, v114
	v_cvt_f32_f16_sdwa v89, v114 dst_sel:DWORD dst_unused:UNUSED_PAD src0_sel:WORD_1
	v_pk_mul_f32 v[88:89], v[28:29], v[88:89]
	s_nop 0
	v_pk_fma_f32 v[84:85], v[84:85], s[38:39], v[88:89] op_sel_hi:[1,0,1]
	s_nop 0
	v_mul_f32_e32 v88, 0x3d372713, v84
	v_mul_f32_e32 v89, 0x3d372713, v85
	v_mul_f32_e32 v88, v84, v88
	v_mul_f32_e32 v89, v85, v89
	v_fma_f32 v88, v84, v88, v84
	v_fma_f32 v89, v85, v89, v85
	v_mul_f32_e32 v88, 0x3f4c422a, v88
	v_mul_f32_e32 v89, 0x3f4c422a, v89
	v_mul_f32_e32 v88, -2.0, v88
	v_mul_f32_e32 v89, -2.0, v89
	v_mul_f32_e32 v88, 0x3fb8aa3b, v88
	v_mul_f32_e32 v89, 0x3fb8aa3b, v89
	v_exp_f32_e32 v88, v88
	v_exp_f32_e32 v89, v89
	v_add_f32_e32 v88, 1.0, v88
	v_add_f32_e32 v89, 1.0, v89
	v_rcp_f32_e32 v88, v88
	v_rcp_f32_e32 v89, v89
	s_nop 0
	v_pk_mul_f32 v[84:85], v[84:85], v[88:89]
	s_nop 0
	v_cvt_pk_f16_f32 v94, v84, v85
	v_cvt_f32_f16_e32 v84, v113
	v_cvt_f32_f16_sdwa v85, v113 dst_sel:DWORD dst_unused:UNUSED_PAD src0_sel:WORD_1
	v_pk_mul_f32 v[84:85], v[34:35], v[84:85]
	s_nop 0
	v_pk_fma_f32 v[84:85], v[90:91], s[38:39], v[84:85] op_sel_hi:[1,0,1]
	s_nop 0
	v_mul_f32_e32 v88, 0x3d372713, v84
	v_mul_f32_e32 v89, 0x3d372713, v85
	v_mul_f32_e32 v88, v84, v88
	v_mul_f32_e32 v89, v85, v89
	v_fma_f32 v88, v84, v88, v84
	v_fma_f32 v89, v85, v89, v85
	v_mul_f32_e32 v88, 0x3f4c422a, v88
	v_mul_f32_e32 v89, 0x3f4c422a, v89
	v_mul_f32_e32 v88, -2.0, v88
	v_mul_f32_e32 v89, -2.0, v89
	v_mul_f32_e32 v88, 0x3fb8aa3b, v88
	v_mul_f32_e32 v89, 0x3fb8aa3b, v89
	v_exp_f32_e32 v88, v88
	v_exp_f32_e32 v89, v89
	v_add_f32_e32 v88, 1.0, v88
	v_add_f32_e32 v89, 1.0, v89
	v_rcp_f32_e32 v88, v88
	v_rcp_f32_e32 v89, v89
	s_nop 0
	v_pk_mul_f32 v[84:85], v[84:85], v[88:89]
	s_nop 0
	v_cvt_pk_f16_f32 v88, v84, v85
	v_cvt_f32_f16_e32 v84, v115
	v_cvt_f32_f16_sdwa v85, v115 dst_sel:DWORD dst_unused:UNUSED_PAD src0_sel:WORD_1
	v_pk_mul_f32 v[84:85], v[30:31], v[84:85]
	s_nop 0
	v_pk_fma_f32 v[84:85], v[86:87], s[38:39], v[84:85] op_sel_hi:[1,0,1]
	s_nop 0
	v_mul_f32_e32 v86, 0x3d372713, v84
	v_mul_f32_e32 v87, 0x3d372713, v85
	v_mul_f32_e32 v86, v84, v86
	v_mul_f32_e32 v87, v85, v87
	v_fma_f32 v86, v84, v86, v84
	v_fma_f32 v87, v85, v87, v85
	v_mul_f32_e32 v86, 0x3f4c422a, v86
	v_mul_f32_e32 v87, 0x3f4c422a, v87
	v_mul_f32_e32 v86, -2.0, v86
	v_mul_f32_e32 v87, -2.0, v87
	v_mul_f32_e32 v86, 0x3fb8aa3b, v86
	v_mul_f32_e32 v87, 0x3fb8aa3b, v87
	v_exp_f32_e32 v86, v86
	v_exp_f32_e32 v87, v87
	v_add_f32_e32 v86, 1.0, v86
	v_add_f32_e32 v87, 1.0, v87
	v_rcp_f32_e32 v86, v86
	v_rcp_f32_e32 v87, v87
	s_nop 0
	v_pk_mul_f32 v[84:85], v[84:85], v[86:87]
	s_nop 0
	v_cvt_pk_f16_f32 v87, v84, v85
	v_lshrrev_b32_e32 v85, 4, v88
	v_and_b32_e32 v85, 0x10001, v85
	v_add3_u32 v85, v88, v85, s21
	v_lshrrev_b32_e32 v88, 4, v87
	v_and_b32_e32 v88, 0x10001, v88
	v_add3_u32 v87, v87, v88, s21
	v_add_u32_e32 v88, v152, v92
	v_ashrrev_i32_e32 v89, 31, v88
	v_lshrrev_b32_e32 v84, 4, v93
	v_lshrrev_b32_e32 v86, 4, v94
	v_lshlrev_b64 v[88:89], 10, v[88:89]
	v_and_b32_e32 v84, 0x10001, v84
	v_and_b32_e32 v86, 0x10001, v86
	v_lshl_add_u64 v[88:89], s[16:17], 0, v[88:89]
	v_add3_u32 v84, v93, v84, s21
	v_add3_u32 v86, v94, v86, s21
	v_lshl_add_u64 v[88:89], v[88:89], 0, s[42:43]
	v_and_b32_e32 v84, 0xfff0fff0, v84
	v_and_b32_e32 v85, 0xfff0fff0, v85
	v_and_b32_e32 v86, 0xfff0fff0, v86
	v_and_b32_e32 v87, 0xfff0fff0, v87
	v_lshl_add_u64 v[88:89], v[88:89], 0, v[2:3]
	global_store_dwordx4 v[88:89], v[84:87], off
	s_nop 1
	v_cvt_f32_f16_e32 v84, v100
	v_cvt_f32_f16_sdwa v85, v100 dst_sel:DWORD dst_unused:UNUSED_PAD src0_sel:WORD_1
	v_pk_mul_f32 v[84:85], v[32:33], v[84:85]
	s_nop 0
	v_pk_fma_f32 v[80:81], v[80:81], s[38:39], v[84:85] op_sel_hi:[1,0,1]
	s_nop 0
	v_mul_f32_e32 v84, 0x3d372713, v80
	v_mul_f32_e32 v85, 0x3d372713, v81
	v_mul_f32_e32 v84, v80, v84
	v_mul_f32_e32 v85, v81, v85
	v_fma_f32 v84, v80, v84, v80
	v_fma_f32 v85, v81, v85, v81
	v_mul_f32_e32 v84, 0x3f4c422a, v84
	v_mul_f32_e32 v85, 0x3f4c422a, v85
	v_mul_f32_e32 v84, -2.0, v84
	v_mul_f32_e32 v85, -2.0, v85
	v_mul_f32_e32 v84, 0x3fb8aa3b, v84
	v_mul_f32_e32 v85, 0x3fb8aa3b, v85
	v_exp_f32_e32 v84, v84
	v_exp_f32_e32 v85, v85
	v_add_f32_e32 v84, 1.0, v84
	v_add_f32_e32 v85, 1.0, v85
	v_rcp_f32_e32 v84, v84
	v_rcp_f32_e32 v85, v85
	s_nop 0
	v_pk_mul_f32 v[80:81], v[80:81], v[84:85]
	s_nop 0
	v_cvt_pk_f16_f32 v84, v80, v81
	v_cvt_f32_f16_e32 v80, v102
	v_cvt_f32_f16_sdwa v81, v102 dst_sel:DWORD dst_unused:UNUSED_PAD src0_sel:WORD_1
	v_pk_mul_f32 v[80:81], v[28:29], v[80:81]
	s_nop 0
	v_pk_fma_f32 v[76:77], v[76:77], s[38:39], v[80:81] op_sel_hi:[1,0,1]
	s_nop 0
	v_mul_f32_e32 v80, 0x3d372713, v76
	v_mul_f32_e32 v81, 0x3d372713, v77
	v_mul_f32_e32 v80, v76, v80
	v_mul_f32_e32 v81, v77, v81
	v_fma_f32 v80, v76, v80, v76
	v_fma_f32 v81, v77, v81, v77
	v_mul_f32_e32 v80, 0x3f4c422a, v80
	v_mul_f32_e32 v81, 0x3f4c422a, v81
	v_mul_f32_e32 v80, -2.0, v80
	v_mul_f32_e32 v81, -2.0, v81
	v_mul_f32_e32 v80, 0x3fb8aa3b, v80
	v_mul_f32_e32 v81, 0x3fb8aa3b, v81
	v_exp_f32_e32 v80, v80
	v_exp_f32_e32 v81, v81
	v_add_f32_e32 v80, 1.0, v80
	v_add_f32_e32 v81, 1.0, v81
	v_rcp_f32_e32 v80, v80
	v_rcp_f32_e32 v81, v81
	s_nop 0
	v_pk_mul_f32 v[76:77], v[76:77], v[80:81]
	s_nop 0
	v_cvt_pk_f16_f32 v85, v76, v77
	v_cvt_f32_f16_e32 v76, v101
	v_cvt_f32_f16_sdwa v77, v101 dst_sel:DWORD dst_unused:UNUSED_PAD src0_sel:WORD_1
	v_lshl_add_u64 v[100:101], v[184:185], 0, s[10:11]
	s_mov_b64 s[10:11], 0x480000
	v_pk_mul_f32 v[76:77], v[34:35], v[76:77]
	s_nop 0
	v_pk_fma_f32 v[76:77], v[82:83], s[38:39], v[76:77] op_sel_hi:[1,0,1]
	s_nop 0
	v_mul_f32_e32 v80, 0x3d372713, v76
	v_mul_f32_e32 v81, 0x3d372713, v77
	v_mul_f32_e32 v80, v76, v80
	v_mul_f32_e32 v81, v77, v81
	v_fma_f32 v80, v76, v80, v76
	v_fma_f32 v81, v77, v81, v77
	v_mul_f32_e32 v80, 0x3f4c422a, v80
	v_mul_f32_e32 v81, 0x3f4c422a, v81
	v_mul_f32_e32 v80, -2.0, v80
	v_mul_f32_e32 v81, -2.0, v81
	v_mul_f32_e32 v80, 0x3fb8aa3b, v80
	v_mul_f32_e32 v81, 0x3fb8aa3b, v81
	v_exp_f32_e32 v80, v80
	v_exp_f32_e32 v81, v81
	v_add_f32_e32 v80, 1.0, v80
	v_add_f32_e32 v81, 1.0, v81
	v_rcp_f32_e32 v80, v80
	v_rcp_f32_e32 v81, v81
	s_nop 0
	v_pk_mul_f32 v[76:77], v[76:77], v[80:81]
	s_nop 0
	v_cvt_pk_f16_f32 v80, v76, v77
	v_cvt_f32_f16_e32 v76, v103
	v_cvt_f32_f16_sdwa v77, v103 dst_sel:DWORD dst_unused:UNUSED_PAD src0_sel:WORD_1
	v_pk_mul_f32 v[76:77], v[30:31], v[76:77]
	s_nop 0
	v_pk_fma_f32 v[76:77], v[78:79], s[38:39], v[76:77] op_sel_hi:[1,0,1]
	s_nop 0
	v_mul_f32_e32 v78, 0x3d372713, v76
	v_mul_f32_e32 v79, 0x3d372713, v77
	v_mul_f32_e32 v78, v76, v78
	v_mul_f32_e32 v79, v77, v79
	v_fma_f32 v78, v76, v78, v76
	v_fma_f32 v79, v77, v79, v77
	v_mul_f32_e32 v78, 0x3f4c422a, v78
	v_mul_f32_e32 v79, 0x3f4c422a, v79
	v_mul_f32_e32 v78, -2.0, v78
	v_mul_f32_e32 v79, -2.0, v79
	v_mul_f32_e32 v78, 0x3fb8aa3b, v78
	v_mul_f32_e32 v79, 0x3fb8aa3b, v79
	v_exp_f32_e32 v78, v78
	v_exp_f32_e32 v79, v79
	v_add_f32_e32 v78, 1.0, v78
	v_add_f32_e32 v79, 1.0, v79
	v_rcp_f32_e32 v78, v78
	v_rcp_f32_e32 v79, v79
	s_nop 0
	v_pk_mul_f32 v[76:77], v[76:77], v[78:79]
	s_nop 0
	v_cvt_pk_f16_f32 v79, v76, v77
	v_lshrrev_b32_e32 v77, 4, v80
	v_and_b32_e32 v77, 0x10001, v77
	v_add3_u32 v77, v80, v77, s21
	v_lshrrev_b32_e32 v80, 4, v79
	v_and_b32_e32 v80, 0x10001, v80
	v_add3_u32 v79, v79, v80, s21
	v_add_u32_e32 v80, v140, v92
	v_ashrrev_i32_e32 v81, 31, v80
	v_lshrrev_b32_e32 v76, 4, v84
	v_lshrrev_b32_e32 v78, 4, v85
	v_lshlrev_b64 v[80:81], 10, v[80:81]
	v_and_b32_e32 v76, 0x10001, v76
	v_and_b32_e32 v78, 0x10001, v78
	v_lshl_add_u64 v[80:81], s[16:17], 0, v[80:81]
	v_add3_u32 v76, v84, v76, s21
	v_add3_u32 v78, v85, v78, s21
	v_lshl_add_u64 v[80:81], v[80:81], 0, s[42:43]
	v_lshl_add_u64 v[92:93], v[184:185], 0, s[10:11]
	s_mov_b64 s[10:11], 0x500000
	v_and_b32_e32 v76, 0xfff0fff0, v76
	v_and_b32_e32 v77, 0xfff0fff0, v77
	v_and_b32_e32 v78, 0xfff0fff0, v78
	v_and_b32_e32 v79, 0xfff0fff0, v79
	v_lshl_add_u64 v[80:81], v[80:81], 0, v[2:3]
	v_lshl_add_u64 v[84:85], v[184:185], 0, s[10:11]
	s_mov_b64 s[10:11], 0x580000
	global_store_dwordx4 v[80:81], v[76:79], off
	s_nop 1
	v_lshl_add_u64 v[76:77], v[184:185], 0, s[10:11]
	s_mov_b32 s10, 0x580000
	v_add_co_u32_e32 v78, vcc, s10, v184
	s_mov_b32 s10, 0x500000
	s_nop 0
	v_addc_co_u32_e32 v79, vcc, 0, v185, vcc
	global_load_dwordx4 v[80:83], v[78:79], off
	v_add_co_u32_e32 v78, vcc, s10, v184
	s_mov_b32 s10, 0x480000
	s_nop 0
	v_addc_co_u32_e32 v79, vcc, 0, v185, vcc
	global_load_dwordx4 v[88:91], v[78:79], off
	v_add_co_u32_e32 v78, vcc, s10, v184
	s_mov_b32 s10, 0x400000
	s_nop 0
	v_addc_co_u32_e32 v79, vcc, 0, v185, vcc
	global_load_dwordx4 v[96:99], v[78:79], off
	v_add_co_u32_e32 v78, vcc, s10, v184
	s_mov_b32 s10, s18
	s_nop 0
	v_addc_co_u32_e32 v79, vcc, 0, v185, vcc
	global_load_dwordx4 v[106:109], v[78:79], off
	s_nop 0
	global_load_dwordx4 v[76:79], v[76:77], off offset:256
	s_nop 0
	global_load_dwordx4 v[84:87], v[84:85], off offset:256
	s_nop 0
	global_load_dwordx4 v[92:95], v[92:93], off offset:256
	s_nop 0
	global_load_dwordx4 v[100:103], v[100:101], off offset:256
	s_waitcnt vmcnt(0)
	s_nop 0
	v_cvt_f32_f16_e32 v110, v106
	v_cvt_f32_f16_sdwa v111, v106 dst_sel:DWORD dst_unused:UNUSED_PAD src0_sel:WORD_1
	s_and_b64 vcc, exec, s[40:41]
	v_pk_mul_f32 v[110:111], v[32:33], v[110:111]
	s_nop 0
	v_pk_fma_f32 v[72:73], v[72:73], s[38:39], v[110:111] op_sel_hi:[1,0,1]
	s_nop 0
	v_mul_f32_e32 v105, 0x3d372713, v72
	v_mul_f32_e32 v105, v72, v105
	v_fma_f32 v105, v72, v105, v72
	v_mul_f32_e32 v105, 0x3f4c422a, v105
	v_mul_f32_e32 v105, -2.0, v105
	v_mul_f32_e32 v105, 0x3fb8aa3b, v105
	v_exp_f32_e32 v105, v105
	s_nop 0
	v_add_f32_e32 v105, 1.0, v105
	v_rcp_f32_e32 v110, v105
	v_mul_f32_e32 v105, 0x3d372713, v73
	v_mul_f32_e32 v105, v73, v105
	v_fma_f32 v105, v73, v105, v73
	v_mul_f32_e32 v105, 0x3f4c422a, v105
	v_mul_f32_e32 v105, -2.0, v105
	v_mul_f32_e32 v105, 0x3fb8aa3b, v105
	v_exp_f32_e32 v105, v105
	s_nop 0
	v_add_f32_e32 v105, 1.0, v105
	v_rcp_f32_e32 v111, v105
	s_nop 0
	v_pk_mul_f32 v[72:73], v[72:73], v[110:111]
	s_nop 0
	v_cvt_pk_f16_f32 v105, v72, v73
	v_cvt_f32_f16_e32 v72, v108
	v_cvt_f32_f16_sdwa v73, v108 dst_sel:DWORD dst_unused:UNUSED_PAD src0_sel:WORD_1
	v_pk_mul_f32 v[72:73], v[28:29], v[72:73]
	s_nop 0
	v_pk_fma_f32 v[68:69], v[68:69], s[38:39], v[72:73] op_sel_hi:[1,0,1]
	s_nop 0
	v_mul_f32_e32 v72, 0x3d372713, v68
	v_mul_f32_e32 v73, 0x3d372713, v69
	v_mul_f32_e32 v72, v68, v72
	v_mul_f32_e32 v73, v69, v73
	v_fma_f32 v72, v68, v72, v68
	v_fma_f32 v73, v69, v73, v69
	v_mul_f32_e32 v72, 0x3f4c422a, v72
	v_mul_f32_e32 v73, 0x3f4c422a, v73
	v_mul_f32_e32 v72, -2.0, v72
	v_mul_f32_e32 v73, -2.0, v73
	v_mul_f32_e32 v72, 0x3fb8aa3b, v72
	v_mul_f32_e32 v73, 0x3fb8aa3b, v73
	v_exp_f32_e32 v72, v72
	v_exp_f32_e32 v73, v73
	v_add_f32_e32 v72, 1.0, v72
	v_add_f32_e32 v73, 1.0, v73
	v_rcp_f32_e32 v72, v72
	v_rcp_f32_e32 v73, v73
	s_nop 0
	v_pk_mul_f32 v[68:69], v[68:69], v[72:73]
	s_nop 0
	v_cvt_pk_f16_f32 v106, v68, v69
	v_cvt_f32_f16_e32 v68, v107
	v_cvt_f32_f16_sdwa v69, v107 dst_sel:DWORD dst_unused:UNUSED_PAD src0_sel:WORD_1
	v_pk_mul_f32 v[68:69], v[34:35], v[68:69]
	s_nop 0
	v_pk_fma_f32 v[68:69], v[74:75], s[38:39], v[68:69] op_sel_hi:[1,0,1]
	s_nop 0
	v_mul_f32_e32 v72, 0x3d372713, v68
	v_mul_f32_e32 v73, 0x3d372713, v69
	v_mul_f32_e32 v72, v68, v72
	v_mul_f32_e32 v73, v69, v73
	v_fma_f32 v72, v68, v72, v68
	v_fma_f32 v73, v69, v73, v69
	v_mul_f32_e32 v72, 0x3f4c422a, v72
	v_mul_f32_e32 v73, 0x3f4c422a, v73
	v_mul_f32_e32 v72, -2.0, v72
	v_mul_f32_e32 v73, -2.0, v73
	v_mul_f32_e32 v72, 0x3fb8aa3b, v72
	v_mul_f32_e32 v73, 0x3fb8aa3b, v73
	v_exp_f32_e32 v72, v72
	v_exp_f32_e32 v73, v73
	v_add_f32_e32 v72, 1.0, v72
	v_add_f32_e32 v73, 1.0, v73
	v_rcp_f32_e32 v72, v72
	v_rcp_f32_e32 v73, v73
	s_nop 0
	v_pk_mul_f32 v[68:69], v[68:69], v[72:73]
	s_nop 0
	v_cvt_pk_f16_f32 v72, v68, v69
	v_cvt_f32_f16_e32 v68, v109
	v_cvt_f32_f16_sdwa v69, v109 dst_sel:DWORD dst_unused:UNUSED_PAD src0_sel:WORD_1
	v_pk_mul_f32 v[68:69], v[30:31], v[68:69]
	s_nop 0
	v_pk_fma_f32 v[68:69], v[70:71], s[38:39], v[68:69] op_sel_hi:[1,0,1]
	s_nop 0
	v_mul_f32_e32 v70, 0x3d372713, v68
	v_mul_f32_e32 v71, 0x3d372713, v69
	v_mul_f32_e32 v70, v68, v70
	v_mul_f32_e32 v71, v69, v71
	v_fma_f32 v70, v68, v70, v68
	v_fma_f32 v71, v69, v71, v69
	v_mul_f32_e32 v70, 0x3f4c422a, v70
	v_mul_f32_e32 v71, 0x3f4c422a, v71
	v_mul_f32_e32 v70, -2.0, v70
	v_mul_f32_e32 v71, -2.0, v71
	v_mul_f32_e32 v70, 0x3fb8aa3b, v70
	v_mul_f32_e32 v71, 0x3fb8aa3b, v71
	v_exp_f32_e32 v70, v70
	v_exp_f32_e32 v71, v71
	v_add_f32_e32 v70, 1.0, v70
	v_add_f32_e32 v71, 1.0, v71
	v_rcp_f32_e32 v70, v70
	v_rcp_f32_e32 v71, v71
	s_nop 0
	v_pk_mul_f32 v[68:69], v[68:69], v[70:71]
	s_nop 0
	v_cvt_pk_f16_f32 v71, v68, v69
	v_lshrrev_b32_e32 v69, 4, v72
	v_and_b32_e32 v69, 0x10001, v69
	v_add3_u32 v69, v72, v69, s21
	v_lshrrev_b32_e32 v72, 4, v71
	v_and_b32_e32 v72, 0x10001, v72
	v_add3_u32 v71, v71, v72, s21
	v_add_u32_e32 v72, v152, v104
	v_ashrrev_i32_e32 v73, 31, v72
	v_lshrrev_b32_e32 v68, 4, v105
	v_lshrrev_b32_e32 v70, 4, v106
	v_lshlrev_b64 v[72:73], 10, v[72:73]
	v_and_b32_e32 v68, 0x10001, v68
	v_and_b32_e32 v70, 0x10001, v70
	v_lshl_add_u64 v[72:73], s[16:17], 0, v[72:73]
	v_add3_u32 v68, v105, v68, s21
	v_add3_u32 v70, v106, v70, s21
	v_lshl_add_u64 v[72:73], v[72:73], 0, s[42:43]
	v_and_b32_e32 v68, 0xfff0fff0, v68
	v_and_b32_e32 v69, 0xfff0fff0, v69
	v_and_b32_e32 v70, 0xfff0fff0, v70
	v_and_b32_e32 v71, 0xfff0fff0, v71
	v_lshl_add_u64 v[72:73], v[72:73], 0, v[2:3]
	global_store_dwordx4 v[72:73], v[68:71], off
	s_nop 1
	v_cvt_f32_f16_e32 v68, v100
	v_cvt_f32_f16_sdwa v69, v100 dst_sel:DWORD dst_unused:UNUSED_PAD src0_sel:WORD_1
	v_pk_mul_f32 v[68:69], v[32:33], v[68:69]
	s_nop 0
	v_pk_fma_f32 v[64:65], v[64:65], s[38:39], v[68:69] op_sel_hi:[1,0,1]
	s_nop 0
	v_mul_f32_e32 v68, 0x3d372713, v64
	v_mul_f32_e32 v69, 0x3d372713, v65
	v_mul_f32_e32 v68, v64, v68
	v_mul_f32_e32 v69, v65, v69
	v_fma_f32 v68, v64, v68, v64
	v_fma_f32 v69, v65, v69, v65
	v_mul_f32_e32 v68, 0x3f4c422a, v68
	v_mul_f32_e32 v69, 0x3f4c422a, v69
	v_mul_f32_e32 v68, -2.0, v68
	v_mul_f32_e32 v69, -2.0, v69
	v_mul_f32_e32 v68, 0x3fb8aa3b, v68
	v_mul_f32_e32 v69, 0x3fb8aa3b, v69
	v_exp_f32_e32 v68, v68
	v_exp_f32_e32 v69, v69
	v_add_f32_e32 v68, 1.0, v68
	v_add_f32_e32 v69, 1.0, v69
	v_rcp_f32_e32 v68, v68
	v_rcp_f32_e32 v69, v69
	s_nop 0
	v_pk_mul_f32 v[64:65], v[64:65], v[68:69]
	s_nop 0
	v_cvt_pk_f16_f32 v68, v64, v65
	v_cvt_f32_f16_e32 v64, v102
	v_cvt_f32_f16_sdwa v65, v102 dst_sel:DWORD dst_unused:UNUSED_PAD src0_sel:WORD_1
	v_pk_mul_f32 v[64:65], v[28:29], v[64:65]
	s_nop 0
	v_pk_fma_f32 v[60:61], v[60:61], s[38:39], v[64:65] op_sel_hi:[1,0,1]
	s_nop 0
	v_mul_f32_e32 v64, 0x3d372713, v60
	v_mul_f32_e32 v65, 0x3d372713, v61
	v_mul_f32_e32 v64, v60, v64
	v_mul_f32_e32 v65, v61, v65
	v_fma_f32 v64, v60, v64, v60
	v_fma_f32 v65, v61, v65, v61
	v_mul_f32_e32 v64, 0x3f4c422a, v64
	v_mul_f32_e32 v65, 0x3f4c422a, v65
	v_mul_f32_e32 v64, -2.0, v64
	v_mul_f32_e32 v65, -2.0, v65
	v_mul_f32_e32 v64, 0x3fb8aa3b, v64
	v_mul_f32_e32 v65, 0x3fb8aa3b, v65
	v_exp_f32_e32 v64, v64
	v_exp_f32_e32 v65, v65
	v_add_f32_e32 v64, 1.0, v64
	v_add_f32_e32 v65, 1.0, v65
	v_rcp_f32_e32 v64, v64
	v_rcp_f32_e32 v65, v65
	s_nop 0
	v_pk_mul_f32 v[60:61], v[60:61], v[64:65]
	s_nop 0
	v_cvt_pk_f16_f32 v69, v60, v61
	v_cvt_f32_f16_e32 v60, v101
	v_cvt_f32_f16_sdwa v61, v101 dst_sel:DWORD dst_unused:UNUSED_PAD src0_sel:WORD_1
	v_pk_mul_f32 v[60:61], v[34:35], v[60:61]
	s_nop 0
	v_pk_fma_f32 v[60:61], v[66:67], s[38:39], v[60:61] op_sel_hi:[1,0,1]
	s_nop 0
	v_mul_f32_e32 v64, 0x3d372713, v60
	v_mul_f32_e32 v65, 0x3d372713, v61
	v_mul_f32_e32 v64, v60, v64
	v_mul_f32_e32 v65, v61, v65
	v_fma_f32 v64, v60, v64, v60
	v_fma_f32 v65, v61, v65, v61
	v_mul_f32_e32 v64, 0x3f4c422a, v64
	v_mul_f32_e32 v65, 0x3f4c422a, v65
	v_mul_f32_e32 v64, -2.0, v64
	v_mul_f32_e32 v65, -2.0, v65
	v_mul_f32_e32 v64, 0x3fb8aa3b, v64
	v_mul_f32_e32 v65, 0x3fb8aa3b, v65
	v_exp_f32_e32 v64, v64
	v_exp_f32_e32 v65, v65
	v_add_f32_e32 v64, 1.0, v64
	v_add_f32_e32 v65, 1.0, v65
	v_rcp_f32_e32 v64, v64
	v_rcp_f32_e32 v65, v65
	s_nop 0
	v_pk_mul_f32 v[60:61], v[60:61], v[64:65]
	s_nop 0
	v_cvt_pk_f16_f32 v64, v60, v61
	v_cvt_f32_f16_e32 v60, v103
	v_cvt_f32_f16_sdwa v61, v103 dst_sel:DWORD dst_unused:UNUSED_PAD src0_sel:WORD_1
	v_pk_mul_f32 v[60:61], v[30:31], v[60:61]
	s_nop 0
	v_pk_fma_f32 v[60:61], v[62:63], s[38:39], v[60:61] op_sel_hi:[1,0,1]
	s_nop 0
	v_mul_f32_e32 v62, 0x3d372713, v60
	v_mul_f32_e32 v63, 0x3d372713, v61
	v_mul_f32_e32 v62, v60, v62
	v_mul_f32_e32 v63, v61, v63
	v_fma_f32 v62, v60, v62, v60
	v_fma_f32 v63, v61, v63, v61
	v_mul_f32_e32 v62, 0x3f4c422a, v62
	v_mul_f32_e32 v63, 0x3f4c422a, v63
	v_mul_f32_e32 v62, -2.0, v62
	v_mul_f32_e32 v63, -2.0, v63
	v_mul_f32_e32 v62, 0x3fb8aa3b, v62
	v_mul_f32_e32 v63, 0x3fb8aa3b, v63
	v_exp_f32_e32 v62, v62
	v_exp_f32_e32 v63, v63
	v_add_f32_e32 v62, 1.0, v62
	v_add_f32_e32 v63, 1.0, v63
	v_rcp_f32_e32 v62, v62
	v_rcp_f32_e32 v63, v63
	s_nop 0
	v_pk_mul_f32 v[60:61], v[60:61], v[62:63]
	s_nop 0
	v_cvt_pk_f16_f32 v63, v60, v61
	v_lshrrev_b32_e32 v61, 4, v64
	v_and_b32_e32 v61, 0x10001, v61
	v_add3_u32 v61, v64, v61, s21
	v_lshrrev_b32_e32 v64, 4, v63
	v_and_b32_e32 v64, 0x10001, v64
	v_add3_u32 v63, v63, v64, s21
	v_add_u32_e32 v64, v140, v104
	v_ashrrev_i32_e32 v65, 31, v64
	v_lshrrev_b32_e32 v60, 4, v68
	v_lshrrev_b32_e32 v62, 4, v69
	v_lshlrev_b64 v[64:65], 10, v[64:65]
	v_and_b32_e32 v60, 0x10001, v60
	v_and_b32_e32 v62, 0x10001, v62
	v_lshl_add_u64 v[64:65], s[16:17], 0, v[64:65]
	v_add3_u32 v60, v68, v60, s21
	v_add3_u32 v62, v69, v62, s21
	v_lshl_add_u64 v[64:65], v[64:65], 0, s[42:43]
	v_and_b32_e32 v60, 0xfff0fff0, v60
	v_and_b32_e32 v61, 0xfff0fff0, v61
	v_and_b32_e32 v62, 0xfff0fff0, v62
	v_and_b32_e32 v63, 0xfff0fff0, v63
	v_lshl_add_u64 v[64:65], v[64:65], 0, v[2:3]
	global_store_dwordx4 v[64:65], v[60:63], off
	s_nop 1
	v_cvt_f32_f16_e32 v62, v96
	v_cvt_f32_f16_sdwa v63, v96 dst_sel:DWORD dst_unused:UNUSED_PAD src0_sel:WORD_1
	v_add_u32_e32 v60, 0x900, v192
	v_pk_mul_f32 v[62:63], v[32:33], v[62:63]
	s_nop 0
	v_pk_fma_f32 v[56:57], v[56:57], s[38:39], v[62:63] op_sel_hi:[1,0,1]
	s_nop 0
	v_mul_f32_e32 v61, 0x3d372713, v56
	v_mul_f32_e32 v61, v56, v61
	v_fma_f32 v61, v56, v61, v56
	v_mul_f32_e32 v61, 0x3f4c422a, v61
	v_mul_f32_e32 v61, -2.0, v61
	v_mul_f32_e32 v61, 0x3fb8aa3b, v61
	v_exp_f32_e32 v61, v61
	s_nop 0
	v_add_f32_e32 v61, 1.0, v61
	v_rcp_f32_e32 v62, v61
	v_mul_f32_e32 v61, 0x3d372713, v57
	v_mul_f32_e32 v61, v57, v61
	v_fma_f32 v61, v57, v61, v57
	v_mul_f32_e32 v61, 0x3f4c422a, v61
	v_mul_f32_e32 v61, -2.0, v61
	v_mul_f32_e32 v61, 0x3fb8aa3b, v61
	v_exp_f32_e32 v61, v61
	s_nop 0
	v_add_f32_e32 v61, 1.0, v61
	v_rcp_f32_e32 v63, v61
	s_nop 0
	v_pk_mul_f32 v[56:57], v[56:57], v[62:63]
	s_nop 0
	v_cvt_pk_f16_f32 v61, v56, v57
	v_cvt_f32_f16_e32 v56, v98
	v_cvt_f32_f16_sdwa v57, v98 dst_sel:DWORD dst_unused:UNUSED_PAD src0_sel:WORD_1
	v_pk_mul_f32 v[56:57], v[28:29], v[56:57]
	s_nop 0
	v_pk_fma_f32 v[52:53], v[52:53], s[38:39], v[56:57] op_sel_hi:[1,0,1]
	s_nop 0
	v_mul_f32_e32 v56, 0x3d372713, v52
	v_mul_f32_e32 v57, 0x3d372713, v53
	v_mul_f32_e32 v56, v52, v56
	v_mul_f32_e32 v57, v53, v57
	v_fma_f32 v56, v52, v56, v52
	v_fma_f32 v57, v53, v57, v53
	v_mul_f32_e32 v56, 0x3f4c422a, v56
	v_mul_f32_e32 v57, 0x3f4c422a, v57
	v_mul_f32_e32 v56, -2.0, v56
	v_mul_f32_e32 v57, -2.0, v57
	v_mul_f32_e32 v56, 0x3fb8aa3b, v56
	v_mul_f32_e32 v57, 0x3fb8aa3b, v57
	v_exp_f32_e32 v56, v56
	v_exp_f32_e32 v57, v57
	v_add_f32_e32 v56, 1.0, v56
	v_add_f32_e32 v57, 1.0, v57
	v_rcp_f32_e32 v56, v56
	v_rcp_f32_e32 v57, v57
	s_nop 0
	v_pk_mul_f32 v[52:53], v[52:53], v[56:57]
	s_nop 0
	v_cvt_pk_f16_f32 v62, v52, v53
	v_cvt_f32_f16_e32 v52, v97
	v_cvt_f32_f16_sdwa v53, v97 dst_sel:DWORD dst_unused:UNUSED_PAD src0_sel:WORD_1
	v_pk_mul_f32 v[52:53], v[34:35], v[52:53]
	s_nop 0
	v_pk_fma_f32 v[52:53], v[58:59], s[38:39], v[52:53] op_sel_hi:[1,0,1]
	s_nop 0
	v_mul_f32_e32 v56, 0x3d372713, v52
	v_mul_f32_e32 v57, 0x3d372713, v53
	v_mul_f32_e32 v56, v52, v56
	v_mul_f32_e32 v57, v53, v57
	v_fma_f32 v56, v52, v56, v52
	v_fma_f32 v57, v53, v57, v53
	v_mul_f32_e32 v56, 0x3f4c422a, v56
	v_mul_f32_e32 v57, 0x3f4c422a, v57
	v_mul_f32_e32 v56, -2.0, v56
	v_mul_f32_e32 v57, -2.0, v57
	v_mul_f32_e32 v56, 0x3fb8aa3b, v56
	v_mul_f32_e32 v57, 0x3fb8aa3b, v57
	v_exp_f32_e32 v56, v56
	v_exp_f32_e32 v57, v57
	v_add_f32_e32 v56, 1.0, v56
	v_add_f32_e32 v57, 1.0, v57
	v_rcp_f32_e32 v56, v56
	v_rcp_f32_e32 v57, v57
	s_nop 0
	v_pk_mul_f32 v[52:53], v[52:53], v[56:57]
	s_nop 0
	v_cvt_pk_f16_f32 v56, v52, v53
	v_cvt_f32_f16_e32 v52, v99
	v_cvt_f32_f16_sdwa v53, v99 dst_sel:DWORD dst_unused:UNUSED_PAD src0_sel:WORD_1
	v_pk_mul_f32 v[52:53], v[30:31], v[52:53]
	s_nop 0
	v_pk_fma_f32 v[52:53], v[54:55], s[38:39], v[52:53] op_sel_hi:[1,0,1]
	s_nop 0
	v_mul_f32_e32 v54, 0x3d372713, v52
	v_mul_f32_e32 v55, 0x3d372713, v53
	v_mul_f32_e32 v54, v52, v54
	v_mul_f32_e32 v55, v53, v55
	v_fma_f32 v54, v52, v54, v52
	v_fma_f32 v55, v53, v55, v53
	v_mul_f32_e32 v54, 0x3f4c422a, v54
	v_mul_f32_e32 v55, 0x3f4c422a, v55
	v_mul_f32_e32 v54, -2.0, v54
	v_mul_f32_e32 v55, -2.0, v55
	v_mul_f32_e32 v54, 0x3fb8aa3b, v54
	v_mul_f32_e32 v55, 0x3fb8aa3b, v55
	v_exp_f32_e32 v54, v54
	v_exp_f32_e32 v55, v55
	v_add_f32_e32 v54, 1.0, v54
	v_add_f32_e32 v55, 1.0, v55
	v_rcp_f32_e32 v54, v54
	v_rcp_f32_e32 v55, v55
	s_nop 0
	v_pk_mul_f32 v[52:53], v[52:53], v[54:55]
	s_nop 0
	v_cvt_pk_f16_f32 v55, v52, v53
	v_lshrrev_b32_e32 v53, 4, v56
	v_and_b32_e32 v53, 0x10001, v53
	v_add3_u32 v53, v56, v53, s21
	v_lshrrev_b32_e32 v56, 4, v55
	v_and_b32_e32 v56, 0x10001, v56
	v_add3_u32 v55, v55, v56, s21
	v_add_u32_e32 v56, v152, v60
	v_ashrrev_i32_e32 v57, 31, v56
	v_lshrrev_b32_e32 v52, 4, v61
	v_lshrrev_b32_e32 v54, 4, v62
	v_lshlrev_b64 v[56:57], 10, v[56:57]
	v_and_b32_e32 v52, 0x10001, v52
	v_and_b32_e32 v54, 0x10001, v54
	v_lshl_add_u64 v[56:57], s[16:17], 0, v[56:57]
	v_add3_u32 v52, v61, v52, s21
	v_add3_u32 v54, v62, v54, s21
	v_lshl_add_u64 v[56:57], v[56:57], 0, s[42:43]
	v_and_b32_e32 v52, 0xfff0fff0, v52
	v_and_b32_e32 v53, 0xfff0fff0, v53
	v_and_b32_e32 v54, 0xfff0fff0, v54
	v_and_b32_e32 v55, 0xfff0fff0, v55
	v_lshl_add_u64 v[56:57], v[56:57], 0, v[2:3]
	global_store_dwordx4 v[56:57], v[52:55], off
	s_nop 1
	v_cvt_f32_f16_e32 v52, v92
	v_cvt_f32_f16_sdwa v53, v92 dst_sel:DWORD dst_unused:UNUSED_PAD src0_sel:WORD_1
	v_pk_mul_f32 v[52:53], v[32:33], v[52:53]
	s_nop 0
	v_pk_fma_f32 v[48:49], v[48:49], s[38:39], v[52:53] op_sel_hi:[1,0,1]
	s_nop 0
	v_mul_f32_e32 v52, 0x3d372713, v48
	v_mul_f32_e32 v53, 0x3d372713, v49
	v_mul_f32_e32 v52, v48, v52
	v_mul_f32_e32 v53, v49, v53
	v_fma_f32 v52, v48, v52, v48
	v_fma_f32 v53, v49, v53, v49
	v_mul_f32_e32 v52, 0x3f4c422a, v52
	v_mul_f32_e32 v53, 0x3f4c422a, v53
	v_mul_f32_e32 v52, -2.0, v52
	v_mul_f32_e32 v53, -2.0, v53
	v_mul_f32_e32 v52, 0x3fb8aa3b, v52
	v_mul_f32_e32 v53, 0x3fb8aa3b, v53
	v_exp_f32_e32 v52, v52
	v_exp_f32_e32 v53, v53
	v_add_f32_e32 v52, 1.0, v52
	v_add_f32_e32 v53, 1.0, v53
	v_rcp_f32_e32 v52, v52
	v_rcp_f32_e32 v53, v53
	s_nop 0
	v_pk_mul_f32 v[48:49], v[48:49], v[52:53]
	s_nop 0
	v_cvt_pk_f16_f32 v52, v48, v49
	v_cvt_f32_f16_e32 v48, v94
	v_cvt_f32_f16_sdwa v49, v94 dst_sel:DWORD dst_unused:UNUSED_PAD src0_sel:WORD_1
	v_pk_mul_f32 v[48:49], v[28:29], v[48:49]
	s_nop 0
	v_pk_fma_f32 v[44:45], v[44:45], s[38:39], v[48:49] op_sel_hi:[1,0,1]
	s_nop 0
	v_mul_f32_e32 v48, 0x3d372713, v44
	v_mul_f32_e32 v49, 0x3d372713, v45
	v_mul_f32_e32 v48, v44, v48
	v_mul_f32_e32 v49, v45, v49
	v_fma_f32 v48, v44, v48, v44
	v_fma_f32 v49, v45, v49, v45
	v_mul_f32_e32 v48, 0x3f4c422a, v48
	v_mul_f32_e32 v49, 0x3f4c422a, v49
	v_mul_f32_e32 v48, -2.0, v48
	v_mul_f32_e32 v49, -2.0, v49
	v_mul_f32_e32 v48, 0x3fb8aa3b, v48
	v_mul_f32_e32 v49, 0x3fb8aa3b, v49
	v_exp_f32_e32 v48, v48
	v_exp_f32_e32 v49, v49
	v_add_f32_e32 v48, 1.0, v48
	v_add_f32_e32 v49, 1.0, v49
	v_rcp_f32_e32 v48, v48
	v_rcp_f32_e32 v49, v49
	s_nop 0
	v_pk_mul_f32 v[44:45], v[44:45], v[48:49]
	s_nop 0
	v_cvt_pk_f16_f32 v53, v44, v45
	v_cvt_f32_f16_e32 v44, v93
	v_cvt_f32_f16_sdwa v45, v93 dst_sel:DWORD dst_unused:UNUSED_PAD src0_sel:WORD_1
	v_pk_mul_f32 v[44:45], v[34:35], v[44:45]
	s_nop 0
	v_pk_fma_f32 v[44:45], v[50:51], s[38:39], v[44:45] op_sel_hi:[1,0,1]
	s_nop 0
	v_mul_f32_e32 v48, 0x3d372713, v44
	v_mul_f32_e32 v49, 0x3d372713, v45
	v_mul_f32_e32 v48, v44, v48
	v_mul_f32_e32 v49, v45, v49
	v_fma_f32 v48, v44, v48, v44
	v_fma_f32 v49, v45, v49, v45
	v_mul_f32_e32 v48, 0x3f4c422a, v48
	v_mul_f32_e32 v49, 0x3f4c422a, v49
	v_mul_f32_e32 v48, -2.0, v48
	v_mul_f32_e32 v49, -2.0, v49
	v_mul_f32_e32 v48, 0x3fb8aa3b, v48
	v_mul_f32_e32 v49, 0x3fb8aa3b, v49
	v_exp_f32_e32 v48, v48
	v_exp_f32_e32 v49, v49
	v_add_f32_e32 v48, 1.0, v48
	v_add_f32_e32 v49, 1.0, v49
	v_rcp_f32_e32 v48, v48
	v_rcp_f32_e32 v49, v49
	s_nop 0
	v_pk_mul_f32 v[44:45], v[44:45], v[48:49]
	s_nop 0
	v_cvt_pk_f16_f32 v48, v44, v45
	v_cvt_f32_f16_e32 v44, v95
	v_cvt_f32_f16_sdwa v45, v95 dst_sel:DWORD dst_unused:UNUSED_PAD src0_sel:WORD_1
	v_pk_mul_f32 v[44:45], v[30:31], v[44:45]
	s_nop 0
	v_pk_fma_f32 v[44:45], v[46:47], s[38:39], v[44:45] op_sel_hi:[1,0,1]
	s_nop 0
	v_mul_f32_e32 v46, 0x3d372713, v44
	v_mul_f32_e32 v47, 0x3d372713, v45
	v_mul_f32_e32 v46, v44, v46
	v_mul_f32_e32 v47, v45, v47
	v_fma_f32 v46, v44, v46, v44
	v_fma_f32 v47, v45, v47, v45
	v_mul_f32_e32 v46, 0x3f4c422a, v46
	v_mul_f32_e32 v47, 0x3f4c422a, v47
	v_mul_f32_e32 v46, -2.0, v46
	v_mul_f32_e32 v47, -2.0, v47
	v_mul_f32_e32 v46, 0x3fb8aa3b, v46
	v_mul_f32_e32 v47, 0x3fb8aa3b, v47
	v_exp_f32_e32 v46, v46
	v_exp_f32_e32 v47, v47
	v_add_f32_e32 v46, 1.0, v46
	v_add_f32_e32 v47, 1.0, v47
	v_rcp_f32_e32 v46, v46
	v_rcp_f32_e32 v47, v47
	s_nop 0
	v_pk_mul_f32 v[44:45], v[44:45], v[46:47]
	s_nop 0
	v_cvt_pk_f16_f32 v47, v44, v45
	v_lshrrev_b32_e32 v45, 4, v48
	v_and_b32_e32 v45, 0x10001, v45
	v_add3_u32 v45, v48, v45, s21
	v_lshrrev_b32_e32 v48, 4, v47
	v_and_b32_e32 v48, 0x10001, v48
	v_add3_u32 v47, v47, v48, s21
	v_add_u32_e32 v48, v140, v60
	v_ashrrev_i32_e32 v49, 31, v48
	v_lshrrev_b32_e32 v44, 4, v52
	v_lshrrev_b32_e32 v46, 4, v53
	v_lshlrev_b64 v[48:49], 10, v[48:49]
	v_and_b32_e32 v44, 0x10001, v44
	v_and_b32_e32 v46, 0x10001, v46
	v_lshl_add_u64 v[48:49], s[16:17], 0, v[48:49]
	v_add3_u32 v44, v52, v44, s21
	v_add3_u32 v46, v53, v46, s21
	v_lshl_add_u64 v[48:49], v[48:49], 0, s[42:43]
	v_and_b32_e32 v44, 0xfff0fff0, v44
	v_and_b32_e32 v45, 0xfff0fff0, v45
	v_and_b32_e32 v46, 0xfff0fff0, v46
	v_and_b32_e32 v47, 0xfff0fff0, v47
	v_lshl_add_u64 v[48:49], v[48:49], 0, v[2:3]
	global_store_dwordx4 v[48:49], v[44:47], off
	s_nop 1
	v_cvt_f32_f16_e32 v46, v88
	v_cvt_f32_f16_sdwa v47, v88 dst_sel:DWORD dst_unused:UNUSED_PAD src0_sel:WORD_1
	v_add_u32_e32 v44, 0xa00, v192
	v_pk_mul_f32 v[46:47], v[32:33], v[46:47]
	s_nop 0
	v_pk_fma_f32 v[40:41], v[40:41], s[38:39], v[46:47] op_sel_hi:[1,0,1]
	s_nop 0
	v_mul_f32_e32 v45, 0x3d372713, v40
	v_mul_f32_e32 v45, v40, v45
	v_fma_f32 v45, v40, v45, v40
	v_mul_f32_e32 v45, 0x3f4c422a, v45
	v_mul_f32_e32 v45, -2.0, v45
	v_mul_f32_e32 v45, 0x3fb8aa3b, v45
	v_exp_f32_e32 v45, v45
	s_nop 0
	v_add_f32_e32 v45, 1.0, v45
	v_rcp_f32_e32 v46, v45
	v_mul_f32_e32 v45, 0x3d372713, v41
	v_mul_f32_e32 v45, v41, v45
	v_fma_f32 v45, v41, v45, v41
	v_mul_f32_e32 v45, 0x3f4c422a, v45
	v_mul_f32_e32 v45, -2.0, v45
	v_mul_f32_e32 v45, 0x3fb8aa3b, v45
	v_exp_f32_e32 v45, v45
	s_nop 0
	v_add_f32_e32 v45, 1.0, v45
	v_rcp_f32_e32 v47, v45
	s_nop 0
	v_pk_mul_f32 v[40:41], v[40:41], v[46:47]
	s_nop 0
	v_cvt_pk_f16_f32 v45, v40, v41
	v_cvt_f32_f16_e32 v40, v90
	v_cvt_f32_f16_sdwa v41, v90 dst_sel:DWORD dst_unused:UNUSED_PAD src0_sel:WORD_1
	v_pk_mul_f32 v[40:41], v[28:29], v[40:41]
	s_nop 0
	v_pk_fma_f32 v[36:37], v[36:37], s[38:39], v[40:41] op_sel_hi:[1,0,1]
	s_nop 0
	v_mul_f32_e32 v40, 0x3d372713, v36
	v_mul_f32_e32 v41, 0x3d372713, v37
	v_mul_f32_e32 v40, v36, v40
	v_mul_f32_e32 v41, v37, v41
	v_fma_f32 v40, v36, v40, v36
	v_fma_f32 v41, v37, v41, v37
	v_mul_f32_e32 v40, 0x3f4c422a, v40
	v_mul_f32_e32 v41, 0x3f4c422a, v41
	v_mul_f32_e32 v40, -2.0, v40
	v_mul_f32_e32 v41, -2.0, v41
	v_mul_f32_e32 v40, 0x3fb8aa3b, v40
	v_mul_f32_e32 v41, 0x3fb8aa3b, v41
	v_exp_f32_e32 v40, v40
	v_exp_f32_e32 v41, v41
	v_add_f32_e32 v40, 1.0, v40
	v_add_f32_e32 v41, 1.0, v41
	v_rcp_f32_e32 v40, v40
	v_rcp_f32_e32 v41, v41
	s_nop 0
	v_pk_mul_f32 v[36:37], v[36:37], v[40:41]
	s_nop 0
	v_cvt_pk_f16_f32 v46, v36, v37
	v_cvt_f32_f16_e32 v36, v89
	v_cvt_f32_f16_sdwa v37, v89 dst_sel:DWORD dst_unused:UNUSED_PAD src0_sel:WORD_1
	v_pk_mul_f32 v[36:37], v[34:35], v[36:37]
	s_nop 0
	v_pk_fma_f32 v[36:37], v[42:43], s[38:39], v[36:37] op_sel_hi:[1,0,1]
	s_nop 0
	v_mul_f32_e32 v40, 0x3d372713, v36
	v_mul_f32_e32 v41, 0x3d372713, v37
	v_mul_f32_e32 v40, v36, v40
	v_mul_f32_e32 v41, v37, v41
	v_fma_f32 v40, v36, v40, v36
	v_fma_f32 v41, v37, v41, v37
	v_mul_f32_e32 v40, 0x3f4c422a, v40
	v_mul_f32_e32 v41, 0x3f4c422a, v41
	v_mul_f32_e32 v40, -2.0, v40
	v_mul_f32_e32 v41, -2.0, v41
	v_mul_f32_e32 v40, 0x3fb8aa3b, v40
	v_mul_f32_e32 v41, 0x3fb8aa3b, v41
	v_exp_f32_e32 v40, v40
	v_exp_f32_e32 v41, v41
	v_add_f32_e32 v40, 1.0, v40
	v_add_f32_e32 v41, 1.0, v41
	v_rcp_f32_e32 v40, v40
	v_rcp_f32_e32 v41, v41
	s_nop 0
	v_pk_mul_f32 v[36:37], v[36:37], v[40:41]
	s_nop 0
	v_cvt_pk_f16_f32 v40, v36, v37
	v_cvt_f32_f16_e32 v36, v91
	v_cvt_f32_f16_sdwa v37, v91 dst_sel:DWORD dst_unused:UNUSED_PAD src0_sel:WORD_1
	v_pk_mul_f32 v[36:37], v[30:31], v[36:37]
	s_nop 0
	v_pk_fma_f32 v[36:37], v[38:39], s[38:39], v[36:37] op_sel_hi:[1,0,1]
	s_nop 0
	v_mul_f32_e32 v38, 0x3d372713, v36
	v_mul_f32_e32 v39, 0x3d372713, v37
	v_mul_f32_e32 v38, v36, v38
	v_mul_f32_e32 v39, v37, v39
	v_fma_f32 v38, v36, v38, v36
	v_fma_f32 v39, v37, v39, v37
	v_mul_f32_e32 v38, 0x3f4c422a, v38
	v_mul_f32_e32 v39, 0x3f4c422a, v39
	v_mul_f32_e32 v38, -2.0, v38
	v_mul_f32_e32 v39, -2.0, v39
	v_mul_f32_e32 v38, 0x3fb8aa3b, v38
	v_mul_f32_e32 v39, 0x3fb8aa3b, v39
	v_exp_f32_e32 v38, v38
	v_exp_f32_e32 v39, v39
	v_add_f32_e32 v38, 1.0, v38
	v_add_f32_e32 v39, 1.0, v39
	v_rcp_f32_e32 v38, v38
	v_rcp_f32_e32 v39, v39
	s_nop 0
	v_pk_mul_f32 v[36:37], v[36:37], v[38:39]
	s_nop 0
	v_cvt_pk_f16_f32 v39, v36, v37
	v_lshrrev_b32_e32 v37, 4, v40
	v_and_b32_e32 v37, 0x10001, v37
	v_add3_u32 v37, v40, v37, s21
	v_lshrrev_b32_e32 v40, 4, v39
	v_and_b32_e32 v40, 0x10001, v40
	v_add3_u32 v39, v39, v40, s21
	v_add_u32_e32 v40, v152, v44
	v_ashrrev_i32_e32 v41, 31, v40
	v_lshrrev_b32_e32 v36, 4, v45
	v_lshrrev_b32_e32 v38, 4, v46
	v_lshlrev_b64 v[40:41], 10, v[40:41]
	v_and_b32_e32 v36, 0x10001, v36
	v_and_b32_e32 v38, 0x10001, v38
	v_lshl_add_u64 v[40:41], s[16:17], 0, v[40:41]
	v_add3_u32 v36, v45, v36, s21
	v_add3_u32 v38, v46, v38, s21
	v_lshl_add_u64 v[40:41], v[40:41], 0, s[42:43]
	v_and_b32_e32 v36, 0xfff0fff0, v36
	v_and_b32_e32 v37, 0xfff0fff0, v37
	v_and_b32_e32 v38, 0xfff0fff0, v38
	v_and_b32_e32 v39, 0xfff0fff0, v39
	v_lshl_add_u64 v[40:41], v[40:41], 0, v[2:3]
	global_store_dwordx4 v[40:41], v[36:39], off
	s_nop 1
	v_cvt_f32_f16_e32 v36, v84
	v_cvt_f32_f16_sdwa v37, v84 dst_sel:DWORD dst_unused:UNUSED_PAD src0_sel:WORD_1
	v_pk_mul_f32 v[36:37], v[32:33], v[36:37]
	s_nop 0
	v_pk_fma_f32 v[24:25], v[24:25], s[38:39], v[36:37] op_sel_hi:[1,0,1]
	s_nop 0
	v_mul_f32_e32 v36, 0x3d372713, v24
	v_mul_f32_e32 v37, 0x3d372713, v25
	v_mul_f32_e32 v36, v24, v36
	v_mul_f32_e32 v37, v25, v37
	v_fma_f32 v36, v24, v36, v24
	v_fma_f32 v37, v25, v37, v25
	v_mul_f32_e32 v36, 0x3f4c422a, v36
	v_mul_f32_e32 v37, 0x3f4c422a, v37
	v_mul_f32_e32 v36, -2.0, v36
	v_mul_f32_e32 v37, -2.0, v37
	v_mul_f32_e32 v36, 0x3fb8aa3b, v36
	v_mul_f32_e32 v37, 0x3fb8aa3b, v37
	v_exp_f32_e32 v36, v36
	v_exp_f32_e32 v37, v37
	v_add_f32_e32 v36, 1.0, v36
	v_add_f32_e32 v37, 1.0, v37
	v_rcp_f32_e32 v36, v36
	v_rcp_f32_e32 v37, v37
	s_nop 0
	v_pk_mul_f32 v[24:25], v[24:25], v[36:37]
	s_nop 0
	v_cvt_pk_f16_f32 v36, v24, v25
	v_cvt_f32_f16_e32 v24, v86
	v_cvt_f32_f16_sdwa v25, v86 dst_sel:DWORD dst_unused:UNUSED_PAD src0_sel:WORD_1
	v_pk_mul_f32 v[24:25], v[28:29], v[24:25]
	s_nop 0
	v_pk_fma_f32 v[20:21], v[20:21], s[38:39], v[24:25] op_sel_hi:[1,0,1]
	s_nop 0
	v_mul_f32_e32 v24, 0x3d372713, v20
	v_mul_f32_e32 v25, 0x3d372713, v21
	v_mul_f32_e32 v24, v20, v24
	v_mul_f32_e32 v25, v21, v25
	v_fma_f32 v24, v20, v24, v20
	v_fma_f32 v25, v21, v25, v21
	v_mul_f32_e32 v24, 0x3f4c422a, v24
	v_mul_f32_e32 v25, 0x3f4c422a, v25
	v_mul_f32_e32 v24, -2.0, v24
	v_mul_f32_e32 v25, -2.0, v25
	v_mul_f32_e32 v24, 0x3fb8aa3b, v24
	v_mul_f32_e32 v25, 0x3fb8aa3b, v25
	v_exp_f32_e32 v24, v24
	v_exp_f32_e32 v25, v25
	v_add_f32_e32 v24, 1.0, v24
	v_add_f32_e32 v25, 1.0, v25
	v_rcp_f32_e32 v24, v24
	v_rcp_f32_e32 v25, v25
	s_nop 0
	v_pk_mul_f32 v[20:21], v[20:21], v[24:25]
	s_nop 0
	v_cvt_pk_f16_f32 v37, v20, v21
	v_cvt_f32_f16_e32 v20, v85
	v_cvt_f32_f16_sdwa v21, v85 dst_sel:DWORD dst_unused:UNUSED_PAD src0_sel:WORD_1
	v_pk_mul_f32 v[20:21], v[34:35], v[20:21]
	s_nop 0
	v_pk_fma_f32 v[20:21], v[26:27], s[38:39], v[20:21] op_sel_hi:[1,0,1]
	s_nop 0
	v_mul_f32_e32 v24, 0x3d372713, v20
	v_mul_f32_e32 v25, 0x3d372713, v21
	v_mul_f32_e32 v24, v20, v24
	v_mul_f32_e32 v25, v21, v25
	v_fma_f32 v24, v20, v24, v20
	v_fma_f32 v25, v21, v25, v21
	v_mul_f32_e32 v24, 0x3f4c422a, v24
	v_mul_f32_e32 v25, 0x3f4c422a, v25
	v_mul_f32_e32 v24, -2.0, v24
	v_mul_f32_e32 v25, -2.0, v25
	v_mul_f32_e32 v24, 0x3fb8aa3b, v24
	v_mul_f32_e32 v25, 0x3fb8aa3b, v25
	v_exp_f32_e32 v24, v24
	v_exp_f32_e32 v25, v25
	v_add_f32_e32 v24, 1.0, v24
	v_add_f32_e32 v25, 1.0, v25
	v_rcp_f32_e32 v24, v24
	v_rcp_f32_e32 v25, v25
	s_nop 0
	v_pk_mul_f32 v[20:21], v[20:21], v[24:25]
	s_nop 0
	v_cvt_pk_f16_f32 v24, v20, v21
	v_cvt_f32_f16_e32 v20, v87
	v_cvt_f32_f16_sdwa v21, v87 dst_sel:DWORD dst_unused:UNUSED_PAD src0_sel:WORD_1
	v_pk_mul_f32 v[20:21], v[30:31], v[20:21]
	s_nop 0
	v_pk_fma_f32 v[20:21], v[22:23], s[38:39], v[20:21] op_sel_hi:[1,0,1]
	s_nop 0
	v_mul_f32_e32 v22, 0x3d372713, v20
	v_mul_f32_e32 v23, 0x3d372713, v21
	v_mul_f32_e32 v22, v20, v22
	v_mul_f32_e32 v23, v21, v23
	v_fma_f32 v22, v20, v22, v20
	v_fma_f32 v23, v21, v23, v21
	v_mul_f32_e32 v22, 0x3f4c422a, v22
	v_mul_f32_e32 v23, 0x3f4c422a, v23
	v_mul_f32_e32 v22, -2.0, v22
	v_mul_f32_e32 v23, -2.0, v23
	v_mul_f32_e32 v22, 0x3fb8aa3b, v22
	v_mul_f32_e32 v23, 0x3fb8aa3b, v23
	v_exp_f32_e32 v22, v22
	v_exp_f32_e32 v23, v23
	v_add_f32_e32 v22, 1.0, v22
	v_add_f32_e32 v23, 1.0, v23
	v_rcp_f32_e32 v22, v22
	v_rcp_f32_e32 v23, v23
	s_nop 0
	v_pk_mul_f32 v[20:21], v[20:21], v[22:23]
	s_nop 0
	v_cvt_pk_f16_f32 v23, v20, v21
	v_lshrrev_b32_e32 v21, 4, v24
	v_and_b32_e32 v21, 0x10001, v21
	v_add3_u32 v21, v24, v21, s21
	v_lshrrev_b32_e32 v24, 4, v23
	v_and_b32_e32 v24, 0x10001, v24
	v_add3_u32 v23, v23, v24, s21
	v_add_u32_e32 v24, v140, v44
	v_ashrrev_i32_e32 v25, 31, v24
	v_lshrrev_b32_e32 v20, 4, v36
	v_lshrrev_b32_e32 v22, 4, v37
	v_lshlrev_b64 v[24:25], 10, v[24:25]
	v_and_b32_e32 v20, 0x10001, v20
	v_and_b32_e32 v22, 0x10001, v22
	v_lshl_add_u64 v[24:25], s[16:17], 0, v[24:25]
	v_add3_u32 v20, v36, v20, s21
	v_add3_u32 v22, v37, v22, s21
	v_lshl_add_u64 v[24:25], v[24:25], 0, s[42:43]
	v_and_b32_e32 v20, 0xfff0fff0, v20
	v_and_b32_e32 v21, 0xfff0fff0, v21
	v_and_b32_e32 v22, 0xfff0fff0, v22
	v_and_b32_e32 v23, 0xfff0fff0, v23
	v_lshl_add_u64 v[24:25], v[24:25], 0, v[2:3]
	global_store_dwordx4 v[24:25], v[20:23], off
	s_nop 1
	v_cvt_f32_f16_e32 v22, v80
	v_cvt_f32_f16_sdwa v23, v80 dst_sel:DWORD dst_unused:UNUSED_PAD src0_sel:WORD_1
	v_add_u32_e32 v20, 0xb00, v192
	v_pk_mul_f32 v[22:23], v[32:33], v[22:23]
	s_nop 0
	v_pk_fma_f32 v[16:17], v[16:17], s[38:39], v[22:23] op_sel_hi:[1,0,1]
	s_nop 0
	v_mul_f32_e32 v21, 0x3d372713, v16
	v_mul_f32_e32 v21, v16, v21
	v_fma_f32 v21, v16, v21, v16
	v_mul_f32_e32 v21, 0x3f4c422a, v21
	v_mul_f32_e32 v21, -2.0, v21
	v_mul_f32_e32 v21, 0x3fb8aa3b, v21
	v_exp_f32_e32 v21, v21
	s_nop 0
	v_add_f32_e32 v21, 1.0, v21
	v_rcp_f32_e32 v22, v21
	v_mul_f32_e32 v21, 0x3d372713, v17
	v_mul_f32_e32 v21, v17, v21
	v_fma_f32 v21, v17, v21, v17
	v_mul_f32_e32 v21, 0x3f4c422a, v21
	v_mul_f32_e32 v21, -2.0, v21
	v_mul_f32_e32 v21, 0x3fb8aa3b, v21
	v_exp_f32_e32 v21, v21
	s_nop 0
	v_add_f32_e32 v21, 1.0, v21
	v_rcp_f32_e32 v23, v21
	s_nop 0
	v_pk_mul_f32 v[16:17], v[16:17], v[22:23]
	s_nop 0
	v_cvt_pk_f16_f32 v21, v16, v17
	v_cvt_f32_f16_e32 v16, v82
	v_cvt_f32_f16_sdwa v17, v82 dst_sel:DWORD dst_unused:UNUSED_PAD src0_sel:WORD_1
	v_pk_mul_f32 v[16:17], v[28:29], v[16:17]
	s_nop 0
	v_pk_fma_f32 v[12:13], v[12:13], s[38:39], v[16:17] op_sel_hi:[1,0,1]
	s_nop 0
	v_mul_f32_e32 v16, 0x3d372713, v12
	v_mul_f32_e32 v17, 0x3d372713, v13
	v_mul_f32_e32 v16, v12, v16
	v_mul_f32_e32 v17, v13, v17
	v_fma_f32 v16, v12, v16, v12
	v_fma_f32 v17, v13, v17, v13
	v_mul_f32_e32 v16, 0x3f4c422a, v16
	v_mul_f32_e32 v17, 0x3f4c422a, v17
	v_mul_f32_e32 v16, -2.0, v16
	v_mul_f32_e32 v17, -2.0, v17
	v_mul_f32_e32 v16, 0x3fb8aa3b, v16
	v_mul_f32_e32 v17, 0x3fb8aa3b, v17
	v_exp_f32_e32 v16, v16
	v_exp_f32_e32 v17, v17
	v_add_f32_e32 v16, 1.0, v16
	v_add_f32_e32 v17, 1.0, v17
	v_rcp_f32_e32 v16, v16
	v_rcp_f32_e32 v17, v17
	s_nop 0
	v_pk_mul_f32 v[12:13], v[12:13], v[16:17]
	s_nop 0
	v_cvt_pk_f16_f32 v22, v12, v13
	v_cvt_f32_f16_e32 v12, v81
	v_cvt_f32_f16_sdwa v13, v81 dst_sel:DWORD dst_unused:UNUSED_PAD src0_sel:WORD_1
	v_pk_mul_f32 v[12:13], v[34:35], v[12:13]
	s_nop 0
	v_pk_fma_f32 v[12:13], v[18:19], s[38:39], v[12:13] op_sel_hi:[1,0,1]
	s_nop 0
	v_mul_f32_e32 v16, 0x3d372713, v12
	v_mul_f32_e32 v17, 0x3d372713, v13
	v_mul_f32_e32 v16, v12, v16
	v_mul_f32_e32 v17, v13, v17
	v_fma_f32 v16, v12, v16, v12
	v_fma_f32 v17, v13, v17, v13
	v_mul_f32_e32 v16, 0x3f4c422a, v16
	v_mul_f32_e32 v17, 0x3f4c422a, v17
	v_mul_f32_e32 v16, -2.0, v16
	v_mul_f32_e32 v17, -2.0, v17
	v_mul_f32_e32 v16, 0x3fb8aa3b, v16
	v_mul_f32_e32 v17, 0x3fb8aa3b, v17
	v_exp_f32_e32 v16, v16
	v_exp_f32_e32 v17, v17
	v_add_f32_e32 v16, 1.0, v16
	v_add_f32_e32 v17, 1.0, v17
	v_rcp_f32_e32 v16, v16
	v_rcp_f32_e32 v17, v17
	s_nop 0
	v_pk_mul_f32 v[12:13], v[12:13], v[16:17]
	s_nop 0
	v_cvt_pk_f16_f32 v16, v12, v13
	v_cvt_f32_f16_e32 v12, v83
	v_cvt_f32_f16_sdwa v13, v83 dst_sel:DWORD dst_unused:UNUSED_PAD src0_sel:WORD_1
	v_pk_mul_f32 v[12:13], v[30:31], v[12:13]
	s_nop 0
	v_pk_fma_f32 v[12:13], v[14:15], s[38:39], v[12:13] op_sel_hi:[1,0,1]
	s_nop 0
	v_mul_f32_e32 v14, 0x3d372713, v12
	v_mul_f32_e32 v15, 0x3d372713, v13
	v_mul_f32_e32 v14, v12, v14
	v_mul_f32_e32 v15, v13, v15
	v_fma_f32 v14, v12, v14, v12
	v_fma_f32 v15, v13, v15, v13
	v_mul_f32_e32 v14, 0x3f4c422a, v14
	v_mul_f32_e32 v15, 0x3f4c422a, v15
	v_mul_f32_e32 v14, -2.0, v14
	v_mul_f32_e32 v15, -2.0, v15
	v_mul_f32_e32 v14, 0x3fb8aa3b, v14
	v_mul_f32_e32 v15, 0x3fb8aa3b, v15
	v_exp_f32_e32 v14, v14
	v_exp_f32_e32 v15, v15
	v_add_f32_e32 v14, 1.0, v14
	v_add_f32_e32 v15, 1.0, v15
	v_rcp_f32_e32 v14, v14
	v_rcp_f32_e32 v15, v15
	s_nop 0
	v_pk_mul_f32 v[12:13], v[12:13], v[14:15]
	s_nop 0
	v_cvt_pk_f16_f32 v15, v12, v13
	v_lshrrev_b32_e32 v13, 4, v16
	v_and_b32_e32 v13, 0x10001, v13
	v_add3_u32 v13, v16, v13, s21
	v_lshrrev_b32_e32 v16, 4, v15
	v_and_b32_e32 v16, 0x10001, v16
	v_add3_u32 v15, v15, v16, s21
	v_add_u32_e32 v16, v152, v20
	v_ashrrev_i32_e32 v17, 31, v16
	v_lshrrev_b32_e32 v12, 4, v21
	v_lshrrev_b32_e32 v14, 4, v22
	v_lshlrev_b64 v[16:17], 10, v[16:17]
	v_and_b32_e32 v12, 0x10001, v12
	v_and_b32_e32 v14, 0x10001, v14
	v_lshl_add_u64 v[16:17], s[16:17], 0, v[16:17]
	v_add3_u32 v12, v21, v12, s21
	v_add3_u32 v14, v22, v14, s21
	v_lshl_add_u64 v[16:17], v[16:17], 0, s[42:43]
	v_and_b32_e32 v12, 0xfff0fff0, v12
	v_and_b32_e32 v13, 0xfff0fff0, v13
	v_and_b32_e32 v14, 0xfff0fff0, v14
	v_and_b32_e32 v15, 0xfff0fff0, v15
	v_lshl_add_u64 v[16:17], v[16:17], 0, v[2:3]
	global_store_dwordx4 v[16:17], v[12:15], off
	s_nop 1
	v_cvt_f32_f16_e32 v12, v76
	v_cvt_f32_f16_sdwa v13, v76 dst_sel:DWORD dst_unused:UNUSED_PAD src0_sel:WORD_1
	v_pk_mul_f32 v[12:13], v[32:33], v[12:13]
	s_nop 0
	v_pk_fma_f32 v[8:9], v[8:9], s[38:39], v[12:13] op_sel_hi:[1,0,1]
	s_nop 0
	v_mul_f32_e32 v12, 0x3d372713, v8
	v_mul_f32_e32 v13, 0x3d372713, v9
	v_mul_f32_e32 v12, v8, v12
	v_mul_f32_e32 v13, v9, v13
	v_fma_f32 v12, v8, v12, v8
	v_fma_f32 v13, v9, v13, v9
	v_mul_f32_e32 v12, 0x3f4c422a, v12
	v_mul_f32_e32 v13, 0x3f4c422a, v13
	v_mul_f32_e32 v12, -2.0, v12
	v_mul_f32_e32 v13, -2.0, v13
	v_mul_f32_e32 v12, 0x3fb8aa3b, v12
	v_mul_f32_e32 v13, 0x3fb8aa3b, v13
	v_exp_f32_e32 v12, v12
	v_exp_f32_e32 v13, v13
	v_add_f32_e32 v12, 1.0, v12
	v_add_f32_e32 v13, 1.0, v13
	v_rcp_f32_e32 v12, v12
	v_rcp_f32_e32 v13, v13
	s_nop 0
	v_pk_mul_f32 v[8:9], v[8:9], v[12:13]
	s_nop 0
	v_cvt_pk_f16_f32 v12, v8, v9
	v_cvt_f32_f16_e32 v8, v78
	v_cvt_f32_f16_sdwa v9, v78 dst_sel:DWORD dst_unused:UNUSED_PAD src0_sel:WORD_1
	v_pk_mul_f32 v[8:9], v[28:29], v[8:9]
	s_nop 0
	v_pk_fma_f32 v[4:5], v[4:5], s[38:39], v[8:9] op_sel_hi:[1,0,1]
	s_nop 0
	v_mul_f32_e32 v8, 0x3d372713, v4
	v_mul_f32_e32 v9, 0x3d372713, v5
	v_mul_f32_e32 v8, v4, v8
	v_mul_f32_e32 v9, v5, v9
	v_fma_f32 v8, v4, v8, v4
	v_fma_f32 v9, v5, v9, v5
	v_mul_f32_e32 v8, 0x3f4c422a, v8
	v_mul_f32_e32 v9, 0x3f4c422a, v9
	v_mul_f32_e32 v8, -2.0, v8
	v_mul_f32_e32 v9, -2.0, v9
	v_mul_f32_e32 v8, 0x3fb8aa3b, v8
	v_mul_f32_e32 v9, 0x3fb8aa3b, v9
	v_exp_f32_e32 v8, v8
	v_exp_f32_e32 v9, v9
	v_add_f32_e32 v8, 1.0, v8
	v_add_f32_e32 v9, 1.0, v9
	v_rcp_f32_e32 v8, v8
	v_rcp_f32_e32 v9, v9
	s_nop 0
	v_pk_mul_f32 v[4:5], v[4:5], v[8:9]
	s_nop 0
	v_cvt_pk_f16_f32 v13, v4, v5
	v_cvt_f32_f16_e32 v4, v77
	v_cvt_f32_f16_sdwa v5, v77 dst_sel:DWORD dst_unused:UNUSED_PAD src0_sel:WORD_1
	v_pk_mul_f32 v[4:5], v[34:35], v[4:5]
	s_nop 0
	v_pk_fma_f32 v[4:5], v[10:11], s[38:39], v[4:5] op_sel_hi:[1,0,1]
	s_nop 0
	v_mul_f32_e32 v8, 0x3d372713, v4
	v_mul_f32_e32 v9, 0x3d372713, v5
	v_mul_f32_e32 v8, v4, v8
	v_mul_f32_e32 v9, v5, v9
	v_fma_f32 v8, v4, v8, v4
	v_fma_f32 v9, v5, v9, v5
	v_mul_f32_e32 v8, 0x3f4c422a, v8
	v_mul_f32_e32 v9, 0x3f4c422a, v9
	v_mul_f32_e32 v8, -2.0, v8
	v_mul_f32_e32 v9, -2.0, v9
	v_mul_f32_e32 v8, 0x3fb8aa3b, v8
	v_mul_f32_e32 v9, 0x3fb8aa3b, v9
	v_exp_f32_e32 v8, v8
	v_exp_f32_e32 v9, v9
	v_add_f32_e32 v8, 1.0, v8
	v_add_f32_e32 v9, 1.0, v9
	v_rcp_f32_e32 v8, v8
	v_rcp_f32_e32 v9, v9
	s_nop 0
	v_pk_mul_f32 v[4:5], v[4:5], v[8:9]
	s_nop 0
	v_cvt_pk_f16_f32 v8, v4, v5
	v_cvt_f32_f16_e32 v4, v79
	v_cvt_f32_f16_sdwa v5, v79 dst_sel:DWORD dst_unused:UNUSED_PAD src0_sel:WORD_1
	v_pk_mul_f32 v[4:5], v[30:31], v[4:5]
	s_nop 0
	v_pk_fma_f32 v[4:5], v[6:7], s[38:39], v[4:5] op_sel_hi:[1,0,1]
	s_mov_b64 s[38:39], s[36:37]
	v_mul_f32_e32 v6, 0x3d372713, v4
	v_mul_f32_e32 v7, 0x3d372713, v5
	v_mul_f32_e32 v6, v4, v6
	v_mul_f32_e32 v7, v5, v7
	v_fma_f32 v6, v4, v6, v4
	v_fma_f32 v7, v5, v7, v5
	v_mul_f32_e32 v6, 0x3f4c422a, v6
	v_mul_f32_e32 v7, 0x3f4c422a, v7
	v_mul_f32_e32 v6, -2.0, v6
	v_mul_f32_e32 v7, -2.0, v7
	v_mul_f32_e32 v6, 0x3fb8aa3b, v6
	v_mul_f32_e32 v7, 0x3fb8aa3b, v7
	v_exp_f32_e32 v6, v6
	v_exp_f32_e32 v7, v7
	v_add_f32_e32 v6, 1.0, v6
	v_add_f32_e32 v7, 1.0, v7
	v_rcp_f32_e32 v6, v6
	v_rcp_f32_e32 v7, v7
	s_nop 0
	v_pk_mul_f32 v[4:5], v[4:5], v[6:7]
	s_nop 0
	v_cvt_pk_f16_f32 v7, v4, v5
	v_lshrrev_b32_e32 v5, 4, v8
	v_and_b32_e32 v5, 0x10001, v5
	v_add3_u32 v5, v8, v5, s21
	v_lshrrev_b32_e32 v8, 4, v7
	v_and_b32_e32 v8, 0x10001, v8
	v_add3_u32 v7, v7, v8, s21
	v_add_u32_e32 v8, v140, v20
	v_ashrrev_i32_e32 v9, 31, v8
	v_lshrrev_b32_e32 v4, 4, v12
	v_lshrrev_b32_e32 v6, 4, v13
	v_lshlrev_b64 v[8:9], 10, v[8:9]
	v_and_b32_e32 v4, 0x10001, v4
	v_and_b32_e32 v6, 0x10001, v6
	v_lshl_add_u64 v[8:9], s[16:17], 0, v[8:9]
	v_add3_u32 v4, v12, v4, s21
	v_add3_u32 v6, v13, v6, s21
	v_lshl_add_u64 v[8:9], v[8:9], 0, s[42:43]
	v_and_b32_e32 v4, 0xfff0fff0, v4
	v_and_b32_e32 v5, 0xfff0fff0, v5
	v_and_b32_e32 v6, 0xfff0fff0, v6
	v_and_b32_e32 v7, 0xfff0fff0, v7
	v_lshl_add_u64 v[8:9], v[8:9], 0, v[2:3]
	global_store_dwordx4 v[8:9], v[4:7], off
	s_mov_b32 s16, s47
	s_cbranch_vccz .LBB0_1338
	s_waitcnt vmcnt(0)
	s_cmpk_gt_u32 s5, 0xff
	s_cbranch_scc1 .LBB0_1345
	s_barrier

.LBB0_1664:
	s_add_u32 s15, s46, 0xfffe0080
	s_addc_u32 s29, s47, -1
	s_add_i32 s30, 0, 0x10000
	v_add_u32_e32 v56, s30, v208
	ds_read_b128 v[32:35], v56
	ds_read_b128 v[40:43], v56 offset:1024
	ds_read_b128 v[48:51], v56 offset:2048
	ds_read_b128 v[56:59], v56 offset:3072
	s_cmp_eq_u32 s14, 4
	s_cselect_b32 s49, s43, s29
	s_cselect_b32 s48, s42, s15
	s_cselect_b32 s39, s45, s11
	s_cselect_b32 s38, s44, s10
	v_lshl_add_u64 v[190:191], s[46:47], 0, v[186:187]
	s_add_i32 m0, s8, 0xc000
	ds_read_b128 v[108:111], v209
	ds_read_b128 v[120:123], v209 offset:1024
	ds_read_b128 v[132:135], v209 offset:2048
	ds_read_b128 v[144:147], v209 offset:3072
	ds_read_b128 v[156:159], v209 offset:4096
	ds_read_b128 v[168:171], v209 offset:5120
	ds_read_b128 v[172:175], v209 offset:6144
	ds_read_b128 v[176:179], v209 offset:7168
	global_load_lds_dwordx4 v[190:191], off
	v_lshl_add_u64 v[190:191], s[46:47], 0, v[188:189]
	s_add_i32 m0, s8, 0xe000
	s_nop 0
	global_load_lds_dwordx4 v[190:191], off
	s_waitcnt lgkmcnt(8)
	s_barrier
	s_waitcnt lgkmcnt(0)
	v_mfma_f32_16x16x32_f16 v[164:167], v[32:35], v[108:111], v[164:167]
	v_mfma_f32_16x16x32_f16 v[160:163], v[48:51], v[108:111], v[160:163]
	v_mfma_f32_16x16x32_f16 v[140:143], v[32:35], v[132:135], v[140:143]
	v_mfma_f32_16x16x32_f16 v[136:139], v[48:51], v[132:135], v[136:139]
	v_mfma_f32_16x16x32_f16 v[116:119], v[32:35], v[156:159], v[116:119]
	v_mfma_f32_16x16x32_f16 v[112:115], v[48:51], v[156:159], v[112:115]
	v_mfma_f32_16x16x32_f16 v[96:99], v[32:35], v[172:175], v[96:99]
	v_mfma_f32_16x16x32_f16 v[92:95], v[48:51], v[172:175], v[92:95]
	v_mfma_f32_16x16x32_f16 v[164:167], v[40:43], v[120:123], v[164:167]
	v_mfma_f32_16x16x32_f16 v[160:163], v[56:59], v[120:123], v[160:163]
	v_mfma_f32_16x16x32_f16 v[140:143], v[40:43], v[144:147], v[140:143]
	v_mfma_f32_16x16x32_f16 v[136:139], v[56:59], v[144:147], v[136:139]
	v_mfma_f32_16x16x32_f16 v[116:119], v[40:43], v[168:171], v[116:119]
	v_mfma_f32_16x16x32_f16 v[112:115], v[56:59], v[168:171], v[112:115]
	v_mfma_f32_16x16x32_f16 v[96:99], v[40:43], v[176:179], v[96:99]
	v_mfma_f32_16x16x32_f16 v[92:95], v[56:59], v[176:179], v[92:95]
	s_barrier
	s_add_i32 s15, 0, 0x14000
	v_add_u32_e32 v202, s15, v208
	s_add_i32 s29, s30, s7
	ds_read_b128 v[190:193], v202
	ds_read_b128 v[194:197], v202 offset:1024
	ds_read_b128 v[198:201], v202 offset:2048
	ds_read_b128 v[210:213], v202 offset:3072
	v_lshl_add_u64 v[202:203], s[38:39], 0, v[2:3]
	s_mov_b32 m0, s29
	v_lshl_add_u64 v[218:219], s[38:39], 0, v[184:185]
	global_load_lds_dwordx4 v[202:203], off
	s_add_i32 m0, s29, 0x2000
	s_nop 0
	global_load_lds_dwordx4 v[218:219], off
	s_barrier
	s_waitcnt lgkmcnt(0)
	v_mfma_f32_16x16x32_f16 v[152:155], v[190:193], v[108:111], v[152:155]
	v_mfma_f32_16x16x32_f16 v[108:111], v[198:201], v[108:111], v[148:151]
	v_mfma_f32_16x16x32_f16 v[124:127], v[198:201], v[132:135], v[124:127]
	v_mfma_f32_16x16x32_f16 v[104:107], v[190:193], v[156:159], v[104:107]
	v_mfma_f32_16x16x32_f16 v[100:103], v[198:201], v[156:159], v[100:103]
	v_mfma_f32_16x16x32_f16 v[88:91], v[190:193], v[172:175], v[88:91]
	v_mfma_f32_16x16x32_f16 v[84:87], v[198:201], v[172:175], v[84:87]
	v_mfma_f32_16x16x32_f16 v[152:155], v[194:197], v[120:123], v[152:155]
	v_mfma_f32_16x16x32_f16 v[108:111], v[210:213], v[120:123], v[108:111]
	v_mfma_f32_16x16x32_f16 v[120:123], v[190:193], v[132:135], v[128:131]
	v_mfma_f32_16x16x32_f16 v[124:127], v[210:213], v[144:147], v[124:127]
	v_mfma_f32_16x16x32_f16 v[104:107], v[194:197], v[168:171], v[104:107]
	v_mfma_f32_16x16x32_f16 v[100:103], v[210:213], v[168:171], v[100:103]
	v_mfma_f32_16x16x32_f16 v[88:91], v[194:197], v[176:179], v[88:91]
	v_mfma_f32_16x16x32_f16 v[84:87], v[210:213], v[176:179], v[84:87]
	v_mfma_f32_16x16x32_f16 v[120:123], v[194:197], v[144:147], v[120:123]
	s_mov_b32 m0, s8
	v_lshl_add_u64 v[220:221], s[48:49], 0, v[180:181]
	s_barrier
	ds_read_b128 v[128:131], v209 offset:16384
	ds_read_b128 v[132:135], v209 offset:17408
	ds_read_b128 v[144:147], v209 offset:18432
	ds_read_b128 v[148:151], v209 offset:19456
	ds_read_b128 v[156:159], v209 offset:20480
	ds_read_b128 v[168:171], v209 offset:21504
	ds_read_b128 v[172:175], v209 offset:22528
	ds_read_b128 v[176:179], v209 offset:23552
	global_load_lds_dwordx4 v[220:221], off
	v_lshl_add_u64 v[232:233], s[48:49], 0, v[182:183]
	s_mov_b32 m0, s9
	s_nop 0
	global_load_lds_dwordx4 v[232:233], off
	s_barrier
	s_waitcnt lgkmcnt(0)
	v_mfma_f32_16x16x32_f16 v[80:83], v[32:35], v[128:131], v[80:83]
	v_mfma_f32_16x16x32_f16 v[76:79], v[48:51], v[128:131], v[76:79]
	v_mfma_f32_16x16x32_f16 v[64:67], v[32:35], v[144:147], v[64:67]
	v_mfma_f32_16x16x32_f16 v[60:63], v[48:51], v[144:147], v[60:63]
	v_mfma_f32_16x16x32_f16 v[36:39], v[32:35], v[156:159], v[36:39]
	v_mfma_f32_16x16x32_f16 v[28:31], v[48:51], v[156:159], v[28:31]
	v_mfma_f32_16x16x32_f16 v[16:19], v[32:35], v[172:175], v[16:19]
	v_mfma_f32_16x16x32_f16 v[12:15], v[48:51], v[172:175], v[12:15]
	v_mfma_f32_16x16x32_f16 v[80:83], v[40:43], v[132:135], v[80:83]
	v_mfma_f32_16x16x32_f16 v[76:79], v[56:59], v[132:135], v[76:79]
	v_mfma_f32_16x16x32_f16 v[64:67], v[40:43], v[148:151], v[64:67]
	v_mfma_f32_16x16x32_f16 v[60:63], v[56:59], v[148:151], v[60:63]
	v_mfma_f32_16x16x32_f16 v[36:39], v[40:43], v[168:171], v[36:39]
	v_mfma_f32_16x16x32_f16 v[28:31], v[56:59], v[168:171], v[28:31]
	v_mfma_f32_16x16x32_f16 v[16:19], v[40:43], v[176:179], v[16:19]
	v_mfma_f32_16x16x32_f16 v[12:15], v[56:59], v[176:179], v[12:15]
	s_barrier
	s_add_u32 s30, s38, 0x20000
	s_addc_u32 s31, s39, 0
	s_add_i32 s15, s15, s7
	v_lshl_add_u64 v[32:33], s[30:31], 0, v[2:3]
	s_mov_b32 m0, s15
	s_nop 0
	global_load_lds_dwordx4 v[32:33], off
	v_lshl_add_u64 v[32:33], s[30:31], 0, v[184:185]
	s_add_i32 m0, s15, 0x2000
	s_nop 0
	global_load_lds_dwordx4 v[32:33], off
	s_waitcnt vmcnt(6)
	s_barrier
	v_mfma_f32_16x16x32_f16 v[44:47], v[198:201], v[144:147], v[44:47]
	v_mfma_f32_16x16x32_f16 v[24:27], v[190:193], v[156:159], v[24:27]
	v_mfma_f32_16x16x32_f16 v[20:23], v[198:201], v[156:159], v[20:23]
	v_mfma_f32_16x16x32_f16 v[8:11], v[190:193], v[172:175], v[8:11]
	v_mfma_f32_16x16x32_f16 v[4:7], v[198:201], v[172:175], v[4:7]
	v_mfma_f32_16x16x32_f16 v[32:35], v[190:193], v[128:131], v[72:75]
	v_mfma_f32_16x16x32_f16 v[40:43], v[198:201], v[128:131], v[68:71]
	v_mfma_f32_16x16x32_f16 v[48:51], v[190:193], v[144:147], v[52:55]
	v_mfma_f32_16x16x32_f16 v[44:47], v[210:213], v[148:151], v[44:47]
	v_mfma_f32_16x16x32_f16 v[24:27], v[194:197], v[168:171], v[24:27]
	v_mfma_f32_16x16x32_f16 v[20:23], v[210:213], v[168:171], v[20:23]
	v_mfma_f32_16x16x32_f16 v[8:11], v[194:197], v[176:179], v[8:11]
	v_mfma_f32_16x16x32_f16 v[4:7], v[210:213], v[176:179], v[4:7]
	v_mfma_f32_16x16x32_f16 v[32:35], v[194:197], v[132:135], v[32:35]
	v_mfma_f32_16x16x32_f16 v[40:43], v[210:213], v[132:135], v[40:43]
	v_mfma_f32_16x16x32_f16 v[48:51], v[194:197], v[148:151], v[48:51]
	s_add_i32 s15, 0, 0x18000
	v_add_u32_e32 v72, s15, v208
	s_barrier
	ds_read_b128 v[52:55], v72
	ds_read_b128 v[56:59], v72 offset:1024
	ds_read_b128 v[68:71], v72 offset:2048
	ds_read_b128 v[72:75], v72 offset:3072
	s_add_u32 s30, s48, 0x20000
	s_addc_u32 s31, s49, 0
	s_mov_b32 m0, s12
	v_lshl_add_u64 v[148:149], s[30:31], 0, v[180:181]
	ds_read_b128 v[128:131], v209 offset:32768
	ds_read_b128 v[132:135], v209 offset:33792
	ds_read_b128 v[144:147], v209 offset:34816
	ds_read_b128 v[156:159], v209 offset:35840
	ds_read_b128 v[168:171], v209 offset:36864
	ds_read_b128 v[172:175], v209 offset:37888
	ds_read_b128 v[176:179], v209 offset:38912
	ds_read_b128 v[190:193], v209 offset:39936
	global_load_lds_dwordx4 v[148:149], off
	v_lshl_add_u64 v[148:149], s[30:31], 0, v[182:183]
	s_mov_b32 m0, s13
	s_nop 0
	global_load_lds_dwordx4 v[148:149], off
	s_waitcnt lgkmcnt(8)
	s_barrier
	s_waitcnt lgkmcnt(0)
	v_mfma_f32_16x16x32_f16 v[148:151], v[52:55], v[128:131], v[164:167]
	v_mfma_f32_16x16x32_f16 v[164:167], v[56:59], v[132:135], v[148:151]
	v_mfma_f32_16x16x32_f16 v[148:151], v[68:71], v[128:131], v[160:163]
	v_mfma_f32_16x16x32_f16 v[140:143], v[52:55], v[144:147], v[140:143]
	v_mfma_f32_16x16x32_f16 v[136:139], v[68:71], v[144:147], v[136:139]
	v_mfma_f32_16x16x32_f16 v[116:119], v[52:55], v[168:171], v[116:119]
	v_mfma_f32_16x16x32_f16 v[112:115], v[68:71], v[168:171], v[112:115]
	v_mfma_f32_16x16x32_f16 v[96:99], v[52:55], v[176:179], v[96:99]
	v_mfma_f32_16x16x32_f16 v[92:95], v[68:71], v[176:179], v[92:95]
	v_mfma_f32_16x16x32_f16 v[160:163], v[72:75], v[132:135], v[148:151]
	v_mfma_f32_16x16x32_f16 v[140:143], v[56:59], v[156:159], v[140:143]
	v_mfma_f32_16x16x32_f16 v[136:139], v[72:75], v[156:159], v[136:139]
	v_mfma_f32_16x16x32_f16 v[116:119], v[56:59], v[172:175], v[116:119]
	v_mfma_f32_16x16x32_f16 v[112:115], v[72:75], v[172:175], v[112:115]
	v_mfma_f32_16x16x32_f16 v[96:99], v[56:59], v[190:193], v[96:99]
	v_mfma_f32_16x16x32_f16 v[92:95], v[72:75], v[190:193], v[92:95]
	s_barrier
	s_add_i32 s29, 0, 0x1c000
	v_add_u32_e32 v148, s29, v208
	s_add_i32 s15, s15, s7
	ds_read_b128 v[194:197], v148
	ds_read_b128 v[198:201], v148 offset:1024
	ds_read_b128 v[210:213], v148 offset:2048
	ds_read_b128 v[214:217], v148 offset:3072
	v_lshl_add_u64 v[148:149], v[202:203], 0, s[88:89]
	s_mov_b32 m0, s15
	s_nop 0
	global_load_lds_dwordx4 v[148:149], off
	v_lshl_add_u64 v[148:149], v[218:219], 0, s[88:89]
	s_add_i32 m0, s15, 0x2000
	s_nop 0
	global_load_lds_dwordx4 v[148:149], off
	s_barrier
	s_waitcnt lgkmcnt(0)
	v_mfma_f32_16x16x32_f16 v[148:151], v[194:197], v[128:131], v[152:155]
	v_mfma_f32_16x16x32_f16 v[108:111], v[210:213], v[128:131], v[108:111]
	v_mfma_f32_16x16x32_f16 v[152:155], v[198:201], v[132:135], v[148:151]
	v_mfma_f32_16x16x32_f16 v[148:151], v[214:217], v[132:135], v[108:111]
	v_mfma_f32_16x16x32_f16 v[108:111], v[194:197], v[144:147], v[120:123]
	v_mfma_f32_16x16x32_f16 v[128:131], v[198:201], v[156:159], v[108:111]
	v_mfma_f32_16x16x32_f16 v[108:111], v[210:213], v[144:147], v[124:127]
	v_mfma_f32_16x16x32_f16 v[104:107], v[194:197], v[168:171], v[104:107]
	v_mfma_f32_16x16x32_f16 v[100:103], v[210:213], v[168:171], v[100:103]
	v_mfma_f32_16x16x32_f16 v[88:91], v[194:197], v[176:179], v[88:91]
	v_mfma_f32_16x16x32_f16 v[84:87], v[210:213], v[176:179], v[84:87]
	v_mfma_f32_16x16x32_f16 v[124:127], v[214:217], v[156:159], v[108:111]
	v_mfma_f32_16x16x32_f16 v[104:107], v[198:201], v[172:175], v[104:107]
	v_mfma_f32_16x16x32_f16 v[100:103], v[214:217], v[172:175], v[100:103]
	v_mfma_f32_16x16x32_f16 v[88:91], v[198:201], v[190:193], v[88:91]
	v_mfma_f32_16x16x32_f16 v[84:87], v[214:217], v[190:193], v[84:87]
	s_mov_b32 m0, s50
	v_lshl_add_u64 v[190:191], v[220:221], 0, s[88:89]
	s_barrier
	ds_read_b128 v[108:111], v209 offset:49152
	ds_read_b128 v[120:123], v209 offset:50176
	ds_read_b128 v[132:135], v209 offset:51200
	ds_read_b128 v[144:147], v209 offset:52224
	ds_read_b128 v[156:159], v209 offset:53248
	ds_read_b128 v[168:171], v209 offset:54272
	ds_read_b128 v[172:175], v209 offset:55296
	ds_read_b128 v[176:179], v209 offset:56320
	global_load_lds_dwordx4 v[190:191], off
	v_lshl_add_u64 v[190:191], v[232:233], 0, s[88:89]
	s_mov_b32 m0, s51
	s_nop 0
	global_load_lds_dwordx4 v[190:191], off
	s_barrier
	s_waitcnt lgkmcnt(0)
	v_mfma_f32_16x16x32_f16 v[80:83], v[52:55], v[108:111], v[80:83]
	v_mfma_f32_16x16x32_f16 v[76:79], v[68:71], v[108:111], v[76:79]
	v_mfma_f32_16x16x32_f16 v[64:67], v[52:55], v[132:135], v[64:67]
	v_mfma_f32_16x16x32_f16 v[60:63], v[68:71], v[132:135], v[60:63]
	v_mfma_f32_16x16x32_f16 v[36:39], v[52:55], v[156:159], v[36:39]
	v_mfma_f32_16x16x32_f16 v[28:31], v[68:71], v[156:159], v[28:31]
	v_mfma_f32_16x16x32_f16 v[16:19], v[52:55], v[172:175], v[16:19]
	v_mfma_f32_16x16x32_f16 v[12:15], v[68:71], v[172:175], v[12:15]
	v_mfma_f32_16x16x32_f16 v[80:83], v[56:59], v[120:123], v[80:83]
	v_mfma_f32_16x16x32_f16 v[76:79], v[72:75], v[120:123], v[76:79]
	v_mfma_f32_16x16x32_f16 v[64:67], v[56:59], v[144:147], v[64:67]
	v_mfma_f32_16x16x32_f16 v[60:63], v[72:75], v[144:147], v[60:63]
	v_mfma_f32_16x16x32_f16 v[36:39], v[56:59], v[168:171], v[36:39]
	v_mfma_f32_16x16x32_f16 v[28:31], v[72:75], v[168:171], v[28:31]
	v_mfma_f32_16x16x32_f16 v[16:19], v[56:59], v[176:179], v[16:19]
	v_mfma_f32_16x16x32_f16 v[12:15], v[72:75], v[176:179], v[12:15]
	s_barrier
	s_add_u32 s30, s38, 0x20080
	s_addc_u32 s31, s39, 0
	s_add_i32 s15, s29, s7
	v_lshl_add_u64 v[52:53], s[30:31], 0, v[2:3]
	s_mov_b32 m0, s15
	s_nop 0
	global_load_lds_dwordx4 v[52:53], off
	v_lshl_add_u64 v[52:53], s[30:31], 0, v[184:185]
	s_add_i32 m0, s15, 0x2000
	s_nop 0
	global_load_lds_dwordx4 v[52:53], off
	s_waitcnt vmcnt(6)
	s_barrier
	v_mfma_f32_16x16x32_f16 v[32:35], v[194:197], v[108:111], v[32:35]
	v_mfma_f32_16x16x32_f16 v[72:75], v[198:201], v[120:123], v[32:35]
	v_mfma_f32_16x16x32_f16 v[32:35], v[210:213], v[108:111], v[40:43]
	v_mfma_f32_16x16x32_f16 v[68:71], v[214:217], v[120:123], v[32:35]
	v_mfma_f32_16x16x32_f16 v[32:35], v[194:197], v[132:135], v[48:51]
	v_mfma_f32_16x16x32_f16 v[52:55], v[198:201], v[144:147], v[32:35]
	v_mfma_f32_16x16x32_f16 v[32:35], v[210:213], v[132:135], v[44:47]
	v_mfma_f32_16x16x32_f16 v[24:27], v[194:197], v[156:159], v[24:27]
	v_mfma_f32_16x16x32_f16 v[20:23], v[210:213], v[156:159], v[20:23]
	v_mfma_f32_16x16x32_f16 v[8:11], v[194:197], v[172:175], v[8:11]
	v_mfma_f32_16x16x32_f16 v[4:7], v[210:213], v[172:175], v[4:7]
	v_mfma_f32_16x16x32_f16 v[44:47], v[214:217], v[144:147], v[32:35]
	v_mfma_f32_16x16x32_f16 v[24:27], v[198:201], v[168:171], v[24:27]
	v_mfma_f32_16x16x32_f16 v[20:23], v[214:217], v[168:171], v[20:23]
	v_mfma_f32_16x16x32_f16 v[8:11], v[198:201], v[176:179], v[8:11]
	v_mfma_f32_16x16x32_f16 v[4:7], v[214:217], v[176:179], v[4:7]
	s_add_i32 s14, s14, 2
	s_add_u32 s46, s46, 0x100
	s_addc_u32 s47, s47, 0
	s_add_u32 s10, s10, 0x100
	s_addc_u32 s11, s11, 0
	s_cmp_gt_u32 s14, 5
	s_barrier
	s_cbranch_scc0 .LBB0_1664
	s_lshl_b32 s11, s16, 8
	v_mov_b32_e32 v110, v206
	v_mov_b32_e32 v32, v207
	s_lshl_b32 s10, s26, 8
	s_or_b32 s11, s11, s27
	s_add_i32 s10, s10, s17
	v_lshl_add_u32 v108, v32, 3, s11
	v_ashrrev_i32_e32 v109, 31, v108
	v_add_u32_e32 v194, s10, v110
	v_readlane_b32 s10, v253, 25
	v_lshlrev_b64 v[190:191], 1, v[108:109]
	v_readlane_b32 s11, v253, 26
	v_ashrrev_i32_e32 v195, 31, v194
	v_add_u32_e32 v200, 16, v194
	v_lshl_add_u64 v[32:33], v[108:109], 2, s[18:19]
	v_lshl_add_u64 v[192:193], s[10:11], 0, v[190:191]
	v_lshlrev_b64 v[108:109], 10, v[194:195]
	v_ashrrev_i32_e32 v201, 31, v200
	v_add_u32_e32 v198, 32, v194
	flat_load_dwordx4 v[56:59], v[32:33]
	flat_load_dwordx4 v[48:51], v[32:33] offset:16
	flat_load_dwordx4 v[40:43], v[32:33] offset:512
	s_nop 0
	flat_load_dwordx4 v[32:35], v[32:33] offset:528
	v_lshl_add_u64 v[176:177], v[192:193], 0, v[108:109]
	v_lshlrev_b64 v[108:109], 10, v[200:201]
	v_ashrrev_i32_e32 v199, 31, v198
	v_add_u32_e32 v196, 48, v194
	v_lshl_add_u64 v[168:169], v[192:193], 0, v[108:109]
	v_lshlrev_b64 v[108:109], 10, v[198:199]
	v_ashrrev_i32_e32 v197, 31, v196
	v_lshl_add_u64 v[144:145], v[192:193], 0, v[108:109]
	v_lshlrev_b64 v[108:109], 10, v[196:197]
	v_lshl_add_u64 v[120:121], v[192:193], 0, v[108:109]
	global_load_dwordx4 v[108:111], v[120:121], off offset:256
	s_nop 0
	global_load_dwordx4 v[120:123], v[120:121], off
	s_nop 0
	global_load_dwordx4 v[132:135], v[144:145], off offset:256
	s_nop 0
	global_load_dwordx4 v[144:147], v[144:145], off
	s_nop 0
	global_load_dwordx4 v[156:159], v[168:169], off offset:256
	s_nop 0
	global_load_dwordx4 v[168:171], v[168:169], off
	s_nop 0
	global_load_dwordx4 v[172:175], v[176:177], off offset:256
	s_nop 0
	global_load_dwordx4 v[176:179], v[176:177], off
	v_readlane_b32 s10, v253, 40
	v_lshlrev_b64 v[202:203], 12, v[194:195]
	v_readlane_b32 s11, v253, 41
	s_and_b64 vcc, exec, s[40:41]
	s_mov_b32 s16, s34
	s_mov_b32 s26, s36
	s_mov_b64 s[48:49], s[44:45]
	s_mov_b64 s[38:39], s[42:43]
	s_waitcnt vmcnt(0)
	s_waitcnt lgkmcnt(0)
	v_add_f32_e32 v164, v164, v56
	v_add_f32_e32 v165, v165, v57
	v_mul_f32_e32 v164, 0xbfb8aa3b, v164
	v_mul_f32_e32 v165, 0xbfb8aa3b, v165
	v_exp_f32_e32 v164, v164
	v_exp_f32_e32 v165, v165
	v_add_f32_e32 v160, v160, v48
	v_add_f32_e32 v161, v161, v49
	v_add_f32_e32 v164, 1.0, v164
	v_mul_f32_e32 v160, 0xbfb8aa3b, v160
	v_add_f32_e32 v165, 1.0, v165
	v_mul_f32_e32 v161, 0xbfb8aa3b, v161
	v_rcp_f32_e32 v164, v164
	v_exp_f32_e32 v160, v160
	v_rcp_f32_e32 v165, v165
	v_cvt_f32_f16_e32 v210, v176
	v_cvt_f32_f16_sdwa v211, v176 dst_sel:DWORD dst_unused:UNUSED_PAD src0_sel:WORD_1
	v_exp_f32_e32 v161, v161
	v_add_f32_e32 v160, 1.0, v160
	v_rcp_f32_e32 v160, v160
	v_pk_mul_f32 v[164:165], v[164:165], v[210:211]
	v_add_f32_e32 v161, 1.0, v161
	v_cvt_pk_f16_f32 v176, v164, v165
	v_rcp_f32_e32 v161, v161
	v_cvt_f32_f16_e32 v164, v178
	v_cvt_f32_f16_sdwa v165, v178 dst_sel:DWORD dst_unused:UNUSED_PAD src0_sel:WORD_1
	v_add_f32_e32 v152, v152, v40
	v_add_f32_e32 v153, v153, v41
	v_mul_f32_e32 v152, 0xbfb8aa3b, v152
	v_pk_mul_f32 v[160:161], v[160:161], v[164:165]
	v_cvt_f32_f16_e32 v164, v177
	v_cvt_pk_f16_f32 v178, v160, v161
	v_add_f32_e32 v161, v162, v50
	v_mul_f32_e32 v161, 0xbfb8aa3b, v161
	v_exp_f32_e32 v161, v161
	v_add_f32_e32 v160, v166, v58
	v_mul_f32_e32 v160, 0xbfb8aa3b, v160
	v_exp_f32_e32 v160, v160
	v_add_f32_e32 v161, 1.0, v161
	v_rcp_f32_e32 v162, v161
	v_add_f32_e32 v161, v167, v59
	v_mul_f32_e32 v161, 0xbfb8aa3b, v161
	v_exp_f32_e32 v161, v161
	v_add_f32_e32 v160, 1.0, v160
	v_rcp_f32_e32 v160, v160
	v_cvt_f32_f16_sdwa v165, v177 dst_sel:DWORD dst_unused:UNUSED_PAD src0_sel:WORD_1
	v_add_f32_e32 v161, 1.0, v161
	v_rcp_f32_e32 v161, v161
	v_mul_f32_e32 v153, 0xbfb8aa3b, v153
	v_exp_f32_e32 v152, v152
	v_exp_f32_e32 v153, v153
	v_pk_mul_f32 v[160:161], v[160:161], v[164:165]
	v_add_f32_e32 v148, v148, v32
	v_cvt_pk_f16_f32 v164, v160, v161
	v_add_f32_e32 v160, v163, v51
	v_mul_f32_e32 v160, 0xbfb8aa3b, v160
	v_exp_f32_e32 v160, v160
	v_cvt_f32_f16_sdwa v161, v179 dst_sel:DWORD dst_unused:UNUSED_PAD src0_sel:WORD_1
	v_add_f32_e32 v149, v149, v33
	v_add_f32_e32 v152, 1.0, v152
	v_add_f32_e32 v160, 1.0, v160
	v_rcp_f32_e32 v163, v160
	v_cvt_f32_f16_e32 v160, v179
	v_mul_f32_e32 v148, 0xbfb8aa3b, v148
	v_add_f32_e32 v153, 1.0, v153
	v_mul_f32_e32 v149, 0xbfb8aa3b, v149
	v_pk_mul_f32 v[160:161], v[162:163], v[160:161]
	v_rcp_f32_e32 v152, v152
	v_cvt_pk_f16_f32 v160, v160, v161
	v_lshrrev_b32_e32 v161, 4, v176
	v_and_b32_e32 v161, 0x10001, v161
	v_add3_u32 v161, v176, v161, s21
	v_and_b32_e32 v162, 0xfff0fff0, v161
	v_lshrrev_b32_e32 v161, 4, v164
	v_and_b32_e32 v161, 0x10001, v161
	v_add3_u32 v161, v164, v161, s21
	v_and_b32_e32 v163, 0xfff0fff0, v161
	v_lshrrev_b32_e32 v161, 4, v178
	v_and_b32_e32 v161, 0x10001, v161
	v_add3_u32 v161, v178, v161, s21
	v_and_b32_e32 v164, 0xfff0fff0, v161
	v_lshrrev_b32_e32 v161, 4, v160
	v_and_b32_e32 v161, 0x10001, v161
	v_add3_u32 v160, v160, v161, s21
	v_and_b32_e32 v165, 0xfff0fff0, v160
	v_lshl_add_u64 v[160:161], s[10:11], 0, v[202:203]
	v_lshl_add_u64 v[160:161], v[160:161], 0, v[190:191]
	global_store_dwordx4 v[160:161], v[162:165], off
	v_exp_f32_e32 v148, v148
	v_rcp_f32_e32 v153, v153
	v_cvt_f32_f16_e32 v162, v172
	v_cvt_f32_f16_sdwa v163, v172 dst_sel:DWORD dst_unused:UNUSED_PAD src0_sel:WORD_1
	v_exp_f32_e32 v149, v149
	v_add_f32_e32 v148, 1.0, v148
	v_rcp_f32_e32 v148, v148
	v_pk_mul_f32 v[152:153], v[152:153], v[162:163]
	v_add_f32_e32 v149, 1.0, v149
	v_cvt_pk_f16_f32 v162, v152, v153
	v_rcp_f32_e32 v149, v149
	v_cvt_f32_f16_e32 v152, v174
	v_cvt_f32_f16_sdwa v153, v174 dst_sel:DWORD dst_unused:UNUSED_PAD src0_sel:WORD_1
	v_add_f32_e32 v140, v140, v56
	v_add_f32_e32 v141, v141, v57
	v_mul_f32_e32 v140, 0xbfb8aa3b, v140
	v_pk_mul_f32 v[148:149], v[148:149], v[152:153]
	v_cvt_f32_f16_e32 v152, v173
	v_cvt_pk_f16_f32 v163, v148, v149
	v_add_f32_e32 v149, v150, v34
	v_mul_f32_e32 v149, 0xbfb8aa3b, v149
	v_exp_f32_e32 v149, v149
	v_add_f32_e32 v148, v154, v42
	v_mul_f32_e32 v148, 0xbfb8aa3b, v148
	v_exp_f32_e32 v148, v148
	v_add_f32_e32 v149, 1.0, v149
	v_rcp_f32_e32 v150, v149
	v_add_f32_e32 v149, v155, v43
	v_mul_f32_e32 v149, 0xbfb8aa3b, v149
	v_exp_f32_e32 v149, v149
	v_add_f32_e32 v148, 1.0, v148
	v_rcp_f32_e32 v148, v148
	v_cvt_f32_f16_sdwa v153, v173 dst_sel:DWORD dst_unused:UNUSED_PAD src0_sel:WORD_1
	v_add_f32_e32 v149, 1.0, v149
	v_rcp_f32_e32 v149, v149
	v_mul_f32_e32 v141, 0xbfb8aa3b, v141
	v_exp_f32_e32 v140, v140
	v_exp_f32_e32 v141, v141
	v_pk_mul_f32 v[148:149], v[148:149], v[152:153]
	v_add_f32_e32 v136, v136, v48
	v_cvt_pk_f16_f32 v152, v148, v149
	v_add_f32_e32 v148, v151, v35
	v_mul_f32_e32 v148, 0xbfb8aa3b, v148
	v_exp_f32_e32 v148, v148
	v_cvt_f32_f16_sdwa v149, v175 dst_sel:DWORD dst_unused:UNUSED_PAD src0_sel:WORD_1
	v_add_f32_e32 v137, v137, v49
	v_add_f32_e32 v140, 1.0, v140
	v_add_f32_e32 v148, 1.0, v148
	v_rcp_f32_e32 v151, v148
	v_cvt_f32_f16_e32 v148, v175
	v_mul_f32_e32 v136, 0xbfb8aa3b, v136
	v_add_f32_e32 v141, 1.0, v141
	v_mul_f32_e32 v137, 0xbfb8aa3b, v137
	v_pk_mul_f32 v[148:149], v[150:151], v[148:149]
	v_lshrrev_b32_e32 v150, 4, v163
	v_cvt_pk_f16_f32 v151, v148, v149
	v_lshrrev_b32_e32 v149, 4, v152
	v_and_b32_e32 v149, 0x10001, v149
	v_lshrrev_b32_e32 v148, 4, v162
	v_add3_u32 v149, v152, v149, s21
	v_lshrrev_b32_e32 v152, 4, v151
	v_and_b32_e32 v148, 0x10001, v148
	v_and_b32_e32 v150, 0x10001, v150
	v_and_b32_e32 v152, 0x10001, v152
	v_add3_u32 v148, v162, v148, s21
	v_add3_u32 v150, v163, v150, s21
	v_add3_u32 v151, v151, v152, s21
	v_and_b32_e32 v148, 0xfff0fff0, v148
	v_and_b32_e32 v149, 0xfff0fff0, v149
	v_and_b32_e32 v150, 0xfff0fff0, v150
	v_and_b32_e32 v151, 0xfff0fff0, v151
	global_store_dwordx4 v[160:161], v[148:151], off offset:256
	v_rcp_f32_e32 v140, v140
	v_exp_f32_e32 v136, v136
	v_rcp_f32_e32 v141, v141
	v_cvt_f32_f16_e32 v150, v168
	v_cvt_f32_f16_sdwa v151, v168 dst_sel:DWORD dst_unused:UNUSED_PAD src0_sel:WORD_1
	v_exp_f32_e32 v137, v137
	v_add_f32_e32 v136, 1.0, v136
	v_rcp_f32_e32 v136, v136
	v_pk_mul_f32 v[140:141], v[140:141], v[150:151]
	v_add_f32_e32 v137, 1.0, v137
	v_cvt_pk_f16_f32 v150, v140, v141
	v_rcp_f32_e32 v137, v137
	v_cvt_f32_f16_e32 v140, v170
	v_cvt_f32_f16_sdwa v141, v170 dst_sel:DWORD dst_unused:UNUSED_PAD src0_sel:WORD_1
	v_add_f32_e32 v128, v128, v40
	v_add_f32_e32 v129, v129, v41
	v_mul_f32_e32 v128, 0xbfb8aa3b, v128
	v_pk_mul_f32 v[136:137], v[136:137], v[140:141]
	v_cvt_f32_f16_e32 v140, v169
	v_cvt_pk_f16_f32 v151, v136, v137
	v_add_f32_e32 v137, v138, v50
	v_mul_f32_e32 v137, 0xbfb8aa3b, v137
	v_exp_f32_e32 v137, v137
	v_add_f32_e32 v136, v142, v58
	v_mul_f32_e32 v136, 0xbfb8aa3b, v136
	v_exp_f32_e32 v136, v136
	v_add_f32_e32 v137, 1.0, v137
	v_rcp_f32_e32 v138, v137
	v_add_f32_e32 v137, v143, v59
	v_mul_f32_e32 v137, 0xbfb8aa3b, v137
	v_exp_f32_e32 v137, v137
	v_add_f32_e32 v136, 1.0, v136
	v_rcp_f32_e32 v136, v136
	v_cvt_f32_f16_sdwa v141, v169 dst_sel:DWORD dst_unused:UNUSED_PAD src0_sel:WORD_1
	v_add_f32_e32 v137, 1.0, v137
	v_rcp_f32_e32 v137, v137
	v_mul_f32_e32 v129, 0xbfb8aa3b, v129
	v_exp_f32_e32 v128, v128
	v_exp_f32_e32 v129, v129
	v_pk_mul_f32 v[136:137], v[136:137], v[140:141]
	v_lshlrev_b64 v[148:149], 12, v[200:201]
	v_cvt_pk_f16_f32 v140, v136, v137
	v_add_f32_e32 v136, v139, v51
	v_mul_f32_e32 v136, 0xbfb8aa3b, v136
	v_exp_f32_e32 v136, v136
	v_cvt_f32_f16_sdwa v137, v171 dst_sel:DWORD dst_unused:UNUSED_PAD src0_sel:WORD_1
	v_add_f32_e32 v124, v124, v32
	v_add_f32_e32 v125, v125, v33
	v_add_f32_e32 v136, 1.0, v136
	v_rcp_f32_e32 v139, v136
	v_cvt_f32_f16_e32 v136, v171
	v_add_f32_e32 v128, 1.0, v128
	v_mul_f32_e32 v124, 0xbfb8aa3b, v124
	v_add_f32_e32 v129, 1.0, v129
	v_pk_mul_f32 v[136:137], v[138:139], v[136:137]
	v_mul_f32_e32 v125, 0xbfb8aa3b, v125
	v_cvt_pk_f16_f32 v136, v136, v137
	v_lshrrev_b32_e32 v137, 4, v150
	v_and_b32_e32 v137, 0x10001, v137
	v_add3_u32 v137, v150, v137, s21
	v_and_b32_e32 v138, 0xfff0fff0, v137
	v_lshrrev_b32_e32 v137, 4, v140
	v_and_b32_e32 v137, 0x10001, v137
	v_add3_u32 v137, v140, v137, s21
	v_and_b32_e32 v139, 0xfff0fff0, v137
	v_lshrrev_b32_e32 v137, 4, v151
	v_and_b32_e32 v137, 0x10001, v137
	v_add3_u32 v137, v151, v137, s21
	v_and_b32_e32 v140, 0xfff0fff0, v137
	v_lshrrev_b32_e32 v137, 4, v136
	v_and_b32_e32 v137, 0x10001, v137
	v_add3_u32 v136, v136, v137, s21
	v_and_b32_e32 v141, 0xfff0fff0, v136
	v_lshl_add_u64 v[136:137], s[10:11], 0, v[148:149]
	v_lshl_add_u64 v[136:137], v[136:137], 0, v[190:191]
	global_store_dwordx4 v[136:137], v[138:141], off
	v_rcp_f32_e32 v128, v128
	v_exp_f32_e32 v124, v124
	v_rcp_f32_e32 v129, v129
	v_cvt_f32_f16_e32 v138, v156
	v_cvt_f32_f16_sdwa v139, v156 dst_sel:DWORD dst_unused:UNUSED_PAD src0_sel:WORD_1
	v_exp_f32_e32 v125, v125
	v_add_f32_e32 v124, 1.0, v124
	v_rcp_f32_e32 v124, v124
	v_pk_mul_f32 v[128:129], v[128:129], v[138:139]
	v_add_f32_e32 v125, 1.0, v125
	v_cvt_pk_f16_f32 v138, v128, v129
	v_rcp_f32_e32 v125, v125
	v_cvt_f32_f16_e32 v128, v158
	v_cvt_f32_f16_sdwa v129, v158 dst_sel:DWORD dst_unused:UNUSED_PAD src0_sel:WORD_1
	v_add_f32_e32 v116, v116, v56
	v_add_f32_e32 v117, v117, v57
	v_mul_f32_e32 v116, 0xbfb8aa3b, v116
	v_pk_mul_f32 v[124:125], v[124:125], v[128:129]
	v_cvt_f32_f16_e32 v128, v157
	v_cvt_pk_f16_f32 v139, v124, v125
	v_add_f32_e32 v125, v126, v34
	v_mul_f32_e32 v125, 0xbfb8aa3b, v125
	v_exp_f32_e32 v125, v125
	v_add_f32_e32 v124, v130, v42
	v_mul_f32_e32 v124, 0xbfb8aa3b, v124
	v_exp_f32_e32 v124, v124
	v_add_f32_e32 v125, 1.0, v125
	v_rcp_f32_e32 v126, v125
	v_add_f32_e32 v125, v131, v43
	v_mul_f32_e32 v125, 0xbfb8aa3b, v125
	v_exp_f32_e32 v125, v125
	v_add_f32_e32 v124, 1.0, v124
	v_rcp_f32_e32 v124, v124
	v_cvt_f32_f16_sdwa v129, v157 dst_sel:DWORD dst_unused:UNUSED_PAD src0_sel:WORD_1
	v_add_f32_e32 v125, 1.0, v125
	v_rcp_f32_e32 v125, v125
	v_mul_f32_e32 v117, 0xbfb8aa3b, v117
	v_exp_f32_e32 v116, v116
	v_exp_f32_e32 v117, v117
	v_pk_mul_f32 v[124:125], v[124:125], v[128:129]
	v_add_f32_e32 v112, v112, v48
	v_cvt_pk_f16_f32 v128, v124, v125
	v_add_f32_e32 v124, v127, v35
	v_mul_f32_e32 v124, 0xbfb8aa3b, v124
	v_exp_f32_e32 v124, v124
	v_cvt_f32_f16_sdwa v125, v159 dst_sel:DWORD dst_unused:UNUSED_PAD src0_sel:WORD_1
	v_add_f32_e32 v113, v113, v49
	v_add_f32_e32 v116, 1.0, v116
	v_add_f32_e32 v124, 1.0, v124
	v_rcp_f32_e32 v127, v124
	v_cvt_f32_f16_e32 v124, v159
	v_mul_f32_e32 v112, 0xbfb8aa3b, v112
	v_add_f32_e32 v117, 1.0, v117
	v_mul_f32_e32 v113, 0xbfb8aa3b, v113
	v_pk_mul_f32 v[124:125], v[126:127], v[124:125]
	v_lshrrev_b32_e32 v126, 4, v139
	v_cvt_pk_f16_f32 v127, v124, v125
	v_lshrrev_b32_e32 v125, 4, v128
	v_and_b32_e32 v125, 0x10001, v125
	v_lshrrev_b32_e32 v124, 4, v138
	v_add3_u32 v125, v128, v125, s21
	v_lshrrev_b32_e32 v128, 4, v127
	v_and_b32_e32 v124, 0x10001, v124
	v_and_b32_e32 v126, 0x10001, v126
	v_and_b32_e32 v128, 0x10001, v128
	v_add3_u32 v124, v138, v124, s21
	v_add3_u32 v126, v139, v126, s21
	v_add3_u32 v127, v127, v128, s21
	v_and_b32_e32 v124, 0xfff0fff0, v124
	v_and_b32_e32 v125, 0xfff0fff0, v125
	v_and_b32_e32 v126, 0xfff0fff0, v126
	v_and_b32_e32 v127, 0xfff0fff0, v127
	global_store_dwordx4 v[136:137], v[124:127], off offset:256
	v_rcp_f32_e32 v116, v116
	v_exp_f32_e32 v112, v112
	v_rcp_f32_e32 v117, v117
	v_cvt_f32_f16_e32 v126, v144
	v_cvt_f32_f16_sdwa v127, v144 dst_sel:DWORD dst_unused:UNUSED_PAD src0_sel:WORD_1
	v_exp_f32_e32 v113, v113
	v_add_f32_e32 v112, 1.0, v112
	v_rcp_f32_e32 v112, v112
	v_pk_mul_f32 v[116:117], v[116:117], v[126:127]
	v_add_f32_e32 v113, 1.0, v113
	v_cvt_pk_f16_f32 v126, v116, v117
	v_rcp_f32_e32 v113, v113
	v_cvt_f32_f16_e32 v116, v146
	v_cvt_f32_f16_sdwa v117, v146 dst_sel:DWORD dst_unused:UNUSED_PAD src0_sel:WORD_1
	v_add_f32_e32 v104, v104, v40
	v_add_f32_e32 v105, v105, v41
	v_mul_f32_e32 v104, 0xbfb8aa3b, v104
	v_pk_mul_f32 v[112:113], v[112:113], v[116:117]
	v_cvt_f32_f16_e32 v116, v145
	v_cvt_pk_f16_f32 v127, v112, v113
	v_add_f32_e32 v113, v114, v50
	v_mul_f32_e32 v113, 0xbfb8aa3b, v113
	v_exp_f32_e32 v113, v113
	v_add_f32_e32 v112, v118, v58
	v_mul_f32_e32 v112, 0xbfb8aa3b, v112
	v_exp_f32_e32 v112, v112
	v_add_f32_e32 v113, 1.0, v113
	v_rcp_f32_e32 v114, v113
	v_add_f32_e32 v113, v119, v59
	v_mul_f32_e32 v113, 0xbfb8aa3b, v113
	v_exp_f32_e32 v113, v113
	v_add_f32_e32 v112, 1.0, v112
	v_rcp_f32_e32 v112, v112
	v_cvt_f32_f16_sdwa v117, v145 dst_sel:DWORD dst_unused:UNUSED_PAD src0_sel:WORD_1
	v_add_f32_e32 v113, 1.0, v113
	v_rcp_f32_e32 v113, v113
	v_mul_f32_e32 v105, 0xbfb8aa3b, v105
	v_exp_f32_e32 v104, v104
	v_exp_f32_e32 v105, v105
	v_pk_mul_f32 v[112:113], v[112:113], v[116:117]
	v_lshlrev_b64 v[124:125], 12, v[198:199]
	v_cvt_pk_f16_f32 v116, v112, v113
	v_add_f32_e32 v112, v115, v51
	v_mul_f32_e32 v112, 0xbfb8aa3b, v112
	v_exp_f32_e32 v112, v112
	v_cvt_f32_f16_sdwa v113, v147 dst_sel:DWORD dst_unused:UNUSED_PAD src0_sel:WORD_1
	v_add_f32_e32 v100, v100, v32
	v_add_f32_e32 v101, v101, v33
	v_add_f32_e32 v112, 1.0, v112
	v_rcp_f32_e32 v115, v112
	v_cvt_f32_f16_e32 v112, v147
	v_add_f32_e32 v104, 1.0, v104
	v_mul_f32_e32 v100, 0xbfb8aa3b, v100
	v_add_f32_e32 v105, 1.0, v105
	v_pk_mul_f32 v[112:113], v[114:115], v[112:113]
	v_mul_f32_e32 v101, 0xbfb8aa3b, v101
	v_cvt_pk_f16_f32 v112, v112, v113
	v_lshrrev_b32_e32 v113, 4, v126
	v_and_b32_e32 v113, 0x10001, v113
	v_add3_u32 v113, v126, v113, s21
	v_and_b32_e32 v114, 0xfff0fff0, v113
	v_lshrrev_b32_e32 v113, 4, v116
	v_and_b32_e32 v113, 0x10001, v113
	v_add3_u32 v113, v116, v113, s21
	v_and_b32_e32 v115, 0xfff0fff0, v113
	v_lshrrev_b32_e32 v113, 4, v127
	v_and_b32_e32 v113, 0x10001, v113
	v_add3_u32 v113, v127, v113, s21
	v_and_b32_e32 v116, 0xfff0fff0, v113
	v_lshrrev_b32_e32 v113, 4, v112
	v_and_b32_e32 v113, 0x10001, v113
	v_add3_u32 v112, v112, v113, s21
	v_and_b32_e32 v117, 0xfff0fff0, v112
	v_lshl_add_u64 v[112:113], s[10:11], 0, v[124:125]
	v_lshl_add_u64 v[112:113], v[112:113], 0, v[190:191]
	global_store_dwordx4 v[112:113], v[114:117], off
	v_rcp_f32_e32 v104, v104
	v_exp_f32_e32 v100, v100
	v_rcp_f32_e32 v105, v105
	v_cvt_f32_f16_e32 v114, v132
	v_cvt_f32_f16_sdwa v115, v132 dst_sel:DWORD dst_unused:UNUSED_PAD src0_sel:WORD_1
	v_exp_f32_e32 v101, v101
	v_add_f32_e32 v100, 1.0, v100
	v_rcp_f32_e32 v100, v100
	v_pk_mul_f32 v[104:105], v[104:105], v[114:115]
	v_add_f32_e32 v101, 1.0, v101
	v_cvt_pk_f16_f32 v114, v104, v105
	v_rcp_f32_e32 v101, v101
	v_cvt_f32_f16_e32 v104, v134
	v_cvt_f32_f16_sdwa v105, v134 dst_sel:DWORD dst_unused:UNUSED_PAD src0_sel:WORD_1
	v_add_f32_e32 v96, v96, v56
	v_add_f32_e32 v97, v97, v57
	v_mul_f32_e32 v96, 0xbfb8aa3b, v96
	v_pk_mul_f32 v[100:101], v[100:101], v[104:105]
	v_cvt_f32_f16_e32 v104, v133
	v_cvt_pk_f16_f32 v115, v100, v101
	v_add_f32_e32 v101, v102, v34
	v_mul_f32_e32 v101, 0xbfb8aa3b, v101
	v_exp_f32_e32 v101, v101
	v_add_f32_e32 v100, v106, v42
	v_mul_f32_e32 v100, 0xbfb8aa3b, v100
	v_exp_f32_e32 v100, v100
	v_add_f32_e32 v101, 1.0, v101
	v_rcp_f32_e32 v102, v101
	v_add_f32_e32 v101, v107, v43
	v_mul_f32_e32 v101, 0xbfb8aa3b, v101
	v_exp_f32_e32 v101, v101
	v_add_f32_e32 v100, 1.0, v100
	v_rcp_f32_e32 v100, v100
	v_cvt_f32_f16_sdwa v105, v133 dst_sel:DWORD dst_unused:UNUSED_PAD src0_sel:WORD_1
	v_add_f32_e32 v101, 1.0, v101
	v_rcp_f32_e32 v101, v101
	v_mul_f32_e32 v97, 0xbfb8aa3b, v97
	v_exp_f32_e32 v96, v96
	v_exp_f32_e32 v97, v97
	v_pk_mul_f32 v[100:101], v[100:101], v[104:105]
	v_add_f32_e32 v92, v92, v48
	v_cvt_pk_f16_f32 v104, v100, v101
	v_add_f32_e32 v100, v103, v35
	v_mul_f32_e32 v100, 0xbfb8aa3b, v100
	v_exp_f32_e32 v100, v100
	v_cvt_f32_f16_sdwa v101, v135 dst_sel:DWORD dst_unused:UNUSED_PAD src0_sel:WORD_1
	v_add_f32_e32 v93, v93, v49
	v_add_f32_e32 v96, 1.0, v96
	v_add_f32_e32 v100, 1.0, v100
	v_rcp_f32_e32 v103, v100
	v_cvt_f32_f16_e32 v100, v135
	v_mul_f32_e32 v92, 0xbfb8aa3b, v92
	v_add_f32_e32 v97, 1.0, v97
	v_mul_f32_e32 v93, 0xbfb8aa3b, v93
	v_pk_mul_f32 v[100:101], v[102:103], v[100:101]
	v_lshrrev_b32_e32 v102, 4, v115
	v_cvt_pk_f16_f32 v103, v100, v101
	v_lshrrev_b32_e32 v101, 4, v104
	v_and_b32_e32 v101, 0x10001, v101
	v_lshrrev_b32_e32 v100, 4, v114
	v_add3_u32 v101, v104, v101, s21
	v_lshrrev_b32_e32 v104, 4, v103
	v_and_b32_e32 v100, 0x10001, v100
	v_and_b32_e32 v102, 0x10001, v102
	v_and_b32_e32 v104, 0x10001, v104
	v_add3_u32 v100, v114, v100, s21
	v_add3_u32 v102, v115, v102, s21
	v_add3_u32 v103, v103, v104, s21
	v_and_b32_e32 v100, 0xfff0fff0, v100
	v_and_b32_e32 v101, 0xfff0fff0, v101
	v_and_b32_e32 v102, 0xfff0fff0, v102
	v_and_b32_e32 v103, 0xfff0fff0, v103
	global_store_dwordx4 v[112:113], v[100:103], off offset:256
	v_rcp_f32_e32 v96, v96
	v_exp_f32_e32 v92, v92
	v_rcp_f32_e32 v97, v97
	v_cvt_f32_f16_e32 v102, v120
	v_cvt_f32_f16_sdwa v103, v120 dst_sel:DWORD dst_unused:UNUSED_PAD src0_sel:WORD_1
	v_exp_f32_e32 v93, v93
	v_add_f32_e32 v92, 1.0, v92
	v_rcp_f32_e32 v92, v92
	v_pk_mul_f32 v[96:97], v[96:97], v[102:103]
	v_add_f32_e32 v93, 1.0, v93
	v_cvt_pk_f16_f32 v102, v96, v97
	v_rcp_f32_e32 v93, v93
	v_cvt_f32_f16_e32 v96, v122
	v_cvt_f32_f16_sdwa v97, v122 dst_sel:DWORD dst_unused:UNUSED_PAD src0_sel:WORD_1
	v_add_f32_e32 v88, v88, v40
	v_add_f32_e32 v89, v89, v41
	v_mul_f32_e32 v88, 0xbfb8aa3b, v88
	v_pk_mul_f32 v[92:93], v[92:93], v[96:97]
	v_cvt_f32_f16_e32 v96, v121
	v_cvt_pk_f16_f32 v103, v92, v93
	v_add_f32_e32 v93, v94, v50
	v_mul_f32_e32 v93, 0xbfb8aa3b, v93
	v_exp_f32_e32 v93, v93
	v_add_f32_e32 v92, v98, v58
	v_mul_f32_e32 v92, 0xbfb8aa3b, v92
	v_exp_f32_e32 v92, v92
	v_add_f32_e32 v93, 1.0, v93
	v_rcp_f32_e32 v94, v93
	v_add_f32_e32 v93, v99, v59
	v_mul_f32_e32 v93, 0xbfb8aa3b, v93
	v_exp_f32_e32 v93, v93
	v_add_f32_e32 v92, 1.0, v92
	v_rcp_f32_e32 v92, v92
	v_cvt_f32_f16_sdwa v97, v121 dst_sel:DWORD dst_unused:UNUSED_PAD src0_sel:WORD_1
	v_add_f32_e32 v93, 1.0, v93
	v_rcp_f32_e32 v93, v93
	v_mul_f32_e32 v89, 0xbfb8aa3b, v89
	v_exp_f32_e32 v88, v88
	v_exp_f32_e32 v89, v89
	v_pk_mul_f32 v[92:93], v[92:93], v[96:97]
	v_lshlrev_b64 v[100:101], 12, v[196:197]
	v_cvt_pk_f16_f32 v96, v92, v93
	v_add_f32_e32 v92, v95, v51
	v_mul_f32_e32 v92, 0xbfb8aa3b, v92
	v_exp_f32_e32 v92, v92
	v_cvt_f32_f16_sdwa v93, v123 dst_sel:DWORD dst_unused:UNUSED_PAD src0_sel:WORD_1
	v_add_f32_e32 v84, v84, v32
	v_add_f32_e32 v85, v85, v33
	v_add_f32_e32 v92, 1.0, v92
	v_rcp_f32_e32 v95, v92
	v_cvt_f32_f16_e32 v92, v123
	v_add_f32_e32 v88, 1.0, v88
	v_mul_f32_e32 v84, 0xbfb8aa3b, v84
	v_add_f32_e32 v89, 1.0, v89
	v_pk_mul_f32 v[92:93], v[94:95], v[92:93]
	v_mul_f32_e32 v85, 0xbfb8aa3b, v85
	v_cvt_pk_f16_f32 v92, v92, v93
	v_lshrrev_b32_e32 v93, 4, v102
	v_and_b32_e32 v93, 0x10001, v93
	v_add3_u32 v93, v102, v93, s21
	v_and_b32_e32 v94, 0xfff0fff0, v93
	v_lshrrev_b32_e32 v93, 4, v96
	v_and_b32_e32 v93, 0x10001, v93
	v_add3_u32 v93, v96, v93, s21
	v_and_b32_e32 v95, 0xfff0fff0, v93
	v_lshrrev_b32_e32 v93, 4, v103
	v_and_b32_e32 v93, 0x10001, v93
	v_add3_u32 v93, v103, v93, s21
	v_and_b32_e32 v96, 0xfff0fff0, v93
	v_lshrrev_b32_e32 v93, 4, v92
	v_and_b32_e32 v93, 0x10001, v93
	v_add3_u32 v92, v92, v93, s21
	v_and_b32_e32 v97, 0xfff0fff0, v92
	v_lshl_add_u64 v[92:93], s[10:11], 0, v[100:101]
	v_lshl_add_u64 v[92:93], v[92:93], 0, v[190:191]
	global_store_dwordx4 v[92:93], v[94:97], off
	v_rcp_f32_e32 v88, v88
	v_exp_f32_e32 v84, v84
	v_rcp_f32_e32 v89, v89
	v_cvt_f32_f16_e32 v94, v108
	v_cvt_f32_f16_sdwa v95, v108 dst_sel:DWORD dst_unused:UNUSED_PAD src0_sel:WORD_1
	v_exp_f32_e32 v85, v85
	v_add_f32_e32 v84, 1.0, v84
	v_rcp_f32_e32 v84, v84
	v_pk_mul_f32 v[88:89], v[88:89], v[94:95]
	v_add_f32_e32 v85, 1.0, v85
	v_cvt_pk_f16_f32 v94, v88, v89
	v_rcp_f32_e32 v85, v85
	v_cvt_f32_f16_e32 v88, v110
	v_cvt_f32_f16_sdwa v89, v110 dst_sel:DWORD dst_unused:UNUSED_PAD src0_sel:WORD_1
	v_add_u32_e32 v118, 0x80, v194
	v_ashrrev_i32_e32 v119, 31, v118
	v_add_u32_e32 v116, 0x90, v194
	v_pk_mul_f32 v[84:85], v[84:85], v[88:89]
	v_cvt_f32_f16_e32 v88, v109
	v_cvt_pk_f16_f32 v95, v84, v85
	v_add_f32_e32 v85, v86, v34
	v_mul_f32_e32 v85, 0xbfb8aa3b, v85
	v_exp_f32_e32 v85, v85
	v_add_f32_e32 v84, v90, v42
	v_mul_f32_e32 v84, 0xbfb8aa3b, v84
	v_exp_f32_e32 v84, v84
	v_add_f32_e32 v85, 1.0, v85
	v_rcp_f32_e32 v86, v85
	v_add_f32_e32 v85, v91, v43
	v_mul_f32_e32 v85, 0xbfb8aa3b, v85
	v_exp_f32_e32 v85, v85
	v_add_f32_e32 v84, 1.0, v84
	v_rcp_f32_e32 v84, v84
	v_cvt_f32_f16_sdwa v89, v109 dst_sel:DWORD dst_unused:UNUSED_PAD src0_sel:WORD_1
	v_add_f32_e32 v85, 1.0, v85
	v_rcp_f32_e32 v85, v85
	v_ashrrev_i32_e32 v117, 31, v116
	v_add_u32_e32 v114, 0xa0, v194
	v_ashrrev_i32_e32 v115, 31, v114
	v_pk_mul_f32 v[84:85], v[84:85], v[88:89]
	v_add_u32_e32 v112, 0xb0, v194
	v_cvt_pk_f16_f32 v88, v84, v85
	v_add_f32_e32 v84, v87, v35
	v_mul_f32_e32 v84, 0xbfb8aa3b, v84
	v_exp_f32_e32 v84, v84
	v_cvt_f32_f16_sdwa v85, v111 dst_sel:DWORD dst_unused:UNUSED_PAD src0_sel:WORD_1
	v_ashrrev_i32_e32 v113, 31, v112
	v_add_f32_e32 v80, v80, v56
	v_add_f32_e32 v84, 1.0, v84
	v_rcp_f32_e32 v87, v84
	v_cvt_f32_f16_e32 v84, v111
	v_add_f32_e32 v81, v81, v57
	v_mul_f32_e32 v80, 0xbfb8aa3b, v80
	v_mul_f32_e32 v81, 0xbfb8aa3b, v81
	v_pk_mul_f32 v[84:85], v[86:87], v[84:85]
	v_lshrrev_b32_e32 v86, 4, v95
	v_cvt_pk_f16_f32 v87, v84, v85
	v_lshrrev_b32_e32 v85, 4, v88
	v_and_b32_e32 v85, 0x10001, v85
	v_lshrrev_b32_e32 v84, 4, v94
	v_add3_u32 v85, v88, v85, s21
	v_lshrrev_b32_e32 v88, 4, v87
	v_and_b32_e32 v84, 0x10001, v84
	v_and_b32_e32 v86, 0x10001, v86
	v_and_b32_e32 v88, 0x10001, v88
	v_add3_u32 v84, v94, v84, s21
	v_add3_u32 v86, v95, v86, s21
	v_add3_u32 v87, v87, v88, s21
	v_and_b32_e32 v84, 0xfff0fff0, v84
	v_and_b32_e32 v85, 0xfff0fff0, v85
	v_and_b32_e32 v86, 0xfff0fff0, v86
	v_and_b32_e32 v87, 0xfff0fff0, v87
	global_store_dwordx4 v[92:93], v[84:87], off offset:256
	v_exp_f32_e32 v80, v80
	v_exp_f32_e32 v81, v81
	v_lshlrev_b64 v[84:85], 10, v[118:119]
	v_lshl_add_u64 v[120:121], v[192:193], 0, v[84:85]
	v_lshlrev_b64 v[84:85], 10, v[116:117]
	v_lshl_add_u64 v[104:105], v[192:193], 0, v[84:85]
	v_lshlrev_b64 v[84:85], 10, v[114:115]
	v_lshl_add_u64 v[96:97], v[192:193], 0, v[84:85]
	v_lshlrev_b64 v[84:85], 10, v[112:113]
	v_lshl_add_u64 v[88:89], v[192:193], 0, v[84:85]
	global_load_dwordx4 v[84:87], v[88:89], off offset:256
	s_nop 0
	global_load_dwordx4 v[88:91], v[88:89], off
	s_nop 0
	global_load_dwordx4 v[92:95], v[96:97], off offset:256
	s_nop 0
	global_load_dwordx4 v[96:99], v[96:97], off
	s_nop 0
	global_load_dwordx4 v[100:103], v[104:105], off offset:256
	s_nop 0
	global_load_dwordx4 v[104:107], v[104:105], off
	s_nop 0
	global_load_dwordx4 v[108:111], v[120:121], off offset:256
	s_nop 0
	global_load_dwordx4 v[120:123], v[120:121], off
	v_add_f32_e32 v76, v76, v48
	v_add_f32_e32 v77, v77, v49
	v_add_f32_e32 v80, 1.0, v80
	v_mul_f32_e32 v76, 0xbfb8aa3b, v76
	v_add_f32_e32 v81, 1.0, v81
	v_mul_f32_e32 v77, 0xbfb8aa3b, v77
	s_waitcnt vmcnt(0)
	v_rcp_f32_e32 v80, v80
	v_exp_f32_e32 v76, v76
	v_rcp_f32_e32 v81, v81
	v_cvt_f32_f16_e32 v124, v120
	v_cvt_f32_f16_sdwa v125, v120 dst_sel:DWORD dst_unused:UNUSED_PAD src0_sel:WORD_1
	v_exp_f32_e32 v77, v77
	v_add_f32_e32 v76, 1.0, v76
	v_rcp_f32_e32 v76, v76
	v_pk_mul_f32 v[80:81], v[80:81], v[124:125]
	v_add_f32_e32 v77, 1.0, v77
	v_cvt_pk_f16_f32 v120, v80, v81
	v_rcp_f32_e32 v77, v77
	v_cvt_f32_f16_e32 v80, v122
	v_cvt_f32_f16_sdwa v81, v122 dst_sel:DWORD dst_unused:UNUSED_PAD src0_sel:WORD_1
	v_add_f32_e32 v72, v72, v40
	v_add_f32_e32 v73, v73, v41
	v_mul_f32_e32 v72, 0xbfb8aa3b, v72
	v_pk_mul_f32 v[76:77], v[76:77], v[80:81]
	v_cvt_f32_f16_e32 v80, v121
	v_cvt_pk_f16_f32 v122, v76, v77
	v_add_f32_e32 v77, v78, v50
	v_mul_f32_e32 v77, 0xbfb8aa3b, v77
	v_exp_f32_e32 v77, v77
	v_add_f32_e32 v76, v82, v58
	v_mul_f32_e32 v76, 0xbfb8aa3b, v76
	v_exp_f32_e32 v76, v76
	v_add_f32_e32 v77, 1.0, v77
	v_rcp_f32_e32 v78, v77
	v_add_f32_e32 v77, v83, v59
	v_mul_f32_e32 v77, 0xbfb8aa3b, v77
	v_exp_f32_e32 v77, v77
	v_add_f32_e32 v76, 1.0, v76
	v_rcp_f32_e32 v76, v76
	v_cvt_f32_f16_sdwa v81, v121 dst_sel:DWORD dst_unused:UNUSED_PAD src0_sel:WORD_1
	v_add_f32_e32 v77, 1.0, v77
	v_rcp_f32_e32 v77, v77
	v_mul_f32_e32 v73, 0xbfb8aa3b, v73
	v_exp_f32_e32 v72, v72
	v_exp_f32_e32 v73, v73
	v_pk_mul_f32 v[76:77], v[76:77], v[80:81]
	v_lshlrev_b64 v[118:119], 12, v[118:119]
	v_cvt_pk_f16_f32 v80, v76, v77
	v_add_f32_e32 v76, v79, v51
	v_mul_f32_e32 v76, 0xbfb8aa3b, v76
	v_exp_f32_e32 v76, v76
	v_cvt_f32_f16_sdwa v77, v123 dst_sel:DWORD dst_unused:UNUSED_PAD src0_sel:WORD_1
	v_add_f32_e32 v68, v68, v32
	v_add_f32_e32 v69, v69, v33
	v_add_f32_e32 v76, 1.0, v76
	v_rcp_f32_e32 v79, v76
	v_cvt_f32_f16_e32 v76, v123
	v_add_f32_e32 v72, 1.0, v72
	v_mul_f32_e32 v68, 0xbfb8aa3b, v68
	v_add_f32_e32 v73, 1.0, v73
	v_pk_mul_f32 v[76:77], v[78:79], v[76:77]
	v_mul_f32_e32 v69, 0xbfb8aa3b, v69
	v_cvt_pk_f16_f32 v76, v76, v77
	v_lshrrev_b32_e32 v77, 4, v120
	v_and_b32_e32 v77, 0x10001, v77
	v_add3_u32 v77, v120, v77, s21
	v_and_b32_e32 v78, 0xfff0fff0, v77
	v_lshrrev_b32_e32 v77, 4, v80
	v_and_b32_e32 v77, 0x10001, v77
	v_add3_u32 v77, v80, v77, s21
	v_and_b32_e32 v79, 0xfff0fff0, v77
	v_lshrrev_b32_e32 v77, 4, v122
	v_and_b32_e32 v77, 0x10001, v77
	v_add3_u32 v77, v122, v77, s21
	v_and_b32_e32 v80, 0xfff0fff0, v77
	v_lshrrev_b32_e32 v77, 4, v76
	v_and_b32_e32 v77, 0x10001, v77
	v_add3_u32 v76, v76, v77, s21
	v_and_b32_e32 v81, 0xfff0fff0, v76
	v_lshl_add_u64 v[76:77], s[10:11], 0, v[118:119]
	v_lshl_add_u64 v[76:77], v[76:77], 0, v[190:191]
	global_store_dwordx4 v[76:77], v[78:81], off
	v_rcp_f32_e32 v72, v72
	v_exp_f32_e32 v68, v68
	v_rcp_f32_e32 v73, v73
	v_cvt_f32_f16_e32 v78, v108
	v_cvt_f32_f16_sdwa v79, v108 dst_sel:DWORD dst_unused:UNUSED_PAD src0_sel:WORD_1
	v_exp_f32_e32 v69, v69
	v_add_f32_e32 v68, 1.0, v68
	v_rcp_f32_e32 v68, v68
	v_pk_mul_f32 v[72:73], v[72:73], v[78:79]
	v_add_f32_e32 v69, 1.0, v69
	v_cvt_pk_f16_f32 v78, v72, v73
	v_rcp_f32_e32 v69, v69
	v_cvt_f32_f16_e32 v72, v110
	v_cvt_f32_f16_sdwa v73, v110 dst_sel:DWORD dst_unused:UNUSED_PAD src0_sel:WORD_1
	v_add_f32_e32 v64, v64, v56
	v_add_f32_e32 v65, v65, v57
	v_mul_f32_e32 v64, 0xbfb8aa3b, v64
	v_pk_mul_f32 v[68:69], v[68:69], v[72:73]
	v_cvt_f32_f16_e32 v72, v109
	v_cvt_pk_f16_f32 v79, v68, v69
	v_add_f32_e32 v69, v70, v34
	v_mul_f32_e32 v69, 0xbfb8aa3b, v69
	v_exp_f32_e32 v69, v69
	v_add_f32_e32 v68, v74, v42
	v_mul_f32_e32 v68, 0xbfb8aa3b, v68
	v_exp_f32_e32 v68, v68
	v_add_f32_e32 v69, 1.0, v69
	v_rcp_f32_e32 v70, v69
	v_add_f32_e32 v69, v75, v43
	v_mul_f32_e32 v69, 0xbfb8aa3b, v69
	v_exp_f32_e32 v69, v69
	v_add_f32_e32 v68, 1.0, v68
	v_rcp_f32_e32 v68, v68
	v_cvt_f32_f16_sdwa v73, v109 dst_sel:DWORD dst_unused:UNUSED_PAD src0_sel:WORD_1
	v_add_f32_e32 v69, 1.0, v69
	v_rcp_f32_e32 v69, v69
	v_mul_f32_e32 v65, 0xbfb8aa3b, v65
	v_exp_f32_e32 v64, v64
	v_exp_f32_e32 v65, v65
	v_pk_mul_f32 v[68:69], v[68:69], v[72:73]
	v_add_f32_e32 v60, v60, v48
	v_cvt_pk_f16_f32 v72, v68, v69
	v_add_f32_e32 v68, v71, v35
	v_mul_f32_e32 v68, 0xbfb8aa3b, v68
	v_exp_f32_e32 v68, v68
	v_cvt_f32_f16_sdwa v69, v111 dst_sel:DWORD dst_unused:UNUSED_PAD src0_sel:WORD_1
	v_add_f32_e32 v61, v61, v49
	v_add_f32_e32 v64, 1.0, v64
	v_add_f32_e32 v68, 1.0, v68
	v_rcp_f32_e32 v71, v68
	v_cvt_f32_f16_e32 v68, v111
	v_mul_f32_e32 v60, 0xbfb8aa3b, v60
	v_add_f32_e32 v65, 1.0, v65
	v_mul_f32_e32 v61, 0xbfb8aa3b, v61
	v_pk_mul_f32 v[68:69], v[70:71], v[68:69]
	v_lshrrev_b32_e32 v70, 4, v79
	v_cvt_pk_f16_f32 v71, v68, v69
	v_lshrrev_b32_e32 v69, 4, v72
	v_and_b32_e32 v69, 0x10001, v69
	v_lshrrev_b32_e32 v68, 4, v78
	v_add3_u32 v69, v72, v69, s21
	v_lshrrev_b32_e32 v72, 4, v71
	v_and_b32_e32 v68, 0x10001, v68
	v_and_b32_e32 v70, 0x10001, v70
	v_and_b32_e32 v72, 0x10001, v72
	v_add3_u32 v68, v78, v68, s21
	v_add3_u32 v70, v79, v70, s21
	v_add3_u32 v71, v71, v72, s21
	v_and_b32_e32 v68, 0xfff0fff0, v68
	v_and_b32_e32 v69, 0xfff0fff0, v69
	v_and_b32_e32 v70, 0xfff0fff0, v70
	v_and_b32_e32 v71, 0xfff0fff0, v71
	global_store_dwordx4 v[76:77], v[68:71], off offset:256
	v_rcp_f32_e32 v64, v64
	v_exp_f32_e32 v60, v60
	v_rcp_f32_e32 v65, v65
	v_cvt_f32_f16_e32 v70, v104
	v_cvt_f32_f16_sdwa v71, v104 dst_sel:DWORD dst_unused:UNUSED_PAD src0_sel:WORD_1
	v_exp_f32_e32 v61, v61
	v_add_f32_e32 v60, 1.0, v60
	v_rcp_f32_e32 v60, v60
	v_pk_mul_f32 v[64:65], v[64:65], v[70:71]
	v_add_f32_e32 v61, 1.0, v61
	v_cvt_pk_f16_f32 v70, v64, v65
	v_rcp_f32_e32 v61, v61
	v_cvt_f32_f16_e32 v64, v106
	v_cvt_f32_f16_sdwa v65, v106 dst_sel:DWORD dst_unused:UNUSED_PAD src0_sel:WORD_1
	v_add_f32_e32 v52, v52, v40
	v_add_f32_e32 v53, v53, v41
	v_mul_f32_e32 v52, 0xbfb8aa3b, v52
	v_pk_mul_f32 v[60:61], v[60:61], v[64:65]
	v_cvt_f32_f16_e32 v64, v105
	v_cvt_pk_f16_f32 v71, v60, v61
	v_add_f32_e32 v61, v62, v50
	v_mul_f32_e32 v61, 0xbfb8aa3b, v61
	v_exp_f32_e32 v61, v61
	v_add_f32_e32 v60, v66, v58
	v_mul_f32_e32 v60, 0xbfb8aa3b, v60
	v_exp_f32_e32 v60, v60
	v_add_f32_e32 v61, 1.0, v61
	v_rcp_f32_e32 v62, v61
	v_add_f32_e32 v61, v67, v59
	v_mul_f32_e32 v61, 0xbfb8aa3b, v61
	v_exp_f32_e32 v61, v61
	v_add_f32_e32 v60, 1.0, v60
	v_rcp_f32_e32 v60, v60
	v_cvt_f32_f16_sdwa v65, v105 dst_sel:DWORD dst_unused:UNUSED_PAD src0_sel:WORD_1
	v_add_f32_e32 v61, 1.0, v61
	v_rcp_f32_e32 v61, v61
	v_mul_f32_e32 v53, 0xbfb8aa3b, v53
	v_exp_f32_e32 v52, v52
	v_exp_f32_e32 v53, v53
	v_pk_mul_f32 v[60:61], v[60:61], v[64:65]
	v_lshlrev_b64 v[68:69], 12, v[116:117]
	v_cvt_pk_f16_f32 v64, v60, v61
	v_add_f32_e32 v60, v63, v51
	v_mul_f32_e32 v60, 0xbfb8aa3b, v60
	v_exp_f32_e32 v60, v60
	v_cvt_f32_f16_sdwa v61, v107 dst_sel:DWORD dst_unused:UNUSED_PAD src0_sel:WORD_1
	v_add_f32_e32 v44, v44, v32
	v_add_f32_e32 v45, v45, v33
	v_add_f32_e32 v60, 1.0, v60
	v_rcp_f32_e32 v63, v60
	v_cvt_f32_f16_e32 v60, v107
	v_add_f32_e32 v52, 1.0, v52
	v_mul_f32_e32 v44, 0xbfb8aa3b, v44
	v_add_f32_e32 v53, 1.0, v53
	v_pk_mul_f32 v[60:61], v[62:63], v[60:61]
	v_mul_f32_e32 v45, 0xbfb8aa3b, v45
	v_cvt_pk_f16_f32 v60, v60, v61
	v_lshrrev_b32_e32 v61, 4, v70
	v_and_b32_e32 v61, 0x10001, v61
	v_add3_u32 v61, v70, v61, s21
	v_and_b32_e32 v62, 0xfff0fff0, v61
	v_lshrrev_b32_e32 v61, 4, v64
	v_and_b32_e32 v61, 0x10001, v61
	v_add3_u32 v61, v64, v61, s21
	v_and_b32_e32 v63, 0xfff0fff0, v61
	v_lshrrev_b32_e32 v61, 4, v71
	v_and_b32_e32 v61, 0x10001, v61
	v_add3_u32 v61, v71, v61, s21
	v_and_b32_e32 v64, 0xfff0fff0, v61
	v_lshrrev_b32_e32 v61, 4, v60
	v_and_b32_e32 v61, 0x10001, v61
	v_add3_u32 v60, v60, v61, s21
	v_and_b32_e32 v65, 0xfff0fff0, v60
	v_lshl_add_u64 v[60:61], s[10:11], 0, v[68:69]
	v_lshl_add_u64 v[60:61], v[60:61], 0, v[190:191]
	global_store_dwordx4 v[60:61], v[62:65], off
	v_rcp_f32_e32 v52, v52
	v_exp_f32_e32 v44, v44
	v_rcp_f32_e32 v53, v53
	v_cvt_f32_f16_e32 v62, v100
	v_cvt_f32_f16_sdwa v63, v100 dst_sel:DWORD dst_unused:UNUSED_PAD src0_sel:WORD_1
	v_exp_f32_e32 v45, v45
	v_add_f32_e32 v44, 1.0, v44
	v_rcp_f32_e32 v44, v44
	v_pk_mul_f32 v[52:53], v[52:53], v[62:63]
	v_add_f32_e32 v45, 1.0, v45
	v_cvt_pk_f16_f32 v62, v52, v53
	v_rcp_f32_e32 v45, v45
	v_cvt_f32_f16_e32 v52, v102
	v_cvt_f32_f16_sdwa v53, v102 dst_sel:DWORD dst_unused:UNUSED_PAD src0_sel:WORD_1
	v_add_f32_e32 v36, v36, v56
	v_add_f32_e32 v37, v37, v57
	v_mul_f32_e32 v36, 0xbfb8aa3b, v36
	v_pk_mul_f32 v[44:45], v[44:45], v[52:53]
	v_cvt_f32_f16_e32 v52, v101
	v_cvt_pk_f16_f32 v63, v44, v45
	v_add_f32_e32 v45, v46, v34
	v_mul_f32_e32 v45, 0xbfb8aa3b, v45
	v_exp_f32_e32 v45, v45
	v_add_f32_e32 v44, v54, v42
	v_mul_f32_e32 v44, 0xbfb8aa3b, v44
	v_exp_f32_e32 v44, v44
	v_add_f32_e32 v45, 1.0, v45
	v_rcp_f32_e32 v46, v45
	v_add_f32_e32 v45, v55, v43
	v_mul_f32_e32 v45, 0xbfb8aa3b, v45
	v_exp_f32_e32 v45, v45
	v_add_f32_e32 v44, 1.0, v44
	v_rcp_f32_e32 v44, v44
	v_cvt_f32_f16_sdwa v53, v101 dst_sel:DWORD dst_unused:UNUSED_PAD src0_sel:WORD_1
	v_add_f32_e32 v45, 1.0, v45
	v_rcp_f32_e32 v45, v45
	v_mul_f32_e32 v37, 0xbfb8aa3b, v37
	v_exp_f32_e32 v36, v36
	v_exp_f32_e32 v37, v37
	v_pk_mul_f32 v[44:45], v[44:45], v[52:53]
	v_add_f32_e32 v28, v28, v48
	v_cvt_pk_f16_f32 v52, v44, v45
	v_add_f32_e32 v44, v47, v35
	v_mul_f32_e32 v44, 0xbfb8aa3b, v44
	v_exp_f32_e32 v44, v44
	v_cvt_f32_f16_sdwa v45, v103 dst_sel:DWORD dst_unused:UNUSED_PAD src0_sel:WORD_1
	v_add_f32_e32 v29, v29, v49
	v_add_f32_e32 v36, 1.0, v36
	v_add_f32_e32 v44, 1.0, v44
	v_rcp_f32_e32 v47, v44
	v_cvt_f32_f16_e32 v44, v103
	v_mul_f32_e32 v28, 0xbfb8aa3b, v28
	v_add_f32_e32 v37, 1.0, v37
	v_mul_f32_e32 v29, 0xbfb8aa3b, v29
	v_pk_mul_f32 v[44:45], v[46:47], v[44:45]
	v_lshrrev_b32_e32 v46, 4, v63
	v_cvt_pk_f16_f32 v47, v44, v45
	v_lshrrev_b32_e32 v45, 4, v52
	v_and_b32_e32 v45, 0x10001, v45
	v_lshrrev_b32_e32 v44, 4, v62
	v_add3_u32 v45, v52, v45, s21
	v_lshrrev_b32_e32 v52, 4, v47
	v_and_b32_e32 v44, 0x10001, v44
	v_and_b32_e32 v46, 0x10001, v46
	v_and_b32_e32 v52, 0x10001, v52
	v_add3_u32 v44, v62, v44, s21
	v_add3_u32 v46, v63, v46, s21
	v_add3_u32 v47, v47, v52, s21
	v_and_b32_e32 v44, 0xfff0fff0, v44
	v_and_b32_e32 v45, 0xfff0fff0, v45
	v_and_b32_e32 v46, 0xfff0fff0, v46
	v_and_b32_e32 v47, 0xfff0fff0, v47
	global_store_dwordx4 v[60:61], v[44:47], off offset:256
	v_rcp_f32_e32 v36, v36
	v_exp_f32_e32 v28, v28
	v_rcp_f32_e32 v37, v37
	v_cvt_f32_f16_e32 v46, v96
	v_cvt_f32_f16_sdwa v47, v96 dst_sel:DWORD dst_unused:UNUSED_PAD src0_sel:WORD_1
	v_exp_f32_e32 v29, v29
	v_add_f32_e32 v28, 1.0, v28
	v_rcp_f32_e32 v28, v28
	v_pk_mul_f32 v[36:37], v[36:37], v[46:47]
	v_add_f32_e32 v29, 1.0, v29
	v_cvt_pk_f16_f32 v46, v36, v37
	v_rcp_f32_e32 v29, v29
	v_cvt_f32_f16_e32 v36, v98
	v_cvt_f32_f16_sdwa v37, v98 dst_sel:DWORD dst_unused:UNUSED_PAD src0_sel:WORD_1
	v_add_f32_e32 v24, v24, v40
	v_add_f32_e32 v25, v25, v41
	v_mul_f32_e32 v24, 0xbfb8aa3b, v24
	v_pk_mul_f32 v[28:29], v[28:29], v[36:37]
	v_cvt_f32_f16_e32 v36, v97
	v_cvt_pk_f16_f32 v47, v28, v29
	v_add_f32_e32 v29, v30, v50
	v_mul_f32_e32 v29, 0xbfb8aa3b, v29
	v_exp_f32_e32 v29, v29
	v_add_f32_e32 v28, v38, v58
	v_mul_f32_e32 v28, 0xbfb8aa3b, v28
	v_exp_f32_e32 v28, v28
	v_add_f32_e32 v29, 1.0, v29
	v_rcp_f32_e32 v30, v29
	v_add_f32_e32 v29, v39, v59
	v_mul_f32_e32 v29, 0xbfb8aa3b, v29
	v_exp_f32_e32 v29, v29
	v_add_f32_e32 v28, 1.0, v28
	v_rcp_f32_e32 v28, v28
	v_cvt_f32_f16_sdwa v37, v97 dst_sel:DWORD dst_unused:UNUSED_PAD src0_sel:WORD_1
	v_add_f32_e32 v29, 1.0, v29
	v_rcp_f32_e32 v29, v29
	v_mul_f32_e32 v25, 0xbfb8aa3b, v25
	v_exp_f32_e32 v24, v24
	v_exp_f32_e32 v25, v25
	v_pk_mul_f32 v[28:29], v[28:29], v[36:37]
	v_add_f32_e32 v20, v20, v32
	v_cvt_pk_f16_f32 v37, v28, v29
	v_add_f32_e32 v28, v31, v51
	v_mul_f32_e32 v28, 0xbfb8aa3b, v28
	v_exp_f32_e32 v28, v28
	v_cvt_f32_f16_sdwa v29, v99 dst_sel:DWORD dst_unused:UNUSED_PAD src0_sel:WORD_1
	v_add_f32_e32 v21, v21, v33
	v_add_f32_e32 v24, 1.0, v24
	v_add_f32_e32 v28, 1.0, v28
	v_rcp_f32_e32 v31, v28
	v_cvt_f32_f16_e32 v28, v99
	v_mul_f32_e32 v20, 0xbfb8aa3b, v20
	v_add_f32_e32 v25, 1.0, v25
	v_mul_f32_e32 v21, 0xbfb8aa3b, v21
	v_pk_mul_f32 v[28:29], v[30:31], v[28:29]
	v_rcp_f32_e32 v24, v24
	v_exp_f32_e32 v20, v20
	v_rcp_f32_e32 v25, v25
	v_cvt_f32_f16_e32 v30, v92
	v_cvt_f32_f16_sdwa v31, v92 dst_sel:DWORD dst_unused:UNUSED_PAD src0_sel:WORD_1
	v_exp_f32_e32 v21, v21
	v_add_f32_e32 v20, 1.0, v20
	v_rcp_f32_e32 v20, v20
	v_pk_mul_f32 v[24:25], v[24:25], v[30:31]
	v_add_f32_e32 v21, 1.0, v21
	v_cvt_pk_f16_f32 v30, v24, v25
	v_rcp_f32_e32 v21, v21
	v_cvt_f32_f16_e32 v24, v94
	v_cvt_f32_f16_sdwa v25, v94 dst_sel:DWORD dst_unused:UNUSED_PAD src0_sel:WORD_1
	v_cvt_pk_f16_f32 v28, v28, v29
	v_lshrrev_b32_e32 v29, 4, v46
	v_and_b32_e32 v29, 0x10001, v29
	v_pk_mul_f32 v[20:21], v[20:21], v[24:25]
	v_cvt_f32_f16_e32 v24, v93
	v_cvt_pk_f16_f32 v31, v20, v21
	v_add_f32_e32 v21, v22, v34
	v_mul_f32_e32 v21, 0xbfb8aa3b, v21
	v_exp_f32_e32 v21, v21
	v_add_f32_e32 v20, v26, v42
	v_mul_f32_e32 v20, 0xbfb8aa3b, v20
	v_exp_f32_e32 v20, v20
	v_add_f32_e32 v21, 1.0, v21
	v_rcp_f32_e32 v22, v21
	v_add_f32_e32 v21, v27, v43
	v_mul_f32_e32 v21, 0xbfb8aa3b, v21
	v_exp_f32_e32 v21, v21
	v_add_f32_e32 v20, 1.0, v20
	v_rcp_f32_e32 v20, v20
	v_cvt_f32_f16_sdwa v25, v93 dst_sel:DWORD dst_unused:UNUSED_PAD src0_sel:WORD_1
	v_add_f32_e32 v21, 1.0, v21
	v_rcp_f32_e32 v21, v21
	v_add3_u32 v29, v46, v29, s21
	v_and_b32_e32 v36, 0xfff0fff0, v29
	v_lshrrev_b32_e32 v29, 4, v37
	v_pk_mul_f32 v[20:21], v[20:21], v[24:25]
	v_and_b32_e32 v29, 0x10001, v29
	v_cvt_pk_f16_f32 v24, v20, v21
	v_add_f32_e32 v20, v23, v35
	v_mul_f32_e32 v20, 0xbfb8aa3b, v20
	v_exp_f32_e32 v20, v20
	v_cvt_f32_f16_sdwa v21, v95 dst_sel:DWORD dst_unused:UNUSED_PAD src0_sel:WORD_1
	v_add3_u32 v29, v37, v29, s21
	v_and_b32_e32 v37, 0xfff0fff0, v29
	v_add_f32_e32 v20, 1.0, v20
	v_rcp_f32_e32 v23, v20
	v_cvt_f32_f16_e32 v20, v95
	v_lshrrev_b32_e32 v29, 4, v47
	v_and_b32_e32 v29, 0x10001, v29
	v_add_f32_e32 v16, v16, v56
	v_pk_mul_f32 v[20:21], v[22:23], v[20:21]
	v_add_f32_e32 v17, v17, v57
	v_add3_u32 v29, v47, v29, s21
	v_cvt_pk_f16_f32 v23, v20, v21
	v_lshrrev_b32_e32 v21, 4, v24
	v_mul_f32_e32 v16, 0xbfb8aa3b, v16
	v_mul_f32_e32 v17, 0xbfb8aa3b, v17
	v_and_b32_e32 v38, 0xfff0fff0, v29
	v_lshrrev_b32_e32 v29, 4, v28
	v_and_b32_e32 v21, 0x10001, v21
	v_exp_f32_e32 v16, v16
	v_exp_f32_e32 v17, v17
	v_and_b32_e32 v29, 0x10001, v29
	v_lshrrev_b32_e32 v20, 4, v30
	v_add3_u32 v21, v24, v21, s21
	v_lshrrev_b32_e32 v22, 4, v31
	v_lshrrev_b32_e32 v24, 4, v23
	v_lshlrev_b64 v[44:45], 12, v[114:115]
	v_add3_u32 v28, v28, v29, s21
	v_and_b32_e32 v20, 0x10001, v20
	v_and_b32_e32 v22, 0x10001, v22
	v_and_b32_e32 v24, 0x10001, v24
	v_and_b32_e32 v39, 0xfff0fff0, v28
	v_lshl_add_u64 v[28:29], s[10:11], 0, v[44:45]
	v_add3_u32 v20, v30, v20, s21
	v_add3_u32 v22, v31, v22, s21
	v_add3_u32 v23, v23, v24, s21
	v_add_f32_e32 v12, v12, v48
	v_add_f32_e32 v13, v13, v49
	v_lshl_add_u64 v[28:29], v[28:29], 0, v[190:191]
	v_and_b32_e32 v20, 0xfff0fff0, v20
	v_and_b32_e32 v21, 0xfff0fff0, v21
	v_and_b32_e32 v22, 0xfff0fff0, v22
	v_and_b32_e32 v23, 0xfff0fff0, v23
	v_add_f32_e32 v16, 1.0, v16
	v_mul_f32_e32 v12, 0xbfb8aa3b, v12
	v_add_f32_e32 v17, 1.0, v17
	v_mul_f32_e32 v13, 0xbfb8aa3b, v13
	global_store_dwordx4 v[28:29], v[20:23], off offset:256
	v_rcp_f32_e32 v16, v16
	v_exp_f32_e32 v12, v12
	v_rcp_f32_e32 v17, v17
	v_cvt_f32_f16_e32 v22, v88
	v_cvt_f32_f16_sdwa v23, v88 dst_sel:DWORD dst_unused:UNUSED_PAD src0_sel:WORD_1
	v_exp_f32_e32 v13, v13
	v_add_f32_e32 v12, 1.0, v12
	v_rcp_f32_e32 v12, v12
	v_pk_mul_f32 v[16:17], v[16:17], v[22:23]
	v_add_f32_e32 v13, 1.0, v13
	v_cvt_pk_f16_f32 v22, v16, v17
	v_rcp_f32_e32 v13, v13
	v_cvt_f32_f16_e32 v16, v90
	v_cvt_f32_f16_sdwa v17, v90 dst_sel:DWORD dst_unused:UNUSED_PAD src0_sel:WORD_1
	v_add_f32_e32 v8, v8, v40
	v_add_f32_e32 v9, v9, v41
	v_mul_f32_e32 v8, 0xbfb8aa3b, v8
	v_pk_mul_f32 v[12:13], v[12:13], v[16:17]
	v_cvt_f32_f16_e32 v16, v89
	v_cvt_pk_f16_f32 v23, v12, v13
	v_add_f32_e32 v13, v14, v50
	v_mul_f32_e32 v13, 0xbfb8aa3b, v13
	v_exp_f32_e32 v13, v13
	v_add_f32_e32 v12, v18, v58
	v_mul_f32_e32 v12, 0xbfb8aa3b, v12
	v_exp_f32_e32 v12, v12
	v_add_f32_e32 v13, 1.0, v13
	v_rcp_f32_e32 v14, v13
	v_add_f32_e32 v13, v19, v59
	v_mul_f32_e32 v13, 0xbfb8aa3b, v13
	v_exp_f32_e32 v13, v13
	v_add_f32_e32 v12, 1.0, v12
	v_rcp_f32_e32 v12, v12
	v_cvt_f32_f16_sdwa v17, v89 dst_sel:DWORD dst_unused:UNUSED_PAD src0_sel:WORD_1
	v_add_f32_e32 v13, 1.0, v13
	v_rcp_f32_e32 v13, v13
	v_mul_f32_e32 v9, 0xbfb8aa3b, v9
	v_exp_f32_e32 v8, v8
	v_exp_f32_e32 v9, v9
	v_pk_mul_f32 v[12:13], v[12:13], v[16:17]
	v_lshlrev_b64 v[20:21], 12, v[112:113]
	v_cvt_pk_f16_f32 v16, v12, v13
	v_add_f32_e32 v12, v15, v51
	v_mul_f32_e32 v12, 0xbfb8aa3b, v12
	v_exp_f32_e32 v12, v12
	v_cvt_f32_f16_sdwa v13, v91 dst_sel:DWORD dst_unused:UNUSED_PAD src0_sel:WORD_1
	v_add_f32_e32 v4, v4, v32
	v_add_f32_e32 v5, v5, v33
	v_add_f32_e32 v12, 1.0, v12
	v_rcp_f32_e32 v15, v12
	v_cvt_f32_f16_e32 v12, v91
	v_add_f32_e32 v8, 1.0, v8
	v_mul_f32_e32 v4, 0xbfb8aa3b, v4
	v_add_f32_e32 v9, 1.0, v9
	v_pk_mul_f32 v[12:13], v[14:15], v[12:13]
	v_mul_f32_e32 v5, 0xbfb8aa3b, v5
	v_cvt_pk_f16_f32 v12, v12, v13
	v_lshrrev_b32_e32 v13, 4, v22
	v_and_b32_e32 v13, 0x10001, v13
	v_add3_u32 v13, v22, v13, s21
	v_and_b32_e32 v14, 0xfff0fff0, v13
	v_lshrrev_b32_e32 v13, 4, v16
	v_and_b32_e32 v13, 0x10001, v13
	v_add3_u32 v13, v16, v13, s21
	v_and_b32_e32 v15, 0xfff0fff0, v13
	v_lshrrev_b32_e32 v13, 4, v23
	v_and_b32_e32 v13, 0x10001, v13
	v_add3_u32 v13, v23, v13, s21
	v_and_b32_e32 v16, 0xfff0fff0, v13
	v_lshrrev_b32_e32 v13, 4, v12
	v_and_b32_e32 v13, 0x10001, v13
	v_add3_u32 v12, v12, v13, s21
	v_and_b32_e32 v17, 0xfff0fff0, v12
	v_lshl_add_u64 v[12:13], s[10:11], 0, v[20:21]
	v_lshl_add_u64 v[12:13], v[12:13], 0, v[190:191]
	global_store_dwordx4 v[12:13], v[14:17], off
	v_rcp_f32_e32 v8, v8
	v_exp_f32_e32 v4, v4
	v_rcp_f32_e32 v9, v9
	v_cvt_f32_f16_e32 v14, v84
	v_cvt_f32_f16_sdwa v15, v84 dst_sel:DWORD dst_unused:UNUSED_PAD src0_sel:WORD_1
	v_exp_f32_e32 v5, v5
	v_add_f32_e32 v4, 1.0, v4
	v_rcp_f32_e32 v4, v4
	v_pk_mul_f32 v[8:9], v[8:9], v[14:15]
	v_add_f32_e32 v5, 1.0, v5
	v_cvt_pk_f16_f32 v14, v8, v9
	v_rcp_f32_e32 v5, v5
	v_cvt_f32_f16_e32 v8, v86
	v_cvt_f32_f16_sdwa v9, v86 dst_sel:DWORD dst_unused:UNUSED_PAD src0_sel:WORD_1
	global_store_dwordx4 v[28:29], v[36:39], off
	v_pk_mul_f32 v[4:5], v[4:5], v[8:9]
	s_nop 0
	v_cvt_pk_f16_f32 v15, v4, v5
	v_add_f32_e32 v5, v6, v34
	v_mul_f32_e32 v5, 0xbfb8aa3b, v5
	v_exp_f32_e32 v5, v5
	v_add_f32_e32 v4, v10, v42
	v_mul_f32_e32 v4, 0xbfb8aa3b, v4
	v_exp_f32_e32 v4, v4
	v_add_f32_e32 v5, 1.0, v5
	v_rcp_f32_e32 v6, v5
	v_add_f32_e32 v5, v11, v43
	v_mul_f32_e32 v5, 0xbfb8aa3b, v5
	v_exp_f32_e32 v5, v5
	v_add_f32_e32 v4, 1.0, v4
	v_rcp_f32_e32 v4, v4
	v_cvt_f32_f16_e32 v8, v85
	v_add_f32_e32 v5, 1.0, v5
	v_rcp_f32_e32 v5, v5
	v_cvt_f32_f16_sdwa v9, v85 dst_sel:DWORD dst_unused:UNUSED_PAD src0_sel:WORD_1
	v_pk_mul_f32 v[4:5], v[4:5], v[8:9]
	s_nop 0
	v_cvt_pk_f16_f32 v8, v4, v5
	v_add_f32_e32 v4, v7, v35
	v_mul_f32_e32 v4, 0xbfb8aa3b, v4
	v_exp_f32_e32 v4, v4
	v_cvt_f32_f16_sdwa v5, v87 dst_sel:DWORD dst_unused:UNUSED_PAD src0_sel:WORD_1
	v_add_f32_e32 v4, 1.0, v4
	v_rcp_f32_e32 v7, v4
	v_cvt_f32_f16_e32 v4, v87
	v_pk_mul_f32 v[4:5], v[6:7], v[4:5]
	s_nop 0
	v_cvt_pk_f16_f32 v7, v4, v5
	v_lshrrev_b32_e32 v5, 4, v8
	v_and_b32_e32 v5, 0x10001, v5
	v_lshrrev_b32_e32 v4, 4, v14
	v_add3_u32 v5, v8, v5, s21
	v_lshrrev_b32_e32 v6, 4, v15
	v_lshrrev_b32_e32 v8, 4, v7
	v_and_b32_e32 v4, 0x10001, v4
	v_and_b32_e32 v6, 0x10001, v6
	v_and_b32_e32 v8, 0x10001, v8
	v_add3_u32 v4, v14, v4, s21
	v_add3_u32 v6, v15, v6, s21
	v_add3_u32 v7, v7, v8, s21
	v_and_b32_e32 v4, 0xfff0fff0, v4
	v_and_b32_e32 v5, 0xfff0fff0, v5
	v_and_b32_e32 v6, 0xfff0fff0, v6
	v_and_b32_e32 v7, 0xfff0fff0, v7
	global_store_dwordx4 v[12:13], v[4:7], off offset:256
	s_cbranch_vccz .LBB0_1657
	s_waitcnt vmcnt(0)
	s_cmpk_gt_u32 s4, 0xff
	s_cbranch_scc1 .LBB0_1668
	s_barrier

.LBB0_1742:
	s_add_i32 s19, 0, 0x10000
	v_add_u32_e32 v237, s19, v235
	ds_read_b128 v[134:137], v237
	ds_read_b128 v[138:141], v237 offset:1024
	ds_read_b128 v[142:145], v237 offset:2048
	ds_read_b128 v[146:149], v237 offset:3072
	v_lshl_add_u64 v[198:199], v[132:133], 0, s[16:17]
	s_add_i32 s14, s7, 0xc000
	v_lshl_add_u64 v[182:183], v[198:199], 0, s[26:27]
	s_mov_b32 m0, s14
	v_lshl_add_u64 v[242:243], v[200:201], 0, s[16:17]
	s_add_i32 s15, s7, 0xe000
	ds_read_b128 v[150:153], v236
	ds_read_b128 v[154:157], v236 offset:1024
	ds_read_b128 v[158:161], v236 offset:2048
	ds_read_b128 v[162:165], v236 offset:3072
	ds_read_b128 v[166:169], v236 offset:4096
	ds_read_b128 v[170:173], v236 offset:5120
	ds_read_b128 v[174:177], v236 offset:6144
	ds_read_b128 v[178:181], v236 offset:7168
	global_load_lds_dwordx4 v[182:183], off
	v_lshl_add_u64 v[182:183], v[242:243], 0, s[26:27]
	s_mov_b32 m0, s15
	s_nop 0
	global_load_lds_dwordx4 v[182:183], off
	s_waitcnt lgkmcnt(8)
	s_barrier
	s_waitcnt lgkmcnt(0)
	v_mfma_f32_16x16x32_f16 v[80:83], v[134:137], v[150:153], v[80:83]
	v_mfma_f32_16x16x32_f16 v[72:75], v[142:145], v[150:153], v[72:75]
	v_mfma_f32_16x16x32_f16 v[56:59], v[134:137], v[158:161], v[56:59]
	v_mfma_f32_16x16x32_f16 v[68:71], v[142:145], v[158:161], v[68:71]
	v_mfma_f32_16x16x32_f16 v[128:131], v[134:137], v[166:169], v[128:131]
	v_mfma_f32_16x16x32_f16 v[124:127], v[142:145], v[166:169], v[124:127]
	v_mfma_f32_16x16x32_f16 v[116:119], v[134:137], v[174:177], v[116:119]
	v_mfma_f32_16x16x32_f16 v[108:111], v[142:145], v[174:177], v[108:111]
	v_mfma_f32_16x16x32_f16 v[80:83], v[138:141], v[154:157], v[80:83]
	v_mfma_f32_16x16x32_f16 v[72:75], v[146:149], v[154:157], v[72:75]
	v_mfma_f32_16x16x32_f16 v[56:59], v[138:141], v[162:165], v[56:59]
	v_mfma_f32_16x16x32_f16 v[68:71], v[146:149], v[162:165], v[68:71]
	v_mfma_f32_16x16x32_f16 v[128:131], v[138:141], v[170:173], v[128:131]
	v_mfma_f32_16x16x32_f16 v[124:127], v[146:149], v[170:173], v[124:127]
	v_mfma_f32_16x16x32_f16 v[116:119], v[138:141], v[178:181], v[116:119]
	v_mfma_f32_16x16x32_f16 v[108:111], v[146:149], v[178:181], v[108:111]
	s_barrier
	s_add_i32 s63, 0, 0x14000
	v_lshl_add_u64 v[244:245], v[202:203], 0, s[16:17]
	s_add_i32 s19, s19, s5
	v_add_u32_e32 v238, s63, v235
	v_lshl_add_u64 v[240:241], v[244:245], 0, s[30:31]
	s_mov_b32 m0, s19
	v_lshl_add_u64 v[246:247], v[220:221], 0, s[16:17]
	s_add_i32 s37, s19, 0x2000
	ds_read_b128 v[182:185], v238
	ds_read_b128 v[186:189], v238 offset:1024
	ds_read_b128 v[190:193], v238 offset:2048
	ds_read_b128 v[194:197], v238 offset:3072
	global_load_lds_dwordx4 v[240:241], off
	v_lshl_add_u64 v[240:241], v[246:247], 0, s[30:31]
	s_mov_b32 m0, s37
	s_nop 0
	global_load_lds_dwordx4 v[240:241], off
	s_barrier
	s_waitcnt lgkmcnt(0)
	v_mfma_f32_16x16x32_f16 v[52:55], v[182:185], v[150:153], v[52:55]
	v_mfma_f32_16x16x32_f16 v[40:43], v[190:193], v[150:153], v[40:43]
	v_mfma_f32_16x16x32_f16 v[36:39], v[182:185], v[158:161], v[36:39]
	v_mfma_f32_16x16x32_f16 v[28:31], v[190:193], v[158:161], v[28:31]
	v_mfma_f32_16x16x32_f16 v[120:123], v[182:185], v[166:169], v[120:123]
	v_mfma_f32_16x16x32_f16 v[112:115], v[190:193], v[166:169], v[112:115]
	v_mfma_f32_16x16x32_f16 v[104:107], v[182:185], v[174:177], v[104:107]
	v_mfma_f32_16x16x32_f16 v[100:103], v[190:193], v[174:177], v[100:103]
	v_mfma_f32_16x16x32_f16 v[52:55], v[186:189], v[154:157], v[52:55]
	v_mfma_f32_16x16x32_f16 v[40:43], v[194:197], v[154:157], v[40:43]
	v_mfma_f32_16x16x32_f16 v[36:39], v[186:189], v[162:165], v[36:39]
	v_mfma_f32_16x16x32_f16 v[28:31], v[194:197], v[162:165], v[28:31]
	v_mfma_f32_16x16x32_f16 v[120:123], v[186:189], v[170:173], v[120:123]
	v_mfma_f32_16x16x32_f16 v[112:115], v[194:197], v[170:173], v[112:115]
	v_mfma_f32_16x16x32_f16 v[104:107], v[186:189], v[178:181], v[104:107]
	v_mfma_f32_16x16x32_f16 v[100:103], v[194:197], v[178:181], v[100:103]
	s_mov_b32 m0, s7
	v_lshl_add_u64 v[240:241], v[198:199], 0, s[30:31]
	s_barrier
	ds_read_b128 v[150:153], v236 offset:16384
	ds_read_b128 v[154:157], v236 offset:17408
	ds_read_b128 v[158:161], v236 offset:18432
	ds_read_b128 v[162:165], v236 offset:19456
	ds_read_b128 v[166:169], v236 offset:20480
	ds_read_b128 v[170:173], v236 offset:21504
	ds_read_b128 v[174:177], v236 offset:22528
	ds_read_b128 v[178:181], v236 offset:23552
	global_load_lds_dwordx4 v[240:241], off
	v_lshl_add_u64 v[240:241], v[242:243], 0, s[30:31]
	s_mov_b32 m0, s8
	s_nop 0
	global_load_lds_dwordx4 v[240:241], off
	s_barrier
	s_waitcnt lgkmcnt(0)
	v_mfma_f32_16x16x32_f16 v[96:99], v[134:137], v[150:153], v[96:99]
	v_mfma_f32_16x16x32_f16 v[92:95], v[142:145], v[150:153], v[92:95]
	v_mfma_f32_16x16x32_f16 v[76:79], v[134:137], v[158:161], v[76:79]
	v_mfma_f32_16x16x32_f16 v[64:67], v[142:145], v[158:161], v[64:67]
	v_mfma_f32_16x16x32_f16 v[44:47], v[134:137], v[166:169], v[44:47]
	v_mfma_f32_16x16x32_f16 v[32:35], v[142:145], v[166:169], v[32:35]
	v_mfma_f32_16x16x32_f16 v[16:19], v[134:137], v[174:177], v[16:19]
	v_mfma_f32_16x16x32_f16 v[12:15], v[142:145], v[174:177], v[12:15]
	v_mfma_f32_16x16x32_f16 v[96:99], v[138:141], v[154:157], v[96:99]
	v_mfma_f32_16x16x32_f16 v[92:95], v[146:149], v[154:157], v[92:95]
	v_mfma_f32_16x16x32_f16 v[76:79], v[138:141], v[162:165], v[76:79]
	v_mfma_f32_16x16x32_f16 v[64:67], v[146:149], v[162:165], v[64:67]
	v_mfma_f32_16x16x32_f16 v[44:47], v[138:141], v[170:173], v[44:47]
	v_mfma_f32_16x16x32_f16 v[32:35], v[146:149], v[170:173], v[32:35]
	v_mfma_f32_16x16x32_f16 v[16:19], v[138:141], v[178:181], v[16:19]
	v_mfma_f32_16x16x32_f16 v[12:15], v[146:149], v[178:181], v[12:15]
	s_barrier
	s_add_i32 s63, s63, s5
	v_lshl_add_u64 v[134:135], v[244:245], 0, s[84:85]
	s_mov_b32 m0, s63
	s_add_i32 s68, s63, 0x2000
	global_load_lds_dwordx4 v[134:135], off
	v_lshl_add_u64 v[134:135], v[246:247], 0, s[84:85]
	s_mov_b32 m0, s68
	s_nop 0
	global_load_lds_dwordx4 v[134:135], off
	s_waitcnt vmcnt(6)
	s_barrier
	v_mfma_f32_16x16x32_f16 v[88:91], v[182:185], v[150:153], v[88:91]
	v_mfma_f32_16x16x32_f16 v[84:87], v[190:193], v[150:153], v[84:87]
	v_mfma_f32_16x16x32_f16 v[60:63], v[182:185], v[158:161], v[60:63]
	v_mfma_f32_16x16x32_f16 v[48:51], v[190:193], v[158:161], v[48:51]
	v_mfma_f32_16x16x32_f16 v[24:27], v[182:185], v[166:169], v[24:27]
	v_mfma_f32_16x16x32_f16 v[20:23], v[190:193], v[166:169], v[20:23]
	v_mfma_f32_16x16x32_f16 v[8:11], v[182:185], v[174:177], v[8:11]
	v_mfma_f32_16x16x32_f16 v[4:7], v[190:193], v[174:177], v[4:7]
	v_mfma_f32_16x16x32_f16 v[88:91], v[186:189], v[154:157], v[88:91]
	v_mfma_f32_16x16x32_f16 v[84:87], v[194:197], v[154:157], v[84:87]
	v_mfma_f32_16x16x32_f16 v[60:63], v[186:189], v[162:165], v[60:63]
	v_mfma_f32_16x16x32_f16 v[48:51], v[194:197], v[162:165], v[48:51]
	v_mfma_f32_16x16x32_f16 v[24:27], v[186:189], v[170:173], v[24:27]
	v_mfma_f32_16x16x32_f16 v[20:23], v[194:197], v[170:173], v[20:23]
	v_mfma_f32_16x16x32_f16 v[8:11], v[186:189], v[178:181], v[8:11]
	v_mfma_f32_16x16x32_f16 v[4:7], v[194:197], v[178:181], v[4:7]
	s_add_i32 s69, 0, 0x18000
	v_add_u32_e32 v239, s69, v235
	s_barrier
	ds_read_b128 v[134:137], v239
	ds_read_b128 v[138:141], v239 offset:1024
	ds_read_b128 v[142:145], v239 offset:2048
	ds_read_b128 v[146:149], v239 offset:3072
	s_mov_b32 m0, s9
	v_lshl_add_u64 v[182:183], v[198:199], 0, s[84:85]
	ds_read_b128 v[150:153], v236 offset:32768
	ds_read_b128 v[154:157], v236 offset:33792
	ds_read_b128 v[158:161], v236 offset:34816
	ds_read_b128 v[162:165], v236 offset:35840
	ds_read_b128 v[166:169], v236 offset:36864
	ds_read_b128 v[170:173], v236 offset:37888
	ds_read_b128 v[174:177], v236 offset:38912
	ds_read_b128 v[178:181], v236 offset:39936
	global_load_lds_dwordx4 v[182:183], off
	v_lshl_add_u64 v[182:183], v[242:243], 0, s[84:85]
	s_mov_b32 m0, s12
	s_nop 0
	global_load_lds_dwordx4 v[182:183], off
	s_waitcnt lgkmcnt(8)
	s_barrier
	s_waitcnt lgkmcnt(0)
	v_mfma_f32_16x16x32_f16 v[80:83], v[134:137], v[150:153], v[80:83]
	v_mfma_f32_16x16x32_f16 v[72:75], v[142:145], v[150:153], v[72:75]
	v_mfma_f32_16x16x32_f16 v[56:59], v[134:137], v[158:161], v[56:59]
	v_mfma_f32_16x16x32_f16 v[68:71], v[142:145], v[158:161], v[68:71]
	v_mfma_f32_16x16x32_f16 v[128:131], v[134:137], v[166:169], v[128:131]
	v_mfma_f32_16x16x32_f16 v[124:127], v[142:145], v[166:169], v[124:127]
	v_mfma_f32_16x16x32_f16 v[116:119], v[134:137], v[174:177], v[116:119]
	v_mfma_f32_16x16x32_f16 v[108:111], v[142:145], v[174:177], v[108:111]
	v_mfma_f32_16x16x32_f16 v[80:83], v[138:141], v[154:157], v[80:83]
	v_mfma_f32_16x16x32_f16 v[72:75], v[146:149], v[154:157], v[72:75]
	v_mfma_f32_16x16x32_f16 v[56:59], v[138:141], v[162:165], v[56:59]
	v_mfma_f32_16x16x32_f16 v[68:71], v[146:149], v[162:165], v[68:71]
	v_mfma_f32_16x16x32_f16 v[128:131], v[138:141], v[170:173], v[128:131]
	v_mfma_f32_16x16x32_f16 v[124:127], v[146:149], v[170:173], v[124:127]
	v_mfma_f32_16x16x32_f16 v[116:119], v[138:141], v[178:181], v[116:119]
	v_mfma_f32_16x16x32_f16 v[108:111], v[146:149], v[178:181], v[108:111]
	s_barrier
	s_add_i32 s71, 0, 0x1c000
	s_add_i32 s69, s69, s5
	v_add_u32_e32 v240, s71, v235
	v_lshl_add_u64 v[248:249], v[244:245], 0, s[78:79]
	s_mov_b32 m0, s69
	s_add_i32 s70, s69, 0x2000
	ds_read_b128 v[182:185], v240
	ds_read_b128 v[186:189], v240 offset:1024
	ds_read_b128 v[190:193], v240 offset:2048
	ds_read_b128 v[194:197], v240 offset:3072
	global_load_lds_dwordx4 v[248:249], off
	v_lshl_add_u64 v[248:249], v[246:247], 0, s[78:79]
	s_mov_b32 m0, s70
	s_nop 0
	global_load_lds_dwordx4 v[248:249], off
	s_barrier
	s_waitcnt lgkmcnt(0)
	v_mfma_f32_16x16x32_f16 v[52:55], v[182:185], v[150:153], v[52:55]
	v_mfma_f32_16x16x32_f16 v[40:43], v[190:193], v[150:153], v[40:43]
	v_mfma_f32_16x16x32_f16 v[36:39], v[182:185], v[158:161], v[36:39]
	v_mfma_f32_16x16x32_f16 v[28:31], v[190:193], v[158:161], v[28:31]
	v_mfma_f32_16x16x32_f16 v[120:123], v[182:185], v[166:169], v[120:123]
	v_mfma_f32_16x16x32_f16 v[112:115], v[190:193], v[166:169], v[112:115]
	v_mfma_f32_16x16x32_f16 v[104:107], v[182:185], v[174:177], v[104:107]
	v_mfma_f32_16x16x32_f16 v[100:103], v[190:193], v[174:177], v[100:103]
	v_mfma_f32_16x16x32_f16 v[52:55], v[186:189], v[154:157], v[52:55]
	v_mfma_f32_16x16x32_f16 v[40:43], v[194:197], v[154:157], v[40:43]
	v_mfma_f32_16x16x32_f16 v[36:39], v[186:189], v[162:165], v[36:39]
	v_mfma_f32_16x16x32_f16 v[28:31], v[194:197], v[162:165], v[28:31]
	v_mfma_f32_16x16x32_f16 v[120:123], v[186:189], v[170:173], v[120:123]
	v_mfma_f32_16x16x32_f16 v[112:115], v[194:197], v[170:173], v[112:115]
	v_mfma_f32_16x16x32_f16 v[104:107], v[186:189], v[178:181], v[104:107]
	v_mfma_f32_16x16x32_f16 v[100:103], v[194:197], v[178:181], v[100:103]
	s_mov_b32 m0, s39
	v_lshl_add_u64 v[198:199], v[198:199], 0, s[78:79]
	s_barrier
	ds_read_b128 v[150:153], v236 offset:49152
	ds_read_b128 v[154:157], v236 offset:50176
	ds_read_b128 v[158:161], v236 offset:51200
	ds_read_b128 v[162:165], v236 offset:52224
	ds_read_b128 v[166:169], v236 offset:53248
	ds_read_b128 v[170:173], v236 offset:54272
	ds_read_b128 v[174:177], v236 offset:55296
	ds_read_b128 v[178:181], v236 offset:56320
	global_load_lds_dwordx4 v[198:199], off
	v_lshl_add_u64 v[198:199], v[242:243], 0, s[78:79]
	s_mov_b32 m0, s47
	s_nop 0
	global_load_lds_dwordx4 v[198:199], off
	s_barrier
	s_waitcnt lgkmcnt(0)
	v_mfma_f32_16x16x32_f16 v[96:99], v[134:137], v[150:153], v[96:99]
	v_mfma_f32_16x16x32_f16 v[92:95], v[142:145], v[150:153], v[92:95]
	v_mfma_f32_16x16x32_f16 v[76:79], v[134:137], v[158:161], v[76:79]
	v_mfma_f32_16x16x32_f16 v[64:67], v[142:145], v[158:161], v[64:67]
	v_mfma_f32_16x16x32_f16 v[44:47], v[134:137], v[166:169], v[44:47]
	v_mfma_f32_16x16x32_f16 v[32:35], v[142:145], v[166:169], v[32:35]
	v_mfma_f32_16x16x32_f16 v[16:19], v[134:137], v[174:177], v[16:19]
	v_mfma_f32_16x16x32_f16 v[12:15], v[142:145], v[174:177], v[12:15]
	v_mfma_f32_16x16x32_f16 v[96:99], v[138:141], v[154:157], v[96:99]
	v_mfma_f32_16x16x32_f16 v[92:95], v[146:149], v[154:157], v[92:95]
	v_mfma_f32_16x16x32_f16 v[76:79], v[138:141], v[162:165], v[76:79]
	v_mfma_f32_16x16x32_f16 v[64:67], v[146:149], v[162:165], v[64:67]
	v_mfma_f32_16x16x32_f16 v[44:47], v[138:141], v[170:173], v[44:47]
	v_mfma_f32_16x16x32_f16 v[32:35], v[146:149], v[170:173], v[32:35]
	v_mfma_f32_16x16x32_f16 v[16:19], v[138:141], v[178:181], v[16:19]
	v_mfma_f32_16x16x32_f16 v[12:15], v[146:149], v[178:181], v[12:15]
	s_barrier
	s_add_i32 s71, s71, s5
	v_lshl_add_u64 v[134:135], v[244:245], 0, vcc
	s_mov_b32 m0, s71
	s_add_i32 s76, s71, 0x2000
	global_load_lds_dwordx4 v[134:135], off
	v_lshl_add_u64 v[134:135], v[246:247], 0, vcc
	s_mov_b32 m0, s76
	s_nop 0
	global_load_lds_dwordx4 v[134:135], off
	s_waitcnt vmcnt(6)
	s_barrier
	v_mfma_f32_16x16x32_f16 v[88:91], v[182:185], v[150:153], v[88:91]
	v_mfma_f32_16x16x32_f16 v[84:87], v[190:193], v[150:153], v[84:87]
	v_mfma_f32_16x16x32_f16 v[60:63], v[182:185], v[158:161], v[60:63]
	v_mfma_f32_16x16x32_f16 v[48:51], v[190:193], v[158:161], v[48:51]
	v_mfma_f32_16x16x32_f16 v[24:27], v[182:185], v[166:169], v[24:27]
	v_mfma_f32_16x16x32_f16 v[20:23], v[190:193], v[166:169], v[20:23]
	v_mfma_f32_16x16x32_f16 v[8:11], v[182:185], v[174:177], v[8:11]
	v_mfma_f32_16x16x32_f16 v[4:7], v[190:193], v[174:177], v[4:7]
	v_mfma_f32_16x16x32_f16 v[88:91], v[186:189], v[154:157], v[88:91]
	v_mfma_f32_16x16x32_f16 v[84:87], v[194:197], v[154:157], v[84:87]
	v_mfma_f32_16x16x32_f16 v[60:63], v[186:189], v[162:165], v[60:63]
	v_mfma_f32_16x16x32_f16 v[48:51], v[194:197], v[162:165], v[48:51]
	v_mfma_f32_16x16x32_f16 v[24:27], v[186:189], v[170:173], v[24:27]
	v_mfma_f32_16x16x32_f16 v[20:23], v[194:197], v[170:173], v[20:23]
	v_mfma_f32_16x16x32_f16 v[8:11], v[186:189], v[178:181], v[8:11]
	v_mfma_f32_16x16x32_f16 v[4:7], v[194:197], v[178:181], v[4:7]
	s_add_i32 s10, s10, 2
	s_add_u32 s16, s16, 0x100
	s_addc_u32 s17, s17, 0
	s_cmp_lt_u32 s10, 6
	s_barrier
	s_cbranch_scc1 .LBB0_1742
	s_ashr_i32 s78, s48, 31
	s_mul_i32 s10, s46, 0x42
	s_mul_hi_i32 s11, s46, 0x42
	s_add_u32 s10, s10, s48
	v_mov_b32_e32 v132, v233
	v_mov_b32_e32 v133, v234
	s_addc_u32 s11, s11, s78
	s_lshl_b64 s[10:11], s[10:11], 17
	v_readlane_b32 s16, v252, 45
	v_lshlrev_b32_e32 v133, 3, v133
	s_add_u32 s16, s16, s10
	v_readlane_b32 s10, v252, 46
	v_lshlrev_b32_e32 v132, 8, v132
	s_addc_u32 s17, s10, s11
	v_add3_u32 v188, v132, s49, v133
	s_add_u32 s26, s16, 0x4200000
	v_ashrrev_i32_e32 v189, 31, v188
	s_addc_u32 s27, s17, 0
	v_lshlrev_b64 v[132:133], 1, v[188:189]
	v_lshl_add_u64 v[134:135], s[16:17], 0, v[132:133]
	v_lshl_add_u64 v[136:137], s[26:27], 0, v[132:133]
	v_add_u32_e32 v132, 0x1000, v188
	v_ashrrev_i32_e32 v133, 31, v132
	v_lshlrev_b64 v[132:133], 1, v[132:133]
	v_lshl_add_u64 v[138:139], s[16:17], 0, v[132:133]
	v_lshl_add_u64 v[176:177], s[26:27], 0, v[132:133]
	v_add_u32_e32 v132, 0x1080, v188
	v_ashrrev_i32_e32 v133, 31, v132
	v_lshlrev_b64 v[132:133], 1, v[132:133]
	v_lshl_add_u64 v[148:149], s[16:17], 0, v[132:133]
	v_lshl_add_u64 v[168:169], s[26:27], 0, v[132:133]
	v_add_u32_e32 v132, 0x2000, v188
	v_ashrrev_i32_e32 v133, 31, v132
	v_lshlrev_b64 v[132:133], 1, v[132:133]
	v_lshl_add_u64 v[144:145], s[16:17], 0, v[132:133]
	v_lshl_add_u64 v[156:157], s[26:27], 0, v[132:133]
	v_add_u32_e32 v132, 0x2080, v188
	v_ashrrev_i32_e32 v133, 31, v132
	v_lshlrev_b64 v[132:133], 1, v[132:133]
	v_lshl_add_u64 v[146:147], s[16:17], 0, v[132:133]
	v_lshl_add_u64 v[158:159], s[26:27], 0, v[132:133]
	v_add_u32_e32 v132, 0x3000, v188
	v_ashrrev_i32_e32 v133, 31, v132
	v_lshlrev_b64 v[132:133], 1, v[132:133]
	v_lshl_add_u64 v[140:141], s[16:17], 0, v[132:133]
	v_lshl_add_u64 v[150:151], s[26:27], 0, v[132:133]
	v_add_u32_e32 v132, 0x3080, v188
	v_ashrrev_i32_e32 v133, 31, v132
	v_lshlrev_b64 v[132:133], 1, v[132:133]
	v_lshl_add_u64 v[142:143], s[16:17], 0, v[132:133]
	v_lshl_add_u64 v[164:165], s[26:27], 0, v[132:133]
	global_load_dwordx4 v[180:183], v[134:135], off offset:256
	global_load_dwordx4 v[190:193], v[134:135], off
	s_nop 0
	global_load_dwordx4 v[132:135], v[142:143], off
	s_nop 0
	global_load_dwordx4 v[140:143], v[140:141], off
	s_nop 0
	global_load_dwordx4 v[152:155], v[146:147], off
	s_nop 0
	global_load_dwordx4 v[144:147], v[144:145], off
	s_nop 0
	global_load_dwordx4 v[160:163], v[148:149], off
	global_load_dwordx4 v[172:175], v[138:139], off
	global_load_dwordx4 v[184:187], v[136:137], off offset:256
	global_load_dwordx4 v[194:197], v[136:137], off
	s_nop 0
	global_load_dwordx4 v[136:139], v[164:165], off
	s_nop 0
	global_load_dwordx4 v[148:151], v[150:151], off
	s_nop 0
	global_load_dwordx4 v[164:167], v[158:159], off
	s_nop 0
	global_load_dwordx4 v[156:159], v[156:157], off
	s_nop 0
	global_load_dwordx4 v[168:171], v[168:169], off
	s_nop 0
	global_load_dwordx4 v[176:179], v[176:177], off
	s_mov_b32 s10, 6
	s_mov_b64 s[30:31], 0x500
	s_mov_b64 s[84:85], 0x80500
	s_mov_b64 vcc, 0x580
	s_mov_b64 s[52:53], 0x80580
	s_waitcnt vmcnt(0)
	s_nop 0
	v_cvt_f32_f16_e32 v189, v190
	v_rcp_f32_e32 v198, v189
	v_cvt_f32_f16_e32 v189, v192
	v_cvt_f32_f16_e32 v244, v194
	v_cvt_f32_f16_sdwa v245, v194 dst_sel:DWORD dst_unused:UNUSED_PAD src0_sel:WORD_1
	v_cvt_f32_f16_e32 v194, v195
	v_rcp_f32_e32 v242, v189
	v_cvt_f32_f16_sdwa v189, v190 dst_sel:DWORD dst_unused:UNUSED_PAD src0_sel:WORD_1
	v_cvt_f32_f16_sdwa v195, v195 dst_sel:DWORD dst_unused:UNUSED_PAD src0_sel:WORD_1
	v_cvt_f32_f16_e32 v246, v196
	v_cvt_f32_f16_sdwa v247, v196 dst_sel:DWORD dst_unused:UNUSED_PAD src0_sel:WORD_1
	v_rcp_f32_e32 v199, v189
	v_cvt_f32_f16_sdwa v189, v192 dst_sel:DWORD dst_unused:UNUSED_PAD src0_sel:WORD_1
	v_cvt_f32_f16_e32 v196, v186
	v_pk_mul_f32 v[198:199], v[198:199], v[244:245]
	v_rcp_f32_e32 v243, v189
	v_cvt_f32_f16_e32 v189, v191
	v_pk_mul_f32 v[80:81], v[80:81], v[198:199]
	v_rcp_f32_e32 v190, v189
	v_cvt_f32_f16_e32 v189, v193
	v_rcp_f32_e32 v192, v189
	v_cvt_f32_f16_sdwa v189, v191 dst_sel:DWORD dst_unused:UNUSED_PAD src0_sel:WORD_1
	v_rcp_f32_e32 v191, v189
	v_cvt_f32_f16_sdwa v189, v193 dst_sel:DWORD dst_unused:UNUSED_PAD src0_sel:WORD_1
	v_pk_mul_f32 v[190:191], v[190:191], v[194:195]
	s_nop 0
	v_pk_mul_f32 v[82:83], v[82:83], v[190:191]
	v_rcp_f32_e32 v193, v189
	v_cvt_f32_f16_e32 v190, v197
	v_cvt_f32_f16_sdwa v191, v197 dst_sel:DWORD dst_unused:UNUSED_PAD src0_sel:WORD_1
	v_cvt_f32_f16_e32 v189, v180
	v_cvt_f32_f16_sdwa v180, v180 dst_sel:DWORD dst_unused:UNUSED_PAD src0_sel:WORD_1
	v_pk_mul_f32 v[194:195], v[242:243], v[246:247]
	v_pk_mul_f32 v[190:191], v[192:193], v[190:191]
	v_pk_mul_f32 v[72:73], v[72:73], v[194:195]
	v_pk_mul_f32 v[74:75], v[74:75], v[190:191]
	v_rcp_f32_e32 v191, v180
	v_cvt_f32_f16_sdwa v180, v182 dst_sel:DWORD dst_unused:UNUSED_PAD src0_sel:WORD_1
	v_cvt_f32_f16_e32 v194, v184
	v_cvt_f32_f16_sdwa v195, v184 dst_sel:DWORD dst_unused:UNUSED_PAD src0_sel:WORD_1
	v_cvt_f32_f16_e32 v184, v185
	v_rcp_f32_e32 v193, v180
	v_cvt_f32_f16_e32 v180, v181
	v_cvt_f32_f16_sdwa v181, v181 dst_sel:DWORD dst_unused:UNUSED_PAD src0_sel:WORD_1
	v_cvt_f32_f16_sdwa v185, v185 dst_sel:DWORD dst_unused:UNUSED_PAD src0_sel:WORD_1
	v_rcp_f32_e32 v190, v189
	v_rcp_f32_e32 v180, v180
	v_rcp_f32_e32 v181, v181
	v_cvt_f32_f16_e32 v189, v182
	v_cvt_f32_f16_e32 v182, v183
	v_cvt_f32_f16_sdwa v197, v186 dst_sel:DWORD dst_unused:UNUSED_PAD src0_sel:WORD_1
	v_pk_mul_f32 v[180:181], v[180:181], v[184:185]
	v_rcp_f32_e32 v192, v189
	v_pk_mul_f32 v[54:55], v[54:55], v[180:181]
	v_cvt_f32_f16_sdwa v180, v183 dst_sel:DWORD dst_unused:UNUSED_PAD src0_sel:WORD_1
	v_rcp_f32_e32 v182, v182
	v_cvt_f32_f16_sdwa v181, v187 dst_sel:DWORD dst_unused:UNUSED_PAD src0_sel:WORD_1
	v_pk_mul_f32 v[184:185], v[192:193], v[196:197]
	v_rcp_f32_e32 v183, v180
	v_cvt_f32_f16_e32 v180, v187
	v_pk_mul_f32 v[40:41], v[40:41], v[184:185]
	v_cvt_f32_f16_e32 v184, v176
	v_cvt_f32_f16_sdwa v185, v176 dst_sel:DWORD dst_unused:UNUSED_PAD src0_sel:WORD_1
	v_pk_mul_f32 v[180:181], v[182:183], v[180:181]
	v_cvt_f32_f16_e32 v176, v177
	v_pk_mul_f32 v[42:43], v[42:43], v[180:181]
	v_cvt_f32_f16_e32 v180, v172
	v_cvt_f32_f16_e32 v181, v174
	v_cvt_f32_f16_sdwa v172, v172 dst_sel:DWORD dst_unused:UNUSED_PAD src0_sel:WORD_1
	v_cvt_f32_f16_sdwa v177, v177 dst_sel:DWORD dst_unused:UNUSED_PAD src0_sel:WORD_1
	v_cvt_f32_f16_e32 v186, v178
	v_rcp_f32_e32 v182, v181
	v_rcp_f32_e32 v181, v172
	v_cvt_f32_f16_sdwa v172, v174 dst_sel:DWORD dst_unused:UNUSED_PAD src0_sel:WORD_1
	v_cvt_f32_f16_e32 v174, v175
	v_cvt_f32_f16_sdwa v187, v178 dst_sel:DWORD dst_unused:UNUSED_PAD src0_sel:WORD_1
	v_cvt_f32_f16_e32 v178, v170
	v_rcp_f32_e32 v183, v172
	v_cvt_f32_f16_e32 v172, v173
	v_cvt_f32_f16_sdwa v173, v173 dst_sel:DWORD dst_unused:UNUSED_PAD src0_sel:WORD_1
	v_rcp_f32_e32 v174, v174
	v_rcp_f32_e32 v180, v180
	v_rcp_f32_e32 v172, v172
	v_rcp_f32_e32 v173, v173
	v_pk_mul_f32 v[190:191], v[190:191], v[194:195]
	v_pk_mul_f32 v[180:181], v[180:181], v[184:185]
	v_pk_mul_f32 v[52:53], v[52:53], v[190:191]
	v_pk_mul_f32 v[172:173], v[172:173], v[176:177]
	v_pk_mul_f32 v[176:177], v[182:183], v[186:187]
	v_pk_mul_f32 v[58:59], v[58:59], v[172:173]
	v_cvt_f32_f16_sdwa v172, v175 dst_sel:DWORD dst_unused:UNUSED_PAD src0_sel:WORD_1
	v_cvt_f32_f16_sdwa v173, v179 dst_sel:DWORD dst_unused:UNUSED_PAD src0_sel:WORD_1
	v_pk_mul_f32 v[68:69], v[68:69], v[176:177]
	v_cvt_f32_f16_e32 v176, v168
	v_rcp_f32_e32 v175, v172
	v_cvt_f32_f16_e32 v172, v179
	v_cvt_f32_f16_sdwa v177, v168 dst_sel:DWORD dst_unused:UNUSED_PAD src0_sel:WORD_1
	v_cvt_f32_f16_e32 v168, v169
	v_cvt_f32_f16_sdwa v169, v169 dst_sel:DWORD dst_unused:UNUSED_PAD src0_sel:WORD_1
	v_pk_mul_f32 v[172:173], v[174:175], v[172:173]
	v_cvt_f32_f16_sdwa v179, v170 dst_sel:DWORD dst_unused:UNUSED_PAD src0_sel:WORD_1
	v_pk_mul_f32 v[70:71], v[70:71], v[172:173]
	v_cvt_f32_f16_e32 v172, v160
	v_cvt_f32_f16_e32 v173, v162
	v_cvt_f32_f16_sdwa v160, v160 dst_sel:DWORD dst_unused:UNUSED_PAD src0_sel:WORD_1
	v_cvt_f32_f16_e32 v170, v158
	v_rcp_f32_e32 v172, v172
	v_rcp_f32_e32 v174, v173
	v_rcp_f32_e32 v173, v160
	v_cvt_f32_f16_sdwa v160, v162 dst_sel:DWORD dst_unused:UNUSED_PAD src0_sel:WORD_1
	v_cvt_f32_f16_e32 v162, v163
	v_pk_mul_f32 v[56:57], v[56:57], v[180:181]
	v_pk_mul_f32 v[172:173], v[172:173], v[176:177]
	v_rcp_f32_e32 v175, v160
	v_cvt_f32_f16_e32 v160, v161
	v_cvt_f32_f16_sdwa v161, v161 dst_sel:DWORD dst_unused:UNUSED_PAD src0_sel:WORD_1
	v_rcp_f32_e32 v162, v162
	v_pk_mul_f32 v[36:37], v[36:37], v[172:173]
	v_rcp_f32_e32 v160, v160
	v_rcp_f32_e32 v161, v161
	s_nop 0
	v_pk_mul_f32 v[160:161], v[160:161], v[168:169]
	s_nop 0
	v_pk_mul_f32 v[38:39], v[38:39], v[160:161]
	v_cvt_f32_f16_sdwa v160, v163 dst_sel:DWORD dst_unused:UNUSED_PAD src0_sel:WORD_1
	v_cvt_f32_f16_sdwa v161, v171 dst_sel:DWORD dst_unused:UNUSED_PAD src0_sel:WORD_1
	v_pk_mul_f32 v[168:169], v[174:175], v[178:179]
	v_rcp_f32_e32 v163, v160
	v_cvt_f32_f16_e32 v160, v171
	v_pk_mul_f32 v[28:29], v[28:29], v[168:169]
	v_cvt_f32_f16_sdwa v171, v158 dst_sel:DWORD dst_unused:UNUSED_PAD src0_sel:WORD_1
	v_pk_mul_f32 v[160:161], v[162:163], v[160:161]
	s_nop 0
	v_pk_mul_f32 v[30:31], v[30:31], v[160:161]
	v_cvt_f32_f16_e32 v160, v144
	v_cvt_f32_f16_e32 v161, v146
	v_cvt_f32_f16_sdwa v144, v144 dst_sel:DWORD dst_unused:UNUSED_PAD src0_sel:WORD_1
	v_cvt_f32_f16_e32 v162, v156
	v_rcp_f32_e32 v160, v160
	v_rcp_f32_e32 v168, v161
	v_rcp_f32_e32 v161, v144
	v_cvt_f32_f16_sdwa v144, v146 dst_sel:DWORD dst_unused:UNUSED_PAD src0_sel:WORD_1
	v_cvt_f32_f16_sdwa v163, v156 dst_sel:DWORD dst_unused:UNUSED_PAD src0_sel:WORD_1
	v_cvt_f32_f16_e32 v156, v157
	v_cvt_f32_f16_sdwa v157, v157 dst_sel:DWORD dst_unused:UNUSED_PAD src0_sel:WORD_1
	v_rcp_f32_e32 v169, v144
	v_cvt_f32_f16_e32 v144, v145
	v_cvt_f32_f16_sdwa v145, v145 dst_sel:DWORD dst_unused:UNUSED_PAD src0_sel:WORD_1
	v_pk_mul_f32 v[160:161], v[160:161], v[162:163]
	v_cvt_f32_f16_e32 v146, v147
	v_rcp_f32_e32 v144, v144
	v_rcp_f32_e32 v145, v145
	v_pk_mul_f32 v[160:161], v[128:129], v[160:161]
	v_cvt_f32_f16_sdwa v128, v147 dst_sel:DWORD dst_unused:UNUSED_PAD src0_sel:WORD_1
	v_rcp_f32_e32 v146, v146
	v_pk_mul_f32 v[144:145], v[144:145], v[156:157]
	v_cvt_f32_f16_sdwa v129, v159 dst_sel:DWORD dst_unused:UNUSED_PAD src0_sel:WORD_1
	v_pk_mul_f32 v[162:163], v[130:131], v[144:145]
	v_rcp_f32_e32 v147, v128
	v_cvt_f32_f16_e32 v128, v159
	v_pk_mul_f32 v[130:131], v[168:169], v[170:171]
	v_cvt_f32_f16_e32 v145, v155
	v_pk_mul_f32 v[156:157], v[124:125], v[130:131]
	v_cvt_f32_f16_e32 v125, v154
	v_pk_mul_f32 v[128:129], v[146:147], v[128:129]
	v_cvt_f32_f16_e32 v124, v152
	v_pk_mul_f32 v[158:159], v[126:127], v[128:129]
	v_rcp_f32_e32 v126, v125
	v_cvt_f32_f16_sdwa v125, v152 dst_sel:DWORD dst_unused:UNUSED_PAD src0_sel:WORD_1
	v_cvt_f32_f16_e32 v144, v153
	v_rcp_f32_e32 v152, v145
	v_cvt_f32_f16_sdwa v145, v153 dst_sel:DWORD dst_unused:UNUSED_PAD src0_sel:WORD_1
	v_rcp_f32_e32 v124, v124
	v_rcp_f32_e32 v125, v125
	v_cvt_f32_f16_e32 v128, v164
	v_cvt_f32_f16_sdwa v129, v164 dst_sel:DWORD dst_unused:UNUSED_PAD src0_sel:WORD_1
	v_cvt_f32_f16_sdwa v127, v154 dst_sel:DWORD dst_unused:UNUSED_PAD src0_sel:WORD_1
	v_rcp_f32_e32 v144, v144
	v_rcp_f32_e32 v145, v145
	v_cvt_f32_f16_e32 v146, v165
	v_cvt_f32_f16_sdwa v147, v165 dst_sel:DWORD dst_unused:UNUSED_PAD src0_sel:WORD_1
	v_pk_mul_f32 v[124:125], v[124:125], v[128:129]
	v_rcp_f32_e32 v127, v127
	v_cvt_f32_f16_e32 v130, v166
	v_cvt_f32_f16_sdwa v131, v166 dst_sel:DWORD dst_unused:UNUSED_PAD src0_sel:WORD_1
	v_pk_mul_f32 v[128:129], v[144:145], v[146:147]
	v_pk_mul_f32 v[144:145], v[120:121], v[124:125]
	v_cvt_f32_f16_sdwa v120, v155 dst_sel:DWORD dst_unused:UNUSED_PAD src0_sel:WORD_1
	v_pk_mul_f32 v[146:147], v[122:123], v[128:129]
	v_cvt_f32_f16_sdwa v121, v167 dst_sel:DWORD dst_unused:UNUSED_PAD src0_sel:WORD_1
	v_pk_mul_f32 v[122:123], v[126:127], v[130:131]
	v_rcp_f32_e32 v153, v120
	v_cvt_f32_f16_e32 v120, v167
	v_pk_mul_f32 v[124:125], v[112:113], v[122:123]
	v_cvt_f32_f16_e32 v113, v142
	v_cvt_f32_f16_e32 v112, v140
	v_pk_mul_f32 v[120:121], v[152:153], v[120:121]
	v_cvt_f32_f16_e32 v129, v143
	v_pk_mul_f32 v[126:127], v[114:115], v[120:121]
	v_rcp_f32_e32 v114, v113
	v_cvt_f32_f16_sdwa v113, v140 dst_sel:DWORD dst_unused:UNUSED_PAD src0_sel:WORD_1
	v_rcp_f32_e32 v112, v112
	v_cvt_f32_f16_e32 v120, v148
	v_cvt_f32_f16_sdwa v121, v148 dst_sel:DWORD dst_unused:UNUSED_PAD src0_sel:WORD_1
	v_rcp_f32_e32 v113, v113
	v_cvt_f32_f16_sdwa v115, v142 dst_sel:DWORD dst_unused:UNUSED_PAD src0_sel:WORD_1
	v_cvt_f32_f16_e32 v122, v150
	v_cvt_f32_f16_sdwa v123, v150 dst_sel:DWORD dst_unused:UNUSED_PAD src0_sel:WORD_1
	v_pk_mul_f32 v[112:113], v[112:113], v[120:121]
	v_rcp_f32_e32 v115, v115
	v_pk_mul_f32 v[152:153], v[116:117], v[112:113]
	v_cvt_f32_f16_sdwa v112, v143 dst_sel:DWORD dst_unused:UNUSED_PAD src0_sel:WORD_1
	v_cvt_f32_f16_e32 v128, v141
	v_rcp_f32_e32 v130, v129
	v_cvt_f32_f16_sdwa v129, v141 dst_sel:DWORD dst_unused:UNUSED_PAD src0_sel:WORD_1
	v_rcp_f32_e32 v131, v112
	v_cvt_f32_f16_e32 v112, v151
	v_cvt_f32_f16_sdwa v113, v151 dst_sel:DWORD dst_unused:UNUSED_PAD src0_sel:WORD_1
	v_pk_mul_f32 v[114:115], v[114:115], v[122:123]
	v_rcp_f32_e32 v128, v128
	v_rcp_f32_e32 v129, v129
	v_cvt_f32_f16_e32 v140, v149
	v_cvt_f32_f16_sdwa v141, v149 dst_sel:DWORD dst_unused:UNUSED_PAD src0_sel:WORD_1
	v_pk_mul_f32 v[148:149], v[108:109], v[114:115]
	v_cvt_f32_f16_e32 v109, v134
	v_cvt_f32_f16_e32 v117, v135
	v_pk_mul_f32 v[112:113], v[130:131], v[112:113]
	v_pk_mul_f32 v[120:121], v[128:129], v[140:141]
	v_pk_mul_f32 v[150:151], v[110:111], v[112:113]
	v_cvt_f32_f16_e32 v108, v132
	v_rcp_f32_e32 v110, v109
	v_cvt_f32_f16_sdwa v109, v132 dst_sel:DWORD dst_unused:UNUSED_PAD src0_sel:WORD_1
	v_pk_mul_f32 v[154:155], v[118:119], v[120:121]
	v_cvt_f32_f16_e32 v116, v133
	v_rcp_f32_e32 v118, v117
	v_cvt_f32_f16_sdwa v117, v133 dst_sel:DWORD dst_unused:UNUSED_PAD src0_sel:WORD_1
	v_rcp_f32_e32 v108, v108
	v_rcp_f32_e32 v109, v109
	v_cvt_f32_f16_e32 v112, v136
	v_cvt_f32_f16_sdwa v113, v136 dst_sel:DWORD dst_unused:UNUSED_PAD src0_sel:WORD_1
	v_rcp_f32_e32 v116, v116
	v_rcp_f32_e32 v117, v117
	v_cvt_f32_f16_e32 v120, v137
	v_cvt_f32_f16_sdwa v121, v137 dst_sel:DWORD dst_unused:UNUSED_PAD src0_sel:WORD_1
	v_cvt_f32_f16_sdwa v111, v134 dst_sel:DWORD dst_unused:UNUSED_PAD src0_sel:WORD_1
	v_pk_mul_f32 v[108:109], v[108:109], v[112:113]
	v_cvt_f32_f16_e32 v114, v138
	v_pk_mul_f32 v[112:113], v[116:117], v[120:121]
	v_pk_mul_f32 v[120:121], v[104:105], v[108:109]
	v_cvt_f32_f16_sdwa v104, v135 dst_sel:DWORD dst_unused:UNUSED_PAD src0_sel:WORD_1
	v_rcp_f32_e32 v111, v111
	v_cvt_f32_f16_sdwa v115, v138 dst_sel:DWORD dst_unused:UNUSED_PAD src0_sel:WORD_1
	v_cvt_f32_f16_sdwa v105, v139 dst_sel:DWORD dst_unused:UNUSED_PAD src0_sel:WORD_1
	v_rcp_f32_e32 v119, v104
	v_cvt_f32_f16_e32 v104, v139
	v_pk_mul_f32 v[122:123], v[106:107], v[112:113]
	v_pk_mul_f32 v[106:107], v[110:111], v[114:115]
	v_pk_mul_f32 v[104:105], v[118:119], v[104:105]
	v_pk_mul_f32 v[116:117], v[100:101], v[106:107]
	v_add_u32_e32 v100, 0x8000, v188
	v_ashrrev_i32_e32 v101, 31, v100
	v_lshlrev_b64 v[100:101], 1, v[100:101]
	v_pk_mul_f32 v[118:119], v[102:103], v[104:105]
	v_lshl_add_u64 v[104:105], s[16:17], 0, v[100:101]
	v_lshl_add_u64 v[112:113], s[26:27], 0, v[100:101]
	v_add_u32_e32 v100, 0x8080, v188
	v_ashrrev_i32_e32 v101, 31, v100
	v_lshlrev_b64 v[100:101], 1, v[100:101]
	v_lshl_add_u64 v[102:103], s[16:17], 0, v[100:101]
	v_lshl_add_u64 v[114:115], s[26:27], 0, v[100:101]
	v_add_u32_e32 v100, 0x9000, v188
	v_ashrrev_i32_e32 v101, 31, v100
	v_lshlrev_b64 v[100:101], 1, v[100:101]
	v_lshl_add_u64 v[106:107], s[16:17], 0, v[100:101]
	v_lshl_add_u64 v[190:191], s[26:27], 0, v[100:101]
	v_add_u32_e32 v100, 0x9080, v188
	v_ashrrev_i32_e32 v101, 31, v100
	v_lshlrev_b64 v[100:101], 1, v[100:101]
	v_lshl_add_u64 v[140:141], s[16:17], 0, v[100:101]
	v_lshl_add_u64 v[180:181], s[26:27], 0, v[100:101]
	v_add_u32_e32 v100, 0xa000, v188
	v_ashrrev_i32_e32 v101, 31, v100
	v_lshlrev_b64 v[100:101], 1, v[100:101]
	v_lshl_add_u64 v[136:137], s[16:17], 0, v[100:101]
	v_lshl_add_u64 v[176:177], s[26:27], 0, v[100:101]
	v_add_u32_e32 v100, 0xa080, v188
	v_ashrrev_i32_e32 v101, 31, v100
	v_lshlrev_b64 v[100:101], 1, v[100:101]
	v_lshl_add_u64 v[132:133], s[16:17], 0, v[100:101]
	v_lshl_add_u64 v[172:173], s[26:27], 0, v[100:101]
	v_add_u32_e32 v100, 0xb000, v188
	v_ashrrev_i32_e32 v101, 31, v100
	v_lshlrev_b64 v[100:101], 1, v[100:101]
	v_lshl_add_u64 v[128:129], s[16:17], 0, v[100:101]
	v_lshl_add_u64 v[168:169], s[26:27], 0, v[100:101]
	v_add_u32_e32 v100, 0xb080, v188
	v_ashrrev_i32_e32 v101, 31, v100
	v_lshlrev_b64 v[100:101], 1, v[100:101]
	v_lshl_add_u64 v[108:109], s[16:17], 0, v[100:101]
	v_lshl_add_u64 v[164:165], s[26:27], 0, v[100:101]
	global_load_dwordx4 v[108:111], v[108:109], off
	s_nop 0
	global_load_dwordx4 v[128:131], v[128:129], off
	s_nop 0
	global_load_dwordx4 v[132:135], v[132:133], off
	s_nop 0
	global_load_dwordx4 v[136:139], v[136:137], off
	s_nop 0
	global_load_dwordx4 v[140:143], v[140:141], off
	s_nop 0
	global_load_dwordx4 v[184:187], v[106:107], off
	s_nop 0
	global_load_dwordx4 v[100:103], v[102:103], off
	s_nop 0
	global_load_dwordx4 v[104:107], v[104:105], off
	s_nop 0
	global_load_dwordx4 v[164:167], v[164:165], off
	s_nop 0
	global_load_dwordx4 v[168:171], v[168:169], off
	s_nop 0
	global_load_dwordx4 v[172:175], v[172:173], off
	s_nop 0
	global_load_dwordx4 v[176:179], v[176:177], off
	s_nop 0
	global_load_dwordx4 v[180:183], v[180:181], off
	s_nop 0
	global_load_dwordx4 v[188:191], v[190:191], off
	s_nop 0
	global_load_dwordx4 v[192:195], v[114:115], off
	global_load_dwordx4 v[196:199], v[112:113], off
	s_waitcnt vmcnt(0)
	s_nop 0
	v_cvt_f32_f16_e32 v112, v104
	v_cvt_f32_f16_e32 v113, v106
	v_cvt_f32_f16_sdwa v104, v104 dst_sel:DWORD dst_unused:UNUSED_PAD src0_sel:WORD_1
	v_rcp_f32_e32 v242, v113
	v_rcp_f32_e32 v113, v104
	v_cvt_f32_f16_sdwa v104, v106 dst_sel:DWORD dst_unused:UNUSED_PAD src0_sel:WORD_1
	v_rcp_f32_e32 v112, v112
	v_cvt_f32_f16_e32 v114, v196
	v_cvt_f32_f16_sdwa v115, v196 dst_sel:DWORD dst_unused:UNUSED_PAD src0_sel:WORD_1
	v_rcp_f32_e32 v243, v104
	v_cvt_f32_f16_e32 v104, v105
	v_cvt_f32_f16_sdwa v105, v105 dst_sel:DWORD dst_unused:UNUSED_PAD src0_sel:WORD_1
	v_cvt_f32_f16_e32 v196, v197
	v_cvt_f32_f16_sdwa v197, v197 dst_sel:DWORD dst_unused:UNUSED_PAD src0_sel:WORD_1
	v_rcp_f32_e32 v104, v104
	v_rcp_f32_e32 v105, v105
	v_pk_mul_f32 v[112:113], v[112:113], v[114:115]
	v_cvt_f32_f16_e32 v244, v198
	v_cvt_f32_f16_sdwa v245, v198 dst_sel:DWORD dst_unused:UNUSED_PAD src0_sel:WORD_1
	v_cvt_f32_f16_e32 v106, v107
	v_pk_mul_f32 v[112:113], v[96:97], v[112:113]
	v_cvt_f32_f16_sdwa v96, v107 dst_sel:DWORD dst_unused:UNUSED_PAD src0_sel:WORD_1
	v_pk_mul_f32 v[104:105], v[104:105], v[196:197]
	v_rcp_f32_e32 v106, v106
	v_pk_mul_f32 v[114:115], v[98:99], v[104:105]
	v_rcp_f32_e32 v107, v96
	v_cvt_f32_f16_e32 v96, v199
	v_cvt_f32_f16_sdwa v97, v199 dst_sel:DWORD dst_unused:UNUSED_PAD src0_sel:WORD_1
	v_pk_mul_f32 v[98:99], v[242:243], v[244:245]
	s_mov_b64 s[16:17], 0
	v_pk_mul_f32 v[104:105], v[92:93], v[98:99]
	v_cvt_f32_f16_e32 v93, v102
	v_pk_mul_f32 v[96:97], v[106:107], v[96:97]
	v_cvt_f32_f16_e32 v92, v100
	v_pk_mul_f32 v[106:107], v[94:95], v[96:97]
	v_rcp_f32_e32 v96, v93
	v_cvt_f32_f16_sdwa v93, v100 dst_sel:DWORD dst_unused:UNUSED_PAD src0_sel:WORD_1
	v_rcp_f32_e32 v92, v92
	v_cvt_f32_f16_e32 v94, v192
	v_cvt_f32_f16_sdwa v95, v192 dst_sel:DWORD dst_unused:UNUSED_PAD src0_sel:WORD_1
	v_rcp_f32_e32 v93, v93
	v_cvt_f32_f16_sdwa v97, v102 dst_sel:DWORD dst_unused:UNUSED_PAD src0_sel:WORD_1
	v_cvt_f32_f16_e32 v102, v103
	v_cvt_f32_f16_e32 v100, v101
	v_pk_mul_f32 v[92:93], v[92:93], v[94:95]
	v_cvt_f32_f16_sdwa v101, v101 dst_sel:DWORD dst_unused:UNUSED_PAD src0_sel:WORD_1
	v_pk_mul_f32 v[92:93], v[88:89], v[92:93]
	v_cvt_f32_f16_sdwa v88, v103 dst_sel:DWORD dst_unused:UNUSED_PAD src0_sel:WORD_1
	v_rcp_f32_e32 v102, v102
	v_cvt_f32_f16_sdwa v89, v195 dst_sel:DWORD dst_unused:UNUSED_PAD src0_sel:WORD_1
	v_rcp_f32_e32 v100, v100
	v_rcp_f32_e32 v103, v88
	v_cvt_f32_f16_e32 v88, v195
	v_rcp_f32_e32 v101, v101
	v_cvt_f32_f16_e32 v192, v193
	v_cvt_f32_f16_sdwa v193, v193 dst_sel:DWORD dst_unused:UNUSED_PAD src0_sel:WORD_1
	v_rcp_f32_e32 v97, v97
	v_cvt_f32_f16_e32 v98, v194
	v_cvt_f32_f16_sdwa v99, v194 dst_sel:DWORD dst_unused:UNUSED_PAD src0_sel:WORD_1
	v_pk_mul_f32 v[88:89], v[102:103], v[88:89]
	v_pk_mul_f32 v[94:95], v[100:101], v[192:193]
	v_pk_mul_f32 v[86:87], v[86:87], v[88:89]
	v_cvt_f32_f16_e32 v89, v186
	v_cvt_f32_f16_e32 v101, v187
	v_pk_mul_f32 v[94:95], v[90:91], v[94:95]
	v_pk_mul_f32 v[90:91], v[96:97], v[98:99]
	v_cvt_f32_f16_e32 v88, v184
	v_pk_mul_f32 v[84:85], v[84:85], v[90:91]
	v_rcp_f32_e32 v90, v89
	v_cvt_f32_f16_sdwa v89, v184 dst_sel:DWORD dst_unused:UNUSED_PAD src0_sel:WORD_1
	v_cvt_f32_f16_e32 v100, v185
	v_rcp_f32_e32 v184, v101
	v_cvt_f32_f16_sdwa v101, v185 dst_sel:DWORD dst_unused:UNUSED_PAD src0_sel:WORD_1
	v_rcp_f32_e32 v88, v88
	v_rcp_f32_e32 v89, v89
	v_cvt_f32_f16_e32 v96, v188
	v_cvt_f32_f16_sdwa v97, v188 dst_sel:DWORD dst_unused:UNUSED_PAD src0_sel:WORD_1
	v_cvt_f32_f16_sdwa v91, v186 dst_sel:DWORD dst_unused:UNUSED_PAD src0_sel:WORD_1
	v_rcp_f32_e32 v100, v100
	v_rcp_f32_e32 v101, v101
	v_cvt_f32_f16_e32 v102, v189
	v_cvt_f32_f16_sdwa v103, v189 dst_sel:DWORD dst_unused:UNUSED_PAD src0_sel:WORD_1
	v_pk_mul_f32 v[88:89], v[88:89], v[96:97]
	v_rcp_f32_e32 v91, v91
	v_cvt_f32_f16_e32 v98, v190
	v_cvt_f32_f16_sdwa v99, v190 dst_sel:DWORD dst_unused:UNUSED_PAD src0_sel:WORD_1
	v_pk_mul_f32 v[96:97], v[100:101], v[102:103]
	v_pk_mul_f32 v[100:101], v[76:77], v[88:89]
	v_cvt_f32_f16_sdwa v76, v187 dst_sel:DWORD dst_unused:UNUSED_PAD src0_sel:WORD_1
	v_pk_mul_f32 v[102:103], v[78:79], v[96:97]
	v_cvt_f32_f16_sdwa v77, v191 dst_sel:DWORD dst_unused:UNUSED_PAD src0_sel:WORD_1
	v_pk_mul_f32 v[78:79], v[90:91], v[98:99]
	v_rcp_f32_e32 v185, v76
	v_cvt_f32_f16_e32 v76, v191
	v_pk_mul_f32 v[96:97], v[64:65], v[78:79]
	v_cvt_f32_f16_e32 v65, v142
	v_cvt_f32_f16_e32 v79, v143
	v_pk_mul_f32 v[76:77], v[184:185], v[76:77]
	v_cvt_f32_f16_e32 v64, v140
	v_pk_mul_f32 v[98:99], v[66:67], v[76:77]
	v_rcp_f32_e32 v66, v65
	v_cvt_f32_f16_sdwa v65, v140 dst_sel:DWORD dst_unused:UNUSED_PAD src0_sel:WORD_1
	v_cvt_f32_f16_e32 v78, v141
	v_rcp_f32_e32 v90, v79
	v_cvt_f32_f16_sdwa v79, v141 dst_sel:DWORD dst_unused:UNUSED_PAD src0_sel:WORD_1
	v_rcp_f32_e32 v64, v64
	v_rcp_f32_e32 v65, v65
	v_cvt_f32_f16_e32 v76, v180
	v_cvt_f32_f16_sdwa v77, v180 dst_sel:DWORD dst_unused:UNUSED_PAD src0_sel:WORD_1
	v_rcp_f32_e32 v78, v78
	v_rcp_f32_e32 v79, v79
	v_cvt_f32_f16_e32 v140, v181
	v_cvt_f32_f16_sdwa v141, v181 dst_sel:DWORD dst_unused:UNUSED_PAD src0_sel:WORD_1
	v_cvt_f32_f16_sdwa v67, v142 dst_sel:DWORD dst_unused:UNUSED_PAD src0_sel:WORD_1
	v_pk_mul_f32 v[64:65], v[64:65], v[76:77]
	v_cvt_f32_f16_e32 v88, v182
	v_pk_mul_f32 v[76:77], v[78:79], v[140:141]
	v_rcp_f32_e32 v67, v67
	v_cvt_f32_f16_sdwa v89, v182 dst_sel:DWORD dst_unused:UNUSED_PAD src0_sel:WORD_1
	v_pk_mul_f32 v[78:79], v[62:63], v[76:77]
	v_pk_mul_f32 v[76:77], v[60:61], v[64:65]
	v_cvt_f32_f16_sdwa v60, v143 dst_sel:DWORD dst_unused:UNUSED_PAD src0_sel:WORD_1
	v_cvt_f32_f16_sdwa v61, v183 dst_sel:DWORD dst_unused:UNUSED_PAD src0_sel:WORD_1
	v_pk_mul_f32 v[62:63], v[66:67], v[88:89]
	v_cvt_f32_f16_e32 v89, v139
	v_rcp_f32_e32 v91, v60
	v_cvt_f32_f16_e32 v60, v183
	v_pk_mul_f32 v[64:65], v[48:49], v[62:63]
	v_cvt_f32_f16_e32 v49, v138
	v_cvt_f32_f16_e32 v48, v136
	v_pk_mul_f32 v[60:61], v[90:91], v[60:61]
	v_cvt_f32_f16_e32 v88, v137
	v_pk_mul_f32 v[66:67], v[50:51], v[60:61]
	v_rcp_f32_e32 v50, v49
	v_cvt_f32_f16_sdwa v49, v136 dst_sel:DWORD dst_unused:UNUSED_PAD src0_sel:WORD_1
	v_rcp_f32_e32 v48, v48
	v_cvt_f32_f16_e32 v60, v176
	v_cvt_f32_f16_sdwa v61, v176 dst_sel:DWORD dst_unused:UNUSED_PAD src0_sel:WORD_1
	v_rcp_f32_e32 v49, v49
	v_rcp_f32_e32 v90, v89
	v_cvt_f32_f16_sdwa v89, v137 dst_sel:DWORD dst_unused:UNUSED_PAD src0_sel:WORD_1
	v_cvt_f32_f16_sdwa v51, v138 dst_sel:DWORD dst_unused:UNUSED_PAD src0_sel:WORD_1
	v_rcp_f32_e32 v88, v88
	v_cvt_f32_f16_e32 v136, v177
	v_rcp_f32_e32 v89, v89
	v_cvt_f32_f16_sdwa v137, v177 dst_sel:DWORD dst_unused:UNUSED_PAD src0_sel:WORD_1
	v_pk_mul_f32 v[48:49], v[48:49], v[60:61]
	v_rcp_f32_e32 v51, v51
	v_cvt_f32_f16_e32 v62, v178
	v_cvt_f32_f16_sdwa v63, v178 dst_sel:DWORD dst_unused:UNUSED_PAD src0_sel:WORD_1
	v_pk_mul_f32 v[140:141], v[44:45], v[48:49]
	v_cvt_f32_f16_sdwa v44, v139 dst_sel:DWORD dst_unused:UNUSED_PAD src0_sel:WORD_1
	v_pk_mul_f32 v[60:61], v[88:89], v[136:137]
	v_cvt_f32_f16_sdwa v45, v179 dst_sel:DWORD dst_unused:UNUSED_PAD src0_sel:WORD_1
	v_pk_mul_f32 v[142:143], v[46:47], v[60:61]
	v_rcp_f32_e32 v91, v44
	v_cvt_f32_f16_e32 v44, v179
	v_pk_mul_f32 v[46:47], v[50:51], v[62:63]
	v_cvt_f32_f16_e32 v49, v135
	v_pk_mul_f32 v[136:137], v[32:33], v[46:47]
	v_cvt_f32_f16_e32 v33, v134
	v_pk_mul_f32 v[44:45], v[90:91], v[44:45]
	v_cvt_f32_f16_e32 v32, v132
	v_pk_mul_f32 v[138:139], v[34:35], v[44:45]
	v_rcp_f32_e32 v34, v33
	v_cvt_f32_f16_sdwa v33, v132 dst_sel:DWORD dst_unused:UNUSED_PAD src0_sel:WORD_1
	v_cvt_f32_f16_e32 v48, v133
	v_rcp_f32_e32 v50, v49
	v_cvt_f32_f16_sdwa v49, v133 dst_sel:DWORD dst_unused:UNUSED_PAD src0_sel:WORD_1
	v_rcp_f32_e32 v32, v32
	v_rcp_f32_e32 v33, v33
	v_cvt_f32_f16_e32 v44, v172
	v_cvt_f32_f16_sdwa v45, v172 dst_sel:DWORD dst_unused:UNUSED_PAD src0_sel:WORD_1
	v_cvt_f32_f16_sdwa v35, v134 dst_sel:DWORD dst_unused:UNUSED_PAD src0_sel:WORD_1
	v_rcp_f32_e32 v48, v48
	v_rcp_f32_e32 v49, v49
	v_cvt_f32_f16_e32 v60, v173
	v_cvt_f32_f16_sdwa v61, v173 dst_sel:DWORD dst_unused:UNUSED_PAD src0_sel:WORD_1
	v_pk_mul_f32 v[32:33], v[32:33], v[44:45]
	v_rcp_f32_e32 v35, v35
	v_cvt_f32_f16_e32 v46, v174
	v_cvt_f32_f16_sdwa v47, v174 dst_sel:DWORD dst_unused:UNUSED_PAD src0_sel:WORD_1
	v_pk_mul_f32 v[44:45], v[48:49], v[60:61]
	v_pk_mul_f32 v[60:61], v[24:25], v[32:33]
	v_cvt_f32_f16_sdwa v24, v135 dst_sel:DWORD dst_unused:UNUSED_PAD src0_sel:WORD_1
	v_pk_mul_f32 v[62:63], v[26:27], v[44:45]
	v_cvt_f32_f16_sdwa v25, v175 dst_sel:DWORD dst_unused:UNUSED_PAD src0_sel:WORD_1
	v_pk_mul_f32 v[26:27], v[34:35], v[46:47]
	v_rcp_f32_e32 v51, v24
	v_cvt_f32_f16_e32 v24, v175
	v_pk_mul_f32 v[48:49], v[20:21], v[26:27]
	v_cvt_f32_f16_e32 v21, v130
	v_cvt_f32_f16_e32 v20, v128
	v_pk_mul_f32 v[24:25], v[50:51], v[24:25]
	v_cvt_f32_f16_e32 v33, v131
	v_pk_mul_f32 v[50:51], v[22:23], v[24:25]
	v_rcp_f32_e32 v22, v21
	v_cvt_f32_f16_sdwa v21, v128 dst_sel:DWORD dst_unused:UNUSED_PAD src0_sel:WORD_1
	v_rcp_f32_e32 v20, v20
	v_cvt_f32_f16_e32 v24, v168
	v_cvt_f32_f16_sdwa v25, v168 dst_sel:DWORD dst_unused:UNUSED_PAD src0_sel:WORD_1
	v_rcp_f32_e32 v21, v21
	v_cvt_f32_f16_e32 v32, v129
	v_rcp_f32_e32 v34, v33
	v_cvt_f32_f16_sdwa v33, v129 dst_sel:DWORD dst_unused:UNUSED_PAD src0_sel:WORD_1
	v_cvt_f32_f16_sdwa v23, v130 dst_sel:DWORD dst_unused:UNUSED_PAD src0_sel:WORD_1
	v_rcp_f32_e32 v32, v32
	v_cvt_f32_f16_e32 v44, v169
	v_rcp_f32_e32 v33, v33
	v_cvt_f32_f16_sdwa v45, v169 dst_sel:DWORD dst_unused:UNUSED_PAD src0_sel:WORD_1
	v_pk_mul_f32 v[20:21], v[20:21], v[24:25]
	v_rcp_f32_e32 v23, v23
	v_cvt_f32_f16_e32 v26, v170
	v_cvt_f32_f16_sdwa v27, v170 dst_sel:DWORD dst_unused:UNUSED_PAD src0_sel:WORD_1
	v_pk_mul_f32 v[132:133], v[16:17], v[20:21]
	v_cvt_f32_f16_sdwa v16, v131 dst_sel:DWORD dst_unused:UNUSED_PAD src0_sel:WORD_1
	v_pk_mul_f32 v[24:25], v[32:33], v[44:45]
	v_cvt_f32_f16_sdwa v17, v171 dst_sel:DWORD dst_unused:UNUSED_PAD src0_sel:WORD_1
	v_pk_mul_f32 v[134:135], v[18:19], v[24:25]
	v_rcp_f32_e32 v35, v16
	v_cvt_f32_f16_e32 v16, v171
	v_pk_mul_f32 v[18:19], v[22:23], v[26:27]
	v_cvt_f32_f16_e32 v21, v111
	v_pk_mul_f32 v[128:129], v[12:13], v[18:19]
	v_cvt_f32_f16_e32 v13, v110
	v_pk_mul_f32 v[16:17], v[34:35], v[16:17]
	v_cvt_f32_f16_e32 v12, v108
	v_pk_mul_f32 v[130:131], v[14:15], v[16:17]
	v_rcp_f32_e32 v14, v13
	v_cvt_f32_f16_sdwa v13, v108 dst_sel:DWORD dst_unused:UNUSED_PAD src0_sel:WORD_1
	v_rcp_f32_e32 v12, v12
	v_cvt_f32_f16_e32 v16, v164
	v_cvt_f32_f16_sdwa v17, v164 dst_sel:DWORD dst_unused:UNUSED_PAD src0_sel:WORD_1
	v_rcp_f32_e32 v13, v13
	v_cvt_f32_f16_e32 v20, v109
	v_rcp_f32_e32 v22, v21
	v_cvt_f32_f16_sdwa v21, v109 dst_sel:DWORD dst_unused:UNUSED_PAD src0_sel:WORD_1
	v_pk_mul_f32 v[12:13], v[12:13], v[16:17]
	v_cvt_f32_f16_sdwa v15, v110 dst_sel:DWORD dst_unused:UNUSED_PAD src0_sel:WORD_1
	v_pk_mul_f32 v[32:33], v[8:9], v[12:13]
	v_cvt_f32_f16_sdwa v8, v111 dst_sel:DWORD dst_unused:UNUSED_PAD src0_sel:WORD_1
	v_rcp_f32_e32 v20, v20
	v_rcp_f32_e32 v21, v21
	v_cvt_f32_f16_e32 v24, v165
	v_cvt_f32_f16_sdwa v25, v165 dst_sel:DWORD dst_unused:UNUSED_PAD src0_sel:WORD_1
	v_rcp_f32_e32 v15, v15
	v_cvt_f32_f16_e32 v18, v166
	v_cvt_f32_f16_sdwa v19, v166 dst_sel:DWORD dst_unused:UNUSED_PAD src0_sel:WORD_1
	v_rcp_f32_e32 v23, v8
	v_cvt_f32_f16_e32 v8, v167
	v_cvt_f32_f16_sdwa v9, v167 dst_sel:DWORD dst_unused:UNUSED_PAD src0_sel:WORD_1
	v_pk_mul_f32 v[16:17], v[20:21], v[24:25]
	s_mov_b64 s[26:27], 0x80480
	v_pk_mul_f32 v[34:35], v[10:11], v[16:17]
	v_pk_mul_f32 v[10:11], v[14:15], v[18:19]
	v_pk_mul_f32 v[8:9], v[22:23], v[8:9]
	v_pk_mul_f32 v[44:45], v[4:5], v[10:11]
	v_pk_mul_f32 v[46:47], v[6:7], v[8:9]
	v_lshl_add_u64 v[4:5], s[34:35], 0, v[210:211]
.LBB0_1744:
	ds_read_b128 v[6:9], v237
	ds_read_b128 v[10:13], v237 offset:1024
	ds_read_b128 v[14:17], v237 offset:2048
	ds_read_b128 v[18:21], v237 offset:3072
	v_lshl_add_u64 v[246:247], v[4:5], 0, s[16:17]
	s_mov_b32 m0, s14
	v_lshl_add_u64 v[26:27], v[246:247], 0, s[26:27]
	v_lshl_add_u64 v[248:249], v[200:201], 0, s[16:17]
	ds_read_b128 v[22:25], v236
	ds_read_b128 v[88:91], v236 offset:1024
	ds_read_b128 v[108:111], v236 offset:2048
	ds_read_b128 v[164:167], v236 offset:3072
	ds_read_b128 v[168:171], v236 offset:4096
	ds_read_b128 v[172:175], v236 offset:5120
	ds_read_b128 v[176:179], v236 offset:6144
	ds_read_b128 v[180:183], v236 offset:7168
	global_load_lds_dwordx4 v[26:27], off
	v_lshl_add_u64 v[26:27], v[248:249], 0, s[26:27]
	s_mov_b32 m0, s15
	s_nop 0
	global_load_lds_dwordx4 v[26:27], off
	s_waitcnt lgkmcnt(8)
	s_barrier
	s_waitcnt lgkmcnt(0)
	v_mfma_f32_16x16x32_f16 v[80:83], v[6:9], v[22:25], v[80:83]
	v_mfma_f32_16x16x32_f16 v[72:75], v[14:17], v[22:25], v[72:75]
	v_mfma_f32_16x16x32_f16 v[56:59], v[6:9], v[108:111], v[56:59]
	v_mfma_f32_16x16x32_f16 v[68:71], v[14:17], v[108:111], v[68:71]
	v_mfma_f32_16x16x32_f16 v[160:163], v[6:9], v[168:171], v[160:163]
	v_mfma_f32_16x16x32_f16 v[156:159], v[14:17], v[168:171], v[156:159]
	v_mfma_f32_16x16x32_f16 v[152:155], v[6:9], v[176:179], v[152:155]
	v_mfma_f32_16x16x32_f16 v[148:151], v[14:17], v[176:179], v[148:151]
	v_mfma_f32_16x16x32_f16 v[80:83], v[10:13], v[88:91], v[80:83]
	v_mfma_f32_16x16x32_f16 v[72:75], v[18:21], v[88:91], v[72:75]
	v_mfma_f32_16x16x32_f16 v[56:59], v[10:13], v[164:167], v[56:59]
	v_mfma_f32_16x16x32_f16 v[68:71], v[18:21], v[164:167], v[68:71]
	v_mfma_f32_16x16x32_f16 v[160:163], v[10:13], v[172:175], v[160:163]
	v_mfma_f32_16x16x32_f16 v[156:159], v[18:21], v[172:175], v[156:159]
	v_mfma_f32_16x16x32_f16 v[152:155], v[10:13], v[180:183], v[152:155]
	v_mfma_f32_16x16x32_f16 v[148:151], v[18:21], v[180:183], v[148:151]
	s_barrier
	v_lshl_add_u64 v[224:225], v[202:203], 0, s[16:17]
	s_mov_b32 m0, s19
	v_lshl_add_u64 v[26:27], v[224:225], 0, s[30:31]
	v_lshl_add_u64 v[226:227], v[220:221], 0, s[16:17]
	ds_read_b128 v[184:187], v238
	ds_read_b128 v[188:191], v238 offset:1024
	ds_read_b128 v[192:195], v238 offset:2048
	ds_read_b128 v[196:199], v238 offset:3072
	global_load_lds_dwordx4 v[26:27], off
	v_lshl_add_u64 v[26:27], v[226:227], 0, s[30:31]
	s_mov_b32 m0, s37
	s_nop 0
	global_load_lds_dwordx4 v[26:27], off
	s_barrier
	s_waitcnt lgkmcnt(0)
	v_mfma_f32_16x16x32_f16 v[52:55], v[184:187], v[22:25], v[52:55]
	v_mfma_f32_16x16x32_f16 v[22:25], v[192:195], v[22:25], v[40:43]
	v_mfma_f32_16x16x32_f16 v[40:43], v[184:187], v[168:171], v[144:147]
	v_mfma_f32_16x16x32_f16 v[52:55], v[188:191], v[88:91], v[52:55]
	v_mfma_f32_16x16x32_f16 v[22:25], v[196:199], v[88:91], v[22:25]
	v_mfma_f32_16x16x32_f16 v[88:91], v[188:191], v[172:175], v[40:43]
	v_mfma_f32_16x16x32_f16 v[40:43], v[192:195], v[168:171], v[124:127]
	v_mfma_f32_16x16x32_f16 v[36:39], v[184:187], v[108:111], v[36:39]
	v_mfma_f32_16x16x32_f16 v[26:29], v[192:195], v[108:111], v[28:31]
	v_mfma_f32_16x16x32_f16 v[108:111], v[196:199], v[172:175], v[40:43]
	v_mfma_f32_16x16x32_f16 v[40:43], v[184:187], v[176:179], v[120:123]
	v_mfma_f32_16x16x32_f16 v[120:123], v[188:191], v[180:183], v[40:43]
	v_mfma_f32_16x16x32_f16 v[40:43], v[192:195], v[176:179], v[116:119]
	v_mfma_f32_16x16x32_f16 v[36:39], v[188:191], v[164:167], v[36:39]
	v_mfma_f32_16x16x32_f16 v[26:29], v[196:199], v[164:167], v[26:29]
	v_mfma_f32_16x16x32_f16 v[116:119], v[196:199], v[180:183], v[40:43]
	s_mov_b32 m0, s7
	v_lshl_add_u64 v[30:31], v[246:247], 0, s[30:31]
	s_barrier
	s_nop 0
	ds_read_b128 v[40:43], v236 offset:16384
	ds_read_b128 v[124:127], v236 offset:17408
	ds_read_b128 v[144:147], v236 offset:18432
	ds_read_b128 v[164:167], v236 offset:19456
	ds_read_b128 v[168:171], v236 offset:20480
	ds_read_b128 v[172:175], v236 offset:21504
	ds_read_b128 v[176:179], v236 offset:22528
	ds_read_b128 v[180:183], v236 offset:23552
	global_load_lds_dwordx4 v[30:31], off
	v_lshl_add_u64 v[30:31], v[248:249], 0, s[30:31]
	s_mov_b32 m0, s8
	s_nop 0
	global_load_lds_dwordx4 v[30:31], off
	s_barrier
	s_waitcnt lgkmcnt(0)
	v_mfma_f32_16x16x32_f16 v[112:115], v[6:9], v[40:43], v[112:115]
	v_mfma_f32_16x16x32_f16 v[104:107], v[14:17], v[40:43], v[104:107]
	v_mfma_f32_16x16x32_f16 v[100:103], v[6:9], v[144:147], v[100:103]
	v_mfma_f32_16x16x32_f16 v[96:99], v[14:17], v[144:147], v[96:99]
	v_mfma_f32_16x16x32_f16 v[140:143], v[6:9], v[168:171], v[140:143]
	v_mfma_f32_16x16x32_f16 v[136:139], v[14:17], v[168:171], v[136:139]
	v_mfma_f32_16x16x32_f16 v[6:9], v[6:9], v[176:179], v[132:135]
	v_mfma_f32_16x16x32_f16 v[112:115], v[10:13], v[124:127], v[112:115]
	v_mfma_f32_16x16x32_f16 v[104:107], v[18:21], v[124:127], v[104:107]
	v_mfma_f32_16x16x32_f16 v[100:103], v[10:13], v[164:167], v[100:103]
	v_mfma_f32_16x16x32_f16 v[96:99], v[18:21], v[164:167], v[96:99]
	v_mfma_f32_16x16x32_f16 v[140:143], v[10:13], v[172:175], v[140:143]
	v_mfma_f32_16x16x32_f16 v[136:139], v[18:21], v[172:175], v[136:139]
	v_mfma_f32_16x16x32_f16 v[6:9], v[10:13], v[180:183], v[6:9]
	v_mfma_f32_16x16x32_f16 v[10:13], v[14:17], v[176:179], v[128:131]
	v_mfma_f32_16x16x32_f16 v[10:13], v[18:21], v[180:183], v[10:13]
	s_barrier
	s_mov_b32 m0, s63
	v_lshl_add_u64 v[14:15], v[224:225], 0, s[84:85]
	global_load_lds_dwordx4 v[14:15], off
	v_lshl_add_u64 v[14:15], v[226:227], 0, s[84:85]
	s_mov_b32 m0, s68
	s_nop 0
	global_load_lds_dwordx4 v[14:15], off
	s_waitcnt vmcnt(6)
	s_barrier
	v_mfma_f32_16x16x32_f16 v[14:17], v[184:187], v[40:43], v[92:95]
	v_mfma_f32_16x16x32_f16 v[18:21], v[192:195], v[40:43], v[84:87]
	v_mfma_f32_16x16x32_f16 v[40:43], v[184:187], v[144:147], v[76:79]
	v_mfma_f32_16x16x32_f16 v[76:79], v[188:191], v[164:167], v[40:43]
	v_mfma_f32_16x16x32_f16 v[40:43], v[192:195], v[144:147], v[64:67]
	v_mfma_f32_16x16x32_f16 v[64:67], v[196:199], v[164:167], v[40:43]
	v_mfma_f32_16x16x32_f16 v[40:43], v[184:187], v[168:171], v[60:63]
	v_mfma_f32_16x16x32_f16 v[60:63], v[188:191], v[172:175], v[40:43]
	v_mfma_f32_16x16x32_f16 v[40:43], v[192:195], v[168:171], v[48:51]
	v_mfma_f32_16x16x32_f16 v[48:51], v[196:199], v[172:175], v[40:43]
	v_mfma_f32_16x16x32_f16 v[30:33], v[184:187], v[176:179], v[32:35]
	v_mfma_f32_16x16x32_f16 v[40:43], v[192:195], v[176:179], v[44:47]
	v_mfma_f32_16x16x32_f16 v[32:35], v[188:191], v[180:183], v[30:33]
	v_mfma_f32_16x16x32_f16 v[44:47], v[196:199], v[180:183], v[40:43]
	v_mfma_f32_16x16x32_f16 v[14:17], v[188:191], v[124:127], v[14:17]
	v_mfma_f32_16x16x32_f16 v[18:21], v[196:199], v[124:127], v[18:21]
	s_barrier
	ds_read_b128 v[84:87], v239
	ds_read_b128 v[92:95], v239 offset:1024
	ds_read_b128 v[128:131], v239 offset:2048
	ds_read_b128 v[164:167], v239 offset:3072
	s_mov_b32 m0, s9
	v_lshl_add_u64 v[30:31], v[246:247], 0, s[84:85]
	ds_read_b128 v[40:43], v236 offset:32768
	ds_read_b128 v[124:127], v236 offset:33792
	ds_read_b128 v[132:135], v236 offset:34816
	ds_read_b128 v[144:147], v236 offset:35840
	ds_read_b128 v[168:171], v236 offset:36864
	ds_read_b128 v[172:175], v236 offset:37888
	ds_read_b128 v[176:179], v236 offset:38912
	ds_read_b128 v[180:183], v236 offset:39936
	global_load_lds_dwordx4 v[30:31], off
	v_lshl_add_u64 v[30:31], v[248:249], 0, s[84:85]
	s_mov_b32 m0, s12
	s_nop 0
	global_load_lds_dwordx4 v[30:31], off
	s_waitcnt lgkmcnt(8)
	s_barrier
	s_waitcnt lgkmcnt(0)
	v_mfma_f32_16x16x32_f16 v[80:83], v[84:87], v[40:43], v[80:83]
	v_mfma_f32_16x16x32_f16 v[72:75], v[128:131], v[40:43], v[72:75]
	v_mfma_f32_16x16x32_f16 v[56:59], v[84:87], v[132:135], v[56:59]
	v_mfma_f32_16x16x32_f16 v[68:71], v[128:131], v[132:135], v[68:71]
	v_mfma_f32_16x16x32_f16 v[160:163], v[84:87], v[168:171], v[160:163]
	v_mfma_f32_16x16x32_f16 v[156:159], v[128:131], v[168:171], v[156:159]
	v_mfma_f32_16x16x32_f16 v[152:155], v[84:87], v[176:179], v[152:155]
	v_mfma_f32_16x16x32_f16 v[148:151], v[128:131], v[176:179], v[148:151]
	v_mfma_f32_16x16x32_f16 v[80:83], v[92:95], v[124:127], v[80:83]
	v_mfma_f32_16x16x32_f16 v[72:75], v[164:167], v[124:127], v[72:75]
	v_mfma_f32_16x16x32_f16 v[56:59], v[92:95], v[144:147], v[56:59]
	v_mfma_f32_16x16x32_f16 v[68:71], v[164:167], v[144:147], v[68:71]
	v_mfma_f32_16x16x32_f16 v[160:163], v[92:95], v[172:175], v[160:163]
	v_mfma_f32_16x16x32_f16 v[156:159], v[164:167], v[172:175], v[156:159]
	v_mfma_f32_16x16x32_f16 v[152:155], v[92:95], v[180:183], v[152:155]
	v_mfma_f32_16x16x32_f16 v[148:151], v[164:167], v[180:183], v[148:151]
	s_barrier
	s_mov_b32 m0, s69
	v_lshl_add_u64 v[30:31], v[224:225], 0, vcc
	ds_read_b128 v[184:187], v240
	ds_read_b128 v[188:191], v240 offset:1024
	ds_read_b128 v[192:195], v240 offset:2048
	ds_read_b128 v[196:199], v240 offset:3072
	global_load_lds_dwordx4 v[30:31], off
	v_lshl_add_u64 v[30:31], v[226:227], 0, vcc
	s_mov_b32 m0, s70
	s_nop 0
	global_load_lds_dwordx4 v[30:31], off
	s_barrier
	s_waitcnt lgkmcnt(0)
	v_mfma_f32_16x16x32_f16 v[22:25], v[192:195], v[40:43], v[22:25]
	v_mfma_f32_16x16x32_f16 v[52:55], v[184:187], v[40:43], v[52:55]
	v_mfma_f32_16x16x32_f16 v[40:43], v[196:199], v[124:127], v[22:25]
	v_mfma_f32_16x16x32_f16 v[22:25], v[184:187], v[132:135], v[36:39]
	v_mfma_f32_16x16x32_f16 v[36:39], v[188:191], v[144:147], v[22:25]
	v_mfma_f32_16x16x32_f16 v[22:25], v[192:195], v[132:135], v[26:29]
	v_mfma_f32_16x16x32_f16 v[28:31], v[196:199], v[144:147], v[22:25]
	v_mfma_f32_16x16x32_f16 v[22:25], v[184:187], v[168:171], v[88:91]
	v_mfma_f32_16x16x32_f16 v[144:147], v[188:191], v[172:175], v[22:25]
	v_mfma_f32_16x16x32_f16 v[22:25], v[192:195], v[168:171], v[108:111]
	v_mfma_f32_16x16x32_f16 v[52:55], v[188:191], v[124:127], v[52:55]
	v_mfma_f32_16x16x32_f16 v[124:127], v[196:199], v[172:175], v[22:25]
	v_mfma_f32_16x16x32_f16 v[22:25], v[184:187], v[176:179], v[120:123]
	v_mfma_f32_16x16x32_f16 v[120:123], v[188:191], v[180:183], v[22:25]
	v_mfma_f32_16x16x32_f16 v[22:25], v[192:195], v[176:179], v[116:119]
	v_mfma_f32_16x16x32_f16 v[116:119], v[196:199], v[180:183], v[22:25]
	s_mov_b32 m0, s39
	v_lshl_add_u64 v[26:27], v[246:247], 0, vcc
	s_barrier
	s_nop 2
	ds_read_b128 v[22:25], v236 offset:49152
	ds_read_b128 v[88:91], v236 offset:50176
	ds_read_b128 v[108:111], v236 offset:51200
	ds_read_b128 v[168:171], v236 offset:52224
	ds_read_b128 v[172:175], v236 offset:53248
	ds_read_b128 v[176:179], v236 offset:54272
	ds_read_b128 v[180:183], v236 offset:55296
	ds_read_b128 v[242:245], v236 offset:56320
	global_load_lds_dwordx4 v[26:27], off
	v_lshl_add_u64 v[26:27], v[248:249], 0, vcc
	s_mov_b32 m0, s47
	s_nop 0
	global_load_lds_dwordx4 v[26:27], off
	s_barrier
	s_waitcnt lgkmcnt(0)
	v_mfma_f32_16x16x32_f16 v[132:135], v[84:87], v[172:175], v[140:143]
	v_mfma_f32_16x16x32_f16 v[140:143], v[92:95], v[176:179], v[132:135]
	v_mfma_f32_16x16x32_f16 v[132:135], v[128:131], v[172:175], v[136:139]
	v_mfma_f32_16x16x32_f16 v[6:9], v[84:87], v[180:183], v[6:9]
	v_mfma_f32_16x16x32_f16 v[112:115], v[84:87], v[22:25], v[112:115]
	v_mfma_f32_16x16x32_f16 v[104:107], v[128:131], v[22:25], v[104:107]
	v_mfma_f32_16x16x32_f16 v[100:103], v[84:87], v[108:111], v[100:103]
	v_mfma_f32_16x16x32_f16 v[96:99], v[128:131], v[108:111], v[96:99]
	v_mfma_f32_16x16x32_f16 v[136:139], v[164:167], v[176:179], v[132:135]
	v_mfma_f32_16x16x32_f16 v[132:135], v[92:95], v[242:245], v[6:9]
	v_mfma_f32_16x16x32_f16 v[6:9], v[128:131], v[180:183], v[10:13]
	v_mfma_f32_16x16x32_f16 v[112:115], v[92:95], v[88:91], v[112:115]
	v_mfma_f32_16x16x32_f16 v[104:107], v[164:167], v[88:91], v[104:107]
	v_mfma_f32_16x16x32_f16 v[100:103], v[92:95], v[168:171], v[100:103]
	v_mfma_f32_16x16x32_f16 v[96:99], v[164:167], v[168:171], v[96:99]
	v_mfma_f32_16x16x32_f16 v[128:131], v[164:167], v[242:245], v[6:9]
	s_barrier
	s_mov_b32 m0, s71
	v_lshl_add_u64 v[6:7], v[224:225], 0, s[52:53]
	global_load_lds_dwordx4 v[6:7], off
	v_lshl_add_u64 v[6:7], v[226:227], 0, s[52:53]
	s_mov_b32 m0, s76
	s_nop 0
	global_load_lds_dwordx4 v[6:7], off
	s_waitcnt vmcnt(6)
	s_barrier
	v_mfma_f32_16x16x32_f16 v[6:9], v[184:187], v[22:25], v[14:17]
	v_mfma_f32_16x16x32_f16 v[92:95], v[188:191], v[88:91], v[6:9]
	v_mfma_f32_16x16x32_f16 v[6:9], v[192:195], v[22:25], v[18:21]
	v_mfma_f32_16x16x32_f16 v[84:87], v[196:199], v[88:91], v[6:9]
	v_mfma_f32_16x16x32_f16 v[6:9], v[184:187], v[108:111], v[76:79]
	v_mfma_f32_16x16x32_f16 v[76:79], v[188:191], v[168:171], v[6:9]
	v_mfma_f32_16x16x32_f16 v[6:9], v[192:195], v[108:111], v[64:67]
	v_mfma_f32_16x16x32_f16 v[64:67], v[196:199], v[168:171], v[6:9]
	v_mfma_f32_16x16x32_f16 v[6:9], v[184:187], v[172:175], v[60:63]
	v_mfma_f32_16x16x32_f16 v[60:63], v[188:191], v[176:179], v[6:9]
	v_mfma_f32_16x16x32_f16 v[6:9], v[192:195], v[172:175], v[48:51]
	v_mfma_f32_16x16x32_f16 v[48:51], v[196:199], v[176:179], v[6:9]
	v_mfma_f32_16x16x32_f16 v[6:9], v[184:187], v[180:183], v[32:35]
	v_mfma_f32_16x16x32_f16 v[32:35], v[188:191], v[242:245], v[6:9]
	v_mfma_f32_16x16x32_f16 v[6:9], v[192:195], v[180:183], v[44:47]
	v_mfma_f32_16x16x32_f16 v[44:47], v[196:199], v[242:245], v[6:9]
	s_add_i32 s10, s10, 2
	s_add_u32 s16, s16, 0x100
	s_addc_u32 s17, s17, 0
	s_cmp_lt_u32 s10, 14
	s_barrier
	s_cbranch_scc1 .LBB0_1744
	s_add_i32 s10, s46, 8
	s_mul_hi_i32 s11, s10, 0x42
	s_mulk_i32 s10, 0x42
	s_add_u32 s10, s10, s48
	v_mov_b32_e32 v4, v233
	v_mov_b32_e32 v5, v234
	s_addc_u32 s11, s11, s78
	s_lshl_b64 s[10:11], s[10:11], 17
	v_readlane_b32 s16, v252, 45
	v_lshlrev_b32_e32 v5, 3, v5
	s_add_u32 s16, s16, s10
	v_readlane_b32 s10, v252, 46
	v_lshlrev_b32_e32 v4, 8, v4
	s_addc_u32 s17, s10, s11
	v_add3_u32 v196, v4, s49, v5
	s_add_u32 s26, s16, 0x4200000
	v_ashrrev_i32_e32 v197, 31, v196
	s_addc_u32 s27, s17, 0
	v_lshlrev_b64 v[4:5], 1, v[196:197]
	v_lshl_add_u64 v[6:7], s[16:17], 0, v[4:5]
	v_lshl_add_u64 v[12:13], s[26:27], 0, v[4:5]
	v_add_u32_e32 v4, 0x1000, v196
	v_ashrrev_i32_e32 v5, 31, v4
	v_lshlrev_b64 v[4:5], 1, v[4:5]
	v_lshl_add_u64 v[14:15], s[16:17], 0, v[4:5]
	v_lshl_add_u64 v[20:21], s[26:27], 0, v[4:5]
	v_add_u32_e32 v4, 0x1080, v196
	v_ashrrev_i32_e32 v5, 31, v4
	v_lshlrev_b64 v[4:5], 1, v[4:5]
	v_lshl_add_u64 v[22:23], s[16:17], 0, v[4:5]
	v_lshl_add_u64 v[26:27], s[26:27], 0, v[4:5]
	v_add_u32_e32 v4, 0x2000, v196
	v_ashrrev_i32_e32 v5, 31, v4
	v_lshlrev_b64 v[4:5], 1, v[4:5]
	v_lshl_add_u64 v[24:25], s[16:17], 0, v[4:5]
	v_lshl_add_u64 v[168:169], s[26:27], 0, v[4:5]
	v_add_u32_e32 v4, 0x2080, v196
	v_ashrrev_i32_e32 v5, 31, v4
	v_lshlrev_b64 v[4:5], 1, v[4:5]
	v_lshl_add_u64 v[16:17], s[16:17], 0, v[4:5]
	v_lshl_add_u64 v[170:171], s[26:27], 0, v[4:5]
	v_add_u32_e32 v4, 0x3000, v196
	v_ashrrev_i32_e32 v5, 31, v4
	v_lshlrev_b64 v[4:5], 1, v[4:5]
	v_lshl_add_u64 v[8:9], s[16:17], 0, v[4:5]
	v_lshl_add_u64 v[176:177], s[26:27], 0, v[4:5]
	v_add_u32_e32 v4, 0x3080, v196
	v_ashrrev_i32_e32 v5, 31, v4
	v_lshlrev_b64 v[4:5], 1, v[4:5]
	v_lshl_add_u64 v[10:11], s[16:17], 0, v[4:5]
	v_lshl_add_u64 v[164:165], s[26:27], 0, v[4:5]
	global_load_dwordx4 v[192:195], v[6:7], off offset:256
	global_load_dwordx4 v[108:111], v[6:7], off
	s_nop 0
	global_load_dwordx4 v[4:7], v[10:11], off
	s_nop 0
	global_load_dwordx4 v[8:11], v[8:9], off
	s_nop 0
	global_load_dwordx4 v[16:19], v[16:17], off
	s_nop 0
	global_load_dwordx4 v[172:175], v[24:25], off
	global_load_dwordx4 v[180:183], v[22:23], off
	global_load_dwordx4 v[188:191], v[14:15], off
	global_load_dwordx4 v[88:91], v[12:13], off offset:256
	global_load_dwordx4 v[198:201], v[12:13], off
	s_nop 0
	global_load_dwordx4 v[164:167], v[164:165], off
	s_nop 0
	global_load_dwordx4 v[12:15], v[176:177], off
	global_load_dwordx4 v[22:25], v[170:171], off
	s_nop 0
	global_load_dwordx4 v[168:171], v[168:169], off
	s_nop 0
	global_load_dwordx4 v[176:179], v[26:27], off
	global_load_dwordx4 v[184:187], v[20:21], off
	s_mov_b32 s29, 14
	s_waitcnt vmcnt(0)
	s_nop 0
	v_cvt_f32_f16_e32 v21, v110
	v_cvt_f32_f16_e32 v20, v108
	v_rcp_f32_e32 v26, v21
	v_cvt_f32_f16_sdwa v21, v108 dst_sel:DWORD dst_unused:UNUSED_PAD src0_sel:WORD_1
	v_rcp_f32_e32 v20, v20
	v_cvt_f32_f16_e32 v202, v198
	v_cvt_f32_f16_sdwa v203, v198 dst_sel:DWORD dst_unused:UNUSED_PAD src0_sel:WORD_1
	v_rcp_f32_e32 v21, v21
	v_cvt_f32_f16_sdwa v27, v110 dst_sel:DWORD dst_unused:UNUSED_PAD src0_sel:WORD_1
	v_cvt_f32_f16_e32 v110, v111
	v_cvt_f32_f16_e32 v108, v109
	v_pk_mul_f32 v[20:21], v[20:21], v[202:203]
	v_cvt_f32_f16_sdwa v109, v109 dst_sel:DWORD dst_unused:UNUSED_PAD src0_sel:WORD_1
	v_pk_mul_f32 v[80:81], v[80:81], v[20:21]
	v_cvt_f32_f16_sdwa v20, v111 dst_sel:DWORD dst_unused:UNUSED_PAD src0_sel:WORD_1
	v_rcp_f32_e32 v110, v110
	v_cvt_f32_f16_sdwa v21, v201 dst_sel:DWORD dst_unused:UNUSED_PAD src0_sel:WORD_1
	v_rcp_f32_e32 v27, v27
	v_rcp_f32_e32 v111, v20
	v_cvt_f32_f16_e32 v20, v201
	v_cvt_f32_f16_e32 v220, v200
	v_cvt_f32_f16_sdwa v221, v200 dst_sel:DWORD dst_unused:UNUSED_PAD src0_sel:WORD_1
	v_rcp_f32_e32 v108, v108
	v_rcp_f32_e32 v109, v109
	v_cvt_f32_f16_e32 v198, v199
	v_cvt_f32_f16_sdwa v199, v199 dst_sel:DWORD dst_unused:UNUSED_PAD src0_sel:WORD_1
	v_pk_mul_f32 v[20:21], v[110:111], v[20:21]
	v_pk_mul_f32 v[26:27], v[26:27], v[220:221]
	v_pk_mul_f32 v[110:111], v[74:75], v[20:21]
	v_cvt_f32_f16_e32 v21, v194
	v_cvt_f32_f16_e32 v75, v195
	v_pk_mul_f32 v[108:109], v[108:109], v[198:199]
	v_cvt_f32_f16_e32 v20, v192
	v_pk_mul_f32 v[82:83], v[82:83], v[108:109]
	v_pk_mul_f32 v[108:109], v[72:73], v[26:27]
	v_rcp_f32_e32 v26, v21
	v_cvt_f32_f16_sdwa v21, v192 dst_sel:DWORD dst_unused:UNUSED_PAD src0_sel:WORD_1
	v_cvt_f32_f16_e32 v72, v88
	v_cvt_f32_f16_sdwa v73, v88 dst_sel:DWORD dst_unused:UNUSED_PAD src0_sel:WORD_1
	v_cvt_f32_f16_e32 v74, v193
	v_rcp_f32_e32 v88, v75
	v_cvt_f32_f16_sdwa v75, v193 dst_sel:DWORD dst_unused:UNUSED_PAD src0_sel:WORD_1
	v_rcp_f32_e32 v20, v20
	v_rcp_f32_e32 v21, v21
	v_rcp_f32_e32 v74, v74
	v_rcp_f32_e32 v75, v75
	v_cvt_f32_f16_e32 v192, v89
	v_cvt_f32_f16_sdwa v193, v89 dst_sel:DWORD dst_unused:UNUSED_PAD src0_sel:WORD_1
	v_pk_mul_f32 v[20:21], v[20:21], v[72:73]
	v_cvt_f32_f16_sdwa v27, v194 dst_sel:DWORD dst_unused:UNUSED_PAD src0_sel:WORD_1
	v_cvt_f32_f16_e32 v198, v90
	v_pk_mul_f32 v[72:73], v[74:75], v[192:193]
	v_cvt_f32_f16_sdwa v199, v90 dst_sel:DWORD dst_unused:UNUSED_PAD src0_sel:WORD_1
	v_pk_mul_f32 v[74:75], v[54:55], v[72:73]
	v_pk_mul_f32 v[72:73], v[52:53], v[20:21]
	v_cvt_f32_f16_sdwa v20, v195 dst_sel:DWORD dst_unused:UNUSED_PAD src0_sel:WORD_1
	v_cvt_f32_f16_sdwa v21, v91 dst_sel:DWORD dst_unused:UNUSED_PAD src0_sel:WORD_1
	v_rcp_f32_e32 v27, v27
	v_cvt_f32_f16_e32 v53, v191
	v_rcp_f32_e32 v89, v20
	v_cvt_f32_f16_e32 v20, v91
	v_pk_mul_f32 v[26:27], v[26:27], v[198:199]
	v_rcp_f32_e32 v54, v53
	v_cvt_f32_f16_e32 v52, v189
	v_pk_mul_f32 v[20:21], v[88:89], v[20:21]
	v_pk_mul_f32 v[88:89], v[40:41], v[26:27]
	v_pk_mul_f32 v[90:91], v[42:43], v[20:21]
	v_cvt_f32_f16_e32 v21, v190
	v_cvt_f32_f16_e32 v20, v188
	v_cvt_f32_f16_e32 v40, v184
	v_cvt_f32_f16_sdwa v41, v184 dst_sel:DWORD dst_unused:UNUSED_PAD src0_sel:WORD_1
	v_rcp_f32_e32 v26, v21
	v_cvt_f32_f16_sdwa v21, v188 dst_sel:DWORD dst_unused:UNUSED_PAD src0_sel:WORD_1
	v_rcp_f32_e32 v20, v20
	v_cvt_f32_f16_sdwa v27, v190 dst_sel:DWORD dst_unused:UNUSED_PAD src0_sel:WORD_1
	v_cvt_f32_f16_e32 v42, v186
	v_rcp_f32_e32 v21, v21
	v_cvt_f32_f16_sdwa v43, v186 dst_sel:DWORD dst_unused:UNUSED_PAD src0_sel:WORD_1
	v_rcp_f32_e32 v27, v27
	v_cvt_f32_f16_sdwa v53, v189 dst_sel:DWORD dst_unused:UNUSED_PAD src0_sel:WORD_1
	v_pk_mul_f32 v[20:21], v[20:21], v[40:41]
	v_rcp_f32_e32 v52, v52
	v_pk_mul_f32 v[56:57], v[56:57], v[20:21]
	v_cvt_f32_f16_sdwa v20, v191 dst_sel:DWORD dst_unused:UNUSED_PAD src0_sel:WORD_1
	v_cvt_f32_f16_sdwa v21, v187 dst_sel:DWORD dst_unused:UNUSED_PAD src0_sel:WORD_1
	v_pk_mul_f32 v[26:27], v[26:27], v[42:43]
	v_cvt_f32_f16_e32 v43, v183
	v_rcp_f32_e32 v55, v20
	v_cvt_f32_f16_e32 v20, v187
	v_rcp_f32_e32 v53, v53
	v_cvt_f32_f16_e32 v184, v185
	v_cvt_f32_f16_sdwa v185, v185 dst_sel:DWORD dst_unused:UNUSED_PAD src0_sel:WORD_1
	v_pk_mul_f32 v[20:21], v[54:55], v[20:21]
	v_pk_mul_f32 v[68:69], v[68:69], v[26:27]
	v_pk_mul_f32 v[70:71], v[70:71], v[20:21]
	v_cvt_f32_f16_e32 v21, v182
	v_cvt_f32_f16_e32 v20, v180
	v_cvt_f32_f16_e32 v42, v181
	v_rcp_f32_e32 v54, v43
	v_rcp_f32_e32 v26, v21
	v_cvt_f32_f16_sdwa v21, v180 dst_sel:DWORD dst_unused:UNUSED_PAD src0_sel:WORD_1
	v_cvt_f32_f16_sdwa v43, v181 dst_sel:DWORD dst_unused:UNUSED_PAD src0_sel:WORD_1
	v_pk_mul_f32 v[40:41], v[52:53], v[184:185]
	v_rcp_f32_e32 v20, v20
	v_pk_mul_f32 v[58:59], v[58:59], v[40:41]
	v_rcp_f32_e32 v21, v21
	v_cvt_f32_f16_e32 v40, v176
	v_cvt_f32_f16_sdwa v41, v176 dst_sel:DWORD dst_unused:UNUSED_PAD src0_sel:WORD_1
	v_rcp_f32_e32 v42, v42
	v_rcp_f32_e32 v43, v43
	v_cvt_f32_f16_e32 v176, v177
	v_cvt_f32_f16_sdwa v177, v177 dst_sel:DWORD dst_unused:UNUSED_PAD src0_sel:WORD_1
	v_pk_mul_f32 v[20:21], v[20:21], v[40:41]
	v_cvt_f32_f16_sdwa v27, v182 dst_sel:DWORD dst_unused:UNUSED_PAD src0_sel:WORD_1
	v_cvt_f32_f16_e32 v52, v178
	v_pk_mul_f32 v[40:41], v[42:43], v[176:177]
	v_cvt_f32_f16_sdwa v53, v178 dst_sel:DWORD dst_unused:UNUSED_PAD src0_sel:WORD_1
	v_pk_mul_f32 v[42:43], v[38:39], v[40:41]
	v_pk_mul_f32 v[40:41], v[36:37], v[20:21]
	v_cvt_f32_f16_sdwa v20, v183 dst_sel:DWORD dst_unused:UNUSED_PAD src0_sel:WORD_1
	v_cvt_f32_f16_sdwa v21, v179 dst_sel:DWORD dst_unused:UNUSED_PAD src0_sel:WORD_1
	v_rcp_f32_e32 v27, v27
	v_cvt_f32_f16_e32 v36, v170
	v_rcp_f32_e32 v55, v20
	v_cvt_f32_f16_e32 v20, v179
	v_pk_mul_f32 v[26:27], v[26:27], v[52:53]
	v_cvt_f32_f16_sdwa v37, v170 dst_sel:DWORD dst_unused:UNUSED_PAD src0_sel:WORD_1
	v_pk_mul_f32 v[52:53], v[28:29], v[26:27]
	v_pk_mul_f32 v[20:21], v[54:55], v[20:21]
	v_cvt_f32_f16_e32 v28, v168
	v_pk_mul_f32 v[54:55], v[30:31], v[20:21]
	v_cvt_f32_f16_e32 v21, v174
	v_cvt_f32_f16_e32 v31, v175
	v_cvt_f32_f16_e32 v20, v172
	v_cvt_f32_f16_e32 v30, v173
	v_rcp_f32_e32 v26, v21
	v_cvt_f32_f16_sdwa v21, v172 dst_sel:DWORD dst_unused:UNUSED_PAD src0_sel:WORD_1
	v_rcp_f32_e32 v38, v31
	v_cvt_f32_f16_sdwa v31, v173 dst_sel:DWORD dst_unused:UNUSED_PAD src0_sel:WORD_1
	v_rcp_f32_e32 v20, v20
	v_rcp_f32_e32 v21, v21
	v_cvt_f32_f16_sdwa v29, v168 dst_sel:DWORD dst_unused:UNUSED_PAD src0_sel:WORD_1
	v_rcp_f32_e32 v30, v30
	v_rcp_f32_e32 v31, v31
	v_cvt_f32_f16_e32 v168, v169
	v_cvt_f32_f16_sdwa v169, v169 dst_sel:DWORD dst_unused:UNUSED_PAD src0_sel:WORD_1
	v_pk_mul_f32 v[20:21], v[20:21], v[28:29]
	v_cvt_f32_f16_sdwa v27, v174 dst_sel:DWORD dst_unused:UNUSED_PAD src0_sel:WORD_1
	v_pk_mul_f32 v[28:29], v[30:31], v[168:169]
	v_rcp_f32_e32 v27, v27
	v_pk_mul_f32 v[30:31], v[162:163], v[28:29]
	v_pk_mul_f32 v[28:29], v[160:161], v[20:21]
	v_cvt_f32_f16_sdwa v20, v175 dst_sel:DWORD dst_unused:UNUSED_PAD src0_sel:WORD_1
	v_cvt_f32_f16_sdwa v21, v171 dst_sel:DWORD dst_unused:UNUSED_PAD src0_sel:WORD_1
	v_pk_mul_f32 v[26:27], v[26:27], v[36:37]
	v_rcp_f32_e32 v39, v20
	v_cvt_f32_f16_e32 v20, v171
	v_pk_mul_f32 v[36:37], v[156:157], v[26:27]
	v_cvt_f32_f16_e32 v156, v22
	v_cvt_f32_f16_sdwa v157, v22 dst_sel:DWORD dst_unused:UNUSED_PAD src0_sel:WORD_1
	v_pk_mul_f32 v[20:21], v[38:39], v[20:21]
	v_cvt_f32_f16_e32 v22, v23
	v_pk_mul_f32 v[38:39], v[158:159], v[20:21]
	v_cvt_f32_f16_e32 v20, v16
	v_cvt_f32_f16_e32 v21, v18
	v_cvt_f32_f16_sdwa v16, v16 dst_sel:DWORD dst_unused:UNUSED_PAD src0_sel:WORD_1
	v_cvt_f32_f16_sdwa v23, v23 dst_sel:DWORD dst_unused:UNUSED_PAD src0_sel:WORD_1
	v_cvt_f32_f16_e32 v158, v24
	v_rcp_f32_e32 v26, v21
	v_rcp_f32_e32 v21, v16
	v_cvt_f32_f16_sdwa v16, v18 dst_sel:DWORD dst_unused:UNUSED_PAD src0_sel:WORD_1
	v_cvt_f32_f16_e32 v18, v19
	v_cvt_f32_f16_sdwa v159, v24 dst_sel:DWORD dst_unused:UNUSED_PAD src0_sel:WORD_1
	v_rcp_f32_e32 v20, v20
	v_rcp_f32_e32 v27, v16
	v_cvt_f32_f16_e32 v16, v17
	v_cvt_f32_f16_sdwa v17, v17 dst_sel:DWORD dst_unused:UNUSED_PAD src0_sel:WORD_1
	v_rcp_f32_e32 v18, v18
	v_pk_mul_f32 v[20:21], v[20:21], v[156:157]
	v_rcp_f32_e32 v16, v16
	v_rcp_f32_e32 v17, v17
	v_pk_mul_f32 v[20:21], v[144:145], v[20:21]
	v_cvt_f32_f16_e32 v144, v165
	v_cvt_f32_f16_sdwa v145, v165 dst_sel:DWORD dst_unused:UNUSED_PAD src0_sel:WORD_1
	v_pk_mul_f32 v[16:17], v[16:17], v[22:23]
	s_nop 0
	v_pk_mul_f32 v[22:23], v[146:147], v[16:17]
	v_cvt_f32_f16_sdwa v16, v19 dst_sel:DWORD dst_unused:UNUSED_PAD src0_sel:WORD_1
	v_cvt_f32_f16_sdwa v17, v25 dst_sel:DWORD dst_unused:UNUSED_PAD src0_sel:WORD_1
	v_rcp_f32_e32 v19, v16
	v_cvt_f32_f16_e32 v16, v25
	v_pk_mul_f32 v[24:25], v[26:27], v[158:159]
	v_pk_mul_f32 v[16:17], v[18:19], v[16:17]
	s_nop 0
	v_pk_mul_f32 v[26:27], v[126:127], v[16:17]
	v_cvt_f32_f16_e32 v16, v8
	v_cvt_f32_f16_e32 v17, v10
	v_cvt_f32_f16_sdwa v8, v8 dst_sel:DWORD dst_unused:UNUSED_PAD src0_sel:WORD_1
	v_pk_mul_f32 v[24:25], v[124:125], v[24:25]
	v_cvt_f32_f16_e32 v18, v12
	v_rcp_f32_e32 v124, v17
	v_rcp_f32_e32 v17, v8
	v_cvt_f32_f16_sdwa v8, v10 dst_sel:DWORD dst_unused:UNUSED_PAD src0_sel:WORD_1
	v_cvt_f32_f16_sdwa v19, v12 dst_sel:DWORD dst_unused:UNUSED_PAD src0_sel:WORD_1
	v_cvt_f32_f16_e32 v12, v13
	v_cvt_f32_f16_sdwa v13, v13 dst_sel:DWORD dst_unused:UNUSED_PAD src0_sel:WORD_1
	v_rcp_f32_e32 v125, v8
	v_cvt_f32_f16_e32 v8, v9
	v_cvt_f32_f16_sdwa v9, v9 dst_sel:DWORD dst_unused:UNUSED_PAD src0_sel:WORD_1
	v_rcp_f32_e32 v16, v16
	v_cvt_f32_f16_e32 v10, v11
	v_rcp_f32_e32 v8, v8
	v_rcp_f32_e32 v9, v9
	v_pk_mul_f32 v[16:17], v[16:17], v[18:19]
	v_rcp_f32_e32 v10, v10
	v_cvt_f32_f16_e32 v126, v14
	v_pk_mul_f32 v[8:9], v[8:9], v[12:13]
	v_cvt_f32_f16_sdwa v127, v14 dst_sel:DWORD dst_unused:UNUSED_PAD src0_sel:WORD_1
	v_pk_mul_f32 v[18:19], v[154:155], v[8:9]
	v_cvt_f32_f16_sdwa v8, v11 dst_sel:DWORD dst_unused:UNUSED_PAD src0_sel:WORD_1
	v_cvt_f32_f16_sdwa v9, v15 dst_sel:DWORD dst_unused:UNUSED_PAD src0_sel:WORD_1
	v_pk_mul_f32 v[12:13], v[124:125], v[126:127]
	v_cvt_f32_f16_e32 v126, v166
	v_rcp_f32_e32 v11, v8
	v_cvt_f32_f16_e32 v8, v15
	v_cvt_f32_f16_sdwa v127, v166 dst_sel:DWORD dst_unused:UNUSED_PAD src0_sel:WORD_1
	v_pk_mul_f32 v[16:17], v[152:153], v[16:17]
	v_pk_mul_f32 v[12:13], v[148:149], v[12:13]
	v_pk_mul_f32 v[8:9], v[10:11], v[8:9]
	v_cvt_f32_f16_e32 v10, v164
	v_pk_mul_f32 v[14:15], v[150:151], v[8:9]
	v_cvt_f32_f16_e32 v8, v4
	v_cvt_f32_f16_e32 v9, v6
	v_cvt_f32_f16_sdwa v4, v4 dst_sel:DWORD dst_unused:UNUSED_PAD src0_sel:WORD_1
	v_cvt_f32_f16_sdwa v11, v164 dst_sel:DWORD dst_unused:UNUSED_PAD src0_sel:WORD_1
	v_rcp_f32_e32 v8, v8
	v_rcp_f32_e32 v124, v9
	v_rcp_f32_e32 v9, v4
	v_cvt_f32_f16_sdwa v4, v6 dst_sel:DWORD dst_unused:UNUSED_PAD src0_sel:WORD_1
	v_cvt_f32_f16_e32 v6, v7
	v_pk_mul_f32 v[8:9], v[8:9], v[10:11]
	v_rcp_f32_e32 v125, v4
	v_cvt_f32_f16_e32 v4, v5
	v_cvt_f32_f16_sdwa v5, v5 dst_sel:DWORD dst_unused:UNUSED_PAD src0_sel:WORD_1
	v_rcp_f32_e32 v6, v6
	v_pk_mul_f32 v[8:9], v[120:121], v[8:9]
	v_rcp_f32_e32 v4, v4
	v_rcp_f32_e32 v5, v5
	v_pk_mul_f32 v[120:121], v[124:125], v[126:127]
	v_pk_mul_f32 v[4:5], v[4:5], v[144:145]
	s_nop 0
	v_pk_mul_f32 v[10:11], v[122:123], v[4:5]
	v_cvt_f32_f16_sdwa v4, v7 dst_sel:DWORD dst_unused:UNUSED_PAD src0_sel:WORD_1
	v_cvt_f32_f16_sdwa v5, v167 dst_sel:DWORD dst_unused:UNUSED_PAD src0_sel:WORD_1
	v_rcp_f32_e32 v7, v4
	v_cvt_f32_f16_e32 v4, v167
	v_pk_mul_f32 v[4:5], v[6:7], v[4:5]
	s_nop 0
	v_pk_mul_f32 v[6:7], v[118:119], v[4:5]
	v_add_u32_e32 v118, 0x8080, v196
	v_ashrrev_i32_e32 v119, 31, v118
	v_lshlrev_b64 v[118:119], 1, v[118:119]
	v_pk_mul_f32 v[4:5], v[116:117], v[120:121]
	v_lshl_add_u64 v[120:121], s[16:17], 0, v[118:119]
	v_lshl_add_u64 v[124:125], s[26:27], 0, v[118:119]
	v_add_u32_e32 v118, 0x9000, v196
	v_ashrrev_i32_e32 v119, 31, v118
	v_lshlrev_b64 v[118:119], 1, v[118:119]
	v_lshl_add_u64 v[126:127], s[16:17], 0, v[118:119]
	v_lshl_add_u64 v[192:193], s[26:27], 0, v[118:119]
	v_add_u32_e32 v118, 0x9080, v196
	v_ashrrev_i32_e32 v119, 31, v118
	v_lshlrev_b64 v[118:119], 1, v[118:119]
	v_lshl_add_u64 v[144:145], s[16:17], 0, v[118:119]
	v_lshl_add_u64 v[184:185], s[26:27], 0, v[118:119]
	v_add_u32_e32 v118, 0xa000, v196
	v_ashrrev_i32_e32 v119, 31, v118
	v_lshlrev_b64 v[118:119], 1, v[118:119]
	v_lshl_add_u64 v[146:147], s[16:17], 0, v[118:119]
	v_lshl_add_u64 v[176:177], s[26:27], 0, v[118:119]
	v_add_u32_e32 v118, 0xa080, v196
	v_ashrrev_i32_e32 v119, 31, v118
	v_lshlrev_b64 v[118:119], 1, v[118:119]
	v_lshl_add_u64 v[152:153], s[16:17], 0, v[118:119]
	v_lshl_add_u64 v[168:169], s[26:27], 0, v[118:119]
	v_add_u32_e32 v118, 0xb000, v196
	v_ashrrev_i32_e32 v119, 31, v118
	v_lshlrev_b64 v[118:119], 1, v[118:119]
	v_lshl_add_u64 v[154:155], s[16:17], 0, v[118:119]
	v_lshl_add_u64 v[160:161], s[26:27], 0, v[118:119]
	v_add_u32_e32 v118, 0xb080, v196
	v_add_u32_e32 v116, 0x8000, v196
	v_ashrrev_i32_e32 v119, 31, v118
	v_ashrrev_i32_e32 v117, 31, v116
	v_lshlrev_b64 v[118:119], 1, v[118:119]
	v_lshlrev_b64 v[116:117], 1, v[116:117]
	v_lshl_add_u64 v[148:149], s[16:17], 0, v[118:119]
	v_lshl_add_u64 v[162:163], s[26:27], 0, v[118:119]
	v_lshl_add_u64 v[122:123], s[16:17], 0, v[116:117]
	v_lshl_add_u64 v[116:117], s[26:27], 0, v[116:117]
	global_load_dwordx4 v[148:151], v[148:149], off
	s_nop 0
	global_load_dwordx4 v[156:159], v[154:155], off
	global_load_dwordx4 v[164:167], v[152:153], off
	global_load_dwordx4 v[172:175], v[146:147], off
	global_load_dwordx4 v[180:183], v[144:145], off
	global_load_dwordx4 v[188:191], v[126:127], off
	s_nop 0
	global_load_dwordx4 v[118:121], v[120:121], off
	s_nop 0
	global_load_dwordx4 v[144:147], v[122:123], off
	global_load_dwordx4 v[152:155], v[162:163], off
	s_nop 0
	global_load_dwordx4 v[160:163], v[160:161], off
	s_nop 0
	global_load_dwordx4 v[168:171], v[168:169], off
	s_nop 0
	global_load_dwordx4 v[176:179], v[176:177], off
	s_nop 0
	global_load_dwordx4 v[184:187], v[184:185], off
	s_nop 0
	global_load_dwordx4 v[192:195], v[192:193], off
	s_nop 0
	global_load_dwordx4 v[196:199], v[124:125], off
	global_load_dwordx4 v[200:203], v[116:117], off
	s_waitcnt vmcnt(0)
	s_nop 0
	v_cvt_f32_f16_e32 v117, v146
	v_cvt_f32_f16_e32 v127, v147
	v_cvt_f32_f16_e32 v116, v144
	v_cvt_f32_f16_e32 v126, v145
	v_rcp_f32_e32 v122, v117
	v_cvt_f32_f16_sdwa v117, v144 dst_sel:DWORD dst_unused:UNUSED_PAD src0_sel:WORD_1
	v_rcp_f32_e32 v144, v127
	v_cvt_f32_f16_sdwa v127, v145 dst_sel:DWORD dst_unused:UNUSED_PAD src0_sel:WORD_1
	v_rcp_f32_e32 v116, v116
	v_rcp_f32_e32 v117, v117
	v_cvt_f32_f16_e32 v124, v200
	v_cvt_f32_f16_sdwa v125, v200 dst_sel:DWORD dst_unused:UNUSED_PAD src0_sel:WORD_1
	v_rcp_f32_e32 v126, v126
	v_rcp_f32_e32 v127, v127
	v_cvt_f32_f16_e32 v200, v201
	v_cvt_f32_f16_sdwa v201, v201 dst_sel:DWORD dst_unused:UNUSED_PAD src0_sel:WORD_1
	v_cvt_f32_f16_sdwa v123, v146 dst_sel:DWORD dst_unused:UNUSED_PAD src0_sel:WORD_1
	v_pk_mul_f32 v[116:117], v[116:117], v[124:125]
	v_cvt_f32_f16_e32 v220, v202
	v_pk_mul_f32 v[124:125], v[126:127], v[200:201]
	v_rcp_f32_e32 v123, v123
	v_pk_mul_f32 v[126:127], v[114:115], v[124:125]
	v_pk_mul_f32 v[124:125], v[112:113], v[116:117]
	v_cvt_f32_f16_sdwa v112, v147 dst_sel:DWORD dst_unused:UNUSED_PAD src0_sel:WORD_1
	v_cvt_f32_f16_sdwa v221, v202 dst_sel:DWORD dst_unused:UNUSED_PAD src0_sel:WORD_1
	v_cvt_f32_f16_sdwa v113, v203 dst_sel:DWORD dst_unused:UNUSED_PAD src0_sel:WORD_1
	v_cvt_f32_f16_e32 v117, v121
	v_rcp_f32_e32 v145, v112
	v_cvt_f32_f16_e32 v112, v203
	v_pk_mul_f32 v[114:115], v[122:123], v[220:221]
	v_cvt_f32_f16_e32 v116, v119
	s_add_u32 s16, s34, 0x80880
	v_pk_mul_f32 v[112:113], v[144:145], v[112:113]
	v_pk_mul_f32 v[144:145], v[104:105], v[114:115]
	v_cvt_f32_f16_e32 v105, v120
	v_pk_mul_f32 v[146:147], v[106:107], v[112:113]
	v_cvt_f32_f16_e32 v104, v118
	v_cvt_f32_f16_sdwa v107, v120 dst_sel:DWORD dst_unused:UNUSED_PAD src0_sel:WORD_1
	v_rcp_f32_e32 v106, v105
	v_cvt_f32_f16_sdwa v105, v118 dst_sel:DWORD dst_unused:UNUSED_PAD src0_sel:WORD_1
	v_rcp_f32_e32 v120, v117
	v_cvt_f32_f16_sdwa v117, v119 dst_sel:DWORD dst_unused:UNUSED_PAD src0_sel:WORD_1
	v_rcp_f32_e32 v104, v104
	v_rcp_f32_e32 v105, v105
	v_cvt_f32_f16_e32 v112, v196
	v_cvt_f32_f16_sdwa v113, v196 dst_sel:DWORD dst_unused:UNUSED_PAD src0_sel:WORD_1
	v_rcp_f32_e32 v116, v116
	v_rcp_f32_e32 v117, v117
	v_cvt_f32_f16_e32 v118, v197
	v_cvt_f32_f16_sdwa v119, v197 dst_sel:DWORD dst_unused:UNUSED_PAD src0_sel:WORD_1
	v_pk_mul_f32 v[104:105], v[104:105], v[112:113]
	v_rcp_f32_e32 v107, v107
	v_cvt_f32_f16_e32 v114, v198
	v_pk_mul_f32 v[112:113], v[116:117], v[118:119]
	v_pk_mul_f32 v[116:117], v[92:93], v[104:105]
	v_cvt_f32_f16_sdwa v92, v121 dst_sel:DWORD dst_unused:UNUSED_PAD src0_sel:WORD_1
	v_cvt_f32_f16_sdwa v115, v198 dst_sel:DWORD dst_unused:UNUSED_PAD src0_sel:WORD_1
	v_cvt_f32_f16_sdwa v93, v199 dst_sel:DWORD dst_unused:UNUSED_PAD src0_sel:WORD_1
	v_pk_mul_f32 v[118:119], v[94:95], v[112:113]
	v_rcp_f32_e32 v121, v92
	v_cvt_f32_f16_e32 v92, v199
	v_pk_mul_f32 v[94:95], v[106:107], v[114:115]
	v_cvt_f32_f16_e32 v105, v191
	v_cvt_f32_f16_e32 v104, v189
	v_pk_mul_f32 v[92:93], v[120:121], v[92:93]
	v_pk_mul_f32 v[120:121], v[84:85], v[94:95]
	v_cvt_f32_f16_e32 v85, v190
	v_pk_mul_f32 v[122:123], v[86:87], v[92:93]
	v_cvt_f32_f16_e32 v84, v188
	v_rcp_f32_e32 v112, v105
	v_rcp_f32_e32 v86, v85
	v_cvt_f32_f16_sdwa v85, v188 dst_sel:DWORD dst_unused:UNUSED_PAD src0_sel:WORD_1
	v_cvt_f32_f16_sdwa v105, v189 dst_sel:DWORD dst_unused:UNUSED_PAD src0_sel:WORD_1
	v_rcp_f32_e32 v84, v84
	v_cvt_f32_f16_e32 v92, v192
	v_rcp_f32_e32 v85, v85
	v_cvt_f32_f16_sdwa v93, v192 dst_sel:DWORD dst_unused:UNUSED_PAD src0_sel:WORD_1
	v_rcp_f32_e32 v104, v104
	v_rcp_f32_e32 v105, v105
	v_cvt_f32_f16_e32 v106, v193
	v_cvt_f32_f16_sdwa v107, v193 dst_sel:DWORD dst_unused:UNUSED_PAD src0_sel:WORD_1
	v_pk_mul_f32 v[84:85], v[84:85], v[92:93]
	v_cvt_f32_f16_sdwa v87, v190 dst_sel:DWORD dst_unused:UNUSED_PAD src0_sel:WORD_1
	v_cvt_f32_f16_e32 v94, v194
	v_pk_mul_f32 v[92:93], v[104:105], v[106:107]
	v_pk_mul_f32 v[104:105], v[100:101], v[84:85]
	v_cvt_f32_f16_sdwa v84, v191 dst_sel:DWORD dst_unused:UNUSED_PAD src0_sel:WORD_1
	v_cvt_f32_f16_sdwa v85, v195 dst_sel:DWORD dst_unused:UNUSED_PAD src0_sel:WORD_1
	v_rcp_f32_e32 v87, v87
	v_cvt_f32_f16_sdwa v95, v194 dst_sel:DWORD dst_unused:UNUSED_PAD src0_sel:WORD_1
	v_rcp_f32_e32 v113, v84
	v_cvt_f32_f16_e32 v84, v195
	v_pk_mul_f32 v[106:107], v[102:103], v[92:93]
	v_pk_mul_f32 v[86:87], v[86:87], v[94:95]
	v_cvt_f32_f16_e32 v92, v184
	v_pk_mul_f32 v[84:85], v[112:113], v[84:85]
	v_pk_mul_f32 v[112:113], v[96:97], v[86:87]
	v_pk_mul_f32 v[114:115], v[98:99], v[84:85]
	v_cvt_f32_f16_e32 v85, v182
	v_cvt_f32_f16_e32 v97, v183
	v_cvt_f32_f16_e32 v84, v180
	v_cvt_f32_f16_e32 v96, v181
	v_rcp_f32_e32 v86, v85
	v_cvt_f32_f16_sdwa v85, v180 dst_sel:DWORD dst_unused:UNUSED_PAD src0_sel:WORD_1
	v_rcp_f32_e32 v100, v97
	v_cvt_f32_f16_sdwa v97, v181 dst_sel:DWORD dst_unused:UNUSED_PAD src0_sel:WORD_1
	v_rcp_f32_e32 v84, v84
	v_rcp_f32_e32 v85, v85
	v_cvt_f32_f16_sdwa v93, v184 dst_sel:DWORD dst_unused:UNUSED_PAD src0_sel:WORD_1
	v_rcp_f32_e32 v96, v96
	v_rcp_f32_e32 v97, v97
	v_cvt_f32_f16_e32 v98, v185
	v_cvt_f32_f16_sdwa v99, v185 dst_sel:DWORD dst_unused:UNUSED_PAD src0_sel:WORD_1
	v_cvt_f32_f16_sdwa v87, v182 dst_sel:DWORD dst_unused:UNUSED_PAD src0_sel:WORD_1
	v_pk_mul_f32 v[84:85], v[84:85], v[92:93]
	v_cvt_f32_f16_e32 v94, v186
	v_pk_mul_f32 v[92:93], v[96:97], v[98:99]
	v_pk_mul_f32 v[96:97], v[76:77], v[84:85]
	v_cvt_f32_f16_sdwa v76, v183 dst_sel:DWORD dst_unused:UNUSED_PAD src0_sel:WORD_1
	v_rcp_f32_e32 v87, v87
	v_cvt_f32_f16_sdwa v95, v186 dst_sel:DWORD dst_unused:UNUSED_PAD src0_sel:WORD_1
	v_cvt_f32_f16_sdwa v77, v187 dst_sel:DWORD dst_unused:UNUSED_PAD src0_sel:WORD_1
	v_rcp_f32_e32 v101, v76
	v_cvt_f32_f16_e32 v76, v187
	v_pk_mul_f32 v[98:99], v[78:79], v[92:93]
	v_pk_mul_f32 v[78:79], v[86:87], v[94:95]
	v_cvt_f32_f16_e32 v85, v175
	v_pk_mul_f32 v[76:77], v[100:101], v[76:77]
	v_pk_mul_f32 v[100:101], v[64:65], v[78:79]
	v_cvt_f32_f16_e32 v65, v174
	v_pk_mul_f32 v[102:103], v[66:67], v[76:77]
	v_cvt_f32_f16_e32 v64, v172
	v_cvt_f32_f16_e32 v84, v173
	v_rcp_f32_e32 v66, v65
	v_cvt_f32_f16_sdwa v65, v172 dst_sel:DWORD dst_unused:UNUSED_PAD src0_sel:WORD_1
	v_rcp_f32_e32 v92, v85
	v_cvt_f32_f16_sdwa v85, v173 dst_sel:DWORD dst_unused:UNUSED_PAD src0_sel:WORD_1
	v_rcp_f32_e32 v64, v64
	v_rcp_f32_e32 v65, v65
	v_cvt_f32_f16_e32 v76, v176
	v_cvt_f32_f16_sdwa v77, v176 dst_sel:DWORD dst_unused:UNUSED_PAD src0_sel:WORD_1
	v_rcp_f32_e32 v84, v84
	v_rcp_f32_e32 v85, v85
	v_cvt_f32_f16_e32 v86, v177
	v_cvt_f32_f16_sdwa v87, v177 dst_sel:DWORD dst_unused:UNUSED_PAD src0_sel:WORD_1
	v_pk_mul_f32 v[64:65], v[64:65], v[76:77]
	v_cvt_f32_f16_sdwa v67, v174 dst_sel:DWORD dst_unused:UNUSED_PAD src0_sel:WORD_1
	v_cvt_f32_f16_e32 v78, v178
	v_pk_mul_f32 v[76:77], v[84:85], v[86:87]
	v_pk_mul_f32 v[84:85], v[140:141], v[64:65]
	v_cvt_f32_f16_sdwa v64, v175 dst_sel:DWORD dst_unused:UNUSED_PAD src0_sel:WORD_1
	v_cvt_f32_f16_sdwa v65, v179 dst_sel:DWORD dst_unused:UNUSED_PAD src0_sel:WORD_1
	v_rcp_f32_e32 v67, v67
	v_cvt_f32_f16_sdwa v79, v178 dst_sel:DWORD dst_unused:UNUSED_PAD src0_sel:WORD_1
	v_rcp_f32_e32 v93, v64
	v_cvt_f32_f16_e32 v64, v179
	v_pk_mul_f32 v[86:87], v[142:143], v[76:77]
	v_pk_mul_f32 v[66:67], v[66:67], v[78:79]
	v_cvt_f32_f16_sdwa v77, v166 dst_sel:DWORD dst_unused:UNUSED_PAD src0_sel:WORD_1
	v_pk_mul_f32 v[64:65], v[92:93], v[64:65]
	v_pk_mul_f32 v[92:93], v[136:137], v[66:67]
	v_pk_mul_f32 v[94:95], v[138:139], v[64:65]
	v_cvt_f32_f16_e32 v65, v166
	v_cvt_f32_f16_e32 v64, v164
	v_cvt_f32_f16_e32 v137, v167
	v_cvt_f32_f16_e32 v66, v168
	v_rcp_f32_e32 v76, v65
	v_cvt_f32_f16_sdwa v65, v164 dst_sel:DWORD dst_unused:UNUSED_PAD src0_sel:WORD_1
	v_rcp_f32_e32 v64, v64
	v_cvt_f32_f16_sdwa v67, v168 dst_sel:DWORD dst_unused:UNUSED_PAD src0_sel:WORD_1
	v_cvt_f32_f16_e32 v136, v165
	v_rcp_f32_e32 v65, v65
	v_rcp_f32_e32 v138, v137
	v_cvt_f32_f16_sdwa v137, v165 dst_sel:DWORD dst_unused:UNUSED_PAD src0_sel:WORD_1
	v_rcp_f32_e32 v136, v136
	v_cvt_f32_f16_e32 v140, v169
	v_cvt_f32_f16_sdwa v141, v169 dst_sel:DWORD dst_unused:UNUSED_PAD src0_sel:WORD_1
	v_rcp_f32_e32 v137, v137
	v_pk_mul_f32 v[64:65], v[64:65], v[66:67]
	v_rcp_f32_e32 v77, v77
	v_cvt_f32_f16_e32 v78, v170
	v_cvt_f32_f16_sdwa v79, v170 dst_sel:DWORD dst_unused:UNUSED_PAD src0_sel:WORD_1
	v_pk_mul_f32 v[64:65], v[60:61], v[64:65]
	v_cvt_f32_f16_sdwa v60, v167 dst_sel:DWORD dst_unused:UNUSED_PAD src0_sel:WORD_1
	v_pk_mul_f32 v[66:67], v[136:137], v[140:141]
	v_cvt_f32_f16_sdwa v61, v171 dst_sel:DWORD dst_unused:UNUSED_PAD src0_sel:WORD_1
	v_pk_mul_f32 v[66:67], v[62:63], v[66:67]
	v_rcp_f32_e32 v139, v60
	v_cvt_f32_f16_e32 v60, v171
	v_pk_mul_f32 v[62:63], v[76:77], v[78:79]
	v_cvt_f32_f16_e32 v137, v159
	v_pk_mul_f32 v[76:77], v[48:49], v[62:63]
	v_cvt_f32_f16_e32 v49, v158
	v_pk_mul_f32 v[60:61], v[138:139], v[60:61]
	v_cvt_f32_f16_e32 v48, v156
	v_pk_mul_f32 v[78:79], v[50:51], v[60:61]
	v_rcp_f32_e32 v60, v49
	v_cvt_f32_f16_sdwa v49, v156 dst_sel:DWORD dst_unused:UNUSED_PAD src0_sel:WORD_1
	v_rcp_f32_e32 v48, v48
	v_cvt_f32_f16_e32 v50, v160
	v_cvt_f32_f16_sdwa v51, v160 dst_sel:DWORD dst_unused:UNUSED_PAD src0_sel:WORD_1
	v_rcp_f32_e32 v49, v49
	v_cvt_f32_f16_sdwa v61, v158 dst_sel:DWORD dst_unused:UNUSED_PAD src0_sel:WORD_1
	v_cvt_f32_f16_e32 v62, v162
	v_cvt_f32_f16_sdwa v63, v162 dst_sel:DWORD dst_unused:UNUSED_PAD src0_sel:WORD_1
	v_pk_mul_f32 v[48:49], v[48:49], v[50:51]
	v_rcp_f32_e32 v61, v61
	v_pk_mul_f32 v[48:49], v[132:133], v[48:49]
	v_cvt_f32_f16_sdwa v132, v159 dst_sel:DWORD dst_unused:UNUSED_PAD src0_sel:WORD_1
	v_rcp_f32_e32 v138, v137
	v_cvt_f32_f16_sdwa v133, v163 dst_sel:DWORD dst_unused:UNUSED_PAD src0_sel:WORD_1
	v_pk_mul_f32 v[60:61], v[60:61], v[62:63]
	v_rcp_f32_e32 v139, v132
	v_cvt_f32_f16_e32 v132, v163
	v_pk_mul_f32 v[60:61], v[128:129], v[60:61]
	v_cvt_f32_f16_e32 v129, v150
	v_cvt_f32_f16_e32 v136, v157
	v_cvt_f32_f16_sdwa v137, v157 dst_sel:DWORD dst_unused:UNUSED_PAD src0_sel:WORD_1
	v_pk_mul_f32 v[62:63], v[138:139], v[132:133]
	v_cvt_f32_f16_e32 v128, v148
	v_pk_mul_f32 v[62:63], v[130:131], v[62:63]
	v_rcp_f32_e32 v130, v129
	v_cvt_f32_f16_sdwa v129, v148 dst_sel:DWORD dst_unused:UNUSED_PAD src0_sel:WORD_1
	v_rcp_f32_e32 v136, v136
	v_rcp_f32_e32 v137, v137
	v_cvt_f32_f16_e32 v140, v161
	v_cvt_f32_f16_sdwa v141, v161 dst_sel:DWORD dst_unused:UNUSED_PAD src0_sel:WORD_1
	v_rcp_f32_e32 v128, v128
	v_rcp_f32_e32 v129, v129
	v_cvt_f32_f16_e32 v132, v152
	v_cvt_f32_f16_sdwa v133, v152 dst_sel:DWORD dst_unused:UNUSED_PAD src0_sel:WORD_1
	v_pk_mul_f32 v[50:51], v[136:137], v[140:141]
	v_cvt_f32_f16_e32 v137, v151
	v_cvt_f32_f16_sdwa v131, v150 dst_sel:DWORD dst_unused:UNUSED_PAD src0_sel:WORD_1
	v_pk_mul_f32 v[128:129], v[128:129], v[132:133]
	v_cvt_f32_f16_e32 v136, v149
	v_rcp_f32_e32 v138, v137
	v_cvt_f32_f16_sdwa v137, v149 dst_sel:DWORD dst_unused:UNUSED_PAD src0_sel:WORD_1
	v_pk_mul_f32 v[32:33], v[32:33], v[128:129]
	v_cvt_f32_f16_sdwa v128, v151 dst_sel:DWORD dst_unused:UNUSED_PAD src0_sel:WORD_1
	v_pk_mul_f32 v[50:51], v[134:135], v[50:51]
	v_rcp_f32_e32 v131, v131
	v_cvt_f32_f16_e32 v134, v154
	v_cvt_f32_f16_sdwa v135, v154 dst_sel:DWORD dst_unused:UNUSED_PAD src0_sel:WORD_1
	v_rcp_f32_e32 v136, v136
	v_rcp_f32_e32 v137, v137
	v_cvt_f32_f16_e32 v140, v153
	v_cvt_f32_f16_sdwa v141, v153 dst_sel:DWORD dst_unused:UNUSED_PAD src0_sel:WORD_1
	v_rcp_f32_e32 v139, v128
	v_cvt_f32_f16_e32 v128, v155
	v_cvt_f32_f16_sdwa v129, v155 dst_sel:DWORD dst_unused:UNUSED_PAD src0_sel:WORD_1
	s_addc_u32 s17, s35, 0
	v_pk_mul_f32 v[132:133], v[136:137], v[140:141]
	v_pk_mul_f32 v[130:131], v[130:131], v[134:135]
	v_pk_mul_f32 v[128:129], v[138:139], v[128:129]
	s_add_u32 s10, s50, 0x900
	v_pk_mul_f32 v[34:35], v[34:35], v[132:133]
	v_pk_mul_f32 v[46:47], v[46:47], v[128:129]
	v_pk_mul_f32 v[44:45], v[44:45], v[130:131]
	s_addc_u32 s11, s51, 0
.LBB0_1746:
	ds_read_b128 v[128:131], v237
	ds_read_b128 v[132:135], v237 offset:1024
	ds_read_b128 v[136:139], v237 offset:2048
	ds_read_b128 v[140:143], v237 offset:3072
	s_add_u32 s26, s16, 0xfff80080
	s_addc_u32 s27, s17, -1
	s_cmp_eq_u32 s29, 28
	s_cselect_b32 s35, s43, s27
	s_cselect_b32 s34, s42, s26
	s_cselect_b32 s27, s45, s11
	s_cselect_b32 s26, s44, s10
	s_mov_b32 m0, s14
	v_lshl_add_u64 v[180:181], s[16:17], 0, v[210:211]
	ds_read_b128 v[148:151], v236
	ds_read_b128 v[152:155], v236 offset:1024
	ds_read_b128 v[156:159], v236 offset:2048
	ds_read_b128 v[160:163], v236 offset:3072
	ds_read_b128 v[164:167], v236 offset:4096
	ds_read_b128 v[168:171], v236 offset:5120
	ds_read_b128 v[172:175], v236 offset:6144
	ds_read_b128 v[176:179], v236 offset:7168
	global_load_lds_dwordx4 v[180:181], off
	v_lshl_add_u64 v[180:181], s[16:17], 0, v[214:215]
	s_mov_b32 m0, s15
	s_nop 0
	global_load_lds_dwordx4 v[180:181], off
	s_waitcnt lgkmcnt(8)
	s_barrier
	s_waitcnt lgkmcnt(0)
	v_mfma_f32_16x16x32_f16 v[80:83], v[128:131], v[148:151], v[80:83]
	v_mfma_f32_16x16x32_f16 v[108:111], v[136:139], v[148:151], v[108:111]
	v_mfma_f32_16x16x32_f16 v[56:59], v[128:131], v[156:159], v[56:59]
	v_mfma_f32_16x16x32_f16 v[68:71], v[136:139], v[156:159], v[68:71]
	v_mfma_f32_16x16x32_f16 v[28:31], v[128:131], v[164:167], v[28:31]
	v_mfma_f32_16x16x32_f16 v[36:39], v[136:139], v[164:167], v[36:39]
	v_mfma_f32_16x16x32_f16 v[16:19], v[128:131], v[172:175], v[16:19]
	v_mfma_f32_16x16x32_f16 v[12:15], v[136:139], v[172:175], v[12:15]
	v_mfma_f32_16x16x32_f16 v[80:83], v[132:135], v[152:155], v[80:83]
	v_mfma_f32_16x16x32_f16 v[108:111], v[140:143], v[152:155], v[108:111]
	v_mfma_f32_16x16x32_f16 v[56:59], v[132:135], v[160:163], v[56:59]
	v_mfma_f32_16x16x32_f16 v[68:71], v[140:143], v[160:163], v[68:71]
	v_mfma_f32_16x16x32_f16 v[28:31], v[132:135], v[168:171], v[28:31]
	v_mfma_f32_16x16x32_f16 v[36:39], v[140:143], v[168:171], v[36:39]
	v_mfma_f32_16x16x32_f16 v[16:19], v[132:135], v[176:179], v[16:19]
	v_mfma_f32_16x16x32_f16 v[12:15], v[140:143], v[176:179], v[12:15]
	s_barrier
	s_mov_b32 m0, s19
	v_lshl_add_u64 v[196:197], s[26:27], 0, v[2:3]
	ds_read_b128 v[180:183], v238
	ds_read_b128 v[184:187], v238 offset:1024
	ds_read_b128 v[188:191], v238 offset:2048
	ds_read_b128 v[192:195], v238 offset:3072
	global_load_lds_dwordx4 v[196:197], off
	v_lshl_add_u64 v[198:199], s[26:27], 0, v[206:207]
	s_mov_b32 m0, s37
	s_nop 0
	global_load_lds_dwordx4 v[198:199], off
	s_barrier
	s_waitcnt lgkmcnt(0)
	v_mfma_f32_16x16x32_f16 v[72:75], v[180:183], v[148:151], v[72:75]
	v_mfma_f32_16x16x32_f16 v[88:91], v[188:191], v[148:151], v[88:91]
	v_mfma_f32_16x16x32_f16 v[40:43], v[180:183], v[156:159], v[40:43]
	v_mfma_f32_16x16x32_f16 v[52:55], v[188:191], v[156:159], v[52:55]
	v_mfma_f32_16x16x32_f16 v[20:23], v[180:183], v[164:167], v[20:23]
	v_mfma_f32_16x16x32_f16 v[24:27], v[188:191], v[164:167], v[24:27]
	v_mfma_f32_16x16x32_f16 v[8:11], v[180:183], v[172:175], v[8:11]
	v_mfma_f32_16x16x32_f16 v[4:7], v[188:191], v[172:175], v[4:7]
	v_mfma_f32_16x16x32_f16 v[72:75], v[184:187], v[152:155], v[72:75]
	v_mfma_f32_16x16x32_f16 v[88:91], v[192:195], v[152:155], v[88:91]
	v_mfma_f32_16x16x32_f16 v[40:43], v[184:187], v[160:163], v[40:43]
	v_mfma_f32_16x16x32_f16 v[52:55], v[192:195], v[160:163], v[52:55]
	v_mfma_f32_16x16x32_f16 v[20:23], v[184:187], v[168:171], v[20:23]
	v_mfma_f32_16x16x32_f16 v[24:27], v[192:195], v[168:171], v[24:27]
	v_mfma_f32_16x16x32_f16 v[8:11], v[184:187], v[176:179], v[8:11]
	v_mfma_f32_16x16x32_f16 v[4:7], v[192:195], v[176:179], v[4:7]
	s_mov_b32 m0, s7
	v_lshl_add_u64 v[200:201], s[34:35], 0, v[210:211]
	s_barrier
	ds_read_b128 v[148:151], v236 offset:16384
	ds_read_b128 v[152:155], v236 offset:17408
	ds_read_b128 v[156:159], v236 offset:18432
	ds_read_b128 v[160:163], v236 offset:19456
	ds_read_b128 v[164:167], v236 offset:20480
	ds_read_b128 v[168:171], v236 offset:21504
	ds_read_b128 v[172:175], v236 offset:22528
	ds_read_b128 v[176:179], v236 offset:23552
	global_load_lds_dwordx4 v[200:201], off
	v_lshl_add_u64 v[202:203], s[34:35], 0, v[208:209]
	s_mov_b32 m0, s8
	s_nop 0
	global_load_lds_dwordx4 v[202:203], off
	s_barrier
	s_waitcnt lgkmcnt(0)
	v_mfma_f32_16x16x32_f16 v[124:127], v[128:131], v[148:151], v[124:127]
	v_mfma_f32_16x16x32_f16 v[144:147], v[136:139], v[148:151], v[144:147]
	v_mfma_f32_16x16x32_f16 v[104:107], v[128:131], v[156:159], v[104:107]
	v_mfma_f32_16x16x32_f16 v[112:115], v[136:139], v[156:159], v[112:115]
	v_mfma_f32_16x16x32_f16 v[84:87], v[128:131], v[164:167], v[84:87]
	v_mfma_f32_16x16x32_f16 v[92:95], v[136:139], v[164:167], v[92:95]
	v_mfma_f32_16x16x32_f16 v[48:51], v[128:131], v[172:175], v[48:51]
	v_mfma_f32_16x16x32_f16 v[60:63], v[136:139], v[172:175], v[60:63]
	v_mfma_f32_16x16x32_f16 v[124:127], v[132:135], v[152:155], v[124:127]
	v_mfma_f32_16x16x32_f16 v[144:147], v[140:143], v[152:155], v[144:147]
	v_mfma_f32_16x16x32_f16 v[104:107], v[132:135], v[160:163], v[104:107]
	v_mfma_f32_16x16x32_f16 v[112:115], v[140:143], v[160:163], v[112:115]
	v_mfma_f32_16x16x32_f16 v[84:87], v[132:135], v[168:171], v[84:87]
	v_mfma_f32_16x16x32_f16 v[92:95], v[140:143], v[168:171], v[92:95]
	v_mfma_f32_16x16x32_f16 v[48:51], v[132:135], v[176:179], v[48:51]
	v_mfma_f32_16x16x32_f16 v[60:63], v[140:143], v[176:179], v[60:63]
	s_barrier
	s_add_u32 s30, s26, 0x80000
	s_addc_u32 s31, s27, 0
	s_mov_b32 m0, s63
	v_lshl_add_u64 v[128:129], s[30:31], 0, v[2:3]
	global_load_lds_dwordx4 v[128:129], off
	v_lshl_add_u64 v[128:129], s[30:31], 0, v[206:207]
	s_mov_b32 m0, s68
	s_nop 0
	global_load_lds_dwordx4 v[128:129], off
	s_waitcnt vmcnt(6)
	s_barrier
	v_mfma_f32_16x16x32_f16 v[116:119], v[180:183], v[148:151], v[116:119]
	v_mfma_f32_16x16x32_f16 v[120:123], v[188:191], v[148:151], v[120:123]
	v_mfma_f32_16x16x32_f16 v[96:99], v[180:183], v[156:159], v[96:99]
	v_mfma_f32_16x16x32_f16 v[100:103], v[188:191], v[156:159], v[100:103]
	v_mfma_f32_16x16x32_f16 v[64:67], v[180:183], v[164:167], v[64:67]
	v_mfma_f32_16x16x32_f16 v[76:79], v[188:191], v[164:167], v[76:79]
	v_mfma_f32_16x16x32_f16 v[32:35], v[180:183], v[172:175], v[32:35]
	v_mfma_f32_16x16x32_f16 v[44:47], v[188:191], v[172:175], v[44:47]
	v_mfma_f32_16x16x32_f16 v[116:119], v[184:187], v[152:155], v[116:119]
	v_mfma_f32_16x16x32_f16 v[120:123], v[192:195], v[152:155], v[120:123]
	v_mfma_f32_16x16x32_f16 v[96:99], v[184:187], v[160:163], v[96:99]
	v_mfma_f32_16x16x32_f16 v[100:103], v[192:195], v[160:163], v[100:103]
	v_mfma_f32_16x16x32_f16 v[64:67], v[184:187], v[168:171], v[64:67]
	v_mfma_f32_16x16x32_f16 v[76:79], v[192:195], v[168:171], v[76:79]
	v_mfma_f32_16x16x32_f16 v[32:35], v[184:187], v[176:179], v[32:35]
	v_mfma_f32_16x16x32_f16 v[44:47], v[192:195], v[176:179], v[44:47]
	s_barrier
	ds_read_b128 v[128:131], v239
	ds_read_b128 v[132:135], v239 offset:1024
	ds_read_b128 v[136:139], v239 offset:2048
	ds_read_b128 v[140:143], v239 offset:3072
	s_add_u32 s30, s34, 0x80000
	s_addc_u32 s31, s35, 0
	s_mov_b32 m0, s9
	v_lshl_add_u64 v[180:181], s[30:31], 0, v[210:211]
	ds_read_b128 v[148:151], v236 offset:32768
	ds_read_b128 v[152:155], v236 offset:33792
	ds_read_b128 v[156:159], v236 offset:34816
	ds_read_b128 v[160:163], v236 offset:35840
	ds_read_b128 v[164:167], v236 offset:36864
	ds_read_b128 v[168:171], v236 offset:37888
	ds_read_b128 v[172:175], v236 offset:38912
	ds_read_b128 v[176:179], v236 offset:39936
	global_load_lds_dwordx4 v[180:181], off
	v_lshl_add_u64 v[180:181], s[30:31], 0, v[208:209]
	s_mov_b32 m0, s12
	s_nop 0
	global_load_lds_dwordx4 v[180:181], off
	s_waitcnt lgkmcnt(8)
	s_barrier
	s_waitcnt lgkmcnt(0)
	v_mfma_f32_16x16x32_f16 v[80:83], v[128:131], v[148:151], v[80:83]
	v_mfma_f32_16x16x32_f16 v[108:111], v[136:139], v[148:151], v[108:111]
	v_mfma_f32_16x16x32_f16 v[56:59], v[128:131], v[156:159], v[56:59]
	v_mfma_f32_16x16x32_f16 v[68:71], v[136:139], v[156:159], v[68:71]
	v_mfma_f32_16x16x32_f16 v[28:31], v[128:131], v[164:167], v[28:31]
	v_mfma_f32_16x16x32_f16 v[36:39], v[136:139], v[164:167], v[36:39]
	v_mfma_f32_16x16x32_f16 v[16:19], v[128:131], v[172:175], v[16:19]
	v_mfma_f32_16x16x32_f16 v[12:15], v[136:139], v[172:175], v[12:15]
	v_mfma_f32_16x16x32_f16 v[80:83], v[132:135], v[152:155], v[80:83]
	v_mfma_f32_16x16x32_f16 v[108:111], v[140:143], v[152:155], v[108:111]
	v_mfma_f32_16x16x32_f16 v[56:59], v[132:135], v[160:163], v[56:59]
	v_mfma_f32_16x16x32_f16 v[68:71], v[140:143], v[160:163], v[68:71]
	v_mfma_f32_16x16x32_f16 v[28:31], v[132:135], v[168:171], v[28:31]
	v_mfma_f32_16x16x32_f16 v[36:39], v[140:143], v[168:171], v[36:39]
	v_mfma_f32_16x16x32_f16 v[16:19], v[132:135], v[176:179], v[16:19]
	v_mfma_f32_16x16x32_f16 v[12:15], v[140:143], v[176:179], v[12:15]
	s_barrier
	s_mov_b32 m0, s69
	v_lshl_add_u64 v[196:197], v[196:197], 0, s[88:89]
	ds_read_b128 v[180:183], v240
	ds_read_b128 v[184:187], v240 offset:1024
	ds_read_b128 v[188:191], v240 offset:2048
	ds_read_b128 v[192:195], v240 offset:3072
	global_load_lds_dwordx4 v[196:197], off
	v_lshl_add_u64 v[196:197], v[198:199], 0, s[88:89]
	s_mov_b32 m0, s70
	s_nop 0
	global_load_lds_dwordx4 v[196:197], off
	s_barrier
	s_waitcnt lgkmcnt(0)
	v_mfma_f32_16x16x32_f16 v[72:75], v[180:183], v[148:151], v[72:75]
	v_mfma_f32_16x16x32_f16 v[88:91], v[188:191], v[148:151], v[88:91]
	v_mfma_f32_16x16x32_f16 v[40:43], v[180:183], v[156:159], v[40:43]
	v_mfma_f32_16x16x32_f16 v[52:55], v[188:191], v[156:159], v[52:55]
	v_mfma_f32_16x16x32_f16 v[20:23], v[180:183], v[164:167], v[20:23]
	v_mfma_f32_16x16x32_f16 v[24:27], v[188:191], v[164:167], v[24:27]
	v_mfma_f32_16x16x32_f16 v[8:11], v[180:183], v[172:175], v[8:11]
	v_mfma_f32_16x16x32_f16 v[4:7], v[188:191], v[172:175], v[4:7]
	v_mfma_f32_16x16x32_f16 v[72:75], v[184:187], v[152:155], v[72:75]
	v_mfma_f32_16x16x32_f16 v[88:91], v[192:195], v[152:155], v[88:91]
	v_mfma_f32_16x16x32_f16 v[40:43], v[184:187], v[160:163], v[40:43]
	v_mfma_f32_16x16x32_f16 v[52:55], v[192:195], v[160:163], v[52:55]
	v_mfma_f32_16x16x32_f16 v[20:23], v[184:187], v[168:171], v[20:23]
	v_mfma_f32_16x16x32_f16 v[24:27], v[192:195], v[168:171], v[24:27]
	v_mfma_f32_16x16x32_f16 v[8:11], v[184:187], v[176:179], v[8:11]
	v_mfma_f32_16x16x32_f16 v[4:7], v[192:195], v[176:179], v[4:7]
	s_mov_b32 m0, s39
	v_lshl_add_u64 v[196:197], v[200:201], 0, s[88:89]
	s_barrier
	ds_read_b128 v[148:151], v236 offset:49152
	ds_read_b128 v[152:155], v236 offset:50176
	ds_read_b128 v[156:159], v236 offset:51200
	ds_read_b128 v[160:163], v236 offset:52224
	ds_read_b128 v[164:167], v236 offset:53248
	ds_read_b128 v[168:171], v236 offset:54272
	ds_read_b128 v[172:175], v236 offset:55296
	ds_read_b128 v[176:179], v236 offset:56320
	global_load_lds_dwordx4 v[196:197], off
	v_lshl_add_u64 v[196:197], v[202:203], 0, s[88:89]
	s_mov_b32 m0, s47
	s_nop 0
	global_load_lds_dwordx4 v[196:197], off
	s_barrier
	s_waitcnt lgkmcnt(0)
	v_mfma_f32_16x16x32_f16 v[124:127], v[128:131], v[148:151], v[124:127]
	v_mfma_f32_16x16x32_f16 v[144:147], v[136:139], v[148:151], v[144:147]
	v_mfma_f32_16x16x32_f16 v[104:107], v[128:131], v[156:159], v[104:107]
	v_mfma_f32_16x16x32_f16 v[112:115], v[136:139], v[156:159], v[112:115]
	v_mfma_f32_16x16x32_f16 v[84:87], v[128:131], v[164:167], v[84:87]
	v_mfma_f32_16x16x32_f16 v[92:95], v[136:139], v[164:167], v[92:95]
	v_mfma_f32_16x16x32_f16 v[48:51], v[128:131], v[172:175], v[48:51]
	v_mfma_f32_16x16x32_f16 v[60:63], v[136:139], v[172:175], v[60:63]
	v_mfma_f32_16x16x32_f16 v[124:127], v[132:135], v[152:155], v[124:127]
	v_mfma_f32_16x16x32_f16 v[144:147], v[140:143], v[152:155], v[144:147]
	v_mfma_f32_16x16x32_f16 v[104:107], v[132:135], v[160:163], v[104:107]
	v_mfma_f32_16x16x32_f16 v[112:115], v[140:143], v[160:163], v[112:115]
	v_mfma_f32_16x16x32_f16 v[84:87], v[132:135], v[168:171], v[84:87]
	v_mfma_f32_16x16x32_f16 v[92:95], v[140:143], v[168:171], v[92:95]
	v_mfma_f32_16x16x32_f16 v[48:51], v[132:135], v[176:179], v[48:51]
	v_mfma_f32_16x16x32_f16 v[60:63], v[140:143], v[176:179], v[60:63]
	s_barrier
	s_add_u32 s26, s26, 0x80080
	s_addc_u32 s27, s27, 0
	s_mov_b32 m0, s71
	v_lshl_add_u64 v[128:129], s[26:27], 0, v[2:3]
	global_load_lds_dwordx4 v[128:129], off
	v_lshl_add_u64 v[128:129], s[26:27], 0, v[206:207]
	s_mov_b32 m0, s76
	s_nop 0
	global_load_lds_dwordx4 v[128:129], off
	s_waitcnt vmcnt(6)
	s_barrier
	v_mfma_f32_16x16x32_f16 v[116:119], v[180:183], v[148:151], v[116:119]
	v_mfma_f32_16x16x32_f16 v[120:123], v[188:191], v[148:151], v[120:123]
	v_mfma_f32_16x16x32_f16 v[96:99], v[180:183], v[156:159], v[96:99]
	v_mfma_f32_16x16x32_f16 v[100:103], v[188:191], v[156:159], v[100:103]
	v_mfma_f32_16x16x32_f16 v[64:67], v[180:183], v[164:167], v[64:67]
	v_mfma_f32_16x16x32_f16 v[76:79], v[188:191], v[164:167], v[76:79]
	v_mfma_f32_16x16x32_f16 v[32:35], v[180:183], v[172:175], v[32:35]
	v_mfma_f32_16x16x32_f16 v[44:47], v[188:191], v[172:175], v[44:47]
	v_mfma_f32_16x16x32_f16 v[116:119], v[184:187], v[152:155], v[116:119]
	v_mfma_f32_16x16x32_f16 v[120:123], v[192:195], v[152:155], v[120:123]
	v_mfma_f32_16x16x32_f16 v[96:99], v[184:187], v[160:163], v[96:99]
	v_mfma_f32_16x16x32_f16 v[100:103], v[192:195], v[160:163], v[100:103]
	v_mfma_f32_16x16x32_f16 v[64:67], v[184:187], v[168:171], v[64:67]
	v_mfma_f32_16x16x32_f16 v[76:79], v[192:195], v[168:171], v[76:79]
	v_mfma_f32_16x16x32_f16 v[32:35], v[184:187], v[176:179], v[32:35]
	v_mfma_f32_16x16x32_f16 v[44:47], v[192:195], v[176:179], v[44:47]
	s_add_i32 s29, s29, 2
	s_add_u32 s16, s16, 0x100
	s_addc_u32 s17, s17, 0
	s_add_u32 s10, s10, 0x100
	s_addc_u32 s11, s11, 0
	s_cmp_lt_u32 s29, 30
	s_barrier
	s_cbranch_scc1 .LBB0_1746
	s_add_i32 s10, s46, 16
	s_mul_hi_i32 s11, s10, 0x42
	s_mulk_i32 s10, 0x42
	s_add_u32 s10, s10, s48
	v_mov_b32_e32 v128, v233
	s_addc_u32 s11, s11, s78
	v_mov_b32_e32 v129, v234
	s_lshl_b64 s[10:11], s[10:11], 17
	v_add_u32_e32 v202, s13, v128
	v_lshlrev_b32_e32 v128, 8, v202
	v_lshlrev_b32_e32 v196, 3, v129
	s_add_u32 s10, s4, s10
	s_addc_u32 s11, s6, s11
	v_ashrrev_i32_e32 v197, 31, v196
	v_add_u32_e32 v140, 0x8000, v128
	v_lshl_add_u64 v[130:131], v[196:197], 1, s[10:11]
	v_ashrrev_i32_e32 v141, 31, v140
	v_lshl_add_u64 v[160:161], v[140:141], 1, v[130:131]
	v_add_u32_e32 v140, 0x9000, v128
	v_ashrrev_i32_e32 v129, 31, v128
	v_ashrrev_i32_e32 v141, 31, v140
	v_lshl_add_u64 v[132:133], v[128:129], 1, v[130:131]
	v_add_u32_e32 v134, 0x1000, v128
	v_add_u32_e32 v136, 0x2000, v128
	v_add_u32_e32 v138, 0x3000, v128
	v_lshl_add_u64 v[152:153], v[140:141], 1, v[130:131]
	v_add_u32_e32 v140, 0xa000, v128
	v_add_u32_e32 v128, 0xb000, v128
	v_ashrrev_i32_e32 v135, 31, v134
	v_ashrrev_i32_e32 v137, 31, v136
	v_ashrrev_i32_e32 v139, 31, v138
	v_ashrrev_i32_e32 v141, 31, v140
	v_ashrrev_i32_e32 v129, 31, v128
	v_lshl_add_u64 v[134:135], v[134:135], 1, v[130:131]
	v_lshl_add_u64 v[136:137], v[136:137], 1, v[130:131]
	v_lshl_add_u64 v[138:139], v[138:139], 1, v[130:131]
	v_lshl_add_u64 v[140:141], v[140:141], 1, v[130:131]
	v_lshl_add_u64 v[142:143], v[128:129], 1, v[130:131]
	global_load_dwordx4 v[164:167], v[138:139], off offset:256
	global_load_dwordx4 v[168:171], v[138:139], off
	global_load_dwordx4 v[172:175], v[136:137], off offset:256
	global_load_dwordx4 v[176:179], v[136:137], off
	global_load_dwordx4 v[180:183], v[134:135], off offset:256
	global_load_dwordx4 v[184:187], v[134:135], off
	global_load_dwordx4 v[188:191], v[132:133], off offset:256
	global_load_dwordx4 v[192:195], v[132:133], off
	global_load_dwordx4 v[128:131], v[142:143], off offset:256
	s_nop 0
	global_load_dwordx4 v[132:135], v[142:143], off
	global_load_dwordx4 v[136:139], v[140:141], off offset:256
	s_nop 0
	global_load_dwordx4 v[140:143], v[140:141], off
	s_nop 0
	global_load_dwordx4 v[148:151], v[152:153], off offset:256
	s_nop 0
	global_load_dwordx4 v[152:155], v[152:153], off
	s_nop 0
	global_load_dwordx4 v[156:159], v[160:161], off offset:256
	s_nop 0
	global_load_dwordx4 v[160:163], v[160:161], off
	v_mov_b32_e32 v199, v82
	v_pk_mov_b32 v[82:83], v[82:83], v[108:109] op_sel:[1,0]
	v_lshl_add_u32 v108, s48, 8, v202
	v_mov_b32_e32 v200, v109
	v_ashrrev_i32_e32 v109, 31, v108
	v_mov_b32_e32 v198, v81
	v_mov_b32_e32 v201, v110
	v_lshlrev_b64 v[202:203], 12, v[108:109]
	s_lshl_b32 s10, s46, 8
	s_or_b32 s10, s10, s38
	v_add_u32_e32 v196, s10, v196
	v_readlane_b32 s10, v254, 26
	v_readlane_b32 s11, v254, 27
	v_ashrrev_i32_e32 v197, 31, v196
	s_mov_b32 s46, s18
	s_mov_b32 s48, s36
	s_mov_b64 s[50:51], s[44:45]
	s_mov_b64 s[34:35], s[42:43]
	s_waitcnt vmcnt(0)
	s_nop 0
	v_cvt_f32_f16_e32 v81, v192
	v_cvt_f32_f16_e32 v108, v194
	v_cvt_f32_f16_sdwa v110, v192 dst_sel:DWORD dst_unused:UNUSED_PAD src0_sel:WORD_1
	v_cvt_f32_f16_e32 v220, v193
	v_cvt_f32_f16_sdwa v224, v193 dst_sel:DWORD dst_unused:UNUSED_PAD src0_sel:WORD_1
	v_cvt_f32_f16_sdwa v194, v194 dst_sel:DWORD dst_unused:UNUSED_PAD src0_sel:WORD_1
	v_cvt_f32_f16_e32 v221, v195
	v_rcp_f32_e32 v81, v81
	v_rcp_f32_e32 v109, v108
	v_rcp_f32_e32 v192, v110
	v_rcp_f32_e32 v193, v220
	v_rcp_f32_e32 v108, v224
	v_cvt_f32_f16_sdwa v225, v195 dst_sel:DWORD dst_unused:UNUSED_PAD src0_sel:WORD_1
	v_rcp_f32_e32 v194, v194
	v_rcp_f32_e32 v195, v221
	v_fma_mixlo_f16 v220, v80, v81, 0
	v_pk_mul_f32 v[80:81], v[198:199], v[192:193]
	v_pk_mul_f32 v[82:83], v[82:83], v[108:109]
	v_cvt_pk_f16_f32 v80, v80, v81
	v_cvt_pk_f16_f32 v82, v82, v83
	v_pack_b32_f16 v83, v220, v80
	v_alignbit_b32 v80, v82, v80, 16
	v_pk_mul_f32 v[192:193], v[200:201], v[194:195]
	v_lshrrev_b32_e32 v109, 4, v80
	v_cvt_pk_f16_f32 v81, v192, v193
	v_and_b32_e32 v109, 0x10001, v109
	v_alignbit_b32 v82, v81, v82, 16
	v_add3_u32 v80, v80, v109, s21
	v_rcp_f32_e32 v110, v225
	v_and_b32_e32 v109, 0xfff0fff0, v80
	v_lshrrev_b32_e32 v80, 4, v82
	v_and_b32_e32 v80, 0x10001, v80
	v_add3_u32 v80, v82, v80, s21
	v_cvt_f32_f16_e32 v82, v188
	v_lshrrev_b32_e32 v81, 16, v81
	v_fma_mixhi_f16 v81, v111, v110, 0
	v_and_b32_e32 v110, 0xfff0fff0, v80
	v_lshrrev_b32_e32 v80, 4, v81
	v_lshrrev_b32_e32 v108, 4, v83
	v_and_b32_e32 v80, 0x10001, v80
	v_rcp_f32_e32 v82, v82
	v_and_b32_e32 v108, 0x10001, v108
	v_add3_u32 v80, v81, v80, s21
	v_add3_u32 v83, v83, v108, s21
	v_and_b32_e32 v111, 0xfff0fff0, v80
	v_lshl_add_u64 v[80:81], s[10:11], 0, v[202:203]
	v_and_b32_e32 v108, 0xfff0fff0, v83
	v_lshl_add_u64 v[80:81], v[196:197], 1, v[80:81]
	global_store_dwordx4 v[80:81], v[108:111], off
	v_fma_mixlo_f16 v82, v72, v82, 0
	v_cvt_f32_f16_e32 v72, v190
	v_cvt_f32_f16_sdwa v108, v188 dst_sel:DWORD dst_unused:UNUSED_PAD src0_sel:WORD_1
	v_cvt_f32_f16_sdwa v109, v190 dst_sel:DWORD dst_unused:UNUSED_PAD src0_sel:WORD_1
	v_cvt_f32_f16_e32 v110, v189
	v_rcp_f32_e32 v83, v72
	v_rcp_f32_e32 v108, v108
	v_rcp_f32_e32 v72, v109
	v_rcp_f32_e32 v109, v110
	v_mov_b32_e32 v110, v73
	v_mov_b32_e32 v111, v74
	v_cvt_f32_f16_e32 v73, v191
	v_pk_mul_f32 v[108:109], v[110:111], v[108:109]
	s_mov_b64 s[10:11], 0x10000
	v_cvt_pk_f16_f32 v74, v108, v109
	v_pack_b32_f16 v110, v82, v74
	v_cvt_f32_f16_sdwa v82, v189 dst_sel:DWORD dst_unused:UNUSED_PAD src0_sel:WORD_1
	v_rcp_f32_e32 v73, v73
	v_mov_b32_e32 v108, v89
	v_mov_b32_e32 v109, v90
	v_rcp_f32_e32 v82, v82
	v_pk_mul_f32 v[72:73], v[108:109], v[72:73]
	v_cvt_f32_f16_sdwa v90, v191 dst_sel:DWORD dst_unused:UNUSED_PAD src0_sel:WORD_1
	v_cvt_pk_f16_f32 v89, v72, v73
	v_pk_mov_b32 v[72:73], v[74:75], v[88:89] op_sel:[1,0]
	s_nop 0
	v_pk_mul_f32 v[72:73], v[72:73], v[82:83]
	v_lshrrev_b32_e32 v82, 16, v89
	v_cvt_pk_f16_f32 v72, v72, v73
	v_rcp_f32_e32 v73, v90
	v_alignbit_b32 v74, v72, v74, 16
	v_alignbit_b32 v75, v89, v72, 16
	v_lshrrev_b32_e32 v72, 4, v110
	v_fma_mixhi_f16 v82, v91, v73, 0
	v_lshrrev_b32_e32 v73, 4, v74
	v_and_b32_e32 v73, 0x10001, v73
	v_add3_u32 v73, v74, v73, s21
	v_lshrrev_b32_e32 v74, 4, v75
	v_and_b32_e32 v74, 0x10001, v74
	v_add3_u32 v74, v75, v74, s21
	v_cvt_f32_f16_e32 v75, v184
	v_lshrrev_b32_e32 v83, 4, v82
	v_and_b32_e32 v72, 0x10001, v72
	v_and_b32_e32 v83, 0x10001, v83
	v_rcp_f32_e32 v88, v75
	v_add3_u32 v72, v110, v72, s21
	v_add3_u32 v75, v82, v83, s21
	v_and_b32_e32 v72, 0xfff0fff0, v72
	v_and_b32_e32 v73, 0xfff0fff0, v73
	v_and_b32_e32 v74, 0xfff0fff0, v74
	v_and_b32_e32 v75, 0xfff0fff0, v75
	global_store_dwordx4 v[80:81], v[72:75], off offset:256
	v_cvt_f32_f16_e32 v82, v185
	v_mov_b32_e32 v83, v58
	v_fma_mixlo_f16 v72, v56, v88, 0
	v_cvt_f32_f16_e32 v56, v186
	v_cvt_f32_f16_sdwa v74, v184 dst_sel:DWORD dst_unused:UNUSED_PAD src0_sel:WORD_1
	v_cvt_f32_f16_sdwa v75, v186 dst_sel:DWORD dst_unused:UNUSED_PAD src0_sel:WORD_1
	v_rcp_f32_e32 v73, v56
	v_rcp_f32_e32 v74, v74
	v_rcp_f32_e32 v56, v75
	v_rcp_f32_e32 v75, v82
	v_mov_b32_e32 v82, v57
	v_cvt_f32_f16_e32 v57, v187
	v_pk_mul_f32 v[74:75], v[82:83], v[74:75]
	s_nop 0
	v_cvt_pk_f16_f32 v58, v74, v75
	v_pack_b32_f16 v82, v72, v58
	v_cvt_f32_f16_sdwa v72, v185 dst_sel:DWORD dst_unused:UNUSED_PAD src0_sel:WORD_1
	v_rcp_f32_e32 v57, v57
	v_mov_b32_e32 v74, v69
	v_mov_b32_e32 v75, v70
	v_rcp_f32_e32 v72, v72
	v_pk_mul_f32 v[56:57], v[74:75], v[56:57]
	v_cvt_f32_f16_sdwa v70, v187 dst_sel:DWORD dst_unused:UNUSED_PAD src0_sel:WORD_1
	v_cvt_pk_f16_f32 v69, v56, v57
	v_pk_mov_b32 v[56:57], v[58:59], v[68:69] op_sel:[1,0]
	v_lshrrev_b32_e32 v68, 16, v69
	v_pk_mul_f32 v[56:57], v[56:57], v[72:73]
	s_nop 0
	v_cvt_pk_f16_f32 v56, v56, v57
	v_rcp_f32_e32 v57, v70
	v_alignbit_b32 v58, v56, v58, 16
	v_alignbit_b32 v59, v69, v56, 16
	v_cvt_f32_f16_e32 v70, v180
	v_fma_mixhi_f16 v68, v71, v57, 0
	v_lshrrev_b32_e32 v57, 4, v58
	v_and_b32_e32 v57, 0x10001, v57
	v_add3_u32 v57, v58, v57, s21
	v_lshrrev_b32_e32 v58, 4, v59
	v_and_b32_e32 v58, 0x10001, v58
	v_add3_u32 v58, v59, v58, s21
	v_lshrrev_b32_e32 v59, 4, v68
	v_lshrrev_b32_e32 v56, 4, v82
	v_and_b32_e32 v59, 0x10001, v59
	v_rcp_f32_e32 v72, v70
	v_and_b32_e32 v56, 0x10001, v56
	v_add3_u32 v59, v68, v59, s21
	v_lshl_add_u64 v[68:69], v[80:81], 0, s[10:11]
	s_mov_b32 s10, 0x10000
	v_add3_u32 v56, v82, v56, s21
	v_add_co_u32_e32 v70, vcc, s10, v80
	v_and_b32_e32 v56, 0xfff0fff0, v56
	v_and_b32_e32 v57, 0xfff0fff0, v57
	v_and_b32_e32 v58, 0xfff0fff0, v58
	v_and_b32_e32 v59, 0xfff0fff0, v59
	v_addc_co_u32_e32 v71, vcc, 0, v81, vcc
	global_store_dwordx4 v[70:71], v[56:59], off
	v_cvt_f32_f16_e32 v70, v181
	v_mov_b32_e32 v71, v42
	v_fma_mixlo_f16 v56, v40, v72, 0
	v_cvt_f32_f16_e32 v40, v182
	v_cvt_f32_f16_sdwa v58, v180 dst_sel:DWORD dst_unused:UNUSED_PAD src0_sel:WORD_1
	v_cvt_f32_f16_sdwa v59, v182 dst_sel:DWORD dst_unused:UNUSED_PAD src0_sel:WORD_1
	s_mov_b64 s[10:11], 0x20000
	v_rcp_f32_e32 v57, v40
	v_rcp_f32_e32 v58, v58
	v_rcp_f32_e32 v40, v59
	v_rcp_f32_e32 v59, v70
	v_mov_b32_e32 v70, v41
	v_cvt_f32_f16_e32 v41, v183
	v_pk_mul_f32 v[58:59], v[70:71], v[58:59]
	s_nop 0
	v_cvt_pk_f16_f32 v42, v58, v59
	v_pack_b32_f16 v70, v56, v42
	v_cvt_f32_f16_sdwa v56, v181 dst_sel:DWORD dst_unused:UNUSED_PAD src0_sel:WORD_1
	v_rcp_f32_e32 v41, v41
	v_mov_b32_e32 v58, v53
	v_mov_b32_e32 v59, v54
	v_rcp_f32_e32 v56, v56
	v_pk_mul_f32 v[40:41], v[58:59], v[40:41]
	v_cvt_f32_f16_sdwa v54, v183 dst_sel:DWORD dst_unused:UNUSED_PAD src0_sel:WORD_1
	v_cvt_pk_f16_f32 v53, v40, v41
	v_pk_mov_b32 v[40:41], v[42:43], v[52:53] op_sel:[1,0]
	v_lshrrev_b32_e32 v52, 16, v53
	v_pk_mul_f32 v[40:41], v[40:41], v[56:57]
	s_nop 0
	v_cvt_pk_f16_f32 v40, v40, v41
	v_rcp_f32_e32 v41, v54
	v_alignbit_b32 v42, v40, v42, 16
	v_alignbit_b32 v43, v53, v40, 16
	v_lshrrev_b32_e32 v40, 4, v70
	v_fma_mixhi_f16 v52, v55, v41, 0
	v_lshrrev_b32_e32 v41, 4, v42
	v_and_b32_e32 v41, 0x10001, v41
	v_add3_u32 v41, v42, v41, s21
	v_lshrrev_b32_e32 v42, 4, v43
	v_and_b32_e32 v42, 0x10001, v42
	v_add3_u32 v42, v43, v42, s21
	v_cvt_f32_f16_e32 v43, v176
	v_lshrrev_b32_e32 v53, 4, v52
	v_and_b32_e32 v40, 0x10001, v40
	v_and_b32_e32 v53, 0x10001, v53
	v_rcp_f32_e32 v54, v43
	v_add3_u32 v40, v70, v40, s21
	v_add3_u32 v43, v52, v53, s21
	v_and_b32_e32 v40, 0xfff0fff0, v40
	v_and_b32_e32 v41, 0xfff0fff0, v41
	v_and_b32_e32 v42, 0xfff0fff0, v42
	v_and_b32_e32 v43, 0xfff0fff0, v43
	global_store_dwordx4 v[68:69], v[40:43], off offset:256
	v_cvt_f32_f16_e32 v52, v177
	v_mov_b32_e32 v53, v30
	v_fma_mixlo_f16 v40, v28, v54, 0
	v_cvt_f32_f16_e32 v28, v178
	v_cvt_f32_f16_sdwa v42, v176 dst_sel:DWORD dst_unused:UNUSED_PAD src0_sel:WORD_1
	v_cvt_f32_f16_sdwa v43, v178 dst_sel:DWORD dst_unused:UNUSED_PAD src0_sel:WORD_1
	v_rcp_f32_e32 v41, v28
	v_rcp_f32_e32 v42, v42
	v_rcp_f32_e32 v28, v43
	v_rcp_f32_e32 v43, v52
	v_mov_b32_e32 v52, v29
	v_cvt_f32_f16_e32 v29, v179
	v_pk_mul_f32 v[42:43], v[52:53], v[42:43]
	s_nop 0
	v_cvt_pk_f16_f32 v30, v42, v43
	v_pack_b32_f16 v52, v40, v30
	v_cvt_f32_f16_sdwa v40, v177 dst_sel:DWORD dst_unused:UNUSED_PAD src0_sel:WORD_1
	v_rcp_f32_e32 v29, v29
	v_mov_b32_e32 v42, v37
	v_mov_b32_e32 v43, v38
	v_rcp_f32_e32 v40, v40
	v_pk_mul_f32 v[28:29], v[42:43], v[28:29]
	v_cvt_f32_f16_sdwa v38, v179 dst_sel:DWORD dst_unused:UNUSED_PAD src0_sel:WORD_1
	v_cvt_pk_f16_f32 v37, v28, v29
	v_pk_mov_b32 v[28:29], v[30:31], v[36:37] op_sel:[1,0]
	v_lshrrev_b32_e32 v36, 16, v37
	v_pk_mul_f32 v[28:29], v[28:29], v[40:41]
	s_nop 0
	v_cvt_pk_f16_f32 v28, v28, v29
	v_rcp_f32_e32 v29, v38
	v_alignbit_b32 v30, v28, v30, 16
	v_alignbit_b32 v31, v37, v28, 16
	v_cvt_f32_f16_e32 v38, v172
	v_fma_mixhi_f16 v36, v39, v29, 0
	v_lshrrev_b32_e32 v29, 4, v30
	v_and_b32_e32 v29, 0x10001, v29
	v_add3_u32 v29, v30, v29, s21
	v_lshrrev_b32_e32 v30, 4, v31
	v_and_b32_e32 v30, 0x10001, v30
	v_add3_u32 v30, v31, v30, s21
	v_lshrrev_b32_e32 v31, 4, v36
	v_lshrrev_b32_e32 v28, 4, v52
	v_and_b32_e32 v31, 0x10001, v31
	v_rcp_f32_e32 v40, v38
	v_and_b32_e32 v28, 0x10001, v28
	v_add3_u32 v31, v36, v31, s21
	v_lshl_add_u64 v[36:37], v[80:81], 0, s[10:11]
	s_mov_b32 s10, 0x20000
	v_add3_u32 v28, v52, v28, s21
	v_add_co_u32_e32 v38, vcc, s10, v80
	v_and_b32_e32 v28, 0xfff0fff0, v28
	v_and_b32_e32 v29, 0xfff0fff0, v29
	v_and_b32_e32 v30, 0xfff0fff0, v30
	v_and_b32_e32 v31, 0xfff0fff0, v31
	v_addc_co_u32_e32 v39, vcc, 0, v81, vcc
	global_store_dwordx4 v[38:39], v[28:31], off
	v_cvt_f32_f16_e32 v38, v173
	v_mov_b32_e32 v39, v22
	v_fma_mixlo_f16 v28, v20, v40, 0
	v_cvt_f32_f16_e32 v20, v174
	v_cvt_f32_f16_sdwa v30, v172 dst_sel:DWORD dst_unused:UNUSED_PAD src0_sel:WORD_1
	v_cvt_f32_f16_sdwa v31, v174 dst_sel:DWORD dst_unused:UNUSED_PAD src0_sel:WORD_1
	s_mov_b64 s[10:11], 0x30000
	v_rcp_f32_e32 v29, v20
	v_rcp_f32_e32 v30, v30
	v_rcp_f32_e32 v20, v31
	v_rcp_f32_e32 v31, v38
	v_mov_b32_e32 v38, v21
	v_cvt_f32_f16_e32 v21, v175
	v_pk_mul_f32 v[30:31], v[38:39], v[30:31]
	s_nop 0
	v_cvt_pk_f16_f32 v22, v30, v31
	v_pack_b32_f16 v38, v28, v22
	v_cvt_f32_f16_sdwa v28, v173 dst_sel:DWORD dst_unused:UNUSED_PAD src0_sel:WORD_1
	v_rcp_f32_e32 v21, v21
	v_mov_b32_e32 v30, v25
	v_mov_b32_e32 v31, v26
	v_rcp_f32_e32 v28, v28
	v_pk_mul_f32 v[20:21], v[30:31], v[20:21]
	v_cvt_f32_f16_sdwa v26, v175 dst_sel:DWORD dst_unused:UNUSED_PAD src0_sel:WORD_1
	v_cvt_pk_f16_f32 v25, v20, v21
	v_pk_mov_b32 v[20:21], v[22:23], v[24:25] op_sel:[1,0]
	v_lshrrev_b32_e32 v24, 16, v25
	v_pk_mul_f32 v[20:21], v[20:21], v[28:29]
	s_nop 0
	v_cvt_pk_f16_f32 v20, v20, v21
	v_rcp_f32_e32 v21, v26
	v_alignbit_b32 v22, v20, v22, 16
	v_alignbit_b32 v23, v25, v20, 16
	v_lshrrev_b32_e32 v20, 4, v38
	v_fma_mixhi_f16 v24, v27, v21, 0
	v_lshrrev_b32_e32 v21, 4, v22
	v_and_b32_e32 v21, 0x10001, v21
	v_add3_u32 v21, v22, v21, s21
	v_lshrrev_b32_e32 v22, 4, v23
	v_and_b32_e32 v22, 0x10001, v22
	v_add3_u32 v22, v23, v22, s21
	v_cvt_f32_f16_e32 v23, v168
	v_lshrrev_b32_e32 v25, 4, v24
	v_and_b32_e32 v20, 0x10001, v20
	v_and_b32_e32 v25, 0x10001, v25
	v_rcp_f32_e32 v26, v23
	v_add3_u32 v20, v38, v20, s21
	v_add3_u32 v23, v24, v25, s21
	v_and_b32_e32 v20, 0xfff0fff0, v20
	v_and_b32_e32 v21, 0xfff0fff0, v21
	v_and_b32_e32 v22, 0xfff0fff0, v22
	v_and_b32_e32 v23, 0xfff0fff0, v23
	global_store_dwordx4 v[36:37], v[20:23], off offset:256
	v_cvt_f32_f16_e32 v24, v169
	v_mov_b32_e32 v25, v18
	v_fma_mixlo_f16 v20, v16, v26, 0
	v_cvt_f32_f16_e32 v16, v170
	v_cvt_f32_f16_sdwa v22, v168 dst_sel:DWORD dst_unused:UNUSED_PAD src0_sel:WORD_1
	v_cvt_f32_f16_sdwa v23, v170 dst_sel:DWORD dst_unused:UNUSED_PAD src0_sel:WORD_1
	v_rcp_f32_e32 v21, v16
	v_rcp_f32_e32 v22, v22
	v_rcp_f32_e32 v16, v23
	v_rcp_f32_e32 v23, v24
	v_mov_b32_e32 v24, v17
	v_cvt_f32_f16_e32 v17, v171
	v_pk_mul_f32 v[22:23], v[24:25], v[22:23]
	s_nop 0
	v_cvt_pk_f16_f32 v18, v22, v23
	v_pack_b32_f16 v24, v20, v18
	v_rcp_f32_e32 v17, v17
	v_cvt_f32_f16_sdwa v20, v169 dst_sel:DWORD dst_unused:UNUSED_PAD src0_sel:WORD_1
	v_mov_b32_e32 v22, v13
	v_mov_b32_e32 v23, v14
	v_pk_mul_f32 v[16:17], v[22:23], v[16:17]
	v_rcp_f32_e32 v20, v20
	v_cvt_pk_f16_f32 v14, v16, v17
	v_cvt_f32_f16_sdwa v16, v171 dst_sel:DWORD dst_unused:UNUSED_PAD src0_sel:WORD_1
	v_pk_mov_b32 v[12:13], v[18:19], v[12:13] op_sel:[1,0]
	s_nop 0
	v_pk_mul_f32 v[12:13], v[12:13], v[20:21]
	s_nop 0
	v_cvt_pk_f16_f32 v12, v12, v13
	v_rcp_f32_e32 v13, v16
	v_alignbit_b32 v16, v12, v18, 16
	v_lshrrev_b32_e32 v18, 16, v14
	v_alignbit_b32 v17, v14, v12, 16
	v_fma_mixhi_f16 v18, v15, v13, 0
	v_lshrrev_b32_e32 v15, 4, v18
	v_and_b32_e32 v15, 0x10001, v15
	v_add3_u32 v15, v18, v15, s21
	v_cvt_f32_f16_e32 v18, v164
	v_lshrrev_b32_e32 v13, 4, v16
	v_lshrrev_b32_e32 v14, 4, v17
	v_lshrrev_b32_e32 v12, 4, v24
	v_and_b32_e32 v13, 0x10001, v13
	v_and_b32_e32 v14, 0x10001, v14
	v_rcp_f32_e32 v20, v18
	v_and_b32_e32 v12, 0x10001, v12
	v_add3_u32 v13, v16, v13, s21
	v_add3_u32 v14, v17, v14, s21
	v_lshl_add_u64 v[16:17], v[80:81], 0, s[10:11]
	s_mov_b32 s10, 0x30000
	v_add3_u32 v12, v24, v12, s21
	v_add_co_u32_e32 v18, vcc, s10, v80
	v_and_b32_e32 v12, 0xfff0fff0, v12
	v_and_b32_e32 v13, 0xfff0fff0, v13
	v_and_b32_e32 v14, 0xfff0fff0, v14
	v_and_b32_e32 v15, 0xfff0fff0, v15
	v_addc_co_u32_e32 v19, vcc, 0, v81, vcc
	global_store_dwordx4 v[18:19], v[12:15], off
	v_cvt_f32_f16_e32 v18, v165
	v_mov_b32_e32 v19, v10
	v_fma_mixlo_f16 v12, v8, v20, 0
	v_cvt_f32_f16_e32 v8, v166
	v_cvt_f32_f16_sdwa v14, v164 dst_sel:DWORD dst_unused:UNUSED_PAD src0_sel:WORD_1
	v_cvt_f32_f16_sdwa v15, v166 dst_sel:DWORD dst_unused:UNUSED_PAD src0_sel:WORD_1
	s_mov_b64 s[10:11], 0x80000
	v_rcp_f32_e32 v13, v8
	v_rcp_f32_e32 v14, v14
	v_rcp_f32_e32 v8, v15
	v_rcp_f32_e32 v15, v18
	v_mov_b32_e32 v18, v9
	v_cvt_f32_f16_e32 v9, v167
	v_pk_mul_f32 v[14:15], v[18:19], v[14:15]
	s_nop 0
	v_cvt_pk_f16_f32 v10, v14, v15
	v_pack_b32_f16 v18, v12, v10
	v_rcp_f32_e32 v9, v9
	v_cvt_f32_f16_sdwa v12, v165 dst_sel:DWORD dst_unused:UNUSED_PAD src0_sel:WORD_1
	v_mov_b32_e32 v14, v5
	v_mov_b32_e32 v15, v6
	v_pk_mul_f32 v[8:9], v[14:15], v[8:9]
	v_rcp_f32_e32 v12, v12
	v_cvt_pk_f16_f32 v6, v8, v9
	v_cvt_f32_f16_sdwa v8, v167 dst_sel:DWORD dst_unused:UNUSED_PAD src0_sel:WORD_1
	v_pk_mov_b32 v[4:5], v[10:11], v[4:5] op_sel:[1,0]
	v_mov_b32_e32 v11, v126
	v_pk_mul_f32 v[4:5], v[4:5], v[12:13]
	v_mov_b32_e32 v13, v118
	v_cvt_pk_f16_f32 v4, v4, v5
	v_rcp_f32_e32 v5, v8
	v_alignbit_b32 v8, v4, v10, 16
	v_lshrrev_b32_e32 v10, 16, v6
	v_alignbit_b32 v9, v6, v4, 16
	v_fma_mixhi_f16 v10, v7, v5, 0
	v_cvt_f32_f16_e32 v7, v160
	v_lshrrev_b32_e32 v5, 4, v8
	v_lshrrev_b32_e32 v6, 4, v9
	v_and_b32_e32 v5, 0x10001, v5
	v_and_b32_e32 v6, 0x10001, v6
	v_lshrrev_b32_e32 v4, 4, v18
	v_add3_u32 v5, v8, v5, s21
	v_add3_u32 v6, v9, v6, s21
	v_lshrrev_b32_e32 v8, 4, v10
	v_rcp_f32_e32 v9, v7
	v_and_b32_e32 v4, 0x10001, v4
	v_and_b32_e32 v8, 0x10001, v8
	v_add3_u32 v4, v18, v4, s21
	v_add3_u32 v8, v10, v8, s21
	v_and_b32_e32 v4, 0xfff0fff0, v4
	v_and_b32_e32 v5, 0xfff0fff0, v5
	v_and_b32_e32 v6, 0xfff0fff0, v6
	v_and_b32_e32 v7, 0xfff0fff0, v8
	global_store_dwordx4 v[16:17], v[4:7], off offset:256
	v_mov_b32_e32 v10, v125
	s_nop 0
	v_fma_mixlo_f16 v4, v124, v9, 0
	v_cvt_f32_f16_sdwa v6, v160 dst_sel:DWORD dst_unused:UNUSED_PAD src0_sel:WORD_1
	v_cvt_f32_f16_sdwa v7, v162 dst_sel:DWORD dst_unused:UNUSED_PAD src0_sel:WORD_1
	v_cvt_f32_f16_e32 v9, v161
	v_cvt_f32_f16_e32 v5, v162
	v_rcp_f32_e32 v6, v6
	v_rcp_f32_e32 v8, v7
	v_rcp_f32_e32 v7, v9
	v_cvt_f32_f16_e32 v9, v163
	v_rcp_f32_e32 v5, v5
	v_pk_mul_f32 v[6:7], v[10:11], v[6:7]
	s_nop 0
	v_cvt_pk_f16_f32 v10, v6, v7
	v_pack_b32_f16 v11, v4, v10
	v_cvt_f32_f16_sdwa v4, v161 dst_sel:DWORD dst_unused:UNUSED_PAD src0_sel:WORD_1
	v_rcp_f32_e32 v9, v9
	v_mov_b32_e32 v6, v145
	v_mov_b32_e32 v7, v146
	v_rcp_f32_e32 v4, v4
	v_pk_mul_f32 v[6:7], v[6:7], v[8:9]
	v_cvt_f32_f16_sdwa v9, v163 dst_sel:DWORD dst_unused:UNUSED_PAD src0_sel:WORD_1
	v_cvt_pk_f16_f32 v8, v6, v7
	v_pk_mov_b32 v[6:7], v[126:127], v[144:145] op_sel:[1,0]
	s_nop 0
	v_pk_mul_f32 v[4:5], v[6:7], v[4:5]
	s_nop 0
	v_cvt_pk_f16_f32 v4, v4, v5
	v_rcp_f32_e32 v5, v9
	v_alignbit_b32 v6, v4, v10, 16
	v_alignbit_b32 v7, v8, v4, 16
	v_lshrrev_b32_e32 v8, 16, v8
	v_fma_mixhi_f16 v8, v147, v5, 0
	v_lshrrev_b32_e32 v5, 4, v6
	v_and_b32_e32 v5, 0x10001, v5
	v_add3_u32 v5, v6, v5, s21
	v_lshrrev_b32_e32 v6, 4, v7
	v_and_b32_e32 v6, 0x10001, v6
	v_cvt_f32_f16_e32 v10, v156
	v_add3_u32 v6, v7, v6, s21
	v_lshrrev_b32_e32 v7, 4, v8
	v_lshrrev_b32_e32 v4, 4, v11
	v_and_b32_e32 v7, 0x10001, v7
	v_and_b32_e32 v4, 0x10001, v4
	v_add3_u32 v7, v8, v7, s21
	v_lshl_add_u64 v[8:9], v[80:81], 0, s[10:11]
	s_mov_b32 s10, 0x80000
	v_add3_u32 v4, v11, v4, s21
	v_rcp_f32_e32 v12, v10
	v_add_co_u32_e32 v10, vcc, s10, v80
	v_and_b32_e32 v4, 0xfff0fff0, v4
	v_and_b32_e32 v5, 0xfff0fff0, v5
	v_and_b32_e32 v6, 0xfff0fff0, v6
	v_and_b32_e32 v7, 0xfff0fff0, v7
	v_addc_co_u32_e32 v11, vcc, 0, v81, vcc
	global_store_dwordx4 v[10:11], v[4:7], off
	v_cvt_f32_f16_e32 v11, v157
	s_mov_b64 s[10:11], 0x90000
	v_cvt_f32_f16_sdwa v6, v156 dst_sel:DWORD dst_unused:UNUSED_PAD src0_sel:WORD_1
	v_cvt_f32_f16_sdwa v7, v158 dst_sel:DWORD dst_unused:UNUSED_PAD src0_sel:WORD_1
	v_fma_mixlo_f16 v4, v116, v12, 0
	v_mov_b32_e32 v12, v117
	v_rcp_f32_e32 v6, v6
	v_rcp_f32_e32 v10, v7
	v_rcp_f32_e32 v7, v11
	v_cvt_f32_f16_e32 v11, v159
	v_cvt_f32_f16_e32 v5, v158
	v_pk_mul_f32 v[6:7], v[12:13], v[6:7]
	s_nop 0
	v_cvt_pk_f16_f32 v12, v6, v7
	v_pack_b32_f16 v13, v4, v12
	v_cvt_f32_f16_sdwa v4, v157 dst_sel:DWORD dst_unused:UNUSED_PAD src0_sel:WORD_1
	v_rcp_f32_e32 v11, v11
	v_rcp_f32_e32 v5, v5
	v_mov_b32_e32 v6, v121
	v_mov_b32_e32 v7, v122
	v_rcp_f32_e32 v4, v4
	v_pk_mul_f32 v[6:7], v[6:7], v[10:11]
	v_cvt_f32_f16_sdwa v11, v159 dst_sel:DWORD dst_unused:UNUSED_PAD src0_sel:WORD_1
	v_cvt_pk_f16_f32 v10, v6, v7
	v_pk_mov_b32 v[6:7], v[118:119], v[120:121] op_sel:[1,0]
	s_nop 0
	v_pk_mul_f32 v[4:5], v[6:7], v[4:5]
	s_nop 0
	v_cvt_pk_f16_f32 v4, v4, v5
	v_rcp_f32_e32 v5, v11
	v_alignbit_b32 v6, v4, v12, 16
	v_alignbit_b32 v7, v10, v4, 16
	v_lshrrev_b32_e32 v10, 16, v10
	v_fma_mixhi_f16 v10, v123, v5, 0
	v_lshrrev_b32_e32 v5, 4, v6
	v_and_b32_e32 v5, 0x10001, v5
	v_add3_u32 v5, v6, v5, s21
	v_lshrrev_b32_e32 v6, 4, v7
	v_and_b32_e32 v6, 0x10001, v6
	v_add3_u32 v6, v7, v6, s21
	v_cvt_f32_f16_e32 v7, v152
	v_lshrrev_b32_e32 v4, 4, v13
	v_lshrrev_b32_e32 v11, 4, v10
	v_and_b32_e32 v4, 0x10001, v4
	v_and_b32_e32 v11, 0x10001, v11
	v_add3_u32 v4, v13, v4, s21
	v_rcp_f32_e32 v12, v7
	v_add3_u32 v7, v10, v11, s21
	v_and_b32_e32 v4, 0xfff0fff0, v4
	v_and_b32_e32 v5, 0xfff0fff0, v5
	v_and_b32_e32 v6, 0xfff0fff0, v6
	v_and_b32_e32 v7, 0xfff0fff0, v7
	global_store_dwordx4 v[8:9], v[4:7], off offset:256
	v_cvt_f32_f16_e32 v9, v153
	v_mov_b32_e32 v10, v105
	v_cvt_f32_f16_sdwa v6, v152 dst_sel:DWORD dst_unused:UNUSED_PAD src0_sel:WORD_1
	v_cvt_f32_f16_sdwa v7, v154 dst_sel:DWORD dst_unused:UNUSED_PAD src0_sel:WORD_1
	v_mov_b32_e32 v11, v106
	v_fma_mixlo_f16 v4, v104, v12, 0
	v_rcp_f32_e32 v6, v6
	v_rcp_f32_e32 v8, v7
	v_rcp_f32_e32 v7, v9
	v_cvt_f32_f16_e32 v9, v155
	v_cvt_f32_f16_e32 v5, v154
	v_mov_b32_e32 v13, v98
	v_pk_mul_f32 v[6:7], v[10:11], v[6:7]
	v_rcp_f32_e32 v9, v9
	v_cvt_pk_f16_f32 v10, v6, v7
	v_pack_b32_f16 v11, v4, v10
	v_cvt_f32_f16_sdwa v4, v153 dst_sel:DWORD dst_unused:UNUSED_PAD src0_sel:WORD_1
	v_rcp_f32_e32 v5, v5
	v_mov_b32_e32 v6, v113
	v_mov_b32_e32 v7, v114
	v_rcp_f32_e32 v4, v4
	v_pk_mul_f32 v[6:7], v[6:7], v[8:9]
	v_cvt_f32_f16_sdwa v9, v155 dst_sel:DWORD dst_unused:UNUSED_PAD src0_sel:WORD_1
	v_cvt_pk_f16_f32 v8, v6, v7
	v_pk_mov_b32 v[6:7], v[106:107], v[112:113] op_sel:[1,0]
	s_nop 0
	v_pk_mul_f32 v[4:5], v[6:7], v[4:5]
	s_nop 0
	v_cvt_pk_f16_f32 v4, v4, v5
	v_rcp_f32_e32 v5, v9
	v_alignbit_b32 v6, v4, v10, 16
	v_alignbit_b32 v7, v8, v4, 16
	v_lshrrev_b32_e32 v8, 16, v8
	v_fma_mixhi_f16 v8, v115, v5, 0
	v_lshrrev_b32_e32 v5, 4, v6
	v_and_b32_e32 v5, 0x10001, v5
	v_add3_u32 v5, v6, v5, s21
	v_lshrrev_b32_e32 v6, 4, v7
	v_and_b32_e32 v6, 0x10001, v6
	v_cvt_f32_f16_e32 v10, v148
	v_add3_u32 v6, v7, v6, s21
	v_lshrrev_b32_e32 v7, 4, v8
	v_lshrrev_b32_e32 v4, 4, v11
	v_and_b32_e32 v7, 0x10001, v7
	v_and_b32_e32 v4, 0x10001, v4
	v_add3_u32 v7, v8, v7, s21
	v_lshl_add_u64 v[8:9], v[80:81], 0, s[10:11]
	s_mov_b32 s10, 0x90000
	v_add3_u32 v4, v11, v4, s21
	v_rcp_f32_e32 v12, v10
	v_add_co_u32_e32 v10, vcc, s10, v80
	v_and_b32_e32 v4, 0xfff0fff0, v4
	v_and_b32_e32 v5, 0xfff0fff0, v5
	v_and_b32_e32 v6, 0xfff0fff0, v6
	v_and_b32_e32 v7, 0xfff0fff0, v7
	v_addc_co_u32_e32 v11, vcc, 0, v81, vcc
	global_store_dwordx4 v[10:11], v[4:7], off
	v_cvt_f32_f16_e32 v11, v149
	s_mov_b64 s[10:11], 0xa0000
	v_cvt_f32_f16_sdwa v6, v148 dst_sel:DWORD dst_unused:UNUSED_PAD src0_sel:WORD_1
	v_cvt_f32_f16_sdwa v7, v150 dst_sel:DWORD dst_unused:UNUSED_PAD src0_sel:WORD_1
	v_fma_mixlo_f16 v4, v96, v12, 0
	v_mov_b32_e32 v12, v97
	v_rcp_f32_e32 v6, v6
	v_rcp_f32_e32 v10, v7
	v_rcp_f32_e32 v7, v11
	v_cvt_f32_f16_e32 v11, v151
	v_cvt_f32_f16_e32 v5, v150
	v_pk_mul_f32 v[6:7], v[12:13], v[6:7]
	s_nop 0
	v_cvt_pk_f16_f32 v12, v6, v7
	v_pack_b32_f16 v13, v4, v12
	v_cvt_f32_f16_sdwa v4, v149 dst_sel:DWORD dst_unused:UNUSED_PAD src0_sel:WORD_1
	v_rcp_f32_e32 v11, v11
	v_rcp_f32_e32 v5, v5
	v_mov_b32_e32 v6, v101
	v_mov_b32_e32 v7, v102
	v_rcp_f32_e32 v4, v4
	v_pk_mul_f32 v[6:7], v[6:7], v[10:11]
	v_cvt_f32_f16_sdwa v11, v151 dst_sel:DWORD dst_unused:UNUSED_PAD src0_sel:WORD_1
	v_cvt_pk_f16_f32 v10, v6, v7
	v_pk_mov_b32 v[6:7], v[98:99], v[100:101] op_sel:[1,0]
	s_nop 0
	v_pk_mul_f32 v[4:5], v[6:7], v[4:5]
	s_nop 0
	v_cvt_pk_f16_f32 v4, v4, v5
	v_rcp_f32_e32 v5, v11
	v_alignbit_b32 v6, v4, v12, 16
	v_alignbit_b32 v7, v10, v4, 16
	v_lshrrev_b32_e32 v10, 16, v10
	v_fma_mixhi_f16 v10, v103, v5, 0
	v_lshrrev_b32_e32 v5, 4, v6
	v_and_b32_e32 v5, 0x10001, v5
	v_add3_u32 v5, v6, v5, s21
	v_lshrrev_b32_e32 v6, 4, v7
	v_and_b32_e32 v6, 0x10001, v6
	v_add3_u32 v6, v7, v6, s21
	v_cvt_f32_f16_e32 v7, v140
	v_lshrrev_b32_e32 v4, 4, v13
	v_lshrrev_b32_e32 v11, 4, v10
	v_and_b32_e32 v4, 0x10001, v4
	v_and_b32_e32 v11, 0x10001, v11
	v_add3_u32 v4, v13, v4, s21
	v_rcp_f32_e32 v12, v7
	v_add3_u32 v7, v10, v11, s21
	v_and_b32_e32 v4, 0xfff0fff0, v4
	v_and_b32_e32 v5, 0xfff0fff0, v5
	v_and_b32_e32 v6, 0xfff0fff0, v6
	v_and_b32_e32 v7, 0xfff0fff0, v7
	global_store_dwordx4 v[8:9], v[4:7], off offset:256
	v_cvt_f32_f16_e32 v9, v141
	v_mov_b32_e32 v10, v85
	v_cvt_f32_f16_sdwa v6, v140 dst_sel:DWORD dst_unused:UNUSED_PAD src0_sel:WORD_1
	v_cvt_f32_f16_sdwa v7, v142 dst_sel:DWORD dst_unused:UNUSED_PAD src0_sel:WORD_1
	v_mov_b32_e32 v11, v86
	v_fma_mixlo_f16 v4, v84, v12, 0
	v_rcp_f32_e32 v6, v6
	v_rcp_f32_e32 v8, v7
	v_rcp_f32_e32 v7, v9
	v_cvt_f32_f16_e32 v9, v143
	v_cvt_f32_f16_e32 v5, v142
	v_mov_b32_e32 v13, v66
	v_pk_mul_f32 v[6:7], v[10:11], v[6:7]
	v_rcp_f32_e32 v9, v9
	v_cvt_pk_f16_f32 v10, v6, v7
	v_pack_b32_f16 v11, v4, v10
	v_cvt_f32_f16_sdwa v4, v141 dst_sel:DWORD dst_unused:UNUSED_PAD src0_sel:WORD_1
	v_rcp_f32_e32 v5, v5
	v_mov_b32_e32 v6, v93
	v_mov_b32_e32 v7, v94
	v_rcp_f32_e32 v4, v4
	v_pk_mul_f32 v[6:7], v[6:7], v[8:9]
	v_cvt_f32_f16_sdwa v9, v143 dst_sel:DWORD dst_unused:UNUSED_PAD src0_sel:WORD_1
	v_cvt_pk_f16_f32 v8, v6, v7
	v_pk_mov_b32 v[6:7], v[86:87], v[92:93] op_sel:[1,0]
	s_nop 0
	v_pk_mul_f32 v[4:5], v[6:7], v[4:5]
	s_nop 0
	v_cvt_pk_f16_f32 v4, v4, v5
	v_rcp_f32_e32 v5, v9
	v_alignbit_b32 v6, v4, v10, 16
	v_alignbit_b32 v7, v8, v4, 16
	v_lshrrev_b32_e32 v8, 16, v8
	v_fma_mixhi_f16 v8, v95, v5, 0
	v_lshrrev_b32_e32 v5, 4, v6
	v_and_b32_e32 v5, 0x10001, v5
	v_add3_u32 v5, v6, v5, s21
	v_lshrrev_b32_e32 v6, 4, v7
	v_and_b32_e32 v6, 0x10001, v6
	v_cvt_f32_f16_e32 v10, v136
	v_add3_u32 v6, v7, v6, s21
	v_lshrrev_b32_e32 v7, 4, v8
	v_lshrrev_b32_e32 v4, 4, v11
	v_and_b32_e32 v7, 0x10001, v7
	v_and_b32_e32 v4, 0x10001, v4
	v_add3_u32 v7, v8, v7, s21
	v_lshl_add_u64 v[8:9], v[80:81], 0, s[10:11]
	s_mov_b32 s10, 0xa0000
	v_add3_u32 v4, v11, v4, s21
	v_rcp_f32_e32 v12, v10
	v_add_co_u32_e32 v10, vcc, s10, v80
	v_and_b32_e32 v4, 0xfff0fff0, v4
	v_and_b32_e32 v5, 0xfff0fff0, v5
	v_and_b32_e32 v6, 0xfff0fff0, v6
	v_and_b32_e32 v7, 0xfff0fff0, v7
	v_addc_co_u32_e32 v11, vcc, 0, v81, vcc
	global_store_dwordx4 v[10:11], v[4:7], off
	v_cvt_f32_f16_e32 v11, v137
	s_mov_b64 s[10:11], 0xb0000
	v_cvt_f32_f16_sdwa v6, v136 dst_sel:DWORD dst_unused:UNUSED_PAD src0_sel:WORD_1
	v_cvt_f32_f16_sdwa v7, v138 dst_sel:DWORD dst_unused:UNUSED_PAD src0_sel:WORD_1
	v_fma_mixlo_f16 v4, v64, v12, 0
	v_mov_b32_e32 v12, v65
	v_rcp_f32_e32 v6, v6
	v_rcp_f32_e32 v10, v7
	v_rcp_f32_e32 v7, v11
	v_cvt_f32_f16_e32 v11, v139
	v_cvt_f32_f16_e32 v5, v138
	v_pk_mul_f32 v[6:7], v[12:13], v[6:7]
	s_nop 0
	v_cvt_pk_f16_f32 v12, v6, v7
	v_pack_b32_f16 v13, v4, v12
	v_cvt_f32_f16_sdwa v4, v137 dst_sel:DWORD dst_unused:UNUSED_PAD src0_sel:WORD_1
	v_rcp_f32_e32 v11, v11
	v_rcp_f32_e32 v5, v5
	v_mov_b32_e32 v6, v77
	v_mov_b32_e32 v7, v78
	v_rcp_f32_e32 v4, v4
	v_pk_mul_f32 v[6:7], v[6:7], v[10:11]
	v_cvt_f32_f16_sdwa v11, v139 dst_sel:DWORD dst_unused:UNUSED_PAD src0_sel:WORD_1
	v_cvt_pk_f16_f32 v10, v6, v7
	v_pk_mov_b32 v[6:7], v[66:67], v[76:77] op_sel:[1,0]
	s_nop 0
	v_pk_mul_f32 v[4:5], v[6:7], v[4:5]
	s_nop 0
	v_cvt_pk_f16_f32 v4, v4, v5
	v_rcp_f32_e32 v5, v11
	v_alignbit_b32 v6, v4, v12, 16
	v_alignbit_b32 v7, v10, v4, 16
	v_lshrrev_b32_e32 v10, 16, v10
	v_fma_mixhi_f16 v10, v79, v5, 0
	v_lshrrev_b32_e32 v5, 4, v6
	v_and_b32_e32 v5, 0x10001, v5
	v_add3_u32 v5, v6, v5, s21
	v_lshrrev_b32_e32 v6, 4, v7
	v_and_b32_e32 v6, 0x10001, v6
	v_add3_u32 v6, v7, v6, s21
	v_cvt_f32_f16_e32 v7, v132
	v_lshrrev_b32_e32 v4, 4, v13
	v_lshrrev_b32_e32 v11, 4, v10
	v_and_b32_e32 v4, 0x10001, v4
	v_and_b32_e32 v11, 0x10001, v11
	v_add3_u32 v4, v13, v4, s21
	v_rcp_f32_e32 v12, v7
	v_add3_u32 v7, v10, v11, s21
	v_and_b32_e32 v4, 0xfff0fff0, v4
	v_and_b32_e32 v5, 0xfff0fff0, v5
	v_and_b32_e32 v6, 0xfff0fff0, v6
	v_and_b32_e32 v7, 0xfff0fff0, v7
	global_store_dwordx4 v[8:9], v[4:7], off offset:256
	v_cvt_f32_f16_e32 v9, v133
	v_mov_b32_e32 v10, v49
	v_cvt_f32_f16_sdwa v6, v132 dst_sel:DWORD dst_unused:UNUSED_PAD src0_sel:WORD_1
	v_cvt_f32_f16_sdwa v7, v134 dst_sel:DWORD dst_unused:UNUSED_PAD src0_sel:WORD_1
	v_mov_b32_e32 v11, v50
	v_fma_mixlo_f16 v4, v48, v12, 0
	v_rcp_f32_e32 v6, v6
	v_rcp_f32_e32 v8, v7
	v_rcp_f32_e32 v7, v9
	v_cvt_f32_f16_e32 v9, v135
	v_cvt_f32_f16_e32 v5, v134
	v_mov_b32_e32 v13, v34
	v_pk_mul_f32 v[6:7], v[10:11], v[6:7]
	v_rcp_f32_e32 v9, v9
	v_cvt_pk_f16_f32 v10, v6, v7
	v_pack_b32_f16 v11, v4, v10
	v_cvt_f32_f16_sdwa v4, v133 dst_sel:DWORD dst_unused:UNUSED_PAD src0_sel:WORD_1
	v_rcp_f32_e32 v5, v5
	v_mov_b32_e32 v6, v61
	v_mov_b32_e32 v7, v62
	v_rcp_f32_e32 v4, v4
	v_pk_mul_f32 v[6:7], v[6:7], v[8:9]
	v_cvt_f32_f16_sdwa v9, v135 dst_sel:DWORD dst_unused:UNUSED_PAD src0_sel:WORD_1
	v_cvt_pk_f16_f32 v8, v6, v7
	v_pk_mov_b32 v[6:7], v[50:51], v[60:61] op_sel:[1,0]
	s_nop 0
	v_pk_mul_f32 v[4:5], v[6:7], v[4:5]
	s_nop 0
	v_cvt_pk_f16_f32 v4, v4, v5
	v_rcp_f32_e32 v5, v9
	v_alignbit_b32 v6, v4, v10, 16
	v_alignbit_b32 v7, v8, v4, 16
	v_lshrrev_b32_e32 v8, 16, v8
	v_fma_mixhi_f16 v8, v63, v5, 0
	v_lshrrev_b32_e32 v5, 4, v6
	v_and_b32_e32 v5, 0x10001, v5
	v_add3_u32 v5, v6, v5, s21
	v_lshrrev_b32_e32 v6, 4, v7
	v_and_b32_e32 v6, 0x10001, v6
	v_cvt_f32_f16_e32 v10, v128
	v_add3_u32 v6, v7, v6, s21
	v_lshrrev_b32_e32 v7, 4, v8
	v_lshrrev_b32_e32 v4, 4, v11
	v_and_b32_e32 v7, 0x10001, v7
	v_and_b32_e32 v4, 0x10001, v4
	v_add3_u32 v7, v8, v7, s21
	v_lshl_add_u64 v[8:9], v[80:81], 0, s[10:11]
	s_mov_b32 s10, 0xb0000
	v_add3_u32 v4, v11, v4, s21
	v_rcp_f32_e32 v12, v10
	v_add_co_u32_e32 v10, vcc, s10, v80
	v_and_b32_e32 v4, 0xfff0fff0, v4
	v_and_b32_e32 v5, 0xfff0fff0, v5
	v_and_b32_e32 v6, 0xfff0fff0, v6
	v_and_b32_e32 v7, 0xfff0fff0, v7
	v_addc_co_u32_e32 v11, vcc, 0, v81, vcc
	global_store_dwordx4 v[10:11], v[4:7], off
	v_cvt_f32_f16_e32 v11, v129
	s_andn2_b64 vcc, exec, s[40:41]
	v_cvt_f32_f16_sdwa v6, v128 dst_sel:DWORD dst_unused:UNUSED_PAD src0_sel:WORD_1
	v_cvt_f32_f16_sdwa v7, v130 dst_sel:DWORD dst_unused:UNUSED_PAD src0_sel:WORD_1
	v_fma_mixlo_f16 v4, v32, v12, 0
	v_mov_b32_e32 v12, v33
	v_rcp_f32_e32 v6, v6
	v_rcp_f32_e32 v10, v7
	v_rcp_f32_e32 v7, v11
	v_cvt_f32_f16_e32 v11, v131
	v_cvt_f32_f16_e32 v5, v130
	v_pk_mul_f32 v[6:7], v[12:13], v[6:7]
	s_nop 0
	v_cvt_pk_f16_f32 v12, v6, v7
	v_pack_b32_f16 v13, v4, v12
	v_cvt_f32_f16_sdwa v4, v129 dst_sel:DWORD dst_unused:UNUSED_PAD src0_sel:WORD_1
	v_rcp_f32_e32 v11, v11
	v_rcp_f32_e32 v5, v5
	v_mov_b32_e32 v6, v45
	v_mov_b32_e32 v7, v46
	v_rcp_f32_e32 v4, v4
	v_pk_mul_f32 v[6:7], v[6:7], v[10:11]
	v_cvt_f32_f16_sdwa v11, v131 dst_sel:DWORD dst_unused:UNUSED_PAD src0_sel:WORD_1
	v_cvt_pk_f16_f32 v10, v6, v7
	v_pk_mov_b32 v[6:7], v[34:35], v[44:45] op_sel:[1,0]
	s_nop 0
	v_pk_mul_f32 v[4:5], v[6:7], v[4:5]
	s_nop 0
	v_cvt_pk_f16_f32 v4, v4, v5
	v_rcp_f32_e32 v5, v11
	v_alignbit_b32 v6, v4, v12, 16
	v_alignbit_b32 v7, v10, v4, 16
	v_lshrrev_b32_e32 v10, 16, v10
	v_fma_mixhi_f16 v10, v47, v5, 0
	v_lshrrev_b32_e32 v5, 4, v6
	v_and_b32_e32 v5, 0x10001, v5
	v_add3_u32 v5, v6, v5, s21
	v_lshrrev_b32_e32 v6, 4, v7
	v_and_b32_e32 v6, 0x10001, v6
	v_lshrrev_b32_e32 v4, 4, v13
	v_add3_u32 v6, v7, v6, s21
	v_lshrrev_b32_e32 v7, 4, v10
	v_and_b32_e32 v4, 0x10001, v4
	v_and_b32_e32 v7, 0x10001, v7
	v_add3_u32 v4, v13, v4, s21
	v_add3_u32 v7, v10, v7, s21
	v_and_b32_e32 v4, 0xfff0fff0, v4
	v_and_b32_e32 v5, 0xfff0fff0, v5
	v_and_b32_e32 v6, 0xfff0fff0, v6
	v_and_b32_e32 v7, 0xfff0fff0, v7
	global_store_dwordx4 v[8:9], v[4:7], off offset:256
	s_cbranch_vccnz .LBB0_1739
	s_waitcnt vmcnt(0)
	v_readlane_b32 s4, v251, 63
	s_cmpk_gt_u32 s4, 0xff
	s_cbranch_scc1 .LBB0_1750
	s_barrier

.LBB0_2120:
	s_add_u32 s27, s42, 0xfff80080
	s_addc_u32 s38, s43, -1
	s_add_i32 s46, 0, 0x10000
	v_add_u32_e32 v128, s46, v198
	ds_read_b128 v[108:111], v128
	ds_read_b128 v[112:115], v128 offset:1024
	ds_read_b128 v[120:123], v128 offset:2048
	ds_read_b128 v[128:131], v128 offset:3072
	s_cmp_eq_u32 s17, 28
	s_cselect_b32 s45, s35, s38
	s_cselect_b32 s44, s34, s27
	s_cselect_b32 s39, s37, s15
	s_cselect_b32 s38, s36, s14
	v_lshl_add_u64 v[186:187], s[42:43], 0, v[182:183]
	s_add_i32 m0, s6, 0xc000
	ds_read_b128 v[148:151], v199
	ds_read_b128 v[152:155], v199 offset:1024
	ds_read_b128 v[156:159], v199 offset:2048
	ds_read_b128 v[160:163], v199 offset:3072
	ds_read_b128 v[164:167], v199 offset:4096
	ds_read_b128 v[168:171], v199 offset:5120
	ds_read_b128 v[172:175], v199 offset:6144
	ds_read_b128 v[176:179], v199 offset:7168
	global_load_lds_dwordx4 v[186:187], off
	v_lshl_add_u64 v[186:187], s[42:43], 0, v[184:185]
	s_add_i32 m0, s6, 0xe000
	s_nop 0
	global_load_lds_dwordx4 v[186:187], off
	s_waitcnt lgkmcnt(8)
	s_barrier
	s_waitcnt lgkmcnt(0)
	v_mfma_f32_16x16x32_f16 v[144:147], v[108:111], v[148:151], v[144:147]
	v_mfma_f32_16x16x32_f16 v[140:143], v[120:123], v[148:151], v[140:143]
	v_mfma_f32_16x16x32_f16 v[124:127], v[108:111], v[156:159], v[124:127]
	v_mfma_f32_16x16x32_f16 v[116:119], v[120:123], v[156:159], v[116:119]
	v_mfma_f32_16x16x32_f16 v[96:99], v[108:111], v[164:167], v[96:99]
	v_mfma_f32_16x16x32_f16 v[92:95], v[120:123], v[164:167], v[92:95]
	v_mfma_f32_16x16x32_f16 v[88:91], v[108:111], v[172:175], v[88:91]
	v_mfma_f32_16x16x32_f16 v[80:83], v[120:123], v[172:175], v[80:83]
	v_mfma_f32_16x16x32_f16 v[144:147], v[112:115], v[152:155], v[144:147]
	v_mfma_f32_16x16x32_f16 v[140:143], v[128:131], v[152:155], v[140:143]
	v_mfma_f32_16x16x32_f16 v[124:127], v[112:115], v[160:163], v[124:127]
	v_mfma_f32_16x16x32_f16 v[116:119], v[128:131], v[160:163], v[116:119]
	v_mfma_f32_16x16x32_f16 v[96:99], v[112:115], v[168:171], v[96:99]
	v_mfma_f32_16x16x32_f16 v[92:95], v[128:131], v[168:171], v[92:95]
	v_mfma_f32_16x16x32_f16 v[88:91], v[112:115], v[176:179], v[88:91]
	v_mfma_f32_16x16x32_f16 v[80:83], v[128:131], v[176:179], v[80:83]
	s_barrier
	s_add_i32 s27, 0, 0x14000
	v_add_u32_e32 v194, s27, v198
	s_add_i32 s46, s46, s5
	ds_read_b128 v[186:189], v194
	ds_read_b128 v[190:193], v194 offset:1024
	ds_read_b128 v[200:203], v194 offset:2048
	ds_read_b128 v[206:209], v194 offset:3072
	v_lshl_add_u64 v[194:195], s[38:39], 0, v[2:3]
	s_mov_b32 m0, s46
	v_lshl_add_u64 v[210:211], s[38:39], 0, v[180:181]
	global_load_lds_dwordx4 v[194:195], off
	s_add_i32 m0, s46, 0x2000
	s_nop 0
	global_load_lds_dwordx4 v[210:211], off
	s_barrier
	s_waitcnt lgkmcnt(0)
	v_mfma_f32_16x16x32_f16 v[136:139], v[186:189], v[148:151], v[136:139]
	v_mfma_f32_16x16x32_f16 v[132:135], v[200:203], v[148:151], v[132:135]
	v_mfma_f32_16x16x32_f16 v[104:107], v[186:189], v[156:159], v[104:107]
	v_mfma_f32_16x16x32_f16 v[100:103], v[200:203], v[156:159], v[100:103]
	v_mfma_f32_16x16x32_f16 v[84:87], v[186:189], v[164:167], v[84:87]
	v_mfma_f32_16x16x32_f16 v[76:79], v[200:203], v[164:167], v[76:79]
	v_mfma_f32_16x16x32_f16 v[72:75], v[186:189], v[172:175], v[72:75]
	v_mfma_f32_16x16x32_f16 v[68:71], v[200:203], v[172:175], v[68:71]
	v_mfma_f32_16x16x32_f16 v[136:139], v[190:193], v[152:155], v[136:139]
	v_mfma_f32_16x16x32_f16 v[132:135], v[206:209], v[152:155], v[132:135]
	v_mfma_f32_16x16x32_f16 v[104:107], v[190:193], v[160:163], v[104:107]
	v_mfma_f32_16x16x32_f16 v[100:103], v[206:209], v[160:163], v[100:103]
	v_mfma_f32_16x16x32_f16 v[84:87], v[190:193], v[168:171], v[84:87]
	v_mfma_f32_16x16x32_f16 v[76:79], v[206:209], v[168:171], v[76:79]
	v_mfma_f32_16x16x32_f16 v[72:75], v[190:193], v[176:179], v[72:75]
	v_mfma_f32_16x16x32_f16 v[68:71], v[206:209], v[176:179], v[68:71]
	s_mov_b32 m0, s6
	v_lshl_add_u64 v[212:213], s[44:45], 0, v[2:3]
	s_barrier
	ds_read_b128 v[148:151], v199 offset:16384
	ds_read_b128 v[152:155], v199 offset:17408
	ds_read_b128 v[156:159], v199 offset:18432
	ds_read_b128 v[160:163], v199 offset:19456
	ds_read_b128 v[164:167], v199 offset:20480
	ds_read_b128 v[168:171], v199 offset:21504
	ds_read_b128 v[172:175], v199 offset:22528
	ds_read_b128 v[176:179], v199 offset:23552
	global_load_lds_dwordx4 v[212:213], off
	v_lshl_add_u64 v[214:215], s[44:45], 0, v[180:181]
	s_mov_b32 m0, s7
	s_nop 0
	global_load_lds_dwordx4 v[214:215], off
	s_barrier
	s_waitcnt lgkmcnt(0)
	v_mfma_f32_16x16x32_f16 v[64:67], v[108:111], v[148:151], v[64:67]
	v_mfma_f32_16x16x32_f16 v[60:63], v[120:123], v[148:151], v[60:63]
	v_mfma_f32_16x16x32_f16 v[48:51], v[108:111], v[156:159], v[48:51]
	v_mfma_f32_16x16x32_f16 v[44:47], v[120:123], v[156:159], v[44:47]
	v_mfma_f32_16x16x32_f16 v[32:35], v[108:111], v[164:167], v[32:35]
	v_mfma_f32_16x16x32_f16 v[28:31], v[120:123], v[164:167], v[28:31]
	v_mfma_f32_16x16x32_f16 v[20:23], v[108:111], v[172:175], v[20:23]
	v_mfma_f32_16x16x32_f16 v[12:15], v[120:123], v[172:175], v[12:15]
	v_mfma_f32_16x16x32_f16 v[64:67], v[112:115], v[152:155], v[64:67]
	v_mfma_f32_16x16x32_f16 v[60:63], v[128:131], v[152:155], v[60:63]
	v_mfma_f32_16x16x32_f16 v[48:51], v[112:115], v[160:163], v[48:51]
	v_mfma_f32_16x16x32_f16 v[44:47], v[128:131], v[160:163], v[44:47]
	v_mfma_f32_16x16x32_f16 v[32:35], v[112:115], v[168:171], v[32:35]
	v_mfma_f32_16x16x32_f16 v[28:31], v[128:131], v[168:171], v[28:31]
	v_mfma_f32_16x16x32_f16 v[20:23], v[112:115], v[176:179], v[20:23]
	v_mfma_f32_16x16x32_f16 v[12:15], v[128:131], v[176:179], v[12:15]
	s_barrier
	s_add_u32 s46, s38, 0x80000
	s_addc_u32 s47, s39, 0
	s_add_i32 s27, s27, s5
	v_lshl_add_u64 v[108:109], s[46:47], 0, v[2:3]
	s_mov_b32 m0, s27
	s_nop 0
	global_load_lds_dwordx4 v[108:109], off
	v_lshl_add_u64 v[108:109], s[46:47], 0, v[180:181]
	s_add_i32 m0, s27, 0x2000
	s_nop 0
	global_load_lds_dwordx4 v[108:109], off
	s_waitcnt vmcnt(6)
	s_barrier
	v_mfma_f32_16x16x32_f16 v[56:59], v[186:189], v[148:151], v[56:59]
	v_mfma_f32_16x16x32_f16 v[52:55], v[200:203], v[148:151], v[52:55]
	v_mfma_f32_16x16x32_f16 v[40:43], v[186:189], v[156:159], v[40:43]
	v_mfma_f32_16x16x32_f16 v[36:39], v[200:203], v[156:159], v[36:39]
	v_mfma_f32_16x16x32_f16 v[24:27], v[186:189], v[164:167], v[24:27]
	v_mfma_f32_16x16x32_f16 v[16:19], v[200:203], v[164:167], v[16:19]
	v_mfma_f32_16x16x32_f16 v[8:11], v[186:189], v[172:175], v[8:11]
	v_mfma_f32_16x16x32_f16 v[4:7], v[200:203], v[172:175], v[4:7]
	v_mfma_f32_16x16x32_f16 v[56:59], v[190:193], v[152:155], v[56:59]
	v_mfma_f32_16x16x32_f16 v[52:55], v[206:209], v[152:155], v[52:55]
	v_mfma_f32_16x16x32_f16 v[40:43], v[190:193], v[160:163], v[40:43]
	v_mfma_f32_16x16x32_f16 v[36:39], v[206:209], v[160:163], v[36:39]
	v_mfma_f32_16x16x32_f16 v[24:27], v[190:193], v[168:171], v[24:27]
	v_mfma_f32_16x16x32_f16 v[16:19], v[206:209], v[168:171], v[16:19]
	v_mfma_f32_16x16x32_f16 v[8:11], v[190:193], v[176:179], v[8:11]
	v_mfma_f32_16x16x32_f16 v[4:7], v[206:209], v[176:179], v[4:7]
	s_add_i32 s27, 0, 0x18000
	v_add_u32_e32 v128, s27, v198
	s_barrier
	ds_read_b128 v[108:111], v128
	ds_read_b128 v[112:115], v128 offset:1024
	ds_read_b128 v[120:123], v128 offset:2048
	ds_read_b128 v[128:131], v128 offset:3072
	s_add_u32 s44, s44, 0x80000
	s_addc_u32 s45, s45, 0
	s_mov_b32 m0, s8
	v_lshl_add_u64 v[186:187], s[44:45], 0, v[2:3]
	ds_read_b128 v[148:151], v199 offset:32768
	ds_read_b128 v[152:155], v199 offset:33792
	ds_read_b128 v[156:159], v199 offset:34816
	ds_read_b128 v[160:163], v199 offset:35840
	ds_read_b128 v[164:167], v199 offset:36864
	ds_read_b128 v[168:171], v199 offset:37888
	ds_read_b128 v[172:175], v199 offset:38912
	ds_read_b128 v[176:179], v199 offset:39936
	global_load_lds_dwordx4 v[186:187], off
	v_lshl_add_u64 v[186:187], s[44:45], 0, v[180:181]
	s_mov_b32 m0, s9
	s_nop 0
	global_load_lds_dwordx4 v[186:187], off
	s_waitcnt lgkmcnt(8)
	s_barrier
	s_waitcnt lgkmcnt(0)
	v_mfma_f32_16x16x32_f16 v[144:147], v[108:111], v[148:151], v[144:147]
	v_mfma_f32_16x16x32_f16 v[140:143], v[120:123], v[148:151], v[140:143]
	v_mfma_f32_16x16x32_f16 v[124:127], v[108:111], v[156:159], v[124:127]
	v_mfma_f32_16x16x32_f16 v[116:119], v[120:123], v[156:159], v[116:119]
	v_mfma_f32_16x16x32_f16 v[96:99], v[108:111], v[164:167], v[96:99]
	v_mfma_f32_16x16x32_f16 v[92:95], v[120:123], v[164:167], v[92:95]
	v_mfma_f32_16x16x32_f16 v[88:91], v[108:111], v[172:175], v[88:91]
	v_mfma_f32_16x16x32_f16 v[80:83], v[120:123], v[172:175], v[80:83]
	v_mfma_f32_16x16x32_f16 v[144:147], v[112:115], v[152:155], v[144:147]
	v_mfma_f32_16x16x32_f16 v[140:143], v[128:131], v[152:155], v[140:143]
	v_mfma_f32_16x16x32_f16 v[124:127], v[112:115], v[160:163], v[124:127]
	v_mfma_f32_16x16x32_f16 v[116:119], v[128:131], v[160:163], v[116:119]
	v_mfma_f32_16x16x32_f16 v[96:99], v[112:115], v[168:171], v[96:99]
	v_mfma_f32_16x16x32_f16 v[92:95], v[128:131], v[168:171], v[92:95]
	v_mfma_f32_16x16x32_f16 v[88:91], v[112:115], v[176:179], v[88:91]
	v_mfma_f32_16x16x32_f16 v[80:83], v[128:131], v[176:179], v[80:83]
	s_barrier
	s_add_i32 s44, 0, 0x1c000
	s_add_i32 s27, s27, s5
	v_add_u32_e32 v206, s44, v198
	v_lshl_add_u64 v[194:195], v[194:195], 0, s[88:89]
	s_mov_b32 m0, s27
	ds_read_b128 v[186:189], v206
	ds_read_b128 v[190:193], v206 offset:1024
	ds_read_b128 v[200:203], v206 offset:2048
	ds_read_b128 v[206:209], v206 offset:3072
	global_load_lds_dwordx4 v[194:195], off
	v_lshl_add_u64 v[194:195], v[210:211], 0, s[88:89]
	s_add_i32 m0, s27, 0x2000
	s_nop 0
	global_load_lds_dwordx4 v[194:195], off
	s_barrier
	s_waitcnt lgkmcnt(0)
	v_mfma_f32_16x16x32_f16 v[136:139], v[186:189], v[148:151], v[136:139]
	v_mfma_f32_16x16x32_f16 v[132:135], v[200:203], v[148:151], v[132:135]
	v_mfma_f32_16x16x32_f16 v[104:107], v[186:189], v[156:159], v[104:107]
	v_mfma_f32_16x16x32_f16 v[100:103], v[200:203], v[156:159], v[100:103]
	v_mfma_f32_16x16x32_f16 v[84:87], v[186:189], v[164:167], v[84:87]
	v_mfma_f32_16x16x32_f16 v[76:79], v[200:203], v[164:167], v[76:79]
	v_mfma_f32_16x16x32_f16 v[72:75], v[186:189], v[172:175], v[72:75]
	v_mfma_f32_16x16x32_f16 v[68:71], v[200:203], v[172:175], v[68:71]
	v_mfma_f32_16x16x32_f16 v[136:139], v[190:193], v[152:155], v[136:139]
	v_mfma_f32_16x16x32_f16 v[132:135], v[206:209], v[152:155], v[132:135]
	v_mfma_f32_16x16x32_f16 v[104:107], v[190:193], v[160:163], v[104:107]
	v_mfma_f32_16x16x32_f16 v[100:103], v[206:209], v[160:163], v[100:103]
	v_mfma_f32_16x16x32_f16 v[84:87], v[190:193], v[168:171], v[84:87]
	v_mfma_f32_16x16x32_f16 v[76:79], v[206:209], v[168:171], v[76:79]
	v_mfma_f32_16x16x32_f16 v[72:75], v[190:193], v[176:179], v[72:75]
	v_mfma_f32_16x16x32_f16 v[68:71], v[206:209], v[176:179], v[68:71]
	s_mov_b32 m0, s10
	v_lshl_add_u64 v[194:195], v[212:213], 0, s[88:89]
	s_barrier
	ds_read_b128 v[148:151], v199 offset:49152
	ds_read_b128 v[152:155], v199 offset:50176
	ds_read_b128 v[156:159], v199 offset:51200
	ds_read_b128 v[160:163], v199 offset:52224
	ds_read_b128 v[164:167], v199 offset:53248
	ds_read_b128 v[168:171], v199 offset:54272
	ds_read_b128 v[172:175], v199 offset:55296
	ds_read_b128 v[176:179], v199 offset:56320
	global_load_lds_dwordx4 v[194:195], off
	v_lshl_add_u64 v[194:195], v[214:215], 0, s[88:89]
	s_mov_b32 m0, s11
	s_nop 0
	global_load_lds_dwordx4 v[194:195], off
	s_barrier
	s_waitcnt lgkmcnt(0)
	v_mfma_f32_16x16x32_f16 v[64:67], v[108:111], v[148:151], v[64:67]
	v_mfma_f32_16x16x32_f16 v[60:63], v[120:123], v[148:151], v[60:63]
	v_mfma_f32_16x16x32_f16 v[48:51], v[108:111], v[156:159], v[48:51]
	v_mfma_f32_16x16x32_f16 v[44:47], v[120:123], v[156:159], v[44:47]
	v_mfma_f32_16x16x32_f16 v[32:35], v[108:111], v[164:167], v[32:35]
	v_mfma_f32_16x16x32_f16 v[28:31], v[120:123], v[164:167], v[28:31]
	v_mfma_f32_16x16x32_f16 v[20:23], v[108:111], v[172:175], v[20:23]
	v_mfma_f32_16x16x32_f16 v[12:15], v[120:123], v[172:175], v[12:15]
	v_mfma_f32_16x16x32_f16 v[64:67], v[112:115], v[152:155], v[64:67]
	v_mfma_f32_16x16x32_f16 v[60:63], v[128:131], v[152:155], v[60:63]
	v_mfma_f32_16x16x32_f16 v[48:51], v[112:115], v[160:163], v[48:51]
	v_mfma_f32_16x16x32_f16 v[44:47], v[128:131], v[160:163], v[44:47]
	v_mfma_f32_16x16x32_f16 v[32:35], v[112:115], v[168:171], v[32:35]
	v_mfma_f32_16x16x32_f16 v[28:31], v[128:131], v[168:171], v[28:31]
	v_mfma_f32_16x16x32_f16 v[20:23], v[112:115], v[176:179], v[20:23]
	v_mfma_f32_16x16x32_f16 v[12:15], v[128:131], v[176:179], v[12:15]
	s_barrier
	s_add_u32 s38, s38, 0x80080
	s_addc_u32 s39, s39, 0
	s_add_i32 s27, s44, s5
	v_lshl_add_u64 v[108:109], s[38:39], 0, v[2:3]
	s_mov_b32 m0, s27
	s_nop 0
	global_load_lds_dwordx4 v[108:109], off
	v_lshl_add_u64 v[108:109], s[38:39], 0, v[180:181]
	s_add_i32 m0, s27, 0x2000
	s_nop 0
	global_load_lds_dwordx4 v[108:109], off
	s_waitcnt vmcnt(6)
	s_barrier
	v_mfma_f32_16x16x32_f16 v[56:59], v[186:189], v[148:151], v[56:59]
	v_mfma_f32_16x16x32_f16 v[52:55], v[200:203], v[148:151], v[52:55]
	v_mfma_f32_16x16x32_f16 v[40:43], v[186:189], v[156:159], v[40:43]
	v_mfma_f32_16x16x32_f16 v[36:39], v[200:203], v[156:159], v[36:39]
	v_mfma_f32_16x16x32_f16 v[24:27], v[186:189], v[164:167], v[24:27]
	v_mfma_f32_16x16x32_f16 v[16:19], v[200:203], v[164:167], v[16:19]
	v_mfma_f32_16x16x32_f16 v[8:11], v[186:189], v[172:175], v[8:11]
	v_mfma_f32_16x16x32_f16 v[4:7], v[200:203], v[172:175], v[4:7]
	v_mfma_f32_16x16x32_f16 v[56:59], v[190:193], v[152:155], v[56:59]
	v_mfma_f32_16x16x32_f16 v[52:55], v[206:209], v[152:155], v[52:55]
	v_mfma_f32_16x16x32_f16 v[40:43], v[190:193], v[160:163], v[40:43]
	v_mfma_f32_16x16x32_f16 v[36:39], v[206:209], v[160:163], v[36:39]
	v_mfma_f32_16x16x32_f16 v[24:27], v[190:193], v[168:171], v[24:27]
	v_mfma_f32_16x16x32_f16 v[16:19], v[206:209], v[168:171], v[16:19]
	v_mfma_f32_16x16x32_f16 v[8:11], v[190:193], v[176:179], v[8:11]
	v_mfma_f32_16x16x32_f16 v[4:7], v[206:209], v[176:179], v[4:7]
	s_add_i32 s17, s17, 2
	s_add_u32 s42, s42, 0x100
	s_addc_u32 s43, s43, 0
	s_add_u32 s14, s14, 0x100
	s_addc_u32 s15, s15, 0
	s_cmp_gt_u32 s17, 29
	s_barrier
	s_cbranch_scc0 .LBB0_2120
	s_lshl_b32 s14, s30, 8
	v_mov_b32_e32 v148, v196
	v_mov_b32_e32 v108, v197
	s_add_i32 s17, s14, s12
	s_lshl_b32 s14, s31, 8
	s_or_b32 s14, s14, s13
	v_lshl_add_u32 v108, v108, 2, s14
	s_cmp_lt_i32 s30, 64
	s_movk_i32 s14, 0x3000
	s_cselect_b32 s14, s14, 0x6000
	s_cmp_gt_i32 s30, 31
	s_cselect_b32 s14, s14, 0
	s_lshl_b32 s14, s14, 2
	v_readlane_b32 s15, v251, 41
	s_add_u32 s14, s15, s14
	v_readlane_b32 s15, v251, 42
	v_ashrrev_i32_e32 v109, 31, v108
	s_addc_u32 s15, s15, 0
	v_lshlrev_b64 v[186:187], 2, v[108:109]
	v_lshl_add_u64 v[108:109], s[14:15], 0, v[186:187]
	s_mov_b64 s[14:15], 0x4000
	v_add_u32_e32 v148, s17, v148
	v_lshl_add_u64 v[110:111], v[108:109], 0, s[14:15]
	s_movk_i32 s14, 0x4000
	v_ashrrev_i32_e32 v149, 31, v148
	v_add_co_u32_e32 v108, vcc, s14, v108
	v_lshlrev_b64 v[190:191], 13, v[148:149]
	s_mov_b64 s[14:15], 0x20000
	v_lshl_add_u64 v[224:225], v[190:191], 0, s[14:15]
	s_mov_b64 s[14:15], 0x40000
	v_lshl_add_u64 v[194:195], v[190:191], 0, s[14:15]
	s_mov_b64 s[14:15], 0x60000
	v_addc_co_u32_e32 v109, vcc, 0, v109, vcc
	v_lshl_add_u64 v[188:189], s[18:19], 0, v[186:187]
	v_lshl_add_u64 v[192:193], v[190:191], 0, s[14:15]
	global_load_dwordx4 v[128:131], v[108:109], off
	global_load_dwordx4 v[120:123], v[110:111], off offset:64
	global_load_dwordx4 v[112:115], v[110:111], off offset:512
	s_nop 0
	global_load_dwordx4 v[108:111], v[110:111], off offset:576
	v_lshl_add_u64 v[148:149], v[188:189], 0, v[190:191]
	v_lshl_add_u64 v[150:151], v[188:189], 0, v[224:225]
	v_lshl_add_u64 v[176:177], v[188:189], 0, v[194:195]
	v_lshl_add_u64 v[160:161], v[188:189], 0, v[192:193]
	flat_load_dwordx4 v[200:203], v[150:151] offset:576
	flat_load_dwordx4 v[206:209], v[150:151] offset:512
	flat_load_dwordx4 v[210:213], v[150:151] offset:64
	flat_load_dwordx4 v[214:217], v[150:151]
	flat_load_dwordx4 v[218:221], v[148:149] offset:576
	flat_load_dwordx4 v[232:235], v[148:149] offset:512
	flat_load_dwordx4 v[236:239], v[148:149] offset:64
	flat_load_dwordx4 v[240:243], v[148:149]
	s_nop 0
	flat_load_dwordx4 v[148:151], v[160:161] offset:576
	flat_load_dwordx4 v[152:155], v[160:161] offset:512
	flat_load_dwordx4 v[156:159], v[160:161] offset:64
	s_nop 0
	flat_load_dwordx4 v[160:163], v[160:161]
	s_nop 0
	flat_load_dwordx4 v[164:167], v[176:177] offset:576
	flat_load_dwordx4 v[168:171], v[176:177] offset:512
	flat_load_dwordx4 v[172:175], v[176:177] offset:64
	s_nop 0
	flat_load_dwordx4 v[176:179], v[176:177]
	v_readlane_b32 s14, v250, 25
	v_readlane_b32 s15, v250, 26
	s_mov_b64 s[30:31], 0x100000
	s_and_b64 vcc, exec, s[40:41]
	v_lshl_add_u64 v[226:227], s[14:15], 0, v[190:191]
	v_lshl_add_u64 v[226:227], v[226:227], 0, v[186:187]
	s_mov_b64 s[38:39], s[36:37]
	s_mov_b64 s[42:43], s[34:35]
	s_waitcnt vmcnt(0) lgkmcnt(0)
	s_nop 0
	v_pk_fma_f32 v[134:135], v[134:135], v[110:111], v[220:221]
	v_pk_fma_f32 v[132:133], v[132:133], v[108:109], v[218:219]
	global_store_dwordx4 v[226:227], v[132:135], off offset:576
	v_pk_fma_f32 v[102:103], v[102:103], v[110:111], v[202:203]
	v_pk_fma_f32 v[100:101], v[100:101], v[108:109], v[200:201]
	v_lshl_add_u64 v[132:133], s[14:15], 0, v[224:225]
	v_lshl_add_u64 v[132:133], v[132:133], 0, v[186:187]
	global_store_dwordx4 v[132:133], v[100:103], off offset:576
	v_pk_fma_f32 v[106:107], v[106:107], v[114:115], v[208:209]
	v_pk_fma_f32 v[104:105], v[104:105], v[112:113], v[206:207]
	v_lshl_add_u64 v[100:101], s[14:15], 0, v[194:195]
	v_lshl_add_u64 v[100:101], v[100:101], 0, v[186:187]
	v_pk_fma_f32 v[78:79], v[78:79], v[110:111], v[166:167]
	v_pk_fma_f32 v[76:77], v[76:77], v[108:109], v[164:165]
	global_store_dwordx4 v[132:133], v[104:107], off offset:512
	v_pk_fma_f32 v[86:87], v[86:87], v[114:115], v[170:171]
	v_pk_fma_f32 v[84:85], v[84:85], v[112:113], v[168:169]
	global_store_dwordx4 v[100:101], v[76:79], off offset:576
	v_lshl_add_u64 v[106:107], v[190:191], 0, s[30:31]
	s_mov_b64 s[30:31], 0x120000
	v_lshl_add_u64 v[76:77], s[14:15], 0, v[192:193]
	global_store_dwordx4 v[100:101], v[84:87], off offset:512
	v_pk_fma_f32 v[78:79], v[90:91], v[130:131], v[162:163]
	v_pk_fma_f32 v[72:73], v[72:73], v[112:113], v[152:153]
	v_lshl_add_u64 v[84:85], v[76:77], 0, v[186:187]
	v_pk_fma_f32 v[76:77], v[88:89], v[128:129], v[160:161]
	v_lshl_add_u64 v[152:153], v[190:191], 0, s[30:31]
	s_mov_b64 s[30:31], 0x140000
	v_pk_fma_f32 v[146:147], v[146:147], v[130:131], v[242:243]
	v_pk_fma_f32 v[144:145], v[144:145], v[128:129], v[240:241]
	v_pk_fma_f32 v[142:143], v[142:143], v[122:123], v[238:239]
	v_pk_fma_f32 v[140:141], v[140:141], v[120:121], v[236:237]
	v_pk_fma_f32 v[138:139], v[138:139], v[114:115], v[234:235]
	v_pk_fma_f32 v[136:137], v[136:137], v[112:113], v[232:233]
	v_pk_fma_f32 v[126:127], v[126:127], v[130:131], v[216:217]
	v_pk_fma_f32 v[124:125], v[124:125], v[128:129], v[214:215]
	v_pk_fma_f32 v[118:119], v[118:119], v[122:123], v[212:213]
	v_pk_fma_f32 v[116:117], v[116:117], v[120:121], v[210:211]
	v_pk_fma_f32 v[98:99], v[98:99], v[130:131], v[178:179]
	v_pk_fma_f32 v[96:97], v[96:97], v[128:129], v[176:177]
	v_pk_fma_f32 v[94:95], v[94:95], v[122:123], v[174:175]
	v_pk_fma_f32 v[92:93], v[92:93], v[120:121], v[172:173]
	global_store_dwordx4 v[84:85], v[76:79], off
	v_pk_fma_f32 v[74:75], v[74:75], v[114:115], v[154:155]
	v_pk_fma_f32 v[70:71], v[70:71], v[110:111], v[150:151]
	v_pk_fma_f32 v[78:79], v[82:83], v[122:123], v[158:159]
	v_pk_fma_f32 v[76:77], v[80:81], v[120:121], v[156:157]
	v_pk_fma_f32 v[68:69], v[68:69], v[108:109], v[148:149]
	v_lshl_add_u64 v[154:155], v[190:191], 0, s[30:31]
	s_mov_b64 s[30:31], 0x160000
	global_store_dwordx4 v[226:227], v[144:147], off
	global_store_dwordx4 v[226:227], v[140:143], off offset:64
	global_store_dwordx4 v[226:227], v[136:139], off offset:512
	global_store_dwordx4 v[132:133], v[124:127], off
	global_store_dwordx4 v[132:133], v[116:119], off offset:64
	global_store_dwordx4 v[100:101], v[96:99], off
	global_store_dwordx4 v[100:101], v[92:95], off offset:64
	global_store_dwordx4 v[84:85], v[76:79], off offset:64
	global_store_dwordx4 v[84:85], v[72:75], off offset:512
	global_store_dwordx4 v[84:85], v[68:71], off offset:576
	v_lshl_add_u64 v[100:101], v[190:191], 0, s[30:31]
	v_lshl_add_u64 v[96:97], v[188:189], 0, v[154:155]
	v_lshl_add_u64 v[68:69], v[188:189], 0, v[106:107]
	v_lshl_add_u64 v[70:71], v[188:189], 0, v[152:153]
	v_lshl_add_u64 v[80:81], v[188:189], 0, v[100:101]
	flat_load_dwordx4 v[102:105], v[70:71] offset:576
	flat_load_dwordx4 v[116:119], v[70:71] offset:512
	flat_load_dwordx4 v[124:127], v[70:71] offset:64
	flat_load_dwordx4 v[132:135], v[70:71]
	flat_load_dwordx4 v[136:139], v[68:69] offset:576
	flat_load_dwordx4 v[140:143], v[68:69] offset:512
	flat_load_dwordx4 v[144:147], v[68:69] offset:64
	flat_load_dwordx4 v[148:151], v[68:69]
	s_nop 0
	flat_load_dwordx4 v[68:71], v[80:81] offset:576
	flat_load_dwordx4 v[72:75], v[80:81] offset:512
	flat_load_dwordx4 v[76:79], v[80:81] offset:64
	s_nop 0
	flat_load_dwordx4 v[80:83], v[80:81]
	s_nop 0
	flat_load_dwordx4 v[84:87], v[96:97] offset:576
	flat_load_dwordx4 v[88:91], v[96:97] offset:512
	flat_load_dwordx4 v[92:95], v[96:97] offset:64
	s_nop 0
	flat_load_dwordx4 v[96:99], v[96:97]
	v_lshl_add_u64 v[106:107], s[14:15], 0, v[106:107]
	s_waitcnt vmcnt(0) lgkmcnt(0)
	v_lshl_add_u64 v[106:107], v[106:107], 0, v[186:187]
	v_pk_fma_f32 v[54:55], v[54:55], v[110:111], v[138:139]
	v_pk_fma_f32 v[52:53], v[52:53], v[108:109], v[136:137]
	global_store_dwordx4 v[106:107], v[52:55], off offset:576
	v_pk_fma_f32 v[38:39], v[38:39], v[110:111], v[104:105]
	v_pk_fma_f32 v[36:37], v[36:37], v[108:109], v[102:103]
	v_lshl_add_u64 v[52:53], s[14:15], 0, v[152:153]
	v_lshl_add_u64 v[52:53], v[52:53], 0, v[186:187]
	global_store_dwordx4 v[52:53], v[36:39], off offset:576
	v_pk_fma_f32 v[18:19], v[18:19], v[110:111], v[86:87]
	v_pk_fma_f32 v[16:17], v[16:17], v[108:109], v[84:85]
	v_lshl_add_u64 v[36:37], s[14:15], 0, v[154:155]
	v_lshl_add_u64 v[36:37], v[36:37], 0, v[186:187]
	v_pk_fma_f32 v[26:27], v[26:27], v[114:115], v[90:91]
	v_pk_fma_f32 v[24:25], v[24:25], v[112:113], v[88:89]
	global_store_dwordx4 v[36:37], v[16:19], off offset:576
	v_pk_fma_f32 v[66:67], v[66:67], v[130:131], v[150:151]
	v_pk_fma_f32 v[64:65], v[64:65], v[128:129], v[148:149]
	v_lshl_add_u64 v[16:17], s[14:15], 0, v[100:101]
	v_pk_fma_f32 v[62:63], v[62:63], v[122:123], v[146:147]
	v_pk_fma_f32 v[60:61], v[60:61], v[120:121], v[144:145]
	v_pk_fma_f32 v[58:59], v[58:59], v[114:115], v[142:143]
	v_pk_fma_f32 v[56:57], v[56:57], v[112:113], v[140:141]
	v_pk_fma_f32 v[50:51], v[50:51], v[130:131], v[134:135]
	v_pk_fma_f32 v[48:49], v[48:49], v[128:129], v[132:133]
	v_pk_fma_f32 v[46:47], v[46:47], v[122:123], v[126:127]
	v_pk_fma_f32 v[44:45], v[44:45], v[120:121], v[124:125]
	v_pk_fma_f32 v[42:43], v[42:43], v[114:115], v[118:119]
	v_pk_fma_f32 v[40:41], v[40:41], v[112:113], v[116:117]
	v_pk_fma_f32 v[34:35], v[34:35], v[130:131], v[98:99]
	v_pk_fma_f32 v[32:33], v[32:33], v[128:129], v[96:97]
	v_pk_fma_f32 v[30:31], v[30:31], v[122:123], v[94:95]
	v_pk_fma_f32 v[28:29], v[28:29], v[120:121], v[92:93]
	global_store_dwordx4 v[36:37], v[24:27], off offset:512
	v_pk_fma_f32 v[18:19], v[22:23], v[130:131], v[82:83]
	v_pk_fma_f32 v[14:15], v[14:15], v[122:123], v[78:79]
	v_lshl_add_u64 v[24:25], v[16:17], 0, v[186:187]
	v_pk_fma_f32 v[16:17], v[20:21], v[128:129], v[80:81]
	v_pk_fma_f32 v[12:13], v[12:13], v[120:121], v[76:77]
	v_pk_fma_f32 v[10:11], v[10:11], v[114:115], v[74:75]
	v_pk_fma_f32 v[8:9], v[8:9], v[112:113], v[72:73]
	v_pk_fma_f32 v[6:7], v[6:7], v[110:111], v[70:71]
	v_pk_fma_f32 v[4:5], v[4:5], v[108:109], v[68:69]
	global_store_dwordx4 v[106:107], v[64:67], off
	global_store_dwordx4 v[106:107], v[60:63], off offset:64
	global_store_dwordx4 v[106:107], v[56:59], off offset:512
	global_store_dwordx4 v[52:53], v[48:51], off
	global_store_dwordx4 v[52:53], v[44:47], off offset:64
	global_store_dwordx4 v[52:53], v[40:43], off offset:512
	global_store_dwordx4 v[36:37], v[32:35], off
	global_store_dwordx4 v[36:37], v[28:31], off offset:64
	global_store_dwordx4 v[24:25], v[16:19], off
	global_store_dwordx4 v[24:25], v[12:15], off offset:64
	global_store_dwordx4 v[24:25], v[8:11], off offset:512
	global_store_dwordx4 v[24:25], v[4:7], off offset:576
	s_mov_b32 s31, s16
	s_mov_b32 s30, s26
	s_cbranch_vccz .LBB0_2113
	s_waitcnt vmcnt(0)
	s_cmpk_gt_u32 s4, 0xff
	s_cbranch_scc1 .LBB0_2124
	s_barrier

.LBB0_2133:
	s_add_u32 s38, s40, 0xfff80080
	s_addc_u32 s39, s41, -1
	s_add_i32 s45, 0, 0x10000
	v_add_u32_e32 v144, s45, v158
	ds_read_b128 v[132:135], v144
	ds_read_b128 v[136:139], v144 offset:1024
	ds_read_b128 v[140:143], v144 offset:2048
	ds_read_b128 v[144:147], v144 offset:3072
	s_cmp_eq_u32 s44, 4
	s_cselect_b32 s43, s27, s39
	s_cselect_b32 s42, s26, s38
	s_cselect_b32 s39, s35, s31
	s_cselect_b32 s38, s34, s19
	v_lshl_add_u64 v[154:155], s[40:41], 0, v[150:151]
	s_add_i32 m0, s6, 0xc000
	ds_read_b128 v[160:163], v159
	ds_read_b128 v[164:167], v159 offset:1024
	ds_read_b128 v[168:171], v159 offset:2048
	ds_read_b128 v[172:175], v159 offset:3072
	ds_read_b128 v[176:179], v159 offset:4096
	ds_read_b128 v[180:183], v159 offset:5120
	ds_read_b128 v[184:187], v159 offset:6144
	ds_read_b128 v[188:191], v159 offset:7168
	global_load_lds_dwordx4 v[154:155], off
	v_lshl_add_u64 v[154:155], s[40:41], 0, v[152:153]
	s_add_i32 m0, s6, 0xe000
	s_nop 0
	global_load_lds_dwordx4 v[154:155], off
	s_waitcnt lgkmcnt(8)
	s_barrier
	s_waitcnt lgkmcnt(0)
	v_mfma_f32_16x16x32_f16 v[128:131], v[132:135], v[160:163], v[128:131]
	v_mfma_f32_16x16x32_f16 v[124:127], v[140:143], v[160:163], v[124:127]
	v_mfma_f32_16x16x32_f16 v[112:115], v[132:135], v[168:171], v[112:115]
	v_mfma_f32_16x16x32_f16 v[108:111], v[140:143], v[168:171], v[108:111]
	v_mfma_f32_16x16x32_f16 v[96:99], v[132:135], v[176:179], v[96:99]
	v_mfma_f32_16x16x32_f16 v[92:95], v[140:143], v[176:179], v[92:95]
	v_mfma_f32_16x16x32_f16 v[80:83], v[132:135], v[184:187], v[80:83]
	v_mfma_f32_16x16x32_f16 v[76:79], v[140:143], v[184:187], v[76:79]
	v_mfma_f32_16x16x32_f16 v[128:131], v[136:139], v[164:167], v[128:131]
	v_mfma_f32_16x16x32_f16 v[124:127], v[144:147], v[164:167], v[124:127]
	v_mfma_f32_16x16x32_f16 v[112:115], v[136:139], v[172:175], v[112:115]
	v_mfma_f32_16x16x32_f16 v[108:111], v[144:147], v[172:175], v[108:111]
	v_mfma_f32_16x16x32_f16 v[96:99], v[136:139], v[180:183], v[96:99]
	v_mfma_f32_16x16x32_f16 v[92:95], v[144:147], v[180:183], v[92:95]
	v_mfma_f32_16x16x32_f16 v[80:83], v[136:139], v[188:191], v[80:83]
	v_mfma_f32_16x16x32_f16 v[76:79], v[144:147], v[188:191], v[76:79]
	s_barrier
	s_add_i32 s48, 0, 0x14000
	v_add_u32_e32 v154, s48, v158
	s_add_i32 s45, s45, s5
	ds_read_b128 v[192:195], v154
	ds_read_b128 v[196:199], v154 offset:1024
	ds_read_b128 v[200:203], v154 offset:2048
	ds_read_b128 v[206:209], v154 offset:3072
	v_lshl_add_u64 v[154:155], s[38:39], 0, v[2:3]
	s_mov_b32 m0, s45
	v_lshl_add_u64 v[210:211], s[38:39], 0, v[148:149]
	global_load_lds_dwordx4 v[154:155], off
	s_add_i32 m0, s45, 0x2000
	s_nop 0
	global_load_lds_dwordx4 v[210:211], off
	s_barrier
	s_waitcnt lgkmcnt(0)
	v_mfma_f32_16x16x32_f16 v[120:123], v[192:195], v[160:163], v[120:123]
	v_mfma_f32_16x16x32_f16 v[116:119], v[200:203], v[160:163], v[116:119]
	v_mfma_f32_16x16x32_f16 v[104:107], v[192:195], v[168:171], v[104:107]
	v_mfma_f32_16x16x32_f16 v[100:103], v[200:203], v[168:171], v[100:103]
	v_mfma_f32_16x16x32_f16 v[88:91], v[192:195], v[176:179], v[88:91]
	v_mfma_f32_16x16x32_f16 v[84:87], v[200:203], v[176:179], v[84:87]
	v_mfma_f32_16x16x32_f16 v[72:75], v[192:195], v[184:187], v[72:75]
	v_mfma_f32_16x16x32_f16 v[68:71], v[200:203], v[184:187], v[68:71]
	v_mfma_f32_16x16x32_f16 v[120:123], v[196:199], v[164:167], v[120:123]
	v_mfma_f32_16x16x32_f16 v[116:119], v[206:209], v[164:167], v[116:119]
	v_mfma_f32_16x16x32_f16 v[104:107], v[196:199], v[172:175], v[104:107]
	v_mfma_f32_16x16x32_f16 v[100:103], v[206:209], v[172:175], v[100:103]
	v_mfma_f32_16x16x32_f16 v[88:91], v[196:199], v[180:183], v[88:91]
	v_mfma_f32_16x16x32_f16 v[84:87], v[206:209], v[180:183], v[84:87]
	v_mfma_f32_16x16x32_f16 v[72:75], v[196:199], v[188:191], v[72:75]
	v_mfma_f32_16x16x32_f16 v[68:71], v[206:209], v[188:191], v[68:71]
	s_mov_b32 m0, s6
	v_lshl_add_u64 v[212:213], s[42:43], 0, v[2:3]
	s_barrier
	ds_read_b128 v[160:163], v159 offset:16384
	ds_read_b128 v[164:167], v159 offset:17408
	ds_read_b128 v[168:171], v159 offset:18432
	ds_read_b128 v[172:175], v159 offset:19456
	ds_read_b128 v[176:179], v159 offset:20480
	ds_read_b128 v[180:183], v159 offset:21504
	ds_read_b128 v[184:187], v159 offset:22528
	ds_read_b128 v[188:191], v159 offset:23552
	global_load_lds_dwordx4 v[212:213], off
	v_lshl_add_u64 v[214:215], s[42:43], 0, v[148:149]
	s_mov_b32 m0, s7
	s_nop 0
	global_load_lds_dwordx4 v[214:215], off
	s_barrier
	s_waitcnt lgkmcnt(0)
	v_mfma_f32_16x16x32_f16 v[64:67], v[132:135], v[160:163], v[64:67]
	v_mfma_f32_16x16x32_f16 v[60:63], v[140:143], v[160:163], v[60:63]
	v_mfma_f32_16x16x32_f16 v[56:59], v[132:135], v[168:171], v[56:59]
	v_mfma_f32_16x16x32_f16 v[44:47], v[140:143], v[168:171], v[44:47]
	v_mfma_f32_16x16x32_f16 v[40:43], v[132:135], v[176:179], v[40:43]
	v_mfma_f32_16x16x32_f16 v[28:31], v[140:143], v[176:179], v[28:31]
	v_mfma_f32_16x16x32_f16 v[24:27], v[132:135], v[184:187], v[24:27]
	v_mfma_f32_16x16x32_f16 v[12:15], v[140:143], v[184:187], v[12:15]
	v_mfma_f32_16x16x32_f16 v[64:67], v[136:139], v[164:167], v[64:67]
	v_mfma_f32_16x16x32_f16 v[60:63], v[144:147], v[164:167], v[60:63]
	v_mfma_f32_16x16x32_f16 v[56:59], v[136:139], v[172:175], v[56:59]
	v_mfma_f32_16x16x32_f16 v[44:47], v[144:147], v[172:175], v[44:47]
	v_mfma_f32_16x16x32_f16 v[40:43], v[136:139], v[180:183], v[40:43]
	v_mfma_f32_16x16x32_f16 v[28:31], v[144:147], v[180:183], v[28:31]
	v_mfma_f32_16x16x32_f16 v[24:27], v[136:139], v[188:191], v[24:27]
	v_mfma_f32_16x16x32_f16 v[12:15], v[144:147], v[188:191], v[12:15]
	s_barrier
	s_add_u32 s46, s38, 0x80000
	s_addc_u32 s47, s39, 0
	s_add_i32 s45, s48, s5
	v_lshl_add_u64 v[132:133], s[46:47], 0, v[2:3]
	s_mov_b32 m0, s45
	s_nop 0
	global_load_lds_dwordx4 v[132:133], off
	v_lshl_add_u64 v[132:133], s[46:47], 0, v[148:149]
	s_add_i32 m0, s45, 0x2000
	s_nop 0
	global_load_lds_dwordx4 v[132:133], off
	s_waitcnt vmcnt(6)
	s_barrier
	v_mfma_f32_16x16x32_f16 v[52:55], v[192:195], v[160:163], v[52:55]
	v_mfma_f32_16x16x32_f16 v[48:51], v[200:203], v[160:163], v[48:51]
	v_mfma_f32_16x16x32_f16 v[36:39], v[192:195], v[168:171], v[36:39]
	v_mfma_f32_16x16x32_f16 v[32:35], v[200:203], v[168:171], v[32:35]
	v_mfma_f32_16x16x32_f16 v[20:23], v[192:195], v[176:179], v[20:23]
	v_mfma_f32_16x16x32_f16 v[16:19], v[200:203], v[176:179], v[16:19]
	v_mfma_f32_16x16x32_f16 v[8:11], v[192:195], v[184:187], v[8:11]
	v_mfma_f32_16x16x32_f16 v[4:7], v[200:203], v[184:187], v[4:7]
	v_mfma_f32_16x16x32_f16 v[52:55], v[196:199], v[164:167], v[52:55]
	v_mfma_f32_16x16x32_f16 v[48:51], v[206:209], v[164:167], v[48:51]
	v_mfma_f32_16x16x32_f16 v[36:39], v[196:199], v[172:175], v[36:39]
	v_mfma_f32_16x16x32_f16 v[32:35], v[206:209], v[172:175], v[32:35]
	v_mfma_f32_16x16x32_f16 v[20:23], v[196:199], v[180:183], v[20:23]
	v_mfma_f32_16x16x32_f16 v[16:19], v[206:209], v[180:183], v[16:19]
	v_mfma_f32_16x16x32_f16 v[8:11], v[196:199], v[188:191], v[8:11]
	v_mfma_f32_16x16x32_f16 v[4:7], v[206:209], v[188:191], v[4:7]
	s_add_i32 s45, 0, 0x18000
	v_add_u32_e32 v144, s45, v158
	s_barrier
	ds_read_b128 v[132:135], v144
	ds_read_b128 v[136:139], v144 offset:1024
	ds_read_b128 v[140:143], v144 offset:2048
	ds_read_b128 v[144:147], v144 offset:3072
	s_add_u32 s42, s42, 0x80000
	s_addc_u32 s43, s43, 0
	s_mov_b32 m0, s8
	v_lshl_add_u64 v[192:193], s[42:43], 0, v[2:3]
	ds_read_b128 v[160:163], v159 offset:32768
	ds_read_b128 v[164:167], v159 offset:33792
	ds_read_b128 v[168:171], v159 offset:34816
	ds_read_b128 v[172:175], v159 offset:35840
	ds_read_b128 v[176:179], v159 offset:36864
	ds_read_b128 v[180:183], v159 offset:37888
	ds_read_b128 v[184:187], v159 offset:38912
	ds_read_b128 v[188:191], v159 offset:39936
	global_load_lds_dwordx4 v[192:193], off
	v_lshl_add_u64 v[192:193], s[42:43], 0, v[148:149]
	s_mov_b32 m0, s9
	s_nop 0
	global_load_lds_dwordx4 v[192:193], off
	s_waitcnt lgkmcnt(8)
	s_barrier
	s_waitcnt lgkmcnt(0)
	v_mfma_f32_16x16x32_f16 v[128:131], v[132:135], v[160:163], v[128:131]
	v_mfma_f32_16x16x32_f16 v[124:127], v[140:143], v[160:163], v[124:127]
	v_mfma_f32_16x16x32_f16 v[112:115], v[132:135], v[168:171], v[112:115]
	v_mfma_f32_16x16x32_f16 v[108:111], v[140:143], v[168:171], v[108:111]
	v_mfma_f32_16x16x32_f16 v[96:99], v[132:135], v[176:179], v[96:99]
	v_mfma_f32_16x16x32_f16 v[92:95], v[140:143], v[176:179], v[92:95]
	v_mfma_f32_16x16x32_f16 v[80:83], v[132:135], v[184:187], v[80:83]
	v_mfma_f32_16x16x32_f16 v[76:79], v[140:143], v[184:187], v[76:79]
	v_mfma_f32_16x16x32_f16 v[128:131], v[136:139], v[164:167], v[128:131]
	v_mfma_f32_16x16x32_f16 v[124:127], v[144:147], v[164:167], v[124:127]
	v_mfma_f32_16x16x32_f16 v[112:115], v[136:139], v[172:175], v[112:115]
	v_mfma_f32_16x16x32_f16 v[108:111], v[144:147], v[172:175], v[108:111]
	v_mfma_f32_16x16x32_f16 v[96:99], v[136:139], v[180:183], v[96:99]
	v_mfma_f32_16x16x32_f16 v[92:95], v[144:147], v[180:183], v[92:95]
	v_mfma_f32_16x16x32_f16 v[80:83], v[136:139], v[188:191], v[80:83]
	v_mfma_f32_16x16x32_f16 v[76:79], v[144:147], v[188:191], v[76:79]
	s_barrier
	s_add_i32 s42, 0, 0x1c000
	s_add_i32 s43, s45, s5
	v_add_u32_e32 v206, s42, v158
	v_lshl_add_u64 v[154:155], v[154:155], 0, s[88:89]
	s_mov_b32 m0, s43
	ds_read_b128 v[192:195], v206
	ds_read_b128 v[196:199], v206 offset:1024
	ds_read_b128 v[200:203], v206 offset:2048
	ds_read_b128 v[206:209], v206 offset:3072
	global_load_lds_dwordx4 v[154:155], off
	v_lshl_add_u64 v[154:155], v[210:211], 0, s[88:89]
	s_add_i32 m0, s43, 0x2000
	s_nop 0
	global_load_lds_dwordx4 v[154:155], off
	s_barrier
	s_waitcnt lgkmcnt(0)
	v_mfma_f32_16x16x32_f16 v[120:123], v[192:195], v[160:163], v[120:123]
	v_mfma_f32_16x16x32_f16 v[116:119], v[200:203], v[160:163], v[116:119]
	v_mfma_f32_16x16x32_f16 v[104:107], v[192:195], v[168:171], v[104:107]
	v_mfma_f32_16x16x32_f16 v[100:103], v[200:203], v[168:171], v[100:103]
	v_mfma_f32_16x16x32_f16 v[88:91], v[192:195], v[176:179], v[88:91]
	v_mfma_f32_16x16x32_f16 v[84:87], v[200:203], v[176:179], v[84:87]
	v_mfma_f32_16x16x32_f16 v[72:75], v[192:195], v[184:187], v[72:75]
	v_mfma_f32_16x16x32_f16 v[68:71], v[200:203], v[184:187], v[68:71]
	v_mfma_f32_16x16x32_f16 v[120:123], v[196:199], v[164:167], v[120:123]
	v_mfma_f32_16x16x32_f16 v[116:119], v[206:209], v[164:167], v[116:119]
	v_mfma_f32_16x16x32_f16 v[104:107], v[196:199], v[172:175], v[104:107]
	v_mfma_f32_16x16x32_f16 v[100:103], v[206:209], v[172:175], v[100:103]
	v_mfma_f32_16x16x32_f16 v[88:91], v[196:199], v[180:183], v[88:91]
	v_mfma_f32_16x16x32_f16 v[84:87], v[206:209], v[180:183], v[84:87]
	v_mfma_f32_16x16x32_f16 v[72:75], v[196:199], v[188:191], v[72:75]
	v_mfma_f32_16x16x32_f16 v[68:71], v[206:209], v[188:191], v[68:71]
	s_mov_b32 m0, s10
	v_lshl_add_u64 v[154:155], v[212:213], 0, s[88:89]
	s_barrier
	ds_read_b128 v[160:163], v159 offset:49152
	ds_read_b128 v[164:167], v159 offset:50176
	ds_read_b128 v[168:171], v159 offset:51200
	ds_read_b128 v[172:175], v159 offset:52224
	ds_read_b128 v[176:179], v159 offset:53248
	ds_read_b128 v[180:183], v159 offset:54272
	ds_read_b128 v[184:187], v159 offset:55296
	ds_read_b128 v[188:191], v159 offset:56320
	global_load_lds_dwordx4 v[154:155], off
	v_lshl_add_u64 v[154:155], v[214:215], 0, s[88:89]
	s_mov_b32 m0, s11
	s_nop 0
	global_load_lds_dwordx4 v[154:155], off
	s_barrier
	s_waitcnt lgkmcnt(0)
	v_mfma_f32_16x16x32_f16 v[64:67], v[132:135], v[160:163], v[64:67]
	v_mfma_f32_16x16x32_f16 v[60:63], v[140:143], v[160:163], v[60:63]
	v_mfma_f32_16x16x32_f16 v[56:59], v[132:135], v[168:171], v[56:59]
	v_mfma_f32_16x16x32_f16 v[44:47], v[140:143], v[168:171], v[44:47]
	v_mfma_f32_16x16x32_f16 v[40:43], v[132:135], v[176:179], v[40:43]
	v_mfma_f32_16x16x32_f16 v[28:31], v[140:143], v[176:179], v[28:31]
	v_mfma_f32_16x16x32_f16 v[24:27], v[132:135], v[184:187], v[24:27]
	v_mfma_f32_16x16x32_f16 v[12:15], v[140:143], v[184:187], v[12:15]
	v_mfma_f32_16x16x32_f16 v[64:67], v[136:139], v[164:167], v[64:67]
	v_mfma_f32_16x16x32_f16 v[60:63], v[144:147], v[164:167], v[60:63]
	v_mfma_f32_16x16x32_f16 v[56:59], v[136:139], v[172:175], v[56:59]
	v_mfma_f32_16x16x32_f16 v[44:47], v[144:147], v[172:175], v[44:47]
	v_mfma_f32_16x16x32_f16 v[40:43], v[136:139], v[180:183], v[40:43]
	v_mfma_f32_16x16x32_f16 v[28:31], v[144:147], v[180:183], v[28:31]
	v_mfma_f32_16x16x32_f16 v[24:27], v[136:139], v[188:191], v[24:27]
	v_mfma_f32_16x16x32_f16 v[12:15], v[144:147], v[188:191], v[12:15]
	s_barrier
	s_add_u32 s38, s38, 0x80080
	s_addc_u32 s39, s39, 0
	s_add_i32 s42, s42, s5
	v_lshl_add_u64 v[132:133], s[38:39], 0, v[2:3]
	s_mov_b32 m0, s42
	s_nop 0
	global_load_lds_dwordx4 v[132:133], off
	v_lshl_add_u64 v[132:133], s[38:39], 0, v[148:149]
	s_add_i32 m0, s42, 0x2000
	s_nop 0
	global_load_lds_dwordx4 v[132:133], off
	s_waitcnt vmcnt(6)
	s_barrier
	v_mfma_f32_16x16x32_f16 v[52:55], v[192:195], v[160:163], v[52:55]
	v_mfma_f32_16x16x32_f16 v[48:51], v[200:203], v[160:163], v[48:51]
	v_mfma_f32_16x16x32_f16 v[36:39], v[192:195], v[168:171], v[36:39]
	v_mfma_f32_16x16x32_f16 v[32:35], v[200:203], v[168:171], v[32:35]
	v_mfma_f32_16x16x32_f16 v[20:23], v[192:195], v[176:179], v[20:23]
	v_mfma_f32_16x16x32_f16 v[16:19], v[200:203], v[176:179], v[16:19]
	v_mfma_f32_16x16x32_f16 v[8:11], v[192:195], v[184:187], v[8:11]
	v_mfma_f32_16x16x32_f16 v[4:7], v[200:203], v[184:187], v[4:7]
	v_mfma_f32_16x16x32_f16 v[52:55], v[196:199], v[164:167], v[52:55]
	v_mfma_f32_16x16x32_f16 v[48:51], v[206:209], v[164:167], v[48:51]
	v_mfma_f32_16x16x32_f16 v[36:39], v[196:199], v[172:175], v[36:39]
	v_mfma_f32_16x16x32_f16 v[32:35], v[206:209], v[172:175], v[32:35]
	v_mfma_f32_16x16x32_f16 v[20:23], v[196:199], v[180:183], v[20:23]
	v_mfma_f32_16x16x32_f16 v[16:19], v[206:209], v[180:183], v[16:19]
	v_mfma_f32_16x16x32_f16 v[8:11], v[196:199], v[188:191], v[8:11]
	v_mfma_f32_16x16x32_f16 v[4:7], v[206:209], v[188:191], v[4:7]
	s_add_i32 s44, s44, 2
	s_add_u32 s40, s40, 0x100
	s_addc_u32 s41, s41, 0
	s_add_u32 s19, s19, 0x100
	s_addc_u32 s31, s31, 0
	s_cmp_gt_u32 s44, 5
	s_barrier
	s_cbranch_scc0 .LBB0_2133
	s_lshl_b32 s19, s30, 8
	s_lshl_b32 s30, s29, 8
	v_mov_b32_e32 v160, v156
	v_mov_b32_e32 v132, v157
	s_and_b32 s30, s30, 0xff00
	s_or_b32 s30, s30, s12
	v_lshl_add_u32 v132, v132, 2, s30
	v_ashrrev_i32_e32 v133, 31, v132
	v_lshlrev_b64 v[154:155], 2, v[132:133]
	v_lshl_add_u64 v[132:133], s[16:17], 0, v[154:155]
	global_load_dwordx4 v[144:147], v[132:133], off
	global_load_dwordx4 v[140:143], v[132:133], off offset:64
	global_load_dwordx4 v[136:139], v[132:133], off offset:512
	s_nop 0
	global_load_dwordx4 v[132:135], v[132:133], off offset:576
	s_ashr_i32 s30, s29, 8
	s_ashr_i32 s31, s30, 31
	s_add_i32 s19, s13, s19
	s_lshl_b64 s[30:31], s[30:31], 22
	v_readlane_b32 s38, v250, 27
	v_add_u32_e32 v160, s19, v160
	v_readlane_b32 s39, v250, 28
	s_add_u32 s30, s38, s30
	s_addc_u32 s31, s39, s31
	v_ashrrev_i32_e32 v161, 31, v160
	v_lshl_add_u64 v[154:155], s[30:31], 0, v[154:155]
	v_lshlrev_b64 v[160:161], 13, v[160:161]
	v_lshl_add_u64 v[154:155], v[154:155], 0, v[160:161]
	s_mov_b32 s19, 0x20000
	s_mov_b64 s[30:31], 0x20000
	s_mov_b32 s29, s15
	s_mov_b64 s[38:39], s[34:35]
	s_mov_b64 s[40:41], s[26:27]
	s_waitcnt vmcnt(0)
	v_pk_mul_f32 v[130:131], v[130:131], v[146:147]
	v_pk_mul_f32 v[128:129], v[128:129], v[144:145]
	v_pk_mul_f32 v[54:55], v[54:55], v[138:139]
	v_pk_mul_f32 v[118:119], v[118:119], v[134:135]
	v_pk_mul_f32 v[116:117], v[116:117], v[132:133]
	global_store_dwordx4 v[154:155], v[116:119], off offset:576
	v_pk_mul_f32 v[102:103], v[102:103], v[134:135]
	v_pk_mul_f32 v[100:101], v[100:101], v[132:133]
	v_add_co_u32_e32 v118, vcc, s19, v154
	v_lshl_add_u64 v[116:117], v[154:155], 0, s[30:31]
	s_nop 0
	v_addc_co_u32_e32 v119, vcc, 0, v155, vcc
	s_mov_b32 s19, 0x40000
	global_store_dwordx4 v[116:117], v[100:103], off offset:576
	s_mov_b64 s[30:31], 0x40000
	v_pk_mul_f32 v[86:87], v[86:87], v[134:135]
	v_add_co_u32_e32 v102, vcc, s19, v154
	v_lshl_add_u64 v[100:101], v[154:155], 0, s[30:31]
	s_nop 0
	v_addc_co_u32_e32 v103, vcc, 0, v155, vcc
	v_pk_mul_f32 v[84:85], v[84:85], v[132:133]
	s_mov_b32 s19, 0x60000
	global_store_dwordx4 v[100:101], v[84:87], off offset:576
	s_mov_b64 s[30:31], 0x60000
	v_pk_mul_f32 v[70:71], v[70:71], v[134:135]
	v_add_co_u32_e32 v86, vcc, s19, v154
	v_lshl_add_u64 v[84:85], v[154:155], 0, s[30:31]
	s_nop 0
	v_addc_co_u32_e32 v87, vcc, 0, v155, vcc
	v_pk_mul_f32 v[68:69], v[68:69], v[132:133]
	s_mov_b32 s19, 0x100000
	global_store_dwordx4 v[84:85], v[68:71], off offset:576
	s_mov_b64 s[30:31], 0x100000
	v_pk_mul_f32 v[52:53], v[52:53], v[136:137]
	v_add_co_u32_e32 v70, vcc, s19, v154
	v_lshl_add_u64 v[68:69], v[154:155], 0, s[30:31]
	s_nop 0
	v_addc_co_u32_e32 v71, vcc, 0, v155, vcc
	s_mov_b32 s19, 0x120000
	global_store_dwordx4 v[68:69], v[52:55], off offset:512
	s_mov_b64 s[30:31], 0x120000
	v_pk_mul_f32 v[38:39], v[38:39], v[138:139]
	v_add_co_u32_e32 v54, vcc, s19, v154
	v_lshl_add_u64 v[52:53], v[154:155], 0, s[30:31]
	s_nop 0
	v_addc_co_u32_e32 v55, vcc, 0, v155, vcc
	v_pk_mul_f32 v[36:37], v[36:37], v[136:137]
	s_mov_b32 s19, 0x140000
	global_store_dwordx4 v[52:53], v[36:39], off offset:512
	s_mov_b64 s[30:31], 0x140000
	v_pk_mul_f32 v[22:23], v[22:23], v[138:139]
	v_add_co_u32_e32 v38, vcc, s19, v154
	v_lshl_add_u64 v[36:37], v[154:155], 0, s[30:31]
	s_nop 0
	v_addc_co_u32_e32 v39, vcc, 0, v155, vcc
	v_pk_mul_f32 v[20:21], v[20:21], v[136:137]
	s_mov_b32 s19, 0x160000
	global_store_dwordx4 v[36:37], v[20:23], off offset:512
	v_pk_mul_f32 v[50:51], v[50:51], v[134:135]
	v_pk_mul_f32 v[48:49], v[48:49], v[132:133]
	v_add_co_u32_e32 v22, vcc, s19, v154
	v_pk_mul_f32 v[34:35], v[34:35], v[134:135]
	v_pk_mul_f32 v[32:33], v[32:33], v[132:133]
	v_pk_mul_f32 v[18:19], v[18:19], v[134:135]
	v_pk_mul_f32 v[16:17], v[16:17], v[132:133]
	s_mov_b64 s[30:31], 0x160000
	v_addc_co_u32_e32 v23, vcc, 0, v155, vcc
	v_pk_mul_f32 v[126:127], v[126:127], v[142:143]
	v_pk_mul_f32 v[124:125], v[124:125], v[140:141]
	v_pk_mul_f32 v[122:123], v[122:123], v[138:139]
	v_pk_mul_f32 v[120:121], v[120:121], v[136:137]
	v_pk_mul_f32 v[114:115], v[114:115], v[146:147]
	v_pk_mul_f32 v[112:113], v[112:113], v[144:145]
	v_pk_mul_f32 v[110:111], v[110:111], v[142:143]
	v_pk_mul_f32 v[108:109], v[108:109], v[140:141]
	v_pk_mul_f32 v[106:107], v[106:107], v[138:139]
	v_pk_mul_f32 v[104:105], v[104:105], v[136:137]
	v_pk_mul_f32 v[98:99], v[98:99], v[146:147]
	v_pk_mul_f32 v[96:97], v[96:97], v[144:145]
	v_pk_mul_f32 v[94:95], v[94:95], v[142:143]
	v_pk_mul_f32 v[92:93], v[92:93], v[140:141]
	v_pk_mul_f32 v[90:91], v[90:91], v[138:139]
	v_pk_mul_f32 v[88:89], v[88:89], v[136:137]
	v_pk_mul_f32 v[82:83], v[82:83], v[146:147]
	v_pk_mul_f32 v[80:81], v[80:81], v[144:145]
	v_pk_mul_f32 v[78:79], v[78:79], v[142:143]
	v_pk_mul_f32 v[76:77], v[76:77], v[140:141]
	v_pk_mul_f32 v[74:75], v[74:75], v[138:139]
	v_pk_mul_f32 v[72:73], v[72:73], v[136:137]
	v_pk_mul_f32 v[66:67], v[66:67], v[146:147]
	v_pk_mul_f32 v[64:65], v[64:65], v[144:145]
	v_pk_mul_f32 v[62:63], v[62:63], v[142:143]
	v_pk_mul_f32 v[60:61], v[60:61], v[140:141]
	global_store_dwordx4 v[68:69], v[48:51], off offset:576
	v_pk_mul_f32 v[46:47], v[46:47], v[142:143]
	v_pk_mul_f32 v[44:45], v[44:45], v[140:141]
	v_pk_mul_f32 v[50:51], v[58:59], v[146:147]
	v_pk_mul_f32 v[48:49], v[56:57], v[144:145]
	global_store_dwordx4 v[52:53], v[32:35], off offset:576
	v_pk_mul_f32 v[30:31], v[30:31], v[142:143]
	v_pk_mul_f32 v[28:29], v[28:29], v[140:141]
	v_pk_mul_f32 v[34:35], v[42:43], v[146:147]
	v_pk_mul_f32 v[32:33], v[40:41], v[144:145]
	global_store_dwordx4 v[36:37], v[16:19], off offset:576
	v_lshl_add_u64 v[20:21], v[154:155], 0, s[30:31]
	v_pk_mul_f32 v[14:15], v[14:15], v[142:143]
	v_pk_mul_f32 v[18:19], v[26:27], v[146:147]
	v_pk_mul_f32 v[16:17], v[24:25], v[144:145]
	v_pk_mul_f32 v[12:13], v[12:13], v[140:141]
	v_pk_mul_f32 v[10:11], v[10:11], v[138:139]
	v_pk_mul_f32 v[8:9], v[8:9], v[136:137]
	v_pk_mul_f32 v[6:7], v[6:7], v[134:135]
	v_pk_mul_f32 v[4:5], v[4:5], v[132:133]
	s_and_b64 vcc, exec, s[36:37]
	s_mov_b32 s30, s18
	global_store_dwordx4 v[154:155], v[128:131], off
	global_store_dwordx4 v[154:155], v[124:127], off offset:64
	global_store_dwordx4 v[154:155], v[120:123], off offset:512
	global_store_dwordx4 v[118:119], v[112:115], off
	global_store_dwordx4 v[116:117], v[108:111], off offset:64
	global_store_dwordx4 v[116:117], v[104:107], off offset:512
	global_store_dwordx4 v[102:103], v[96:99], off
	global_store_dwordx4 v[100:101], v[92:95], off offset:64
	global_store_dwordx4 v[100:101], v[88:91], off offset:512
	global_store_dwordx4 v[86:87], v[80:83], off
	global_store_dwordx4 v[84:85], v[76:79], off offset:64
	global_store_dwordx4 v[84:85], v[72:75], off offset:512
	global_store_dwordx4 v[70:71], v[64:67], off
	global_store_dwordx4 v[68:69], v[60:63], off offset:64
	global_store_dwordx4 v[54:55], v[48:51], off
	global_store_dwordx4 v[52:53], v[44:47], off offset:64
	global_store_dwordx4 v[38:39], v[32:35], off
	global_store_dwordx4 v[36:37], v[28:31], off offset:64
	global_store_dwordx4 v[22:23], v[16:19], off
	global_store_dwordx4 v[20:21], v[12:15], off offset:64
	global_store_dwordx4 v[20:21], v[8:11], off offset:512
	global_store_dwordx4 v[20:21], v[4:7], off offset:576
	s_cbranch_vccz .LBB0_2130
	s_waitcnt vmcnt(0)
	s_cmpk_gt_u32 s4, 0xff
	s_cbranch_scc1 .LBB0_2137
	s_barrier

.LBB0_2566:
	s_add_u32 s15, s44, 0xfff80080
	s_addc_u32 s17, s45, -1
	s_add_i32 s29, 0, 0x10000
	v_add_u32_e32 v2, s29, v202
	ds_read_b128 v[132:135], v2
	ds_read_b128 v[136:139], v2 offset:1024
	ds_read_b128 v[140:143], v2 offset:2048
	ds_read_b128 v[144:147], v2 offset:3072
	s_cmp_eq_u32 s14, 28
	s_cselect_b32 s47, s85, s17
	s_cselect_b32 s46, s84, s15
	s_cselect_b32 s39, s27, s11
	s_cselect_b32 s38, s26, s10
	v_lshl_add_u64 v[192:193], s[44:45], 0, v[184:185]
	s_add_i32 m0, s6, 0xc000
	ds_read_b128 v[148:151], v208
	ds_read_b128 v[152:155], v208 offset:1024
	ds_read_b128 v[156:159], v208 offset:2048
	ds_read_b128 v[160:163], v208 offset:3072
	ds_read_b128 v[164:167], v208 offset:4096
	ds_read_b128 v[168:171], v208 offset:5120
	ds_read_b128 v[172:175], v208 offset:6144
	ds_read_b128 v[188:191], v208 offset:7168
	global_load_lds_dwordx4 v[192:193], off
	v_lshl_add_u64 v[192:193], s[44:45], 0, v[186:187]
	s_add_i32 m0, s6, 0xe000
	s_nop 0
	global_load_lds_dwordx4 v[192:193], off
	s_waitcnt lgkmcnt(8)
	s_barrier
	s_waitcnt lgkmcnt(0)
	v_mfma_f32_16x16x32_f16 v[128:131], v[132:135], v[148:151], v[128:131]
	v_mfma_f32_16x16x32_f16 v[88:91], v[140:143], v[148:151], v[88:91]
	v_mfma_f32_16x16x32_f16 v[120:123], v[132:135], v[156:159], v[120:123]
	v_mfma_f32_16x16x32_f16 v[92:95], v[140:143], v[156:159], v[92:95]
	v_mfma_f32_16x16x32_f16 v[112:115], v[132:135], v[164:167], v[112:115]
	v_mfma_f32_16x16x32_f16 v[80:83], v[140:143], v[164:167], v[80:83]
	v_mfma_f32_16x16x32_f16 v[104:107], v[132:135], v[172:175], v[104:107]
	v_mfma_f32_16x16x32_f16 v[68:71], v[140:143], v[172:175], v[68:71]
	v_mfma_f32_16x16x32_f16 v[128:131], v[136:139], v[152:155], v[128:131]
	v_mfma_f32_16x16x32_f16 v[88:91], v[144:147], v[152:155], v[88:91]
	v_mfma_f32_16x16x32_f16 v[120:123], v[136:139], v[160:163], v[120:123]
	v_mfma_f32_16x16x32_f16 v[92:95], v[144:147], v[160:163], v[92:95]
	v_mfma_f32_16x16x32_f16 v[112:115], v[136:139], v[168:171], v[112:115]
	v_mfma_f32_16x16x32_f16 v[80:83], v[144:147], v[168:171], v[80:83]
	v_mfma_f32_16x16x32_f16 v[104:107], v[136:139], v[188:191], v[104:107]
	v_mfma_f32_16x16x32_f16 v[68:71], v[144:147], v[188:191], v[68:71]
	s_barrier
	s_add_i32 s15, 0, 0x14000
	s_add_i32 s17, s29, s5
	v_add_u32_e32 v2, s15, v202
	v_lshl_add_u64 v[218:219], s[38:39], 0, v[178:179]
	s_mov_b32 m0, s17
	ds_read_b128 v[192:195], v2
	ds_read_b128 v[196:199], v2 offset:1024
	ds_read_b128 v[210:213], v2 offset:2048
	ds_read_b128 v[214:217], v2 offset:3072
	global_load_lds_dwordx4 v[218:219], off
	v_lshl_add_u64 v[220:221], s[38:39], 0, v[182:183]
	s_add_i32 m0, s17, 0x2000
	s_nop 0
	global_load_lds_dwordx4 v[220:221], off
	s_barrier
	s_waitcnt lgkmcnt(0)
	v_mfma_f32_16x16x32_f16 v[124:127], v[192:195], v[148:151], v[124:127]
	v_mfma_f32_16x16x32_f16 v[96:99], v[210:213], v[148:151], v[96:99]
	v_mfma_f32_16x16x32_f16 v[116:119], v[192:195], v[156:159], v[116:119]
	v_mfma_f32_16x16x32_f16 v[84:87], v[210:213], v[156:159], v[84:87]
	v_mfma_f32_16x16x32_f16 v[108:111], v[192:195], v[164:167], v[108:111]
	v_mfma_f32_16x16x32_f16 v[76:79], v[210:213], v[164:167], v[76:79]
	v_mfma_f32_16x16x32_f16 v[100:103], v[192:195], v[172:175], v[100:103]
	v_mfma_f32_16x16x32_f16 v[72:75], v[210:213], v[172:175], v[72:75]
	v_mfma_f32_16x16x32_f16 v[124:127], v[196:199], v[152:155], v[124:127]
	v_mfma_f32_16x16x32_f16 v[96:99], v[214:217], v[152:155], v[96:99]
	v_mfma_f32_16x16x32_f16 v[116:119], v[196:199], v[160:163], v[116:119]
	v_mfma_f32_16x16x32_f16 v[84:87], v[214:217], v[160:163], v[84:87]
	v_mfma_f32_16x16x32_f16 v[108:111], v[196:199], v[168:171], v[108:111]
	v_mfma_f32_16x16x32_f16 v[76:79], v[214:217], v[168:171], v[76:79]
	v_mfma_f32_16x16x32_f16 v[100:103], v[196:199], v[188:191], v[100:103]
	v_mfma_f32_16x16x32_f16 v[72:75], v[214:217], v[188:191], v[72:75]
	s_mov_b32 m0, s6
	v_lshl_add_u64 v[224:225], s[46:47], 0, v[176:177]
	s_barrier
	ds_read_b128 v[148:151], v208 offset:16384
	ds_read_b128 v[152:155], v208 offset:17408
	ds_read_b128 v[156:159], v208 offset:18432
	ds_read_b128 v[160:163], v208 offset:19456
	ds_read_b128 v[164:167], v208 offset:20480
	ds_read_b128 v[168:171], v208 offset:21504
	ds_read_b128 v[172:175], v208 offset:22528
	ds_read_b128 v[188:191], v208 offset:23552
	global_load_lds_dwordx4 v[224:225], off
	v_lshl_add_u64 v[226:227], s[46:47], 0, v[180:181]
	s_mov_b32 m0, s7
	s_nop 0
	global_load_lds_dwordx4 v[226:227], off
	s_barrier
	s_waitcnt lgkmcnt(0)
	v_mfma_f32_16x16x32_f16 v[64:67], v[132:135], v[148:151], v[64:67]
	v_mfma_f32_16x16x32_f16 v[48:51], v[140:143], v[148:151], v[48:51]
	v_mfma_f32_16x16x32_f16 v[56:59], v[132:135], v[156:159], v[56:59]
	v_mfma_f32_16x16x32_f16 v[40:43], v[140:143], v[156:159], v[40:43]
	v_mfma_f32_16x16x32_f16 v[28:31], v[132:135], v[164:167], v[28:31]
	v_mfma_f32_16x16x32_f16 v[20:23], v[140:143], v[164:167], v[20:23]
	v_mfma_f32_16x16x32_f16 v[32:35], v[132:135], v[172:175], v[32:35]
	v_mfma_f32_16x16x32_f16 v[8:11], v[140:143], v[172:175], v[8:11]
	v_mfma_f32_16x16x32_f16 v[64:67], v[136:139], v[152:155], v[64:67]
	v_mfma_f32_16x16x32_f16 v[48:51], v[144:147], v[152:155], v[48:51]
	v_mfma_f32_16x16x32_f16 v[56:59], v[136:139], v[160:163], v[56:59]
	v_mfma_f32_16x16x32_f16 v[40:43], v[144:147], v[160:163], v[40:43]
	v_mfma_f32_16x16x32_f16 v[28:31], v[136:139], v[168:171], v[28:31]
	v_mfma_f32_16x16x32_f16 v[20:23], v[144:147], v[168:171], v[20:23]
	v_mfma_f32_16x16x32_f16 v[32:35], v[136:139], v[188:191], v[32:35]
	v_mfma_f32_16x16x32_f16 v[8:11], v[144:147], v[188:191], v[8:11]
	s_barrier
	s_add_u32 s30, s38, 0x80000
	s_addc_u32 s31, s39, 0
	s_add_i32 s15, s15, s5
	v_lshl_add_u64 v[132:133], s[30:31], 0, v[178:179]
	s_mov_b32 m0, s15
	s_nop 0
	global_load_lds_dwordx4 v[132:133], off
	v_lshl_add_u64 v[132:133], s[30:31], 0, v[182:183]
	s_add_i32 m0, s15, 0x2000
	s_nop 0
	global_load_lds_dwordx4 v[132:133], off
	s_waitcnt vmcnt(6)
	s_barrier
	v_mfma_f32_16x16x32_f16 v[60:63], v[192:195], v[148:151], v[60:63]
	v_mfma_f32_16x16x32_f16 v[44:47], v[210:213], v[148:151], v[44:47]
	v_mfma_f32_16x16x32_f16 v[52:55], v[192:195], v[156:159], v[52:55]
	v_mfma_f32_16x16x32_f16 v[36:39], v[210:213], v[156:159], v[36:39]
	v_mfma_f32_16x16x32_f16 v[16:19], v[192:195], v[164:167], v[16:19]
	v_mfma_f32_16x16x32_f16 v[12:15], v[210:213], v[164:167], v[12:15]
	v_mfma_f32_16x16x32_f16 v[24:27], v[192:195], v[172:175], v[24:27]
	v_mfma_f32_16x16x32_f16 v[4:7], v[210:213], v[172:175], v[4:7]
	v_mfma_f32_16x16x32_f16 v[60:63], v[196:199], v[152:155], v[60:63]
	v_mfma_f32_16x16x32_f16 v[44:47], v[214:217], v[152:155], v[44:47]
	v_mfma_f32_16x16x32_f16 v[52:55], v[196:199], v[160:163], v[52:55]
	v_mfma_f32_16x16x32_f16 v[36:39], v[214:217], v[160:163], v[36:39]
	v_mfma_f32_16x16x32_f16 v[16:19], v[196:199], v[168:171], v[16:19]
	v_mfma_f32_16x16x32_f16 v[12:15], v[214:217], v[168:171], v[12:15]
	v_mfma_f32_16x16x32_f16 v[24:27], v[196:199], v[188:191], v[24:27]
	v_mfma_f32_16x16x32_f16 v[4:7], v[214:217], v[188:191], v[4:7]
	s_add_i32 s15, 0, 0x18000
	v_add_u32_e32 v2, s15, v202
	s_barrier
	ds_read_b128 v[132:135], v2
	ds_read_b128 v[136:139], v2 offset:1024
	ds_read_b128 v[140:143], v2 offset:2048
	ds_read_b128 v[144:147], v2 offset:3072
	s_add_u32 s30, s46, 0x80000
	s_addc_u32 s31, s47, 0
	s_mov_b32 m0, s8
	v_lshl_add_u64 v[192:193], s[30:31], 0, v[176:177]
	ds_read_b128 v[148:151], v208 offset:32768
	ds_read_b128 v[152:155], v208 offset:33792
	ds_read_b128 v[156:159], v208 offset:34816
	ds_read_b128 v[160:163], v208 offset:35840
	ds_read_b128 v[164:167], v208 offset:36864
	ds_read_b128 v[168:171], v208 offset:37888
	ds_read_b128 v[172:175], v208 offset:38912
	ds_read_b128 v[188:191], v208 offset:39936
	global_load_lds_dwordx4 v[192:193], off
	v_lshl_add_u64 v[192:193], s[30:31], 0, v[180:181]
	s_mov_b32 m0, s9
	s_nop 0
	global_load_lds_dwordx4 v[192:193], off
	s_waitcnt lgkmcnt(8)
	s_barrier
	s_waitcnt lgkmcnt(0)
	v_mfma_f32_16x16x32_f16 v[128:131], v[132:135], v[148:151], v[128:131]
	v_mfma_f32_16x16x32_f16 v[88:91], v[140:143], v[148:151], v[88:91]
	v_mfma_f32_16x16x32_f16 v[120:123], v[132:135], v[156:159], v[120:123]
	v_mfma_f32_16x16x32_f16 v[92:95], v[140:143], v[156:159], v[92:95]
	v_mfma_f32_16x16x32_f16 v[112:115], v[132:135], v[164:167], v[112:115]
	v_mfma_f32_16x16x32_f16 v[80:83], v[140:143], v[164:167], v[80:83]
	v_mfma_f32_16x16x32_f16 v[104:107], v[132:135], v[172:175], v[104:107]
	v_mfma_f32_16x16x32_f16 v[68:71], v[140:143], v[172:175], v[68:71]
	v_mfma_f32_16x16x32_f16 v[128:131], v[136:139], v[152:155], v[128:131]
	v_mfma_f32_16x16x32_f16 v[88:91], v[144:147], v[152:155], v[88:91]
	v_mfma_f32_16x16x32_f16 v[120:123], v[136:139], v[160:163], v[120:123]
	v_mfma_f32_16x16x32_f16 v[92:95], v[144:147], v[160:163], v[92:95]
	v_mfma_f32_16x16x32_f16 v[112:115], v[136:139], v[168:171], v[112:115]
	v_mfma_f32_16x16x32_f16 v[80:83], v[144:147], v[168:171], v[80:83]
	v_mfma_f32_16x16x32_f16 v[104:107], v[136:139], v[188:191], v[104:107]
	v_mfma_f32_16x16x32_f16 v[68:71], v[144:147], v[188:191], v[68:71]
	s_barrier
	s_add_i32 s17, 0, 0x1c000
	s_add_i32 s15, s15, s5
	v_add_u32_e32 v2, s17, v202
	v_lshl_add_u64 v[218:219], v[218:219], 0, s[88:89]
	s_mov_b32 m0, s15
	ds_read_b128 v[192:195], v2
	ds_read_b128 v[196:199], v2 offset:1024
	ds_read_b128 v[210:213], v2 offset:2048
	ds_read_b128 v[214:217], v2 offset:3072
	global_load_lds_dwordx4 v[218:219], off
	v_lshl_add_u64 v[218:219], v[220:221], 0, s[88:89]
	s_add_i32 m0, s15, 0x2000
	s_nop 0
	global_load_lds_dwordx4 v[218:219], off
	s_barrier
	s_waitcnt lgkmcnt(0)
	v_mfma_f32_16x16x32_f16 v[124:127], v[192:195], v[148:151], v[124:127]
	v_mfma_f32_16x16x32_f16 v[96:99], v[210:213], v[148:151], v[96:99]
	v_mfma_f32_16x16x32_f16 v[116:119], v[192:195], v[156:159], v[116:119]
	v_mfma_f32_16x16x32_f16 v[84:87], v[210:213], v[156:159], v[84:87]
	v_mfma_f32_16x16x32_f16 v[108:111], v[192:195], v[164:167], v[108:111]
	v_mfma_f32_16x16x32_f16 v[76:79], v[210:213], v[164:167], v[76:79]
	v_mfma_f32_16x16x32_f16 v[100:103], v[192:195], v[172:175], v[100:103]
	v_mfma_f32_16x16x32_f16 v[72:75], v[210:213], v[172:175], v[72:75]
	v_mfma_f32_16x16x32_f16 v[124:127], v[196:199], v[152:155], v[124:127]
	v_mfma_f32_16x16x32_f16 v[96:99], v[214:217], v[152:155], v[96:99]
	v_mfma_f32_16x16x32_f16 v[116:119], v[196:199], v[160:163], v[116:119]
	v_mfma_f32_16x16x32_f16 v[84:87], v[214:217], v[160:163], v[84:87]
	v_mfma_f32_16x16x32_f16 v[108:111], v[196:199], v[168:171], v[108:111]
	v_mfma_f32_16x16x32_f16 v[76:79], v[214:217], v[168:171], v[76:79]
	v_mfma_f32_16x16x32_f16 v[100:103], v[196:199], v[188:191], v[100:103]
	v_mfma_f32_16x16x32_f16 v[72:75], v[214:217], v[188:191], v[72:75]
	s_mov_b32 m0, s69
	v_lshl_add_u64 v[218:219], v[224:225], 0, s[88:89]
	s_barrier
	ds_read_b128 v[148:151], v208 offset:49152
	ds_read_b128 v[152:155], v208 offset:50176
	ds_read_b128 v[156:159], v208 offset:51200
	ds_read_b128 v[160:163], v208 offset:52224
	ds_read_b128 v[164:167], v208 offset:53248
	ds_read_b128 v[168:171], v208 offset:54272
	ds_read_b128 v[172:175], v208 offset:55296
	ds_read_b128 v[188:191], v208 offset:56320
	global_load_lds_dwordx4 v[218:219], off
	v_lshl_add_u64 v[218:219], v[226:227], 0, s[88:89]
	s_mov_b32 m0, s70
	s_nop 0
	global_load_lds_dwordx4 v[218:219], off
	s_barrier
	s_waitcnt lgkmcnt(0)
	v_mfma_f32_16x16x32_f16 v[64:67], v[132:135], v[148:151], v[64:67]
	v_mfma_f32_16x16x32_f16 v[48:51], v[140:143], v[148:151], v[48:51]
	v_mfma_f32_16x16x32_f16 v[56:59], v[132:135], v[156:159], v[56:59]
	v_mfma_f32_16x16x32_f16 v[40:43], v[140:143], v[156:159], v[40:43]
	v_mfma_f32_16x16x32_f16 v[28:31], v[132:135], v[164:167], v[28:31]
	v_mfma_f32_16x16x32_f16 v[20:23], v[140:143], v[164:167], v[20:23]
	v_mfma_f32_16x16x32_f16 v[32:35], v[132:135], v[172:175], v[32:35]
	v_mfma_f32_16x16x32_f16 v[8:11], v[140:143], v[172:175], v[8:11]
	v_mfma_f32_16x16x32_f16 v[64:67], v[136:139], v[152:155], v[64:67]
	v_mfma_f32_16x16x32_f16 v[48:51], v[144:147], v[152:155], v[48:51]
	v_mfma_f32_16x16x32_f16 v[56:59], v[136:139], v[160:163], v[56:59]
	v_mfma_f32_16x16x32_f16 v[40:43], v[144:147], v[160:163], v[40:43]
	v_mfma_f32_16x16x32_f16 v[28:31], v[136:139], v[168:171], v[28:31]
	v_mfma_f32_16x16x32_f16 v[20:23], v[144:147], v[168:171], v[20:23]
	v_mfma_f32_16x16x32_f16 v[32:35], v[136:139], v[188:191], v[32:35]
	v_mfma_f32_16x16x32_f16 v[8:11], v[144:147], v[188:191], v[8:11]
	s_barrier
	s_add_u32 s30, s38, 0x80080
	s_addc_u32 s31, s39, 0
	s_add_i32 s15, s17, s5
	v_lshl_add_u64 v[132:133], s[30:31], 0, v[178:179]
	s_mov_b32 m0, s15
	s_nop 0
	global_load_lds_dwordx4 v[132:133], off
	v_lshl_add_u64 v[132:133], s[30:31], 0, v[182:183]
	s_add_i32 m0, s15, 0x2000
	s_nop 0
	global_load_lds_dwordx4 v[132:133], off
	s_waitcnt vmcnt(6)
	s_barrier
	v_mfma_f32_16x16x32_f16 v[60:63], v[192:195], v[148:151], v[60:63]
	v_mfma_f32_16x16x32_f16 v[44:47], v[210:213], v[148:151], v[44:47]
	v_mfma_f32_16x16x32_f16 v[52:55], v[192:195], v[156:159], v[52:55]
	v_mfma_f32_16x16x32_f16 v[36:39], v[210:213], v[156:159], v[36:39]
	v_mfma_f32_16x16x32_f16 v[16:19], v[192:195], v[164:167], v[16:19]
	v_mfma_f32_16x16x32_f16 v[12:15], v[210:213], v[164:167], v[12:15]
	v_mfma_f32_16x16x32_f16 v[24:27], v[192:195], v[172:175], v[24:27]
	v_mfma_f32_16x16x32_f16 v[4:7], v[210:213], v[172:175], v[4:7]
	v_mfma_f32_16x16x32_f16 v[60:63], v[196:199], v[152:155], v[60:63]
	v_mfma_f32_16x16x32_f16 v[44:47], v[214:217], v[152:155], v[44:47]
	v_mfma_f32_16x16x32_f16 v[52:55], v[196:199], v[160:163], v[52:55]
	v_mfma_f32_16x16x32_f16 v[36:39], v[214:217], v[160:163], v[36:39]
	v_mfma_f32_16x16x32_f16 v[16:19], v[196:199], v[168:171], v[16:19]
	v_mfma_f32_16x16x32_f16 v[12:15], v[214:217], v[168:171], v[12:15]
	v_mfma_f32_16x16x32_f16 v[24:27], v[196:199], v[188:191], v[24:27]
	v_mfma_f32_16x16x32_f16 v[4:7], v[214:217], v[188:191], v[4:7]
	s_add_i32 s14, s14, 2
	s_add_u32 s44, s44, 0x100
	s_addc_u32 s45, s45, 0
	s_add_u32 s10, s10, 0x100
	s_addc_u32 s11, s11, 0
	s_cmp_gt_u32 s14, 29
	s_barrier
	s_cbranch_scc0 .LBB0_2566
	v_mov_b32_e32 v209, v200
	v_mov_b32_e32 v2, v201
	s_mov_b64 s[38:39], 0
	v_lshlrev_b32_e32 v136, 5, v2
	v_add_u32_e32 v137, s92, v136
	v_cmp_lt_i32_e32 vcc, 14, v209
	s_and_saveexec_b64 s[10:11], vcc
	s_xor_b64 s[14:15], exec, s[10:11]
	s_cbranch_execz .LBB0_2571
	v_cmp_eq_u32_e32 vcc, 15, v209
	s_and_saveexec_b64 s[44:45], vcc
	s_mov_b64 s[38:39], exec
	ds_write_b128 v137, v[104:107] offset:128
	s_or_b64 exec, exec, s[44:45]
	s_and_b64 s[38:39], s[38:39], exec

.LBB0_3035:
	s_add_u32 s34, s26, 0x100
	s_addc_u32 s35, s27, 0
	s_add_i32 s45, 0, 0x10000
	v_add_u32_e32 v128, s45, v198
	ds_read_b128 v[108:111], v128
	ds_read_b128 v[112:115], v128 offset:1024
	ds_read_b128 v[120:123], v128 offset:2048
	ds_read_b128 v[128:131], v128 offset:3072
	s_cmpk_eq_i32 s44, 0x54
	s_cselect_b32 s39, s17, s35
	s_cselect_b32 s38, s16, s34
	s_cselect_b32 s37, s19, s15
	s_cselect_b32 s36, s18, s14
	v_lshl_add_u64 v[186:187], s[26:27], 0, v[182:183]
	s_add_i32 m0, s6, 0xc000
	ds_read_b128 v[148:151], v199
	ds_read_b128 v[152:155], v199 offset:1024
	ds_read_b128 v[156:159], v199 offset:2048
	ds_read_b128 v[160:163], v199 offset:3072
	ds_read_b128 v[164:167], v199 offset:4096
	ds_read_b128 v[168:171], v199 offset:5120
	ds_read_b128 v[172:175], v199 offset:6144
	ds_read_b128 v[176:179], v199 offset:7168
	global_load_lds_dwordx4 v[186:187], off
	v_lshl_add_u64 v[186:187], s[26:27], 0, v[184:185]
	s_add_i32 m0, s6, 0xe000
	s_nop 0
	global_load_lds_dwordx4 v[186:187], off
	s_waitcnt lgkmcnt(8)
	s_barrier
	s_waitcnt lgkmcnt(0)
	v_mfma_f32_16x16x32_f16 v[144:147], v[108:111], v[148:151], v[144:147]
	v_mfma_f32_16x16x32_f16 v[140:143], v[120:123], v[148:151], v[140:143]
	v_mfma_f32_16x16x32_f16 v[124:127], v[108:111], v[156:159], v[124:127]
	v_mfma_f32_16x16x32_f16 v[116:119], v[120:123], v[156:159], v[116:119]
	v_mfma_f32_16x16x32_f16 v[96:99], v[108:111], v[164:167], v[96:99]
	v_mfma_f32_16x16x32_f16 v[92:95], v[120:123], v[164:167], v[92:95]
	v_mfma_f32_16x16x32_f16 v[88:91], v[108:111], v[172:175], v[88:91]
	v_mfma_f32_16x16x32_f16 v[80:83], v[120:123], v[172:175], v[80:83]
	v_mfma_f32_16x16x32_f16 v[144:147], v[112:115], v[152:155], v[144:147]
	v_mfma_f32_16x16x32_f16 v[140:143], v[128:131], v[152:155], v[140:143]
	v_mfma_f32_16x16x32_f16 v[124:127], v[112:115], v[160:163], v[124:127]
	v_mfma_f32_16x16x32_f16 v[116:119], v[128:131], v[160:163], v[116:119]
	v_mfma_f32_16x16x32_f16 v[96:99], v[112:115], v[168:171], v[96:99]
	v_mfma_f32_16x16x32_f16 v[92:95], v[128:131], v[168:171], v[92:95]
	v_mfma_f32_16x16x32_f16 v[88:91], v[112:115], v[176:179], v[88:91]
	v_mfma_f32_16x16x32_f16 v[80:83], v[128:131], v[176:179], v[80:83]
	s_barrier
	s_add_i32 s46, 0, 0x14000
	v_add_u32_e32 v194, s46, v198
	s_add_i32 s26, s45, s5
	ds_read_b128 v[186:189], v194
	ds_read_b128 v[190:193], v194 offset:1024
	ds_read_b128 v[200:203], v194 offset:2048
	ds_read_b128 v[206:209], v194 offset:3072
	v_lshl_add_u64 v[194:195], s[36:37], 0, v[2:3]
	s_mov_b32 m0, s26
	v_lshl_add_u64 v[210:211], s[36:37], 0, v[180:181]
	global_load_lds_dwordx4 v[194:195], off
	s_add_i32 m0, s26, 0x2000
	s_nop 0
	global_load_lds_dwordx4 v[210:211], off
	s_barrier
	s_waitcnt lgkmcnt(0)
	v_mfma_f32_16x16x32_f16 v[136:139], v[186:189], v[148:151], v[136:139]
	v_mfma_f32_16x16x32_f16 v[132:135], v[200:203], v[148:151], v[132:135]
	v_mfma_f32_16x16x32_f16 v[104:107], v[186:189], v[156:159], v[104:107]
	v_mfma_f32_16x16x32_f16 v[100:103], v[200:203], v[156:159], v[100:103]
	v_mfma_f32_16x16x32_f16 v[84:87], v[186:189], v[164:167], v[84:87]
	v_mfma_f32_16x16x32_f16 v[76:79], v[200:203], v[164:167], v[76:79]
	v_mfma_f32_16x16x32_f16 v[72:75], v[186:189], v[172:175], v[72:75]
	v_mfma_f32_16x16x32_f16 v[68:71], v[200:203], v[172:175], v[68:71]
	v_mfma_f32_16x16x32_f16 v[136:139], v[190:193], v[152:155], v[136:139]
	v_mfma_f32_16x16x32_f16 v[132:135], v[206:209], v[152:155], v[132:135]
	v_mfma_f32_16x16x32_f16 v[104:107], v[190:193], v[160:163], v[104:107]
	v_mfma_f32_16x16x32_f16 v[100:103], v[206:209], v[160:163], v[100:103]
	v_mfma_f32_16x16x32_f16 v[84:87], v[190:193], v[168:171], v[84:87]
	v_mfma_f32_16x16x32_f16 v[76:79], v[206:209], v[168:171], v[76:79]
	v_mfma_f32_16x16x32_f16 v[72:75], v[190:193], v[176:179], v[72:75]
	v_mfma_f32_16x16x32_f16 v[68:71], v[206:209], v[176:179], v[68:71]
	s_mov_b32 m0, s6
	v_lshl_add_u64 v[212:213], s[38:39], 0, v[2:3]
	s_barrier
	ds_read_b128 v[148:151], v199 offset:16384
	ds_read_b128 v[152:155], v199 offset:17408
	ds_read_b128 v[156:159], v199 offset:18432
	ds_read_b128 v[160:163], v199 offset:19456
	ds_read_b128 v[164:167], v199 offset:20480
	ds_read_b128 v[168:171], v199 offset:21504
	ds_read_b128 v[172:175], v199 offset:22528
	ds_read_b128 v[176:179], v199 offset:23552
	global_load_lds_dwordx4 v[212:213], off
	v_lshl_add_u64 v[214:215], s[38:39], 0, v[180:181]
	s_mov_b32 m0, s7
	s_nop 0
	global_load_lds_dwordx4 v[214:215], off
	s_barrier
	s_waitcnt lgkmcnt(0)
	v_mfma_f32_16x16x32_f16 v[64:67], v[108:111], v[148:151], v[64:67]
	v_mfma_f32_16x16x32_f16 v[60:63], v[120:123], v[148:151], v[60:63]
	v_mfma_f32_16x16x32_f16 v[48:51], v[108:111], v[156:159], v[48:51]
	v_mfma_f32_16x16x32_f16 v[44:47], v[120:123], v[156:159], v[44:47]
	v_mfma_f32_16x16x32_f16 v[32:35], v[108:111], v[164:167], v[32:35]
	v_mfma_f32_16x16x32_f16 v[28:31], v[120:123], v[164:167], v[28:31]
	v_mfma_f32_16x16x32_f16 v[20:23], v[108:111], v[172:175], v[20:23]
	v_mfma_f32_16x16x32_f16 v[12:15], v[120:123], v[172:175], v[12:15]
	v_mfma_f32_16x16x32_f16 v[64:67], v[112:115], v[152:155], v[64:67]
	v_mfma_f32_16x16x32_f16 v[60:63], v[128:131], v[152:155], v[60:63]
	v_mfma_f32_16x16x32_f16 v[48:51], v[112:115], v[160:163], v[48:51]
	v_mfma_f32_16x16x32_f16 v[44:47], v[128:131], v[160:163], v[44:47]
	v_mfma_f32_16x16x32_f16 v[32:35], v[112:115], v[168:171], v[32:35]
	v_mfma_f32_16x16x32_f16 v[28:31], v[128:131], v[168:171], v[28:31]
	v_mfma_f32_16x16x32_f16 v[20:23], v[112:115], v[176:179], v[20:23]
	v_mfma_f32_16x16x32_f16 v[12:15], v[128:131], v[176:179], v[12:15]
	s_barrier
	s_add_u32 s26, s36, 0x160000
	s_addc_u32 s27, s37, 0
	s_add_i32 s45, s46, s5
	v_lshl_add_u64 v[108:109], s[26:27], 0, v[2:3]
	s_mov_b32 m0, s45
	s_nop 0
	global_load_lds_dwordx4 v[108:109], off
	v_lshl_add_u64 v[108:109], s[26:27], 0, v[180:181]
	s_add_i32 m0, s45, 0x2000
	s_nop 0
	global_load_lds_dwordx4 v[108:109], off
	s_waitcnt vmcnt(6)
	s_barrier
	v_mfma_f32_16x16x32_f16 v[56:59], v[186:189], v[148:151], v[56:59]
	v_mfma_f32_16x16x32_f16 v[52:55], v[200:203], v[148:151], v[52:55]
	v_mfma_f32_16x16x32_f16 v[40:43], v[186:189], v[156:159], v[40:43]
	v_mfma_f32_16x16x32_f16 v[36:39], v[200:203], v[156:159], v[36:39]
	v_mfma_f32_16x16x32_f16 v[24:27], v[186:189], v[164:167], v[24:27]
	v_mfma_f32_16x16x32_f16 v[16:19], v[200:203], v[164:167], v[16:19]
	v_mfma_f32_16x16x32_f16 v[8:11], v[186:189], v[172:175], v[8:11]
	v_mfma_f32_16x16x32_f16 v[4:7], v[200:203], v[172:175], v[4:7]
	v_mfma_f32_16x16x32_f16 v[56:59], v[190:193], v[152:155], v[56:59]
	v_mfma_f32_16x16x32_f16 v[52:55], v[206:209], v[152:155], v[52:55]
	v_mfma_f32_16x16x32_f16 v[40:43], v[190:193], v[160:163], v[40:43]
	v_mfma_f32_16x16x32_f16 v[36:39], v[206:209], v[160:163], v[36:39]
	v_mfma_f32_16x16x32_f16 v[24:27], v[190:193], v[168:171], v[24:27]
	v_mfma_f32_16x16x32_f16 v[16:19], v[206:209], v[168:171], v[16:19]
	v_mfma_f32_16x16x32_f16 v[8:11], v[190:193], v[176:179], v[8:11]
	v_mfma_f32_16x16x32_f16 v[4:7], v[206:209], v[176:179], v[4:7]
	s_add_i32 s45, 0, 0x18000
	v_add_u32_e32 v128, s45, v198
	s_barrier
	ds_read_b128 v[108:111], v128
	ds_read_b128 v[112:115], v128 offset:1024
	ds_read_b128 v[120:123], v128 offset:2048
	ds_read_b128 v[128:131], v128 offset:3072
	s_add_u32 s26, s38, 0x160000
	s_addc_u32 s27, s39, 0
	s_mov_b32 m0, s8
	v_lshl_add_u64 v[186:187], s[26:27], 0, v[2:3]
	ds_read_b128 v[148:151], v199 offset:32768
	ds_read_b128 v[152:155], v199 offset:33792
	ds_read_b128 v[156:159], v199 offset:34816
	ds_read_b128 v[160:163], v199 offset:35840
	ds_read_b128 v[164:167], v199 offset:36864
	ds_read_b128 v[168:171], v199 offset:37888
	ds_read_b128 v[172:175], v199 offset:38912
	ds_read_b128 v[176:179], v199 offset:39936
	global_load_lds_dwordx4 v[186:187], off
	v_lshl_add_u64 v[186:187], s[26:27], 0, v[180:181]
	s_mov_b32 m0, s9
	s_nop 0
	global_load_lds_dwordx4 v[186:187], off
	s_waitcnt lgkmcnt(8)
	s_barrier
	s_waitcnt lgkmcnt(0)
	v_mfma_f32_16x16x32_f16 v[144:147], v[108:111], v[148:151], v[144:147]
	v_mfma_f32_16x16x32_f16 v[140:143], v[120:123], v[148:151], v[140:143]
	v_mfma_f32_16x16x32_f16 v[124:127], v[108:111], v[156:159], v[124:127]
	v_mfma_f32_16x16x32_f16 v[116:119], v[120:123], v[156:159], v[116:119]
	v_mfma_f32_16x16x32_f16 v[96:99], v[108:111], v[164:167], v[96:99]
	v_mfma_f32_16x16x32_f16 v[92:95], v[120:123], v[164:167], v[92:95]
	v_mfma_f32_16x16x32_f16 v[88:91], v[108:111], v[172:175], v[88:91]
	v_mfma_f32_16x16x32_f16 v[80:83], v[120:123], v[172:175], v[80:83]
	v_mfma_f32_16x16x32_f16 v[144:147], v[112:115], v[152:155], v[144:147]
	v_mfma_f32_16x16x32_f16 v[140:143], v[128:131], v[152:155], v[140:143]
	v_mfma_f32_16x16x32_f16 v[124:127], v[112:115], v[160:163], v[124:127]
	v_mfma_f32_16x16x32_f16 v[116:119], v[128:131], v[160:163], v[116:119]
	v_mfma_f32_16x16x32_f16 v[96:99], v[112:115], v[168:171], v[96:99]
	v_mfma_f32_16x16x32_f16 v[92:95], v[128:131], v[168:171], v[92:95]
	v_mfma_f32_16x16x32_f16 v[88:91], v[112:115], v[176:179], v[88:91]
	v_mfma_f32_16x16x32_f16 v[80:83], v[128:131], v[176:179], v[80:83]
	s_barrier
	s_add_i32 s38, 0, 0x1c000
	s_add_i32 s26, s45, s5
	v_add_u32_e32 v206, s38, v198
	v_lshl_add_u64 v[194:195], v[194:195], 0, s[88:89]
	s_mov_b32 m0, s26
	ds_read_b128 v[186:189], v206
	ds_read_b128 v[190:193], v206 offset:1024
	ds_read_b128 v[200:203], v206 offset:2048
	ds_read_b128 v[206:209], v206 offset:3072
	global_load_lds_dwordx4 v[194:195], off
	v_lshl_add_u64 v[194:195], v[210:211], 0, s[88:89]
	s_add_i32 m0, s26, 0x2000
	s_nop 0
	global_load_lds_dwordx4 v[194:195], off
	s_barrier
	s_waitcnt lgkmcnt(0)
	v_mfma_f32_16x16x32_f16 v[136:139], v[186:189], v[148:151], v[136:139]
	v_mfma_f32_16x16x32_f16 v[132:135], v[200:203], v[148:151], v[132:135]
	v_mfma_f32_16x16x32_f16 v[104:107], v[186:189], v[156:159], v[104:107]
	v_mfma_f32_16x16x32_f16 v[100:103], v[200:203], v[156:159], v[100:103]
	v_mfma_f32_16x16x32_f16 v[84:87], v[186:189], v[164:167], v[84:87]
	v_mfma_f32_16x16x32_f16 v[76:79], v[200:203], v[164:167], v[76:79]
	v_mfma_f32_16x16x32_f16 v[72:75], v[186:189], v[172:175], v[72:75]
	v_mfma_f32_16x16x32_f16 v[68:71], v[200:203], v[172:175], v[68:71]
	v_mfma_f32_16x16x32_f16 v[136:139], v[190:193], v[152:155], v[136:139]
	v_mfma_f32_16x16x32_f16 v[132:135], v[206:209], v[152:155], v[132:135]
	v_mfma_f32_16x16x32_f16 v[104:107], v[190:193], v[160:163], v[104:107]
	v_mfma_f32_16x16x32_f16 v[100:103], v[206:209], v[160:163], v[100:103]
	v_mfma_f32_16x16x32_f16 v[84:87], v[190:193], v[168:171], v[84:87]
	v_mfma_f32_16x16x32_f16 v[76:79], v[206:209], v[168:171], v[76:79]
	v_mfma_f32_16x16x32_f16 v[72:75], v[190:193], v[176:179], v[72:75]
	v_mfma_f32_16x16x32_f16 v[68:71], v[206:209], v[176:179], v[68:71]
	s_mov_b32 m0, s10
	v_lshl_add_u64 v[194:195], v[212:213], 0, s[88:89]
	s_barrier
	ds_read_b128 v[148:151], v199 offset:49152
	ds_read_b128 v[152:155], v199 offset:50176
	ds_read_b128 v[156:159], v199 offset:51200
	ds_read_b128 v[160:163], v199 offset:52224
	ds_read_b128 v[164:167], v199 offset:53248
	ds_read_b128 v[168:171], v199 offset:54272
	ds_read_b128 v[172:175], v199 offset:55296
	ds_read_b128 v[176:179], v199 offset:56320
	global_load_lds_dwordx4 v[194:195], off
	v_lshl_add_u64 v[194:195], v[214:215], 0, s[88:89]
	s_mov_b32 m0, s11
	s_nop 0
	global_load_lds_dwordx4 v[194:195], off
	s_barrier
	s_waitcnt lgkmcnt(0)
	v_mfma_f32_16x16x32_f16 v[64:67], v[108:111], v[148:151], v[64:67]
	v_mfma_f32_16x16x32_f16 v[60:63], v[120:123], v[148:151], v[60:63]
	v_mfma_f32_16x16x32_f16 v[48:51], v[108:111], v[156:159], v[48:51]
	v_mfma_f32_16x16x32_f16 v[44:47], v[120:123], v[156:159], v[44:47]
	v_mfma_f32_16x16x32_f16 v[32:35], v[108:111], v[164:167], v[32:35]
	v_mfma_f32_16x16x32_f16 v[28:31], v[120:123], v[164:167], v[28:31]
	v_mfma_f32_16x16x32_f16 v[20:23], v[108:111], v[172:175], v[20:23]
	v_mfma_f32_16x16x32_f16 v[12:15], v[120:123], v[172:175], v[12:15]
	v_mfma_f32_16x16x32_f16 v[64:67], v[112:115], v[152:155], v[64:67]
	v_mfma_f32_16x16x32_f16 v[60:63], v[128:131], v[152:155], v[60:63]
	v_mfma_f32_16x16x32_f16 v[48:51], v[112:115], v[160:163], v[48:51]
	v_mfma_f32_16x16x32_f16 v[44:47], v[128:131], v[160:163], v[44:47]
	v_mfma_f32_16x16x32_f16 v[32:35], v[112:115], v[168:171], v[32:35]
	v_mfma_f32_16x16x32_f16 v[28:31], v[128:131], v[168:171], v[28:31]
	v_mfma_f32_16x16x32_f16 v[20:23], v[112:115], v[176:179], v[20:23]
	v_mfma_f32_16x16x32_f16 v[12:15], v[128:131], v[176:179], v[12:15]
	s_barrier
	s_add_u32 s26, s36, 0x160080
	s_addc_u32 s27, s37, 0
	s_add_i32 s36, s38, s5
	v_lshl_add_u64 v[108:109], s[26:27], 0, v[2:3]
	s_mov_b32 m0, s36
	s_nop 0
	global_load_lds_dwordx4 v[108:109], off
	v_lshl_add_u64 v[108:109], s[26:27], 0, v[180:181]
	s_add_i32 m0, s36, 0x2000
	s_nop 0
	global_load_lds_dwordx4 v[108:109], off
	s_waitcnt vmcnt(6)
	s_barrier
	v_mfma_f32_16x16x32_f16 v[56:59], v[186:189], v[148:151], v[56:59]
	v_mfma_f32_16x16x32_f16 v[52:55], v[200:203], v[148:151], v[52:55]
	v_mfma_f32_16x16x32_f16 v[40:43], v[186:189], v[156:159], v[40:43]
	v_mfma_f32_16x16x32_f16 v[36:39], v[200:203], v[156:159], v[36:39]
	v_mfma_f32_16x16x32_f16 v[24:27], v[186:189], v[164:167], v[24:27]
	v_mfma_f32_16x16x32_f16 v[16:19], v[200:203], v[164:167], v[16:19]
	v_mfma_f32_16x16x32_f16 v[8:11], v[186:189], v[172:175], v[8:11]
	v_mfma_f32_16x16x32_f16 v[4:7], v[200:203], v[172:175], v[4:7]
	v_mfma_f32_16x16x32_f16 v[56:59], v[190:193], v[152:155], v[56:59]
	v_mfma_f32_16x16x32_f16 v[52:55], v[206:209], v[152:155], v[52:55]
	v_mfma_f32_16x16x32_f16 v[40:43], v[190:193], v[160:163], v[40:43]
	v_mfma_f32_16x16x32_f16 v[36:39], v[206:209], v[160:163], v[36:39]
	v_mfma_f32_16x16x32_f16 v[24:27], v[190:193], v[168:171], v[24:27]
	v_mfma_f32_16x16x32_f16 v[16:19], v[206:209], v[168:171], v[16:19]
	v_mfma_f32_16x16x32_f16 v[8:11], v[190:193], v[176:179], v[8:11]
	v_mfma_f32_16x16x32_f16 v[4:7], v[206:209], v[176:179], v[4:7]
	s_add_i32 s44, s44, 2
	s_add_u32 s14, s14, 0x100
	s_addc_u32 s15, s15, 0
	s_cmpk_gt_u32 s44, 0x55
	s_mov_b64 s[26:27], s[34:35]
	s_barrier
	s_cbranch_scc0 .LBB0_3035
	s_lshl_b32 s14, s42, 8
	v_mov_b32_e32 v148, v196
	v_mov_b32_e32 v108, v197
	s_add_i32 s26, s14, s12
	s_lshl_b32 s14, s43, 8
	s_or_b32 s14, s14, s13
	v_lshl_add_u32 v108, v108, 2, s14
	s_cmp_lt_i32 s42, 64
	s_movk_i32 s14, 0x3000
	s_cselect_b32 s14, s14, 0x6000
	s_cmp_gt_i32 s42, 31
	s_cselect_b32 s14, s14, 0
	s_lshl_b32 s14, s14, 2
	v_readlane_b32 s15, v251, 41
	s_add_u32 s14, s15, s14
	v_readlane_b32 s15, v251, 42
	v_ashrrev_i32_e32 v109, 31, v108
	s_addc_u32 s15, s15, 0
	v_lshlrev_b64 v[186:187], 2, v[108:109]
	v_add_u32_e32 v148, s26, v148
	v_lshl_add_u64 v[108:109], s[14:15], 0, v[186:187]
	s_mov_b64 s[14:15], 0xa000
	v_ashrrev_i32_e32 v149, 31, v148
	v_lshl_add_u64 v[110:111], v[108:109], 0, s[14:15]
	s_mov_b32 s14, 0xa000
	v_lshlrev_b64 v[190:191], 13, v[148:149]
	s_mov_b64 s[26:27], 0x20000
	v_add_co_u32_e32 v108, vcc, s14, v108
	v_readlane_b32 s14, v250, 25
	v_lshl_add_u64 v[224:225], v[190:191], 0, s[26:27]
	s_mov_b64 s[26:27], 0x40000
	v_readlane_b32 s15, v250, 26
	v_lshl_add_u64 v[194:195], v[190:191], 0, s[26:27]
	s_mov_b64 s[26:27], 0x60000
	v_addc_co_u32_e32 v109, vcc, 0, v109, vcc
	v_lshl_add_u64 v[188:189], s[14:15], 0, v[186:187]
	v_lshl_add_u64 v[192:193], v[190:191], 0, s[26:27]
	global_load_dwordx4 v[128:131], v[108:109], off
	global_load_dwordx4 v[120:123], v[110:111], off offset:64
	global_load_dwordx4 v[112:115], v[110:111], off offset:512
	s_nop 0
	global_load_dwordx4 v[108:111], v[110:111], off offset:576
	v_lshl_add_u64 v[148:149], v[188:189], 0, v[190:191]
	v_lshl_add_u64 v[150:151], v[188:189], 0, v[224:225]
	v_lshl_add_u64 v[176:177], v[188:189], 0, v[194:195]
	v_lshl_add_u64 v[160:161], v[188:189], 0, v[192:193]
	global_load_dwordx4 v[200:203], v[150:151], off offset:576
	global_load_dwordx4 v[206:209], v[150:151], off offset:512
	global_load_dwordx4 v[210:213], v[150:151], off offset:64
	global_load_dwordx4 v[214:217], v[150:151], off
	global_load_dwordx4 v[218:221], v[148:149], off offset:576
	global_load_dwordx4 v[232:235], v[148:149], off offset:512
	global_load_dwordx4 v[236:239], v[148:149], off offset:64
	global_load_dwordx4 v[240:243], v[148:149], off
	s_nop 0
	global_load_dwordx4 v[148:151], v[160:161], off offset:576
	global_load_dwordx4 v[152:155], v[160:161], off offset:512
	global_load_dwordx4 v[156:159], v[160:161], off offset:64
	s_nop 0
	global_load_dwordx4 v[160:163], v[160:161], off
	s_nop 0
	global_load_dwordx4 v[164:167], v[176:177], off offset:576
	global_load_dwordx4 v[168:171], v[176:177], off offset:512
	global_load_dwordx4 v[172:175], v[176:177], off offset:64
	s_nop 0
	global_load_dwordx4 v[176:179], v[176:177], off
	v_lshl_add_u64 v[226:227], s[14:15], 0, v[190:191]
	v_lshl_add_u64 v[226:227], v[226:227], 0, v[186:187]
	s_mov_b64 s[26:27], 0x100000
	s_and_b64 vcc, exec, s[40:41]
	s_mov_b32 s43, s30
	s_mov_b32 s42, s31
	s_mov_b64 s[34:35], s[18:19]
	s_waitcnt vmcnt(0)
	s_nop 0
	v_pk_fma_f32 v[134:135], v[134:135], v[110:111], v[220:221]
	v_pk_fma_f32 v[132:133], v[132:133], v[108:109], v[218:219]
	global_store_dwordx4 v[226:227], v[132:135], off offset:576
	v_pk_fma_f32 v[102:103], v[102:103], v[110:111], v[202:203]
	v_pk_fma_f32 v[100:101], v[100:101], v[108:109], v[200:201]
	v_lshl_add_u64 v[132:133], s[14:15], 0, v[224:225]
	v_lshl_add_u64 v[132:133], v[132:133], 0, v[186:187]
	global_store_dwordx4 v[132:133], v[100:103], off offset:576
	v_pk_fma_f32 v[106:107], v[106:107], v[114:115], v[208:209]
	v_pk_fma_f32 v[104:105], v[104:105], v[112:113], v[206:207]
	v_lshl_add_u64 v[100:101], s[14:15], 0, v[194:195]
	v_lshl_add_u64 v[100:101], v[100:101], 0, v[186:187]
	v_pk_fma_f32 v[78:79], v[78:79], v[110:111], v[166:167]
	v_pk_fma_f32 v[76:77], v[76:77], v[108:109], v[164:165]
	global_store_dwordx4 v[132:133], v[104:107], off offset:512
	v_pk_fma_f32 v[86:87], v[86:87], v[114:115], v[170:171]
	v_pk_fma_f32 v[84:85], v[84:85], v[112:113], v[168:169]
	global_store_dwordx4 v[100:101], v[76:79], off offset:576
	v_lshl_add_u64 v[106:107], v[190:191], 0, s[26:27]
	s_mov_b64 s[26:27], 0x120000
	v_lshl_add_u64 v[76:77], s[14:15], 0, v[192:193]
	global_store_dwordx4 v[100:101], v[84:87], off offset:512
	v_pk_fma_f32 v[78:79], v[90:91], v[130:131], v[162:163]
	v_pk_fma_f32 v[72:73], v[72:73], v[112:113], v[152:153]
	v_lshl_add_u64 v[84:85], v[76:77], 0, v[186:187]
	v_pk_fma_f32 v[76:77], v[88:89], v[128:129], v[160:161]
	v_lshl_add_u64 v[152:153], v[190:191], 0, s[26:27]
	s_mov_b64 s[26:27], 0x140000
	v_pk_fma_f32 v[146:147], v[146:147], v[130:131], v[242:243]
	v_pk_fma_f32 v[144:145], v[144:145], v[128:129], v[240:241]
	v_pk_fma_f32 v[142:143], v[142:143], v[122:123], v[238:239]
	v_pk_fma_f32 v[140:141], v[140:141], v[120:121], v[236:237]
	v_pk_fma_f32 v[138:139], v[138:139], v[114:115], v[234:235]
	v_pk_fma_f32 v[136:137], v[136:137], v[112:113], v[232:233]
	v_pk_fma_f32 v[126:127], v[126:127], v[130:131], v[216:217]
	v_pk_fma_f32 v[124:125], v[124:125], v[128:129], v[214:215]
	v_pk_fma_f32 v[118:119], v[118:119], v[122:123], v[212:213]
	v_pk_fma_f32 v[116:117], v[116:117], v[120:121], v[210:211]
	v_pk_fma_f32 v[98:99], v[98:99], v[130:131], v[178:179]
	v_pk_fma_f32 v[96:97], v[96:97], v[128:129], v[176:177]
	v_pk_fma_f32 v[94:95], v[94:95], v[122:123], v[174:175]
	v_pk_fma_f32 v[92:93], v[92:93], v[120:121], v[172:173]
	global_store_dwordx4 v[84:85], v[76:79], off
	v_pk_fma_f32 v[74:75], v[74:75], v[114:115], v[154:155]
	v_pk_fma_f32 v[70:71], v[70:71], v[110:111], v[150:151]
	v_pk_fma_f32 v[78:79], v[82:83], v[122:123], v[158:159]
	v_pk_fma_f32 v[76:77], v[80:81], v[120:121], v[156:157]
	v_pk_fma_f32 v[68:69], v[68:69], v[108:109], v[148:149]
	v_lshl_add_u64 v[154:155], v[190:191], 0, s[26:27]
	s_mov_b64 s[26:27], 0x160000
	global_store_dwordx4 v[226:227], v[144:147], off
	global_store_dwordx4 v[226:227], v[140:143], off offset:64
	global_store_dwordx4 v[226:227], v[136:139], off offset:512
	global_store_dwordx4 v[132:133], v[124:127], off
	global_store_dwordx4 v[132:133], v[116:119], off offset:64
	global_store_dwordx4 v[100:101], v[96:99], off
	global_store_dwordx4 v[100:101], v[92:95], off offset:64
	global_store_dwordx4 v[84:85], v[76:79], off offset:64
	global_store_dwordx4 v[84:85], v[72:75], off offset:512
	global_store_dwordx4 v[84:85], v[68:71], off offset:576
	v_lshl_add_u64 v[100:101], v[190:191], 0, s[26:27]
	v_lshl_add_u64 v[96:97], v[188:189], 0, v[154:155]
	v_lshl_add_u64 v[68:69], v[188:189], 0, v[106:107]
	v_lshl_add_u64 v[70:71], v[188:189], 0, v[152:153]
	v_lshl_add_u64 v[80:81], v[188:189], 0, v[100:101]
	global_load_dwordx4 v[102:105], v[70:71], off offset:576
	global_load_dwordx4 v[116:119], v[70:71], off offset:512
	global_load_dwordx4 v[124:127], v[70:71], off offset:64
	global_load_dwordx4 v[132:135], v[70:71], off
	global_load_dwordx4 v[136:139], v[68:69], off offset:576
	global_load_dwordx4 v[140:143], v[68:69], off offset:512
	global_load_dwordx4 v[144:147], v[68:69], off offset:64
	global_load_dwordx4 v[148:151], v[68:69], off
	s_nop 0
	global_load_dwordx4 v[68:71], v[80:81], off offset:576
	global_load_dwordx4 v[72:75], v[80:81], off offset:512
	global_load_dwordx4 v[76:79], v[80:81], off offset:64
	s_nop 0
	global_load_dwordx4 v[80:83], v[80:81], off
	s_nop 0
	global_load_dwordx4 v[84:87], v[96:97], off offset:576
	global_load_dwordx4 v[88:91], v[96:97], off offset:512
	global_load_dwordx4 v[92:95], v[96:97], off offset:64
	s_nop 0
	global_load_dwordx4 v[96:99], v[96:97], off
	v_lshl_add_u64 v[106:107], s[14:15], 0, v[106:107]
	s_waitcnt vmcnt(0)
	v_lshl_add_u64 v[106:107], v[106:107], 0, v[186:187]
	v_pk_fma_f32 v[54:55], v[54:55], v[110:111], v[138:139]
	v_pk_fma_f32 v[52:53], v[52:53], v[108:109], v[136:137]
	global_store_dwordx4 v[106:107], v[52:55], off offset:576
	v_pk_fma_f32 v[38:39], v[38:39], v[110:111], v[104:105]
	v_pk_fma_f32 v[36:37], v[36:37], v[108:109], v[102:103]
	v_lshl_add_u64 v[52:53], s[14:15], 0, v[152:153]
	v_lshl_add_u64 v[52:53], v[52:53], 0, v[186:187]
	global_store_dwordx4 v[52:53], v[36:39], off offset:576
	v_pk_fma_f32 v[18:19], v[18:19], v[110:111], v[86:87]
	v_pk_fma_f32 v[16:17], v[16:17], v[108:109], v[84:85]
	v_lshl_add_u64 v[36:37], s[14:15], 0, v[154:155]
	v_lshl_add_u64 v[36:37], v[36:37], 0, v[186:187]
	v_pk_fma_f32 v[26:27], v[26:27], v[114:115], v[90:91]
	v_pk_fma_f32 v[24:25], v[24:25], v[112:113], v[88:89]
	global_store_dwordx4 v[36:37], v[16:19], off offset:576
	v_pk_fma_f32 v[66:67], v[66:67], v[130:131], v[150:151]
	v_pk_fma_f32 v[64:65], v[64:65], v[128:129], v[148:149]
	v_lshl_add_u64 v[16:17], s[14:15], 0, v[100:101]
	v_pk_fma_f32 v[62:63], v[62:63], v[122:123], v[146:147]
	v_pk_fma_f32 v[60:61], v[60:61], v[120:121], v[144:145]
	v_pk_fma_f32 v[58:59], v[58:59], v[114:115], v[142:143]
	v_pk_fma_f32 v[56:57], v[56:57], v[112:113], v[140:141]
	v_pk_fma_f32 v[50:51], v[50:51], v[130:131], v[134:135]
	v_pk_fma_f32 v[48:49], v[48:49], v[128:129], v[132:133]
	v_pk_fma_f32 v[46:47], v[46:47], v[122:123], v[126:127]
	v_pk_fma_f32 v[44:45], v[44:45], v[120:121], v[124:125]
	v_pk_fma_f32 v[42:43], v[42:43], v[114:115], v[118:119]
	v_pk_fma_f32 v[40:41], v[40:41], v[112:113], v[116:117]
	v_pk_fma_f32 v[34:35], v[34:35], v[130:131], v[98:99]
	v_pk_fma_f32 v[32:33], v[32:33], v[128:129], v[96:97]
	v_pk_fma_f32 v[30:31], v[30:31], v[122:123], v[94:95]
	v_pk_fma_f32 v[28:29], v[28:29], v[120:121], v[92:93]
	global_store_dwordx4 v[36:37], v[24:27], off offset:512
	v_pk_fma_f32 v[18:19], v[22:23], v[130:131], v[82:83]
	v_pk_fma_f32 v[14:15], v[14:15], v[122:123], v[78:79]
	v_lshl_add_u64 v[24:25], v[16:17], 0, v[186:187]
	v_pk_fma_f32 v[16:17], v[20:21], v[128:129], v[80:81]
	v_pk_fma_f32 v[12:13], v[12:13], v[120:121], v[76:77]
	v_pk_fma_f32 v[10:11], v[10:11], v[114:115], v[74:75]
	v_pk_fma_f32 v[8:9], v[8:9], v[112:113], v[72:73]
	v_pk_fma_f32 v[6:7], v[6:7], v[110:111], v[70:71]
	v_pk_fma_f32 v[4:5], v[4:5], v[108:109], v[68:69]
	global_store_dwordx4 v[106:107], v[64:67], off
	global_store_dwordx4 v[106:107], v[60:63], off offset:64
	global_store_dwordx4 v[106:107], v[56:59], off offset:512
	global_store_dwordx4 v[52:53], v[48:51], off
	global_store_dwordx4 v[52:53], v[44:47], off offset:64
	global_store_dwordx4 v[52:53], v[40:43], off offset:512
	global_store_dwordx4 v[36:37], v[32:35], off
	global_store_dwordx4 v[36:37], v[28:31], off offset:64
	global_store_dwordx4 v[24:25], v[16:19], off
	global_store_dwordx4 v[24:25], v[12:15], off offset:64
	global_store_dwordx4 v[24:25], v[8:11], off offset:512
	global_store_dwordx4 v[24:25], v[4:7], off offset:576
	s_mov_b64 s[26:27], s[16:17]
	s_cbranch_vccz .LBB0_3028
	s_waitcnt vmcnt(0)
	s_cmpk_gt_u32 s4, 0xff
	s_cbranch_scc1 .LBB0_3039
	s_barrier

.LBB0_3048:
	s_add_u32 s40, s36, 0x100
	s_addc_u32 s41, s37, 0
	s_add_i32 s47, 0, 0x10000
	v_add_u32_e32 v144, s47, v158
	ds_read_b128 v[132:135], v144
	ds_read_b128 v[136:139], v144 offset:1024
	ds_read_b128 v[140:143], v144 offset:2048
	ds_read_b128 v[144:147], v144 offset:3072
	s_cmp_eq_u32 s46, 4
	s_cselect_b32 s43, s19, s41
	s_cselect_b32 s42, s18, s40
	s_cselect_b32 s39, s27, s45
	s_cselect_b32 s38, s26, s44
	v_lshl_add_u64 v[154:155], s[36:37], 0, v[150:151]
	s_add_i32 m0, s6, 0xc000
	ds_read_b128 v[160:163], v159
	ds_read_b128 v[164:167], v159 offset:1024
	ds_read_b128 v[168:171], v159 offset:2048
	ds_read_b128 v[172:175], v159 offset:3072
	ds_read_b128 v[176:179], v159 offset:4096
	ds_read_b128 v[180:183], v159 offset:5120
	ds_read_b128 v[184:187], v159 offset:6144
	ds_read_b128 v[188:191], v159 offset:7168
	global_load_lds_dwordx4 v[154:155], off
	v_lshl_add_u64 v[154:155], s[36:37], 0, v[152:153]
	s_add_i32 m0, s6, 0xe000
	s_nop 0
	global_load_lds_dwordx4 v[154:155], off
	s_waitcnt lgkmcnt(8)
	s_barrier
	s_waitcnt lgkmcnt(0)
	v_mfma_f32_16x16x32_f16 v[128:131], v[132:135], v[160:163], v[128:131]
	v_mfma_f32_16x16x32_f16 v[124:127], v[140:143], v[160:163], v[124:127]
	v_mfma_f32_16x16x32_f16 v[112:115], v[132:135], v[168:171], v[112:115]
	v_mfma_f32_16x16x32_f16 v[108:111], v[140:143], v[168:171], v[108:111]
	v_mfma_f32_16x16x32_f16 v[96:99], v[132:135], v[176:179], v[96:99]
	v_mfma_f32_16x16x32_f16 v[92:95], v[140:143], v[176:179], v[92:95]
	v_mfma_f32_16x16x32_f16 v[80:83], v[132:135], v[184:187], v[80:83]
	v_mfma_f32_16x16x32_f16 v[76:79], v[140:143], v[184:187], v[76:79]
	v_mfma_f32_16x16x32_f16 v[128:131], v[136:139], v[164:167], v[128:131]
	v_mfma_f32_16x16x32_f16 v[124:127], v[144:147], v[164:167], v[124:127]
	v_mfma_f32_16x16x32_f16 v[112:115], v[136:139], v[172:175], v[112:115]
	v_mfma_f32_16x16x32_f16 v[108:111], v[144:147], v[172:175], v[108:111]
	v_mfma_f32_16x16x32_f16 v[96:99], v[136:139], v[180:183], v[96:99]
	v_mfma_f32_16x16x32_f16 v[92:95], v[144:147], v[180:183], v[92:95]
	v_mfma_f32_16x16x32_f16 v[80:83], v[136:139], v[188:191], v[80:83]
	v_mfma_f32_16x16x32_f16 v[76:79], v[144:147], v[188:191], v[76:79]
	s_barrier
	s_add_i32 s48, 0, 0x14000
	v_add_u32_e32 v154, s48, v158
	s_add_i32 s36, s47, s5
	ds_read_b128 v[192:195], v154
	ds_read_b128 v[196:199], v154 offset:1024
	ds_read_b128 v[200:203], v154 offset:2048
	ds_read_b128 v[206:209], v154 offset:3072
	v_lshl_add_u64 v[154:155], s[38:39], 0, v[2:3]
	s_mov_b32 m0, s36
	v_lshl_add_u64 v[210:211], s[38:39], 0, v[148:149]
	global_load_lds_dwordx4 v[154:155], off
	s_add_i32 m0, s36, 0x2000
	s_nop 0
	global_load_lds_dwordx4 v[210:211], off
	s_barrier
	s_waitcnt lgkmcnt(0)
	v_mfma_f32_16x16x32_f16 v[120:123], v[192:195], v[160:163], v[120:123]
	v_mfma_f32_16x16x32_f16 v[116:119], v[200:203], v[160:163], v[116:119]
	v_mfma_f32_16x16x32_f16 v[104:107], v[192:195], v[168:171], v[104:107]
	v_mfma_f32_16x16x32_f16 v[100:103], v[200:203], v[168:171], v[100:103]
	v_mfma_f32_16x16x32_f16 v[88:91], v[192:195], v[176:179], v[88:91]
	v_mfma_f32_16x16x32_f16 v[84:87], v[200:203], v[176:179], v[84:87]
	v_mfma_f32_16x16x32_f16 v[72:75], v[192:195], v[184:187], v[72:75]
	v_mfma_f32_16x16x32_f16 v[68:71], v[200:203], v[184:187], v[68:71]
	v_mfma_f32_16x16x32_f16 v[120:123], v[196:199], v[164:167], v[120:123]
	v_mfma_f32_16x16x32_f16 v[116:119], v[206:209], v[164:167], v[116:119]
	v_mfma_f32_16x16x32_f16 v[104:107], v[196:199], v[172:175], v[104:107]
	v_mfma_f32_16x16x32_f16 v[100:103], v[206:209], v[172:175], v[100:103]
	v_mfma_f32_16x16x32_f16 v[88:91], v[196:199], v[180:183], v[88:91]
	v_mfma_f32_16x16x32_f16 v[84:87], v[206:209], v[180:183], v[84:87]
	v_mfma_f32_16x16x32_f16 v[72:75], v[196:199], v[188:191], v[72:75]
	v_mfma_f32_16x16x32_f16 v[68:71], v[206:209], v[188:191], v[68:71]
	s_mov_b32 m0, s6
	v_lshl_add_u64 v[212:213], s[42:43], 0, v[2:3]
	s_barrier
	ds_read_b128 v[160:163], v159 offset:16384
	ds_read_b128 v[164:167], v159 offset:17408
	ds_read_b128 v[168:171], v159 offset:18432
	ds_read_b128 v[172:175], v159 offset:19456
	ds_read_b128 v[176:179], v159 offset:20480
	ds_read_b128 v[180:183], v159 offset:21504
	ds_read_b128 v[184:187], v159 offset:22528
	ds_read_b128 v[188:191], v159 offset:23552
	global_load_lds_dwordx4 v[212:213], off
	v_lshl_add_u64 v[214:215], s[42:43], 0, v[148:149]
	s_mov_b32 m0, s7
	s_nop 0
	global_load_lds_dwordx4 v[214:215], off
	s_barrier
	s_waitcnt lgkmcnt(0)
	v_mfma_f32_16x16x32_f16 v[64:67], v[132:135], v[160:163], v[64:67]
	v_mfma_f32_16x16x32_f16 v[60:63], v[140:143], v[160:163], v[60:63]
	v_mfma_f32_16x16x32_f16 v[56:59], v[132:135], v[168:171], v[56:59]
	v_mfma_f32_16x16x32_f16 v[44:47], v[140:143], v[168:171], v[44:47]
	v_mfma_f32_16x16x32_f16 v[40:43], v[132:135], v[176:179], v[40:43]
	v_mfma_f32_16x16x32_f16 v[28:31], v[140:143], v[176:179], v[28:31]
	v_mfma_f32_16x16x32_f16 v[24:27], v[132:135], v[184:187], v[24:27]
	v_mfma_f32_16x16x32_f16 v[12:15], v[140:143], v[184:187], v[12:15]
	v_mfma_f32_16x16x32_f16 v[64:67], v[136:139], v[164:167], v[64:67]
	v_mfma_f32_16x16x32_f16 v[60:63], v[144:147], v[164:167], v[60:63]
	v_mfma_f32_16x16x32_f16 v[56:59], v[136:139], v[172:175], v[56:59]
	v_mfma_f32_16x16x32_f16 v[44:47], v[144:147], v[172:175], v[44:47]
	v_mfma_f32_16x16x32_f16 v[40:43], v[136:139], v[180:183], v[40:43]
	v_mfma_f32_16x16x32_f16 v[28:31], v[144:147], v[180:183], v[28:31]
	v_mfma_f32_16x16x32_f16 v[24:27], v[136:139], v[188:191], v[24:27]
	v_mfma_f32_16x16x32_f16 v[12:15], v[144:147], v[188:191], v[12:15]
	s_barrier
	s_add_u32 s36, s38, 0x160000
	s_addc_u32 s37, s39, 0
	s_add_i32 s47, s48, s5
	v_lshl_add_u64 v[132:133], s[36:37], 0, v[2:3]
	s_mov_b32 m0, s47
	s_nop 0
	global_load_lds_dwordx4 v[132:133], off
	v_lshl_add_u64 v[132:133], s[36:37], 0, v[148:149]
	s_add_i32 m0, s47, 0x2000
	s_nop 0
	global_load_lds_dwordx4 v[132:133], off
	s_waitcnt vmcnt(6)
	s_barrier
	v_mfma_f32_16x16x32_f16 v[52:55], v[192:195], v[160:163], v[52:55]
	v_mfma_f32_16x16x32_f16 v[48:51], v[200:203], v[160:163], v[48:51]
	v_mfma_f32_16x16x32_f16 v[36:39], v[192:195], v[168:171], v[36:39]
	v_mfma_f32_16x16x32_f16 v[32:35], v[200:203], v[168:171], v[32:35]
	v_mfma_f32_16x16x32_f16 v[20:23], v[192:195], v[176:179], v[20:23]
	v_mfma_f32_16x16x32_f16 v[16:19], v[200:203], v[176:179], v[16:19]
	v_mfma_f32_16x16x32_f16 v[8:11], v[192:195], v[184:187], v[8:11]
	v_mfma_f32_16x16x32_f16 v[4:7], v[200:203], v[184:187], v[4:7]
	v_mfma_f32_16x16x32_f16 v[52:55], v[196:199], v[164:167], v[52:55]
	v_mfma_f32_16x16x32_f16 v[48:51], v[206:209], v[164:167], v[48:51]
	v_mfma_f32_16x16x32_f16 v[36:39], v[196:199], v[172:175], v[36:39]
	v_mfma_f32_16x16x32_f16 v[32:35], v[206:209], v[172:175], v[32:35]
	v_mfma_f32_16x16x32_f16 v[20:23], v[196:199], v[180:183], v[20:23]
	v_mfma_f32_16x16x32_f16 v[16:19], v[206:209], v[180:183], v[16:19]
	v_mfma_f32_16x16x32_f16 v[8:11], v[196:199], v[188:191], v[8:11]
	v_mfma_f32_16x16x32_f16 v[4:7], v[206:209], v[188:191], v[4:7]
	s_add_i32 s47, 0, 0x18000
	v_add_u32_e32 v144, s47, v158
	s_barrier
	ds_read_b128 v[132:135], v144
	ds_read_b128 v[136:139], v144 offset:1024
	ds_read_b128 v[140:143], v144 offset:2048
	ds_read_b128 v[144:147], v144 offset:3072
	s_add_u32 s36, s42, 0x160000
	s_addc_u32 s37, s43, 0
	s_mov_b32 m0, s8
	v_lshl_add_u64 v[192:193], s[36:37], 0, v[2:3]
	ds_read_b128 v[160:163], v159 offset:32768
	ds_read_b128 v[164:167], v159 offset:33792
	ds_read_b128 v[168:171], v159 offset:34816
	ds_read_b128 v[172:175], v159 offset:35840
	ds_read_b128 v[176:179], v159 offset:36864
	ds_read_b128 v[180:183], v159 offset:37888
	ds_read_b128 v[184:187], v159 offset:38912
	ds_read_b128 v[188:191], v159 offset:39936
	global_load_lds_dwordx4 v[192:193], off
	v_lshl_add_u64 v[192:193], s[36:37], 0, v[148:149]
	s_mov_b32 m0, s9
	s_nop 0
	global_load_lds_dwordx4 v[192:193], off
	s_waitcnt lgkmcnt(8)
	s_barrier
	s_waitcnt lgkmcnt(0)
	v_mfma_f32_16x16x32_f16 v[128:131], v[132:135], v[160:163], v[128:131]
	v_mfma_f32_16x16x32_f16 v[124:127], v[140:143], v[160:163], v[124:127]
	v_mfma_f32_16x16x32_f16 v[112:115], v[132:135], v[168:171], v[112:115]
	v_mfma_f32_16x16x32_f16 v[108:111], v[140:143], v[168:171], v[108:111]
	v_mfma_f32_16x16x32_f16 v[96:99], v[132:135], v[176:179], v[96:99]
	v_mfma_f32_16x16x32_f16 v[92:95], v[140:143], v[176:179], v[92:95]
	v_mfma_f32_16x16x32_f16 v[80:83], v[132:135], v[184:187], v[80:83]
	v_mfma_f32_16x16x32_f16 v[76:79], v[140:143], v[184:187], v[76:79]
	v_mfma_f32_16x16x32_f16 v[128:131], v[136:139], v[164:167], v[128:131]
	v_mfma_f32_16x16x32_f16 v[124:127], v[144:147], v[164:167], v[124:127]
	v_mfma_f32_16x16x32_f16 v[112:115], v[136:139], v[172:175], v[112:115]
	v_mfma_f32_16x16x32_f16 v[108:111], v[144:147], v[172:175], v[108:111]
	v_mfma_f32_16x16x32_f16 v[96:99], v[136:139], v[180:183], v[96:99]
	v_mfma_f32_16x16x32_f16 v[92:95], v[144:147], v[180:183], v[92:95]
	v_mfma_f32_16x16x32_f16 v[80:83], v[136:139], v[188:191], v[80:83]
	v_mfma_f32_16x16x32_f16 v[76:79], v[144:147], v[188:191], v[76:79]
	s_barrier
	s_add_i32 s42, 0, 0x1c000
	s_add_i32 s36, s47, s5
	v_add_u32_e32 v206, s42, v158
	v_lshl_add_u64 v[154:155], v[154:155], 0, s[88:89]
	s_mov_b32 m0, s36
	ds_read_b128 v[192:195], v206
	ds_read_b128 v[196:199], v206 offset:1024
	ds_read_b128 v[200:203], v206 offset:2048
	ds_read_b128 v[206:209], v206 offset:3072
	global_load_lds_dwordx4 v[154:155], off
	v_lshl_add_u64 v[154:155], v[210:211], 0, s[88:89]
	s_add_i32 m0, s36, 0x2000
	s_nop 0
	global_load_lds_dwordx4 v[154:155], off
	s_barrier
	s_waitcnt lgkmcnt(0)
	v_mfma_f32_16x16x32_f16 v[120:123], v[192:195], v[160:163], v[120:123]
	v_mfma_f32_16x16x32_f16 v[116:119], v[200:203], v[160:163], v[116:119]
	v_mfma_f32_16x16x32_f16 v[104:107], v[192:195], v[168:171], v[104:107]
	v_mfma_f32_16x16x32_f16 v[100:103], v[200:203], v[168:171], v[100:103]
	v_mfma_f32_16x16x32_f16 v[88:91], v[192:195], v[176:179], v[88:91]
	v_mfma_f32_16x16x32_f16 v[84:87], v[200:203], v[176:179], v[84:87]
	v_mfma_f32_16x16x32_f16 v[72:75], v[192:195], v[184:187], v[72:75]
	v_mfma_f32_16x16x32_f16 v[68:71], v[200:203], v[184:187], v[68:71]
	v_mfma_f32_16x16x32_f16 v[120:123], v[196:199], v[164:167], v[120:123]
	v_mfma_f32_16x16x32_f16 v[116:119], v[206:209], v[164:167], v[116:119]
	v_mfma_f32_16x16x32_f16 v[104:107], v[196:199], v[172:175], v[104:107]
	v_mfma_f32_16x16x32_f16 v[100:103], v[206:209], v[172:175], v[100:103]
	v_mfma_f32_16x16x32_f16 v[88:91], v[196:199], v[180:183], v[88:91]
	v_mfma_f32_16x16x32_f16 v[84:87], v[206:209], v[180:183], v[84:87]
	v_mfma_f32_16x16x32_f16 v[72:75], v[196:199], v[188:191], v[72:75]
	v_mfma_f32_16x16x32_f16 v[68:71], v[206:209], v[188:191], v[68:71]
	s_mov_b32 m0, s10
	v_lshl_add_u64 v[154:155], v[212:213], 0, s[88:89]
	s_barrier
	ds_read_b128 v[160:163], v159 offset:49152
	ds_read_b128 v[164:167], v159 offset:50176
	ds_read_b128 v[168:171], v159 offset:51200
	ds_read_b128 v[172:175], v159 offset:52224
	ds_read_b128 v[176:179], v159 offset:53248
	ds_read_b128 v[180:183], v159 offset:54272
	ds_read_b128 v[184:187], v159 offset:55296
	ds_read_b128 v[188:191], v159 offset:56320
	global_load_lds_dwordx4 v[154:155], off
	v_lshl_add_u64 v[154:155], v[214:215], 0, s[88:89]
	s_mov_b32 m0, s11
	s_nop 0
	global_load_lds_dwordx4 v[154:155], off
	s_barrier
	s_waitcnt lgkmcnt(0)
	v_mfma_f32_16x16x32_f16 v[64:67], v[132:135], v[160:163], v[64:67]
	v_mfma_f32_16x16x32_f16 v[60:63], v[140:143], v[160:163], v[60:63]
	v_mfma_f32_16x16x32_f16 v[56:59], v[132:135], v[168:171], v[56:59]
	v_mfma_f32_16x16x32_f16 v[44:47], v[140:143], v[168:171], v[44:47]
	v_mfma_f32_16x16x32_f16 v[40:43], v[132:135], v[176:179], v[40:43]
	v_mfma_f32_16x16x32_f16 v[28:31], v[140:143], v[176:179], v[28:31]
	v_mfma_f32_16x16x32_f16 v[24:27], v[132:135], v[184:187], v[24:27]
	v_mfma_f32_16x16x32_f16 v[12:15], v[140:143], v[184:187], v[12:15]
	v_mfma_f32_16x16x32_f16 v[64:67], v[136:139], v[164:167], v[64:67]
	v_mfma_f32_16x16x32_f16 v[60:63], v[144:147], v[164:167], v[60:63]
	v_mfma_f32_16x16x32_f16 v[56:59], v[136:139], v[172:175], v[56:59]
	v_mfma_f32_16x16x32_f16 v[44:47], v[144:147], v[172:175], v[44:47]
	v_mfma_f32_16x16x32_f16 v[40:43], v[136:139], v[180:183], v[40:43]
	v_mfma_f32_16x16x32_f16 v[28:31], v[144:147], v[180:183], v[28:31]
	v_mfma_f32_16x16x32_f16 v[24:27], v[136:139], v[188:191], v[24:27]
	v_mfma_f32_16x16x32_f16 v[12:15], v[144:147], v[188:191], v[12:15]
	s_barrier
	s_add_u32 s36, s38, 0x160080
	s_addc_u32 s37, s39, 0
	s_add_i32 s38, s42, s5
	v_lshl_add_u64 v[132:133], s[36:37], 0, v[2:3]
	s_mov_b32 m0, s38
	s_nop 0
	global_load_lds_dwordx4 v[132:133], off
	v_lshl_add_u64 v[132:133], s[36:37], 0, v[148:149]
	s_add_i32 m0, s38, 0x2000
	s_nop 0
	global_load_lds_dwordx4 v[132:133], off
	s_waitcnt vmcnt(6)
	s_barrier
	v_mfma_f32_16x16x32_f16 v[52:55], v[192:195], v[160:163], v[52:55]
	v_mfma_f32_16x16x32_f16 v[48:51], v[200:203], v[160:163], v[48:51]
	v_mfma_f32_16x16x32_f16 v[36:39], v[192:195], v[168:171], v[36:39]
	v_mfma_f32_16x16x32_f16 v[32:35], v[200:203], v[168:171], v[32:35]
	v_mfma_f32_16x16x32_f16 v[20:23], v[192:195], v[176:179], v[20:23]
	v_mfma_f32_16x16x32_f16 v[16:19], v[200:203], v[176:179], v[16:19]
	v_mfma_f32_16x16x32_f16 v[8:11], v[192:195], v[184:187], v[8:11]
	v_mfma_f32_16x16x32_f16 v[4:7], v[200:203], v[184:187], v[4:7]
	v_mfma_f32_16x16x32_f16 v[52:55], v[196:199], v[164:167], v[52:55]
	v_mfma_f32_16x16x32_f16 v[48:51], v[206:209], v[164:167], v[48:51]
	v_mfma_f32_16x16x32_f16 v[36:39], v[196:199], v[172:175], v[36:39]
	v_mfma_f32_16x16x32_f16 v[32:35], v[206:209], v[172:175], v[32:35]
	v_mfma_f32_16x16x32_f16 v[20:23], v[196:199], v[180:183], v[20:23]
	v_mfma_f32_16x16x32_f16 v[16:19], v[206:209], v[180:183], v[16:19]
	v_mfma_f32_16x16x32_f16 v[8:11], v[196:199], v[188:191], v[8:11]
	v_mfma_f32_16x16x32_f16 v[4:7], v[206:209], v[188:191], v[4:7]
	s_add_i32 s46, s46, 2
	s_add_u32 s44, s44, 0x100
	s_addc_u32 s45, s45, 0
	s_cmp_gt_u32 s46, 5
	s_mov_b64 s[36:37], s[40:41]
	s_barrier
	s_cbranch_scc0 .LBB0_3048
	s_lshl_b32 s36, s30, 8
	v_mov_b32_e32 v160, v156
	v_mov_b32_e32 v132, v157
	s_and_b32 s36, s36, 0xff00
	s_or_b32 s36, s36, s12
	v_lshl_add_u32 v132, v132, 2, s36
	v_ashrrev_i32_e32 v133, 31, v132
	v_lshlrev_b64 v[154:155], 2, v[132:133]
	v_lshl_add_u64 v[132:133], s[16:17], 0, v[154:155]
	global_load_dwordx4 v[144:147], v[132:133], off
	global_load_dwordx4 v[140:143], v[132:133], off offset:64
	global_load_dwordx4 v[136:139], v[132:133], off offset:512
	s_nop 0
	global_load_dwordx4 v[132:135], v[132:133], off offset:576
	s_lshl_b32 s31, s31, 8
	s_ashr_i32 s30, s30, 8
	s_add_i32 s31, s13, s31
	v_add_u32_e32 v160, s31, v160
	s_ashr_i32 s31, s30, 31
	s_lshl_b64 s[30:31], s[30:31], 22
	v_readlane_b32 s36, v250, 27
	v_readlane_b32 s37, v250, 28
	s_add_u32 s30, s36, s30
	s_addc_u32 s31, s37, s31
	v_ashrrev_i32_e32 v161, 31, v160
	v_lshl_add_u64 v[154:155], s[30:31], 0, v[154:155]
	v_lshlrev_b64 v[160:161], 13, v[160:161]
	v_lshl_add_u64 v[154:155], v[154:155], 0, v[160:161]
	s_mov_b64 s[30:31], 0x20000
	s_mov_b64 s[38:39], s[26:27]
	s_mov_b64 s[36:37], s[18:19]
	s_waitcnt vmcnt(0)
	v_pk_mul_f32 v[130:131], v[130:131], v[146:147]
	v_pk_mul_f32 v[128:129], v[128:129], v[144:145]
	v_pk_mul_f32 v[54:55], v[54:55], v[138:139]
	v_pk_mul_f32 v[118:119], v[118:119], v[134:135]
	v_pk_mul_f32 v[116:117], v[116:117], v[132:133]
	global_store_dwordx4 v[154:155], v[116:119], off offset:576
	v_pk_mul_f32 v[102:103], v[102:103], v[134:135]
	v_pk_mul_f32 v[100:101], v[100:101], v[132:133]
	v_lshl_add_u64 v[116:117], v[154:155], 0, s[30:31]
	s_mov_b32 s30, 0x20000
	v_add_co_u32_e32 v118, vcc, s30, v154
	s_mov_b64 s[30:31], 0x40000
	s_nop 0
	v_addc_co_u32_e32 v119, vcc, 0, v155, vcc
	global_store_dwordx4 v[116:117], v[100:103], off offset:576
	v_pk_mul_f32 v[86:87], v[86:87], v[134:135]
	v_pk_mul_f32 v[84:85], v[84:85], v[132:133]
	v_lshl_add_u64 v[100:101], v[154:155], 0, s[30:31]
	s_mov_b32 s30, 0x40000
	v_add_co_u32_e32 v102, vcc, s30, v154
	s_mov_b64 s[30:31], 0x60000
	s_nop 0
	v_addc_co_u32_e32 v103, vcc, 0, v155, vcc
	global_store_dwordx4 v[100:101], v[84:87], off offset:576
	v_pk_mul_f32 v[70:71], v[70:71], v[134:135]
	v_pk_mul_f32 v[68:69], v[68:69], v[132:133]
	v_lshl_add_u64 v[84:85], v[154:155], 0, s[30:31]
	s_mov_b32 s30, 0x60000
	v_add_co_u32_e32 v86, vcc, s30, v154
	s_mov_b64 s[30:31], 0x100000
	s_nop 0
	v_addc_co_u32_e32 v87, vcc, 0, v155, vcc
	global_store_dwordx4 v[84:85], v[68:71], off offset:576
	v_pk_mul_f32 v[52:53], v[52:53], v[136:137]
	v_pk_mul_f32 v[38:39], v[38:39], v[138:139]
	v_lshl_add_u64 v[68:69], v[154:155], 0, s[30:31]
	s_mov_b32 s30, 0x100000
	v_add_co_u32_e32 v70, vcc, s30, v154
	s_mov_b64 s[30:31], 0x120000
	s_nop 0
	v_addc_co_u32_e32 v71, vcc, 0, v155, vcc
	global_store_dwordx4 v[68:69], v[52:55], off offset:512
	v_pk_mul_f32 v[36:37], v[36:37], v[136:137]
	v_pk_mul_f32 v[22:23], v[22:23], v[138:139]
	v_lshl_add_u64 v[52:53], v[154:155], 0, s[30:31]
	s_mov_b32 s30, 0x120000
	v_add_co_u32_e32 v54, vcc, s30, v154
	s_mov_b64 s[30:31], 0x140000
	s_nop 0
	v_addc_co_u32_e32 v55, vcc, 0, v155, vcc
	global_store_dwordx4 v[52:53], v[36:39], off offset:512
	v_pk_mul_f32 v[20:21], v[20:21], v[136:137]
	v_pk_mul_f32 v[50:51], v[50:51], v[134:135]
	v_lshl_add_u64 v[36:37], v[154:155], 0, s[30:31]
	s_mov_b32 s30, 0x140000
	v_add_co_u32_e32 v38, vcc, s30, v154
	s_mov_b64 s[30:31], 0x160000
	s_nop 0
	v_addc_co_u32_e32 v39, vcc, 0, v155, vcc
	global_store_dwordx4 v[36:37], v[20:23], off offset:512
	v_pk_mul_f32 v[48:49], v[48:49], v[132:133]
	v_pk_mul_f32 v[34:35], v[34:35], v[134:135]
	v_lshl_add_u64 v[20:21], v[154:155], 0, s[30:31]
	s_mov_b32 s30, 0x160000
	v_add_co_u32_e32 v22, vcc, s30, v154
	v_pk_mul_f32 v[32:33], v[32:33], v[132:133]
	v_pk_mul_f32 v[18:19], v[18:19], v[134:135]
	v_pk_mul_f32 v[16:17], v[16:17], v[132:133]
	v_addc_co_u32_e32 v23, vcc, 0, v155, vcc
	v_pk_mul_f32 v[126:127], v[126:127], v[142:143]
	v_pk_mul_f32 v[124:125], v[124:125], v[140:141]
	v_pk_mul_f32 v[122:123], v[122:123], v[138:139]
	v_pk_mul_f32 v[120:121], v[120:121], v[136:137]
	v_pk_mul_f32 v[114:115], v[114:115], v[146:147]
	v_pk_mul_f32 v[112:113], v[112:113], v[144:145]
	v_pk_mul_f32 v[110:111], v[110:111], v[142:143]
	v_pk_mul_f32 v[108:109], v[108:109], v[140:141]
	v_pk_mul_f32 v[106:107], v[106:107], v[138:139]
	v_pk_mul_f32 v[104:105], v[104:105], v[136:137]
	v_pk_mul_f32 v[98:99], v[98:99], v[146:147]
	v_pk_mul_f32 v[96:97], v[96:97], v[144:145]
	v_pk_mul_f32 v[94:95], v[94:95], v[142:143]
	v_pk_mul_f32 v[92:93], v[92:93], v[140:141]
	v_pk_mul_f32 v[90:91], v[90:91], v[138:139]
	v_pk_mul_f32 v[88:89], v[88:89], v[136:137]
	v_pk_mul_f32 v[82:83], v[82:83], v[146:147]
	v_pk_mul_f32 v[80:81], v[80:81], v[144:145]
	v_pk_mul_f32 v[78:79], v[78:79], v[142:143]
	v_pk_mul_f32 v[76:77], v[76:77], v[140:141]
	v_pk_mul_f32 v[74:75], v[74:75], v[138:139]
	v_pk_mul_f32 v[72:73], v[72:73], v[136:137]
	v_pk_mul_f32 v[66:67], v[66:67], v[146:147]
	v_pk_mul_f32 v[64:65], v[64:65], v[144:145]
	v_pk_mul_f32 v[62:63], v[62:63], v[142:143]
	v_pk_mul_f32 v[60:61], v[60:61], v[140:141]
	global_store_dwordx4 v[68:69], v[48:51], off offset:576
	v_pk_mul_f32 v[46:47], v[46:47], v[142:143]
	v_pk_mul_f32 v[44:45], v[44:45], v[140:141]
	v_pk_mul_f32 v[50:51], v[58:59], v[146:147]
	v_pk_mul_f32 v[48:49], v[56:57], v[144:145]
	global_store_dwordx4 v[52:53], v[32:35], off offset:576
	v_pk_mul_f32 v[30:31], v[30:31], v[142:143]
	v_pk_mul_f32 v[28:29], v[28:29], v[140:141]
	v_pk_mul_f32 v[34:35], v[42:43], v[146:147]
	v_pk_mul_f32 v[32:33], v[40:41], v[144:145]
	global_store_dwordx4 v[36:37], v[16:19], off offset:576
	v_pk_mul_f32 v[14:15], v[14:15], v[142:143]
	v_pk_mul_f32 v[12:13], v[12:13], v[140:141]
	v_pk_mul_f32 v[18:19], v[26:27], v[146:147]
	v_pk_mul_f32 v[16:17], v[24:25], v[144:145]
	v_pk_mul_f32 v[10:11], v[10:11], v[138:139]
	v_pk_mul_f32 v[8:9], v[8:9], v[136:137]
	v_pk_mul_f32 v[6:7], v[6:7], v[134:135]
	v_pk_mul_f32 v[4:5], v[4:5], v[132:133]
	s_and_b64 vcc, exec, s[34:35]
	s_mov_b32 s30, s29
	s_mov_b32 s31, s15
	global_store_dwordx4 v[154:155], v[128:131], off
	global_store_dwordx4 v[154:155], v[124:127], off offset:64
	global_store_dwordx4 v[154:155], v[120:123], off offset:512
	global_store_dwordx4 v[118:119], v[112:115], off
	global_store_dwordx4 v[116:117], v[108:111], off offset:64
	global_store_dwordx4 v[116:117], v[104:107], off offset:512
	global_store_dwordx4 v[102:103], v[96:99], off
	global_store_dwordx4 v[100:101], v[92:95], off offset:64
	global_store_dwordx4 v[100:101], v[88:91], off offset:512
	global_store_dwordx4 v[86:87], v[80:83], off
	global_store_dwordx4 v[84:85], v[76:79], off offset:64
	global_store_dwordx4 v[84:85], v[72:75], off offset:512
	global_store_dwordx4 v[70:71], v[64:67], off
	global_store_dwordx4 v[68:69], v[60:63], off offset:64
	global_store_dwordx4 v[54:55], v[48:51], off
	global_store_dwordx4 v[52:53], v[44:47], off offset:64
	global_store_dwordx4 v[38:39], v[32:35], off
	global_store_dwordx4 v[36:37], v[28:31], off offset:64
	global_store_dwordx4 v[22:23], v[16:19], off
	global_store_dwordx4 v[20:21], v[12:15], off offset:64
	global_store_dwordx4 v[20:21], v[8:11], off offset:512
	global_store_dwordx4 v[20:21], v[4:7], off offset:576
	s_cbranch_vccz .LBB0_3045
	s_waitcnt vmcnt(0)
	s_cmpk_gt_u32 s4, 0xff
	s_cbranch_scc1 .LBB0_3052
	s_barrier
